# GEMM K loops: waves 4-7 run a copy whose per-phase priority flips are 2/1 instead of 1/0 (static raise of one half, template flips kept)
# baseline (speedup 1.0000x reference)
; template <class Epi>
; __device__ __forceinline__ void gemm_phase(LAS unsigned char* lds, const Gemm g, const StaticOrder& S, const Epi& E) {
;     ...
;     for (;;) {
;         const bool has_next = S.next(ui + 1, nxt);
;         const char* nA = has_next ? (const char*)g.A + (size_t)nxt.pm * tstepA : cA; const char* nB = has_next ? (const char*)g.Bt + (size_t)nxt.pn * tstepB : cB;
;     ...
;         cur = nxt; cA = nA; cB = nB; ++ui;
.LBB0_201:
	s_and_b64 vcc, exec, s[0:1]
	s_mov_b32 s43, s10
	s_mov_b32 s18, s12
	s_mov_b64 s[22:23], s[16:17]
	s_mov_b64 s[20:21], s[14:15]
	s_cbranch_vccnz .LBB0_211
	s_branch .LBB0_202

; #define PG8_STAGE(bufoff, gbase, voff) do { _Pragma("unroll") for (int _i = 0; _i < 2; ++_i) \
;         __builtin_amdgcn_global_load_lds((const unsigned*)((const char*)(gbase) + (voff)[_i]), (LAS unsigned*)(lds + (bufoff) + ldsw + _i * 8192), 16, 0, 0); } while (0)
; #define PG8_LDA(dst, b, h) do { _Pragma("unroll") for (int m = 0; m < 4; ++m) _Pragma("unroll") for (int k = 0; k < 2; ++k) dst[m][k] = *(const LAS bf16x8*)(lds + PG8_SA(b, h) + aoff + m * 2048 + k * 1024); } while (0)
; #define PG8_LDB(dst, b, h) do { _Pragma("unroll") for (int n = 0; n < 2; ++n) _Pragma("unroll") for (int k = 0; k < 2; ++k) dst[n][k] = *(const LAS bf16x8*)(lds + PG8_SB(b, h) + boff + n * 2048 + k * 1024); } while (0)
; #define PG8_WAIT_V(n) asm volatile("s_waitcnt vmcnt(" #n ")" ::: "memory")
; #define PG8_WAIT_L(n) asm volatile("s_waitcnt lgkmcnt(" #n ")" ::: "memory")
; #define PG8_BAR __builtin_amdgcn_s_barrier()
; #define PG8_SCHED __builtin_amdgcn_sched_barrier(0)
; template <class Epi>
; __device__ __forceinline__ void gemm_phase(LAS unsigned char* lds, const Gemm g, const StaticOrder& S, const Epi& E) {
;     ...
;         const char* nA = has_next ? (const char*)g.A + (size_t)nxt.pm * tstepA : cA; const char* nB = has_next ? (const char*)g.Bt + (size_t)nxt.pn * tstepB : cB;
;         for (int t = 0; t < nt; t += 2) {
;             const bool last = (t == nt - 2);
;             const char* a1 = cA + (size_t)(t + 1) * kstep;
;             const char* a2 = last ? nA : cA + (size_t)(t + 2) * kstep; const char* b2 = last ? nB : cB + (size_t)(t + 2) * kstep;
;             const char* a3 = a2 + kstep; const char* b3 = b2 + kstep;
;             if (last) E.pre(cur, wr, fr, epre);
;             PG8_LDB(B0, 0, 0); PG8_SCHED; PG8_LDA(At, 0, 0); PG8_STAGE(PG8_SA(1, 1), a1 + hstepA, voffA);
;             PG8_WAIT_L(8); PG8_BAR; PG8_WAIT_L(0); PG8_MMA(0, 0, At, B0); PG8_BAR; PG8_SCHED;
;             PG8_LDB(B1, 0, 1); PG8_STAGE(PG8_SB(0, 0), b2, voffB);
;             PG8_BAR; PG8_WAIT_L(0); PG8_MMA(0, 1, At, B1); PG8_BAR;
;             PG8_LDA(At, 0, 1); PG8_STAGE(PG8_SA(0, 0), a2, voffA);
;             PG8_BAR; PG8_WAIT_L(0); PG8_MMA(1, 0, At, B0); PG8_BAR; PG8_SCHED;
;             PG8_STAGE(PG8_SB(0, 1), b2 + hstepB, voffB);
;             PG8_WAIT_V(6); PG8_BAR; PG8_MMA(1, 1, At, B1); PG8_BAR;
.Lkp0_204:
	s_ashr_i32 s13, s12, 31
	v_cmp_lt_i64_e32 vcc, s[14:15], v[142:143]
	s_lshl_b64 s[14:15], s[12:13], 19
	s_add_u32 s14, s76, s14
	s_addc_u32 s15, s77, s15
	s_and_b64 s[16:17], vcc, exec
	s_cselect_b32 s13, s15, s21
	s_cselect_b32 s19, s14, s20
	s_ashr_i32 s11, s10, 31
	s_lshl_b64 s[16:17], s[10:11], 19
	s_add_u32 s16, s74, s16
	s_addc_u32 s17, s75, s17
	s_and_b64 s[24:25], vcc, exec
	s_cselect_b32 s11, s17, s23
	s_cselect_b32 s44, s16, s22
	s_add_u32 s20, s20, 0x40080
	s_addc_u32 s21, s21, 0
	s_add_u32 s45, s22, 0x100
	s_addc_u32 s46, s23, 0
	s_mov_b32 s47, -2
	s_waitcnt lgkmcnt(0)
	ds_read_b128 v[146:149], v170
	ds_read_b128 v[154:157], v170 offset:1024
	ds_read_b128 v[158:161], v170 offset:2048
	ds_read_b128 v[162:165], v170 offset:3072
	s_add_u32 s22, s20, 0xfffc0080
	s_addc_u32 s23, s21, -1
	s_cmp_eq_u32 s47, 12
	s_cselect_b32 s25, s13, s23
	s_cselect_b32 s24, s19, s22
	s_cselect_b32 s23, s11, s46
	s_cselect_b32 s22, s44, s45
	v_lshl_add_u64 v[150:151], s[20:21], 0, v[138:139]
	s_add_i32 m0, s30, 0xc000
	ds_read_b128 v[174:177], v171
	ds_read_b128 v[178:181], v171 offset:1024
	ds_read_b128 v[182:185], v171 offset:2048
	ds_read_b128 v[186:189], v171 offset:3072
	ds_read_b128 v[190:193], v171 offset:4096
	ds_read_b128 v[194:197], v171 offset:5120
	ds_read_b128 v[198:201], v171 offset:6144
	ds_read_b128 v[202:205], v171 offset:7168
	global_load_lds_dwordx4 v[150:151], off
	v_lshl_add_u64 v[150:151], s[20:21], 0, v[140:141]
	s_add_i32 m0, s30, 0xe000
	s_nop 0
	global_load_lds_dwordx4 v[150:151], off
	s_waitcnt lgkmcnt(8)
	s_barrier
	s_waitcnt lgkmcnt(0)
	s_setprio 2
	s_waitcnt lgkmcnt(0)
	v_mfma_f32_16x16x32_bf16 v[76:79], v[146:149], v[174:177], 0
	v_mfma_f32_16x16x32_bf16 v[64:67], v[158:161], v[174:177], 0
	v_mfma_f32_16x16x32_bf16 v[60:63], v[146:149], v[182:185], 0
	v_mfma_f32_16x16x32_bf16 v[56:59], v[158:161], v[182:185], 0
	v_mfma_f32_16x16x32_bf16 v[48:51], v[146:149], v[190:193], 0
	v_mfma_f32_16x16x32_bf16 v[40:43], v[158:161], v[190:193], 0
	v_mfma_f32_16x16x32_bf16 v[36:39], v[146:149], v[198:201], 0
	v_mfma_f32_16x16x32_bf16 v[32:35], v[158:161], v[198:201], 0
	v_mfma_f32_16x16x32_bf16 v[76:79], v[154:157], v[178:181], v[76:79]
	v_mfma_f32_16x16x32_bf16 v[64:67], v[162:165], v[178:181], v[64:67]
	v_mfma_f32_16x16x32_bf16 v[60:63], v[154:157], v[186:189], v[60:63]
	v_mfma_f32_16x16x32_bf16 v[56:59], v[162:165], v[186:189], v[56:59]
	v_mfma_f32_16x16x32_bf16 v[48:51], v[154:157], v[194:197], v[48:51]
	v_mfma_f32_16x16x32_bf16 v[40:43], v[162:165], v[194:197], v[40:43]
	v_mfma_f32_16x16x32_bf16 v[36:39], v[154:157], v[202:205], v[36:39]
	v_mfma_f32_16x16x32_bf16 v[32:35], v[162:165], v[202:205], v[32:35]
	s_setprio 1
	s_barrier
	s_add_i32 s48, s39, s27
	v_lshl_add_u64 v[150:151], s[22:23], 0, v[132:133]
	s_mov_b32 m0, s48
	ds_read_b128 v[206:209], v172
	ds_read_b128 v[210:213], v172 offset:1024
	ds_read_b128 v[214:217], v172 offset:2048
	ds_read_b128 v[218:221], v172 offset:3072
	global_load_lds_dwordx4 v[150:151], off
	v_lshl_add_u64 v[166:167], s[22:23], 0, v[128:129]
	s_add_i32 m0, s48, 0x2000
	s_nop 0
	global_load_lds_dwordx4 v[166:167], off
	s_barrier
	s_waitcnt lgkmcnt(0)
	s_setprio 2
	s_waitcnt lgkmcnt(0)
	v_mfma_f32_16x16x32_bf16 v[124:127], v[206:209], v[174:177], 0
	v_mfma_f32_16x16x32_bf16 v[120:123], v[214:217], v[174:177], 0
	v_mfma_f32_16x16x32_bf16 v[116:119], v[206:209], v[182:185], 0
	v_mfma_f32_16x16x32_bf16 v[112:115], v[214:217], v[182:185], 0
	v_mfma_f32_16x16x32_bf16 v[108:111], v[206:209], v[190:193], 0
	v_mfma_f32_16x16x32_bf16 v[104:107], v[214:217], v[190:193], 0
	v_mfma_f32_16x16x32_bf16 v[100:103], v[206:209], v[198:201], 0
	v_mfma_f32_16x16x32_bf16 v[96:99], v[214:217], v[198:201], 0
	v_mfma_f32_16x16x32_bf16 v[124:127], v[210:213], v[178:181], v[124:127]
	v_mfma_f32_16x16x32_bf16 v[120:123], v[218:221], v[178:181], v[120:123]
	v_mfma_f32_16x16x32_bf16 v[116:119], v[210:213], v[186:189], v[116:119]
	v_mfma_f32_16x16x32_bf16 v[112:115], v[218:221], v[186:189], v[112:115]
	v_mfma_f32_16x16x32_bf16 v[108:111], v[210:213], v[194:197], v[108:111]
	v_mfma_f32_16x16x32_bf16 v[104:107], v[218:221], v[194:197], v[104:107]
	v_mfma_f32_16x16x32_bf16 v[100:103], v[210:213], v[202:205], v[100:103]
	v_mfma_f32_16x16x32_bf16 v[96:99], v[218:221], v[202:205], v[96:99]
	s_setprio 1
	s_mov_b32 m0, s30
	v_lshl_add_u64 v[222:223], s[24:25], 0, v[134:135]
	s_barrier
	ds_read_b128 v[174:177], v171 offset:16384
	ds_read_b128 v[178:181], v171 offset:17408
	ds_read_b128 v[182:185], v171 offset:18432
	ds_read_b128 v[186:189], v171 offset:19456
	ds_read_b128 v[190:193], v171 offset:20480
	ds_read_b128 v[194:197], v171 offset:21504
	ds_read_b128 v[198:201], v171 offset:22528
	ds_read_b128 v[202:205], v171 offset:23552
	global_load_lds_dwordx4 v[222:223], off
	v_lshl_add_u64 v[224:225], s[24:25], 0, v[130:131]
	s_mov_b32 m0, s31
	s_nop 0
	global_load_lds_dwordx4 v[224:225], off
	s_barrier
	s_waitcnt lgkmcnt(0)
	s_setprio 2
	s_waitcnt lgkmcnt(0)
	v_mfma_f32_16x16x32_bf16 v[28:31], v[146:149], v[174:177], 0
	v_mfma_f32_16x16x32_bf16 v[24:27], v[158:161], v[174:177], 0
	v_mfma_f32_16x16x32_bf16 v[20:23], v[146:149], v[182:185], 0
	v_mfma_f32_16x16x32_bf16 v[16:19], v[158:161], v[182:185], 0
	v_mfma_f32_16x16x32_bf16 v[12:15], v[146:149], v[190:193], 0
	v_mfma_f32_16x16x32_bf16 v[8:11], v[158:161], v[190:193], 0
	v_mfma_f32_16x16x32_bf16 v[4:7], v[146:149], v[198:201], 0
	v_mfma_f32_16x16x32_bf16 v[0:3], v[158:161], v[198:201], 0
	v_mfma_f32_16x16x32_bf16 v[28:31], v[154:157], v[178:181], v[28:31]
	v_mfma_f32_16x16x32_bf16 v[24:27], v[162:165], v[178:181], v[24:27]
	v_mfma_f32_16x16x32_bf16 v[20:23], v[154:157], v[186:189], v[20:23]
	v_mfma_f32_16x16x32_bf16 v[16:19], v[162:165], v[186:189], v[16:19]
	v_mfma_f32_16x16x32_bf16 v[12:15], v[154:157], v[194:197], v[12:15]
	v_mfma_f32_16x16x32_bf16 v[8:11], v[162:165], v[194:197], v[8:11]
	v_mfma_f32_16x16x32_bf16 v[4:7], v[154:157], v[202:205], v[4:7]
	v_mfma_f32_16x16x32_bf16 v[0:3], v[162:165], v[202:205], v[0:3]
	s_setprio 1
	s_barrier
; #define PG8_STAGE(bufoff, gbase, voff) do { _Pragma("unroll") for (int _i = 0; _i < 2; ++_i) \
;         __builtin_amdgcn_global_load_lds((const unsigned*)((const char*)(gbase) + (voff)[_i]), (LAS unsigned*)(lds + (bufoff) + ldsw + _i * 8192), 16, 0, 0); } while (0)
; #define PG8_LDA(dst, b, h) do { _Pragma("unroll") for (int m = 0; m < 4; ++m) _Pragma("unroll") for (int k = 0; k < 2; ++k) dst[m][k] = *(const LAS bf16x8*)(lds + PG8_SA(b, h) + aoff + m * 2048 + k * 1024); } while (0)
; #define PG8_LDB(dst, b, h) do { _Pragma("unroll") for (int n = 0; n < 2; ++n) _Pragma("unroll") for (int k = 0; k < 2; ++k) dst[n][k] = *(const LAS bf16x8*)(lds + PG8_SB(b, h) + boff + n * 2048 + k * 1024); } while (0)
; #define PG8_MMA(ai, bj, At, Bt) do { __builtin_amdgcn_s_setprio(1); _Pragma("unroll") for (int m = 0; m < 4; ++m) _Pragma("unroll") for (int n = 0; n < 2; ++n) _Pragma("unroll") for (int k = 0; k < 2; ++k) \
;         acc[ai][bj][m][n] = __builtin_amdgcn_mfma_f32_16x16x32_bf16(Bt[n][k], At[m][k], acc[ai][bj][m][n], 0, 0, 0); __builtin_amdgcn_s_setprio(0); } while (0)
; #define PG8_WAIT_V(n) asm volatile("s_waitcnt vmcnt(" #n ")" ::: "memory")
; #define PG8_WAIT_L(n) asm volatile("s_waitcnt lgkmcnt(" #n ")" ::: "memory")
; #define PG8_BAR __builtin_amdgcn_s_barrier()
; #define PG8_SCHED __builtin_amdgcn_sched_barrier(0)
; template <class Epi>
; __device__ __forceinline__ void gemm_phase(LAS unsigned char* lds, const Gemm g, const StaticOrder& S, const Epi& E) {
;     ...
;             PG8_STAGE(PG8_SB(0, 1), b2 + hstepB, voffB);
;             PG8_WAIT_V(6); PG8_BAR; PG8_MMA(1, 1, At, B1); PG8_BAR;
;             PG8_LDB(B0, 1, 0); PG8_SCHED; PG8_LDA(At, 1, 0); PG8_STAGE(PG8_SA(0, 1), a2 + hstepA, voffA);
;             PG8_WAIT_L(8); PG8_BAR; PG8_WAIT_L(0); PG8_MMA(0, 0, At, B0); PG8_BAR; PG8_SCHED;
;             PG8_LDB(B1, 1, 1); PG8_STAGE(PG8_SB(1, 0), b3, voffB);
;             PG8_BAR; PG8_WAIT_L(0); PG8_MMA(0, 1, At, B1); PG8_BAR;
;             PG8_LDA(At, 1, 1); PG8_STAGE(PG8_SA(1, 0), a3, voffA);
;             PG8_BAR; PG8_WAIT_L(0); PG8_MMA(1, 0, At, B0); PG8_BAR; PG8_SCHED;
;             PG8_STAGE(PG8_SB(1, 1), b3 + hstepB, voffB);
;             PG8_WAIT_V(6); PG8_BAR; PG8_MMA(1, 1, At, B1); PG8_BAR;
	s_add_u32 s48, s22, 0x40000
	s_addc_u32 s49, s23, 0
	s_add_i32 s50, s40, s27
	v_lshl_add_u64 v[146:147], s[48:49], 0, v[132:133]
	s_mov_b32 m0, s50
	s_nop 0
	global_load_lds_dwordx4 v[146:147], off
	v_lshl_add_u64 v[146:147], s[48:49], 0, v[128:129]
	s_add_i32 m0, s50, 0x2000
	s_nop 0
	global_load_lds_dwordx4 v[146:147], off
	s_waitcnt vmcnt(6)
	s_barrier
	s_setprio 2
	v_mfma_f32_16x16x32_bf16 v[92:95], v[206:209], v[174:177], 0
	v_mfma_f32_16x16x32_bf16 v[88:91], v[214:217], v[174:177], 0
	v_mfma_f32_16x16x32_bf16 v[84:87], v[206:209], v[182:185], 0
	v_mfma_f32_16x16x32_bf16 v[80:83], v[214:217], v[182:185], 0
	v_mfma_f32_16x16x32_bf16 v[72:75], v[206:209], v[190:193], 0
	v_mfma_f32_16x16x32_bf16 v[68:71], v[214:217], v[190:193], 0
	v_mfma_f32_16x16x32_bf16 v[52:55], v[206:209], v[198:201], 0
	v_mfma_f32_16x16x32_bf16 v[44:47], v[214:217], v[198:201], 0
	v_mfma_f32_16x16x32_bf16 v[92:95], v[210:213], v[178:181], v[92:95]
	v_mfma_f32_16x16x32_bf16 v[88:91], v[218:221], v[178:181], v[88:91]
	v_mfma_f32_16x16x32_bf16 v[84:87], v[210:213], v[186:189], v[84:87]
	v_mfma_f32_16x16x32_bf16 v[80:83], v[218:221], v[186:189], v[80:83]
	v_mfma_f32_16x16x32_bf16 v[72:75], v[210:213], v[194:197], v[72:75]
	v_mfma_f32_16x16x32_bf16 v[68:71], v[218:221], v[194:197], v[68:71]
	v_mfma_f32_16x16x32_bf16 v[52:55], v[210:213], v[202:205], v[52:55]
	v_mfma_f32_16x16x32_bf16 v[44:47], v[218:221], v[202:205], v[44:47]
	s_setprio 1
	s_add_i32 s48, 0, 0x18000
	v_add_u32_e32 v162, s48, v168
	s_barrier
	ds_read_b128 v[146:149], v162
	ds_read_b128 v[154:157], v162 offset:1024
	ds_read_b128 v[158:161], v162 offset:2048
	ds_read_b128 v[162:165], v162 offset:3072
	s_add_u32 s24, s24, 0x40000
	s_addc_u32 s25, s25, 0
	s_mov_b32 m0, s33
	v_lshl_add_u64 v[206:207], s[24:25], 0, v[134:135]
	ds_read_b128 v[174:177], v171 offset:32768
	ds_read_b128 v[178:181], v171 offset:33792
	ds_read_b128 v[182:185], v171 offset:34816
	ds_read_b128 v[186:189], v171 offset:35840
	ds_read_b128 v[190:193], v171 offset:36864
	ds_read_b128 v[194:197], v171 offset:37888
	ds_read_b128 v[198:201], v171 offset:38912
	ds_read_b128 v[202:205], v171 offset:39936
	global_load_lds_dwordx4 v[206:207], off
	v_lshl_add_u64 v[206:207], s[24:25], 0, v[130:131]
	s_mov_b32 m0, s34
	s_nop 0
	global_load_lds_dwordx4 v[206:207], off
	s_waitcnt lgkmcnt(8)
	s_barrier
	s_waitcnt lgkmcnt(0)
	s_setprio 2
	s_waitcnt lgkmcnt(0)
	v_mfma_f32_16x16x32_bf16 v[76:79], v[146:149], v[174:177], v[76:79]
	v_mfma_f32_16x16x32_bf16 v[64:67], v[158:161], v[174:177], v[64:67]
	v_mfma_f32_16x16x32_bf16 v[60:63], v[146:149], v[182:185], v[60:63]
	v_mfma_f32_16x16x32_bf16 v[56:59], v[158:161], v[182:185], v[56:59]
	v_mfma_f32_16x16x32_bf16 v[48:51], v[146:149], v[190:193], v[48:51]
	v_mfma_f32_16x16x32_bf16 v[40:43], v[158:161], v[190:193], v[40:43]
	v_mfma_f32_16x16x32_bf16 v[36:39], v[146:149], v[198:201], v[36:39]
	v_mfma_f32_16x16x32_bf16 v[32:35], v[158:161], v[198:201], v[32:35]
	v_mfma_f32_16x16x32_bf16 v[76:79], v[154:157], v[178:181], v[76:79]
	v_mfma_f32_16x16x32_bf16 v[64:67], v[162:165], v[178:181], v[64:67]
	v_mfma_f32_16x16x32_bf16 v[60:63], v[154:157], v[186:189], v[60:63]
	v_mfma_f32_16x16x32_bf16 v[56:59], v[162:165], v[186:189], v[56:59]
	v_mfma_f32_16x16x32_bf16 v[48:51], v[154:157], v[194:197], v[48:51]
	v_mfma_f32_16x16x32_bf16 v[40:43], v[162:165], v[194:197], v[40:43]
	v_mfma_f32_16x16x32_bf16 v[36:39], v[154:157], v[202:205], v[36:39]
	v_mfma_f32_16x16x32_bf16 v[32:35], v[162:165], v[202:205], v[32:35]
	s_setprio 1
	s_barrier
	s_add_i32 s24, 0, 0x1c000
	s_add_i32 s25, s48, s27
	v_add_u32_e32 v218, s24, v168
	v_lshl_add_u64 v[150:151], v[150:151], 0, s[6:7]
	s_mov_b32 m0, s25
	ds_read_b128 v[206:209], v218
	ds_read_b128 v[210:213], v218 offset:1024
	ds_read_b128 v[214:217], v218 offset:2048
	ds_read_b128 v[218:221], v218 offset:3072
	global_load_lds_dwordx4 v[150:151], off
	v_lshl_add_u64 v[150:151], v[166:167], 0, s[6:7]
	s_add_i32 m0, s25, 0x2000
	s_nop 0
	global_load_lds_dwordx4 v[150:151], off
	s_barrier
	s_waitcnt lgkmcnt(0)
	s_setprio 2
	s_waitcnt lgkmcnt(0)
	v_mfma_f32_16x16x32_bf16 v[124:127], v[206:209], v[174:177], v[124:127]
	v_mfma_f32_16x16x32_bf16 v[120:123], v[214:217], v[174:177], v[120:123]
	v_mfma_f32_16x16x32_bf16 v[116:119], v[206:209], v[182:185], v[116:119]
	v_mfma_f32_16x16x32_bf16 v[112:115], v[214:217], v[182:185], v[112:115]
	v_mfma_f32_16x16x32_bf16 v[108:111], v[206:209], v[190:193], v[108:111]
	v_mfma_f32_16x16x32_bf16 v[104:107], v[214:217], v[190:193], v[104:107]
	v_mfma_f32_16x16x32_bf16 v[100:103], v[206:209], v[198:201], v[100:103]
	v_mfma_f32_16x16x32_bf16 v[96:99], v[214:217], v[198:201], v[96:99]
	v_mfma_f32_16x16x32_bf16 v[124:127], v[210:213], v[178:181], v[124:127]
	v_mfma_f32_16x16x32_bf16 v[120:123], v[218:221], v[178:181], v[120:123]
	v_mfma_f32_16x16x32_bf16 v[116:119], v[210:213], v[186:189], v[116:119]
	v_mfma_f32_16x16x32_bf16 v[112:115], v[218:221], v[186:189], v[112:115]
	v_mfma_f32_16x16x32_bf16 v[108:111], v[210:213], v[194:197], v[108:111]
	v_mfma_f32_16x16x32_bf16 v[104:107], v[218:221], v[194:197], v[104:107]
	v_mfma_f32_16x16x32_bf16 v[100:103], v[210:213], v[202:205], v[100:103]
	v_mfma_f32_16x16x32_bf16 v[96:99], v[218:221], v[202:205], v[96:99]
	s_setprio 1
	s_mov_b32 m0, s36
	v_lshl_add_u64 v[150:151], v[222:223], 0, s[6:7]
	s_barrier
	ds_read_b128 v[174:177], v171 offset:49152
	ds_read_b128 v[178:181], v171 offset:50176
	ds_read_b128 v[182:185], v171 offset:51200
	ds_read_b128 v[186:189], v171 offset:52224
	ds_read_b128 v[190:193], v171 offset:53248
	ds_read_b128 v[194:197], v171 offset:54272
	ds_read_b128 v[198:201], v171 offset:55296
	ds_read_b128 v[202:205], v171 offset:56320
	global_load_lds_dwordx4 v[150:151], off
	v_lshl_add_u64 v[150:151], v[224:225], 0, s[6:7]
	s_mov_b32 m0, s37
	s_nop 0
	global_load_lds_dwordx4 v[150:151], off
	s_barrier
; #define PG8_STAGE(bufoff, gbase, voff) do { _Pragma("unroll") for (int _i = 0; _i < 2; ++_i) \
;         __builtin_amdgcn_global_load_lds((const unsigned*)((const char*)(gbase) + (voff)[_i]), (LAS unsigned*)(lds + (bufoff) + ldsw + _i * 8192), 16, 0, 0); } while (0)
; #define PG8_LDA(dst, b, h) do { _Pragma("unroll") for (int m = 0; m < 4; ++m) _Pragma("unroll") for (int k = 0; k < 2; ++k) dst[m][k] = *(const LAS bf16x8*)(lds + PG8_SA(b, h) + aoff + m * 2048 + k * 1024); } while (0)
; #define PG8_WAIT_V(n) asm volatile("s_waitcnt vmcnt(" #n ")" ::: "memory")
; template <class Epi>
; __device__ __forceinline__ void gemm_phase(LAS unsigned char* lds, const Gemm g, const StaticOrder& S, const Epi& E) {
;     ...
;         for (int t = 0; t < nt; t += 2) {
;             const bool last = (t == nt - 2);
;             const char* a1 = cA + (size_t)(t + 1) * kstep;
;             const char* a2 = last ? nA : cA + (size_t)(t + 2) * kstep; const char* b2 = last ? nB : cB + (size_t)(t + 2) * kstep;
;             const char* a3 = a2 + kstep; const char* b3 = b2 + kstep;
;             if (last) E.pre(cur, wr, fr, epre);
;             PG8_LDB(B0, 0, 0); PG8_SCHED; PG8_LDA(At, 0, 0); PG8_STAGE(PG8_SA(1, 1), a1 + hstepA, voffA);
;             PG8_WAIT_L(8); PG8_BAR; PG8_WAIT_L(0); PG8_MMA(0, 0, At, B0); PG8_BAR; PG8_SCHED;
;             PG8_LDB(B1, 0, 1); PG8_STAGE(PG8_SB(0, 0), b2, voffB);
;             PG8_BAR; PG8_WAIT_L(0); PG8_MMA(0, 1, At, B1); PG8_BAR;
;             PG8_LDA(At, 0, 1); PG8_STAGE(PG8_SA(0, 0), a2, voffA);
;             PG8_BAR; PG8_WAIT_L(0); PG8_MMA(1, 0, At, B0); PG8_BAR; PG8_SCHED;
;             PG8_STAGE(PG8_SB(0, 1), b2 + hstepB, voffB);
;             PG8_WAIT_V(6); PG8_BAR; PG8_MMA(1, 1, At, B1); PG8_BAR;
;             PG8_LDB(B0, 1, 0); PG8_SCHED; PG8_LDA(At, 1, 0); PG8_STAGE(PG8_SA(0, 1), a2 + hstepA, voffA);
;             PG8_WAIT_L(8); PG8_BAR; PG8_WAIT_L(0); PG8_MMA(0, 0, At, B0); PG8_BAR; PG8_SCHED;
;             PG8_LDB(B1, 1, 1); PG8_STAGE(PG8_SB(1, 0), b3, voffB);
;             PG8_BAR; PG8_WAIT_L(0); PG8_MMA(0, 1, At, B1); PG8_BAR;
;             PG8_LDA(At, 1, 1); PG8_STAGE(PG8_SA(1, 0), a3, voffA);
;             PG8_BAR; PG8_WAIT_L(0); PG8_MMA(1, 0, At, B0); PG8_BAR; PG8_SCHED;
;             PG8_STAGE(PG8_SB(1, 1), b3 + hstepB, voffB);
;             PG8_WAIT_V(6); PG8_BAR; PG8_MMA(1, 1, At, B1); PG8_BAR;
	s_waitcnt lgkmcnt(0)
	s_setprio 2
	s_waitcnt lgkmcnt(0)
	v_mfma_f32_16x16x32_bf16 v[28:31], v[146:149], v[174:177], v[28:31]
	v_mfma_f32_16x16x32_bf16 v[24:27], v[158:161], v[174:177], v[24:27]
	v_mfma_f32_16x16x32_bf16 v[20:23], v[146:149], v[182:185], v[20:23]
	v_mfma_f32_16x16x32_bf16 v[16:19], v[158:161], v[182:185], v[16:19]
	v_mfma_f32_16x16x32_bf16 v[12:15], v[146:149], v[190:193], v[12:15]
	v_mfma_f32_16x16x32_bf16 v[8:11], v[158:161], v[190:193], v[8:11]
	v_mfma_f32_16x16x32_bf16 v[4:7], v[146:149], v[198:201], v[4:7]
	v_mfma_f32_16x16x32_bf16 v[0:3], v[158:161], v[198:201], v[0:3]
	v_mfma_f32_16x16x32_bf16 v[28:31], v[154:157], v[178:181], v[28:31]
	v_mfma_f32_16x16x32_bf16 v[24:27], v[162:165], v[178:181], v[24:27]
	v_mfma_f32_16x16x32_bf16 v[20:23], v[154:157], v[186:189], v[20:23]
	v_mfma_f32_16x16x32_bf16 v[16:19], v[162:165], v[186:189], v[16:19]
	v_mfma_f32_16x16x32_bf16 v[12:15], v[154:157], v[194:197], v[12:15]
	v_mfma_f32_16x16x32_bf16 v[8:11], v[162:165], v[194:197], v[8:11]
	v_mfma_f32_16x16x32_bf16 v[4:7], v[154:157], v[202:205], v[4:7]
	v_mfma_f32_16x16x32_bf16 v[0:3], v[162:165], v[202:205], v[0:3]
	s_setprio 1
	s_barrier
	s_add_u32 s22, s22, 0x40080
	s_addc_u32 s23, s23, 0
	s_add_i32 s24, s24, s27
	v_lshl_add_u64 v[146:147], s[22:23], 0, v[132:133]
	s_mov_b32 m0, s24
	s_nop 0
	global_load_lds_dwordx4 v[146:147], off
	v_lshl_add_u64 v[146:147], s[22:23], 0, v[128:129]
	s_add_i32 m0, s24, 0x2000
	s_nop 0
	global_load_lds_dwordx4 v[146:147], off
	s_waitcnt vmcnt(6)
	s_barrier
	s_setprio 2
	v_mfma_f32_16x16x32_bf16 v[92:95], v[206:209], v[174:177], v[92:95]
	v_mfma_f32_16x16x32_bf16 v[88:91], v[214:217], v[174:177], v[88:91]
	v_mfma_f32_16x16x32_bf16 v[84:87], v[206:209], v[182:185], v[84:87]
	v_mfma_f32_16x16x32_bf16 v[80:83], v[214:217], v[182:185], v[80:83]
	v_mfma_f32_16x16x32_bf16 v[72:75], v[206:209], v[190:193], v[72:75]
	v_mfma_f32_16x16x32_bf16 v[68:71], v[214:217], v[190:193], v[68:71]
	v_mfma_f32_16x16x32_bf16 v[52:55], v[206:209], v[198:201], v[52:55]
	v_mfma_f32_16x16x32_bf16 v[44:47], v[214:217], v[198:201], v[44:47]
	v_mfma_f32_16x16x32_bf16 v[92:95], v[210:213], v[178:181], v[92:95]
	v_mfma_f32_16x16x32_bf16 v[88:91], v[218:221], v[178:181], v[88:91]
	v_mfma_f32_16x16x32_bf16 v[84:87], v[210:213], v[186:189], v[84:87]
	v_mfma_f32_16x16x32_bf16 v[80:83], v[218:221], v[186:189], v[80:83]
	v_mfma_f32_16x16x32_bf16 v[72:75], v[210:213], v[194:197], v[72:75]
	v_mfma_f32_16x16x32_bf16 v[68:71], v[218:221], v[194:197], v[68:71]
	v_mfma_f32_16x16x32_bf16 v[52:55], v[210:213], v[202:205], v[52:55]
	v_mfma_f32_16x16x32_bf16 v[44:47], v[218:221], v[202:205], v[44:47]
	s_setprio 1
	s_add_i32 s47, s47, 2
	s_add_u32 s20, s20, 0x100
	s_addc_u32 s21, s21, 0
	s_add_u32 s45, s45, 0x100
	s_addc_u32 s46, s46, 0
	s_cmp_gt_u32 s47, 13
	s_barrier
.Lkp0_205:
	ds_read_b128 v[146:149], v170
	ds_read_b128 v[154:157], v170 offset:1024
	ds_read_b128 v[158:161], v170 offset:2048
	ds_read_b128 v[162:165], v170 offset:3072
	s_add_u32 s22, s20, 0xfffc0080
	s_addc_u32 s23, s21, -1
	s_cmp_eq_u32 s47, 12
	s_cselect_b32 s25, s13, s23
	s_cselect_b32 s24, s19, s22
	s_cselect_b32 s23, s11, s46
	s_cselect_b32 s22, s44, s45
	v_lshl_add_u64 v[150:151], s[20:21], 0, v[138:139]
	s_add_i32 m0, s30, 0xc000
	ds_read_b128 v[174:177], v171
	ds_read_b128 v[178:181], v171 offset:1024
	ds_read_b128 v[182:185], v171 offset:2048
	ds_read_b128 v[186:189], v171 offset:3072
	ds_read_b128 v[190:193], v171 offset:4096
	ds_read_b128 v[194:197], v171 offset:5120
	ds_read_b128 v[198:201], v171 offset:6144
	ds_read_b128 v[202:205], v171 offset:7168
	global_load_lds_dwordx4 v[150:151], off
	v_lshl_add_u64 v[150:151], s[20:21], 0, v[140:141]
	s_add_i32 m0, s30, 0xe000
	s_nop 0
	global_load_lds_dwordx4 v[150:151], off
	s_waitcnt lgkmcnt(8)
	s_barrier
	s_waitcnt lgkmcnt(0)
	s_setprio 2
	s_waitcnt lgkmcnt(0)
	v_mfma_f32_16x16x32_bf16 v[76:79], v[146:149], v[174:177], v[76:79]
	v_mfma_f32_16x16x32_bf16 v[64:67], v[158:161], v[174:177], v[64:67]
	v_mfma_f32_16x16x32_bf16 v[60:63], v[146:149], v[182:185], v[60:63]
	v_mfma_f32_16x16x32_bf16 v[56:59], v[158:161], v[182:185], v[56:59]
	v_mfma_f32_16x16x32_bf16 v[48:51], v[146:149], v[190:193], v[48:51]
	v_mfma_f32_16x16x32_bf16 v[40:43], v[158:161], v[190:193], v[40:43]
	v_mfma_f32_16x16x32_bf16 v[36:39], v[146:149], v[198:201], v[36:39]
	v_mfma_f32_16x16x32_bf16 v[32:35], v[158:161], v[198:201], v[32:35]
	v_mfma_f32_16x16x32_bf16 v[76:79], v[154:157], v[178:181], v[76:79]
	v_mfma_f32_16x16x32_bf16 v[64:67], v[162:165], v[178:181], v[64:67]
	v_mfma_f32_16x16x32_bf16 v[60:63], v[154:157], v[186:189], v[60:63]
	v_mfma_f32_16x16x32_bf16 v[56:59], v[162:165], v[186:189], v[56:59]
	v_mfma_f32_16x16x32_bf16 v[48:51], v[154:157], v[194:197], v[48:51]
	v_mfma_f32_16x16x32_bf16 v[40:43], v[162:165], v[194:197], v[40:43]
	v_mfma_f32_16x16x32_bf16 v[36:39], v[154:157], v[202:205], v[36:39]
	v_mfma_f32_16x16x32_bf16 v[32:35], v[162:165], v[202:205], v[32:35]
	s_setprio 1
	s_barrier
	s_add_i32 s48, s39, s27
	v_lshl_add_u64 v[150:151], s[22:23], 0, v[132:133]
	s_mov_b32 m0, s48
	ds_read_b128 v[206:209], v172
	ds_read_b128 v[210:213], v172 offset:1024
	ds_read_b128 v[214:217], v172 offset:2048
	ds_read_b128 v[218:221], v172 offset:3072
	global_load_lds_dwordx4 v[150:151], off
	v_lshl_add_u64 v[166:167], s[22:23], 0, v[128:129]
	s_add_i32 m0, s48, 0x2000
	s_nop 0
	global_load_lds_dwordx4 v[166:167], off
	s_barrier
; #define PG8_STAGE(bufoff, gbase, voff) do { _Pragma("unroll") for (int _i = 0; _i < 2; ++_i) \
;         __builtin_amdgcn_global_load_lds((const unsigned*)((const char*)(gbase) + (voff)[_i]), (LAS unsigned*)(lds + (bufoff) + ldsw + _i * 8192), 16, 0, 0); } while (0)
; #define PG8_LDA(dst, b, h) do { _Pragma("unroll") for (int m = 0; m < 4; ++m) _Pragma("unroll") for (int k = 0; k < 2; ++k) dst[m][k] = *(const LAS bf16x8*)(lds + PG8_SA(b, h) + aoff + m * 2048 + k * 1024); } while (0)
; #define PG8_LDB(dst, b, h) do { _Pragma("unroll") for (int n = 0; n < 2; ++n) _Pragma("unroll") for (int k = 0; k < 2; ++k) dst[n][k] = *(const LAS bf16x8*)(lds + PG8_SB(b, h) + boff + n * 2048 + k * 1024); } while (0)
; #define PG8_MMA(ai, bj, At, Bt) do { __builtin_amdgcn_s_setprio(1); _Pragma("unroll") for (int m = 0; m < 4; ++m) _Pragma("unroll") for (int n = 0; n < 2; ++n) _Pragma("unroll") for (int k = 0; k < 2; ++k) \
;         acc[ai][bj][m][n] = __builtin_amdgcn_mfma_f32_16x16x32_bf16(Bt[n][k], At[m][k], acc[ai][bj][m][n], 0, 0, 0); __builtin_amdgcn_s_setprio(0); } while (0)
; #define PG8_WAIT_V(n) asm volatile("s_waitcnt vmcnt(" #n ")" ::: "memory")
; #define PG8_WAIT_L(n) asm volatile("s_waitcnt lgkmcnt(" #n ")" ::: "memory")
; #define PG8_BAR __builtin_amdgcn_s_barrier()
; #define PG8_SCHED __builtin_amdgcn_sched_barrier(0)
; template <class Epi>
; __device__ __forceinline__ void gemm_phase(LAS unsigned char* lds, const Gemm g, const StaticOrder& S, const Epi& E) {
;     ...
;             PG8_BAR; PG8_WAIT_L(0); PG8_MMA(0, 1, At, B1); PG8_BAR;
;             PG8_LDA(At, 0, 1); PG8_STAGE(PG8_SA(0, 0), a2, voffA);
;             PG8_BAR; PG8_WAIT_L(0); PG8_MMA(1, 0, At, B0); PG8_BAR; PG8_SCHED;
;             PG8_STAGE(PG8_SB(0, 1), b2 + hstepB, voffB);
;             PG8_WAIT_V(6); PG8_BAR; PG8_MMA(1, 1, At, B1); PG8_BAR;
;             PG8_LDB(B0, 1, 0); PG8_SCHED; PG8_LDA(At, 1, 0); PG8_STAGE(PG8_SA(0, 1), a2 + hstepA, voffA);
	s_waitcnt lgkmcnt(0)
	s_setprio 2
	s_waitcnt lgkmcnt(0)
	v_mfma_f32_16x16x32_bf16 v[124:127], v[206:209], v[174:177], v[124:127]
	v_mfma_f32_16x16x32_bf16 v[120:123], v[214:217], v[174:177], v[120:123]
	v_mfma_f32_16x16x32_bf16 v[116:119], v[206:209], v[182:185], v[116:119]
	v_mfma_f32_16x16x32_bf16 v[112:115], v[214:217], v[182:185], v[112:115]
	v_mfma_f32_16x16x32_bf16 v[108:111], v[206:209], v[190:193], v[108:111]
	v_mfma_f32_16x16x32_bf16 v[104:107], v[214:217], v[190:193], v[104:107]
	v_mfma_f32_16x16x32_bf16 v[100:103], v[206:209], v[198:201], v[100:103]
	v_mfma_f32_16x16x32_bf16 v[96:99], v[214:217], v[198:201], v[96:99]
	v_mfma_f32_16x16x32_bf16 v[124:127], v[210:213], v[178:181], v[124:127]
	v_mfma_f32_16x16x32_bf16 v[120:123], v[218:221], v[178:181], v[120:123]
	v_mfma_f32_16x16x32_bf16 v[116:119], v[210:213], v[186:189], v[116:119]
	v_mfma_f32_16x16x32_bf16 v[112:115], v[218:221], v[186:189], v[112:115]
	v_mfma_f32_16x16x32_bf16 v[108:111], v[210:213], v[194:197], v[108:111]
	v_mfma_f32_16x16x32_bf16 v[104:107], v[218:221], v[194:197], v[104:107]
	v_mfma_f32_16x16x32_bf16 v[100:103], v[210:213], v[202:205], v[100:103]
	v_mfma_f32_16x16x32_bf16 v[96:99], v[218:221], v[202:205], v[96:99]
	s_setprio 1
	s_mov_b32 m0, s30
	v_lshl_add_u64 v[222:223], s[24:25], 0, v[134:135]
	s_barrier
	ds_read_b128 v[174:177], v171 offset:16384
	ds_read_b128 v[178:181], v171 offset:17408
	ds_read_b128 v[182:185], v171 offset:18432
	ds_read_b128 v[186:189], v171 offset:19456
	ds_read_b128 v[190:193], v171 offset:20480
	ds_read_b128 v[194:197], v171 offset:21504
	ds_read_b128 v[198:201], v171 offset:22528
	ds_read_b128 v[202:205], v171 offset:23552
	global_load_lds_dwordx4 v[222:223], off
	v_lshl_add_u64 v[224:225], s[24:25], 0, v[130:131]
	s_mov_b32 m0, s31
	s_nop 0
	global_load_lds_dwordx4 v[224:225], off
	s_barrier
	s_waitcnt lgkmcnt(0)
	s_setprio 2
	s_waitcnt lgkmcnt(0)
	v_mfma_f32_16x16x32_bf16 v[28:31], v[146:149], v[174:177], v[28:31]
	v_mfma_f32_16x16x32_bf16 v[24:27], v[158:161], v[174:177], v[24:27]
	v_mfma_f32_16x16x32_bf16 v[20:23], v[146:149], v[182:185], v[20:23]
	v_mfma_f32_16x16x32_bf16 v[16:19], v[158:161], v[182:185], v[16:19]
	v_mfma_f32_16x16x32_bf16 v[12:15], v[146:149], v[190:193], v[12:15]
	v_mfma_f32_16x16x32_bf16 v[8:11], v[158:161], v[190:193], v[8:11]
	v_mfma_f32_16x16x32_bf16 v[4:7], v[146:149], v[198:201], v[4:7]
	v_mfma_f32_16x16x32_bf16 v[0:3], v[158:161], v[198:201], v[0:3]
	v_mfma_f32_16x16x32_bf16 v[28:31], v[154:157], v[178:181], v[28:31]
	v_mfma_f32_16x16x32_bf16 v[24:27], v[162:165], v[178:181], v[24:27]
	v_mfma_f32_16x16x32_bf16 v[20:23], v[154:157], v[186:189], v[20:23]
	v_mfma_f32_16x16x32_bf16 v[16:19], v[162:165], v[186:189], v[16:19]
	v_mfma_f32_16x16x32_bf16 v[12:15], v[154:157], v[194:197], v[12:15]
	v_mfma_f32_16x16x32_bf16 v[8:11], v[162:165], v[194:197], v[8:11]
	v_mfma_f32_16x16x32_bf16 v[4:7], v[154:157], v[202:205], v[4:7]
	v_mfma_f32_16x16x32_bf16 v[0:3], v[162:165], v[202:205], v[0:3]
	s_setprio 1
	s_barrier
	s_add_u32 s48, s22, 0x40000
	s_addc_u32 s49, s23, 0
	s_add_i32 s50, s40, s27
	v_lshl_add_u64 v[146:147], s[48:49], 0, v[132:133]
	s_mov_b32 m0, s50
	s_nop 0
	global_load_lds_dwordx4 v[146:147], off
	v_lshl_add_u64 v[146:147], s[48:49], 0, v[128:129]
	s_add_i32 m0, s50, 0x2000
	s_nop 0
	global_load_lds_dwordx4 v[146:147], off
	s_waitcnt vmcnt(6)
	s_barrier
	s_setprio 2
	v_mfma_f32_16x16x32_bf16 v[92:95], v[206:209], v[174:177], v[92:95]
	v_mfma_f32_16x16x32_bf16 v[88:91], v[214:217], v[174:177], v[88:91]
	v_mfma_f32_16x16x32_bf16 v[84:87], v[206:209], v[182:185], v[84:87]
	v_mfma_f32_16x16x32_bf16 v[80:83], v[214:217], v[182:185], v[80:83]
	v_mfma_f32_16x16x32_bf16 v[72:75], v[206:209], v[190:193], v[72:75]
	v_mfma_f32_16x16x32_bf16 v[68:71], v[214:217], v[190:193], v[68:71]
	v_mfma_f32_16x16x32_bf16 v[52:55], v[206:209], v[198:201], v[52:55]
	v_mfma_f32_16x16x32_bf16 v[44:47], v[214:217], v[198:201], v[44:47]
	v_mfma_f32_16x16x32_bf16 v[92:95], v[210:213], v[178:181], v[92:95]
	v_mfma_f32_16x16x32_bf16 v[88:91], v[218:221], v[178:181], v[88:91]
	v_mfma_f32_16x16x32_bf16 v[84:87], v[210:213], v[186:189], v[84:87]
	v_mfma_f32_16x16x32_bf16 v[80:83], v[218:221], v[186:189], v[80:83]
	v_mfma_f32_16x16x32_bf16 v[72:75], v[210:213], v[194:197], v[72:75]
	v_mfma_f32_16x16x32_bf16 v[68:71], v[218:221], v[194:197], v[68:71]
	v_mfma_f32_16x16x32_bf16 v[52:55], v[210:213], v[202:205], v[52:55]
	v_mfma_f32_16x16x32_bf16 v[44:47], v[218:221], v[202:205], v[44:47]
	s_setprio 1
	s_add_i32 s48, 0, 0x18000
	v_add_u32_e32 v162, s48, v168
	s_barrier
	ds_read_b128 v[146:149], v162
	ds_read_b128 v[154:157], v162 offset:1024
	ds_read_b128 v[158:161], v162 offset:2048
	ds_read_b128 v[162:165], v162 offset:3072
	s_add_u32 s24, s24, 0x40000
	s_addc_u32 s25, s25, 0
	s_mov_b32 m0, s33
	v_lshl_add_u64 v[206:207], s[24:25], 0, v[134:135]
	ds_read_b128 v[174:177], v171 offset:32768
	ds_read_b128 v[178:181], v171 offset:33792
	ds_read_b128 v[182:185], v171 offset:34816
	ds_read_b128 v[186:189], v171 offset:35840
	ds_read_b128 v[190:193], v171 offset:36864
	ds_read_b128 v[194:197], v171 offset:37888
	ds_read_b128 v[198:201], v171 offset:38912
	ds_read_b128 v[202:205], v171 offset:39936
	global_load_lds_dwordx4 v[206:207], off
	v_lshl_add_u64 v[206:207], s[24:25], 0, v[130:131]
	s_mov_b32 m0, s34
	s_nop 0
	global_load_lds_dwordx4 v[206:207], off
	s_waitcnt lgkmcnt(8)
	s_barrier
; #define PG8_STAGE(bufoff, gbase, voff) do { _Pragma("unroll") for (int _i = 0; _i < 2; ++_i) \
;         __builtin_amdgcn_global_load_lds((const unsigned*)((const char*)(gbase) + (voff)[_i]), (LAS unsigned*)(lds + (bufoff) + ldsw + _i * 8192), 16, 0, 0); } while (0)
; #define PG8_LDA(dst, b, h) do { _Pragma("unroll") for (int m = 0; m < 4; ++m) _Pragma("unroll") for (int k = 0; k < 2; ++k) dst[m][k] = *(const LAS bf16x8*)(lds + PG8_SA(b, h) + aoff + m * 2048 + k * 1024); } while (0)
; #define PG8_LDB(dst, b, h) do { _Pragma("unroll") for (int n = 0; n < 2; ++n) _Pragma("unroll") for (int k = 0; k < 2; ++k) dst[n][k] = *(const LAS bf16x8*)(lds + PG8_SB(b, h) + boff + n * 2048 + k * 1024); } while (0)
; #define PG8_MMA(ai, bj, At, Bt) do { __builtin_amdgcn_s_setprio(1); _Pragma("unroll") for (int m = 0; m < 4; ++m) _Pragma("unroll") for (int n = 0; n < 2; ++n) _Pragma("unroll") for (int k = 0; k < 2; ++k) \
;         acc[ai][bj][m][n] = __builtin_amdgcn_mfma_f32_16x16x32_bf16(Bt[n][k], At[m][k], acc[ai][bj][m][n], 0, 0, 0); __builtin_amdgcn_s_setprio(0); } while (0)
; #define PG8_WAIT_V(n) asm volatile("s_waitcnt vmcnt(" #n ")" ::: "memory")
; #define PG8_WAIT_L(n) asm volatile("s_waitcnt lgkmcnt(" #n ")" ::: "memory")
; #define PG8_BAR __builtin_amdgcn_s_barrier()
; #define PG8_SCHED __builtin_amdgcn_sched_barrier(0)
; template <class Epi>
; __device__ __forceinline__ void gemm_phase(LAS unsigned char* lds, const Gemm g, const StaticOrder& S, const Epi& E) {
;     ...
;             PG8_WAIT_L(8); PG8_BAR; PG8_WAIT_L(0); PG8_MMA(0, 0, At, B0); PG8_BAR; PG8_SCHED;
;             PG8_LDB(B1, 1, 1); PG8_STAGE(PG8_SB(1, 0), b3, voffB);
;             PG8_BAR; PG8_WAIT_L(0); PG8_MMA(0, 1, At, B1); PG8_BAR;
;             PG8_LDA(At, 1, 1); PG8_STAGE(PG8_SA(1, 0), a3, voffA);
;             PG8_BAR; PG8_WAIT_L(0); PG8_MMA(1, 0, At, B0); PG8_BAR; PG8_SCHED;
;             PG8_STAGE(PG8_SB(1, 1), b3 + hstepB, voffB);
;             PG8_WAIT_V(6); PG8_BAR; PG8_MMA(1, 1, At, B1); PG8_BAR;
;         }
	s_waitcnt lgkmcnt(0)
	s_setprio 2
	s_waitcnt lgkmcnt(0)
	v_mfma_f32_16x16x32_bf16 v[76:79], v[146:149], v[174:177], v[76:79]
	v_mfma_f32_16x16x32_bf16 v[64:67], v[158:161], v[174:177], v[64:67]
	v_mfma_f32_16x16x32_bf16 v[60:63], v[146:149], v[182:185], v[60:63]
	v_mfma_f32_16x16x32_bf16 v[56:59], v[158:161], v[182:185], v[56:59]
	v_mfma_f32_16x16x32_bf16 v[48:51], v[146:149], v[190:193], v[48:51]
	v_mfma_f32_16x16x32_bf16 v[40:43], v[158:161], v[190:193], v[40:43]
	v_mfma_f32_16x16x32_bf16 v[36:39], v[146:149], v[198:201], v[36:39]
	v_mfma_f32_16x16x32_bf16 v[32:35], v[158:161], v[198:201], v[32:35]
	v_mfma_f32_16x16x32_bf16 v[76:79], v[154:157], v[178:181], v[76:79]
	v_mfma_f32_16x16x32_bf16 v[64:67], v[162:165], v[178:181], v[64:67]
	v_mfma_f32_16x16x32_bf16 v[60:63], v[154:157], v[186:189], v[60:63]
	v_mfma_f32_16x16x32_bf16 v[56:59], v[162:165], v[186:189], v[56:59]
	v_mfma_f32_16x16x32_bf16 v[48:51], v[154:157], v[194:197], v[48:51]
	v_mfma_f32_16x16x32_bf16 v[40:43], v[162:165], v[194:197], v[40:43]
	v_mfma_f32_16x16x32_bf16 v[36:39], v[154:157], v[202:205], v[36:39]
	v_mfma_f32_16x16x32_bf16 v[32:35], v[162:165], v[202:205], v[32:35]
	s_setprio 1
	s_barrier
	s_add_i32 s24, 0, 0x1c000
	s_add_i32 s25, s48, s27
	v_add_u32_e32 v218, s24, v168
	v_lshl_add_u64 v[150:151], v[150:151], 0, s[6:7]
	s_mov_b32 m0, s25
	ds_read_b128 v[206:209], v218
	ds_read_b128 v[210:213], v218 offset:1024
	ds_read_b128 v[214:217], v218 offset:2048
	ds_read_b128 v[218:221], v218 offset:3072
	global_load_lds_dwordx4 v[150:151], off
	v_lshl_add_u64 v[150:151], v[166:167], 0, s[6:7]
	s_add_i32 m0, s25, 0x2000
	s_nop 0
	global_load_lds_dwordx4 v[150:151], off
	s_barrier
	s_waitcnt lgkmcnt(0)
	s_setprio 2
	s_waitcnt lgkmcnt(0)
	v_mfma_f32_16x16x32_bf16 v[124:127], v[206:209], v[174:177], v[124:127]
	v_mfma_f32_16x16x32_bf16 v[120:123], v[214:217], v[174:177], v[120:123]
	v_mfma_f32_16x16x32_bf16 v[116:119], v[206:209], v[182:185], v[116:119]
	v_mfma_f32_16x16x32_bf16 v[112:115], v[214:217], v[182:185], v[112:115]
	v_mfma_f32_16x16x32_bf16 v[108:111], v[206:209], v[190:193], v[108:111]
	v_mfma_f32_16x16x32_bf16 v[104:107], v[214:217], v[190:193], v[104:107]
	v_mfma_f32_16x16x32_bf16 v[100:103], v[206:209], v[198:201], v[100:103]
	v_mfma_f32_16x16x32_bf16 v[96:99], v[214:217], v[198:201], v[96:99]
	v_mfma_f32_16x16x32_bf16 v[124:127], v[210:213], v[178:181], v[124:127]
	v_mfma_f32_16x16x32_bf16 v[120:123], v[218:221], v[178:181], v[120:123]
	v_mfma_f32_16x16x32_bf16 v[116:119], v[210:213], v[186:189], v[116:119]
	v_mfma_f32_16x16x32_bf16 v[112:115], v[218:221], v[186:189], v[112:115]
	v_mfma_f32_16x16x32_bf16 v[108:111], v[210:213], v[194:197], v[108:111]
	v_mfma_f32_16x16x32_bf16 v[104:107], v[218:221], v[194:197], v[104:107]
	v_mfma_f32_16x16x32_bf16 v[100:103], v[210:213], v[202:205], v[100:103]
	v_mfma_f32_16x16x32_bf16 v[96:99], v[218:221], v[202:205], v[96:99]
	s_setprio 1
	s_mov_b32 m0, s36
	v_lshl_add_u64 v[150:151], v[222:223], 0, s[6:7]
	s_barrier
	ds_read_b128 v[174:177], v171 offset:49152
	ds_read_b128 v[178:181], v171 offset:50176
	ds_read_b128 v[182:185], v171 offset:51200
	ds_read_b128 v[186:189], v171 offset:52224
	ds_read_b128 v[190:193], v171 offset:53248
	ds_read_b128 v[194:197], v171 offset:54272
	ds_read_b128 v[198:201], v171 offset:55296
	ds_read_b128 v[202:205], v171 offset:56320
	global_load_lds_dwordx4 v[150:151], off
	v_lshl_add_u64 v[150:151], v[224:225], 0, s[6:7]
	s_mov_b32 m0, s37
	s_nop 0
	global_load_lds_dwordx4 v[150:151], off
	s_barrier
	s_waitcnt lgkmcnt(0)
	s_setprio 2
	s_waitcnt lgkmcnt(0)
	v_mfma_f32_16x16x32_bf16 v[28:31], v[146:149], v[174:177], v[28:31]
	v_mfma_f32_16x16x32_bf16 v[24:27], v[158:161], v[174:177], v[24:27]
	v_mfma_f32_16x16x32_bf16 v[20:23], v[146:149], v[182:185], v[20:23]
	v_mfma_f32_16x16x32_bf16 v[16:19], v[158:161], v[182:185], v[16:19]
	v_mfma_f32_16x16x32_bf16 v[12:15], v[146:149], v[190:193], v[12:15]
	v_mfma_f32_16x16x32_bf16 v[8:11], v[158:161], v[190:193], v[8:11]
	v_mfma_f32_16x16x32_bf16 v[4:7], v[146:149], v[198:201], v[4:7]
	v_mfma_f32_16x16x32_bf16 v[0:3], v[158:161], v[198:201], v[0:3]
	v_mfma_f32_16x16x32_bf16 v[28:31], v[154:157], v[178:181], v[28:31]
	v_mfma_f32_16x16x32_bf16 v[24:27], v[162:165], v[178:181], v[24:27]
	v_mfma_f32_16x16x32_bf16 v[20:23], v[154:157], v[186:189], v[20:23]
	v_mfma_f32_16x16x32_bf16 v[16:19], v[162:165], v[186:189], v[16:19]
	v_mfma_f32_16x16x32_bf16 v[12:15], v[154:157], v[194:197], v[12:15]
	v_mfma_f32_16x16x32_bf16 v[8:11], v[162:165], v[194:197], v[8:11]
	v_mfma_f32_16x16x32_bf16 v[4:7], v[154:157], v[202:205], v[4:7]
	v_mfma_f32_16x16x32_bf16 v[0:3], v[162:165], v[202:205], v[0:3]
	s_setprio 1
	s_barrier
	s_add_u32 s22, s22, 0x40080
	s_addc_u32 s23, s23, 0
	s_add_i32 s24, s24, s27
	v_lshl_add_u64 v[146:147], s[22:23], 0, v[132:133]
	s_mov_b32 m0, s24
	s_nop 0
	global_load_lds_dwordx4 v[146:147], off
	v_lshl_add_u64 v[146:147], s[22:23], 0, v[128:129]
	s_add_i32 m0, s24, 0x2000
	s_nop 0
	global_load_lds_dwordx4 v[146:147], off
	s_waitcnt vmcnt(6)
	s_barrier
	s_setprio 2
	v_mfma_f32_16x16x32_bf16 v[92:95], v[206:209], v[174:177], v[92:95]
	v_mfma_f32_16x16x32_bf16 v[88:91], v[214:217], v[174:177], v[88:91]
	v_mfma_f32_16x16x32_bf16 v[84:87], v[206:209], v[182:185], v[84:87]
	v_mfma_f32_16x16x32_bf16 v[80:83], v[214:217], v[182:185], v[80:83]
	v_mfma_f32_16x16x32_bf16 v[72:75], v[206:209], v[190:193], v[72:75]
	v_mfma_f32_16x16x32_bf16 v[68:71], v[214:217], v[190:193], v[68:71]
	v_mfma_f32_16x16x32_bf16 v[52:55], v[206:209], v[198:201], v[52:55]
	v_mfma_f32_16x16x32_bf16 v[44:47], v[214:217], v[198:201], v[44:47]
	v_mfma_f32_16x16x32_bf16 v[92:95], v[210:213], v[178:181], v[92:95]
	v_mfma_f32_16x16x32_bf16 v[88:91], v[218:221], v[178:181], v[88:91]
	v_mfma_f32_16x16x32_bf16 v[84:87], v[210:213], v[186:189], v[84:87]
	v_mfma_f32_16x16x32_bf16 v[80:83], v[218:221], v[186:189], v[80:83]
	v_mfma_f32_16x16x32_bf16 v[72:75], v[210:213], v[194:197], v[72:75]
	v_mfma_f32_16x16x32_bf16 v[68:71], v[218:221], v[194:197], v[68:71]
	v_mfma_f32_16x16x32_bf16 v[52:55], v[210:213], v[202:205], v[52:55]
	v_mfma_f32_16x16x32_bf16 v[44:47], v[218:221], v[202:205], v[44:47]
	s_setprio 1
	s_add_i32 s47, s47, 2
	s_add_u32 s20, s20, 0x100
	s_addc_u32 s21, s21, 0
	s_add_u32 s45, s45, 0x100
	s_addc_u32 s46, s46, 0
	s_cmp_gt_u32 s47, 13
	s_barrier
	s_cbranch_scc0 .Lkp0_205
	s_branch .Lkp0_epi
;     __device__ bool next(int i, Unit& u) const {
;         const long L = (long)i * G + c; if (L >= nwg) return false;
;         int wgid = (int)L; { const int q = nwg / NXCD, r = nwg % NXCD, xcd = wgid % NXCD, off = wgid / NXCD; wgid = (xcd < r ? xcd * (q + 1) : r * (q + 1) + (xcd - r) * q) + off; }
;         const int nig = WGM * nN, gid = wgid / nig, fm = gid * WGM, gsz = (nM - fm) < WGM ? (nM - fm) : WGM;
;         u.pm = fm + ((wgid % nig) % gsz); u.pn = (wgid % nig) / gsz; return true;
; template <class Epi>
; __device__ __forceinline__ void gemm_phase(LAS unsigned char* lds, const Gemm g, const StaticOrder& S, const Epi& E) {
;     ...
;         const bool has_next = S.next(ui + 1, nxt);
;         const char* nA = has_next ? (const char*)g.A + (size_t)nxt.pm * tstepA : cA; const char* nB = has_next ? (const char*)g.Bt + (size_t)nxt.pn * tstepB : cB;
.LBB0_202:
	v_readfirstlane_b32 s98, v152
	s_nop 3
	s_cmp_ge_u32 s98, 0x100
	s_cbranch_scc1 .Lkp0_head
	s_add_i32 s35, s35, 1
	s_mul_i32 s0, s35, s38
	s_mul_hi_u32 s1, s35, s92
	s_add_i32 s1, s1, s0
	s_mul_i32 s0, s35, s92
	s_add_u32 s14, s0, s93
	s_addc_u32 s15, s1, s28
	v_cmp_gt_i64_e64 s[0:1], s[14:15], v[144:145]
	s_and_b64 vcc, exec, s[0:1]
	s_cbranch_vccnz .LBB0_204
	s_lshr_b32 s10, s14, 3
	s_mov_b32 s13, 0
	s_sub_u32 s11, s10, 0xa8
	s_cmp_ge_u32 s10, 0xa8
	s_cselect_b32 s10, s11, s10
	s_addc_u32 s13, s13, 0
	s_sub_u32 s11, s10, 0xa8
	s_cmp_ge_u32 s10, 0xa8
	s_cselect_b32 s10, s11, s10
	s_addc_u32 s13, s13, 0
	s_sub_u32 s11, s10, 0xa8
	s_cmp_ge_u32 s10, 0xa8
	s_cselect_b32 s10, s11, s10
	s_addc_u32 s13, s13, 0
	s_and_b32 s12, s14, 7
	s_lshl_b32 s12, s12, 2
	s_add_i32 s12, s12, s13
	s_lshl_b32 s12, s12, 3
	s_and_b32 s13, s10, 7
	s_add_i32 s12, s12, s13
	s_lshr_b32 s10, s10, 3

; __device__ __forceinline__ unsigned pk2(float lo, float hi) { const f32x2 v = (f32x2){lo, hi}; const bf16x2_t b = __builtin_convertvector(v, bf16x2_t); return __builtin_bit_cast(unsigned, b); }
;     __device__ __forceinline__ void operator()(const f32x4 (&acc)[2][2][4][2], const Unit& u, int wr, int wc, int fr, int fq, const float (&)[8]) const {
;         const int row0 = u.pm * BM + wr * 64 + fr;
;         float ep[8];
; #pragma unroll
;         for (int ai = 0; ai < 2; ++ai)
; #pragma unroll
;             for (int m = 0; m < 4; ++m) { const int row = row0 + ai * HALF + m * 16;
;                 if (SLOTS == 1) ep[ai * 4 + m] = ss[row];
;                 else { const f32x4 pq = *(const f32x4*)(ss + (size_t)row * 16 + 4 * fq); ep[ai * 4 + m] = (pq[0] + pq[1]) + (pq[2] + pq[3]); } }
;     ...
;         const int col0 = u.pn * BM + wc * 32 + 8 * fq;
; #pragma unroll
;         for (int ai = 0; ai < 2; ++ai)
; #pragma unroll
;             for (int m = 0; m < 4; ++m) { const int row = row0 + ai * HALF + m * 16; const float rs = rsqrtf(ep[ai * 4 + m] * (1.0f / 1024.0f) + EPS);
;                 u16* rowp = O + (size_t)row * ldc + col0;
; #pragma unroll
;                 for (int bj = 0; bj < 2; ++bj) { f32x4 v0 = acc[ai][bj][m][0] * rs, v1 = acc[ai][bj][m][1] * rs;
;                     if (ACT == 1) {
; #pragma unroll
;                         for (int j = 0; j < 4; ++j) { const float a0 = fmaxf(v0[j], 0.f), a1 = fmaxf(v1[j], 0.f); v0[j] = a0 * a0; v1[j] = a1 * a1; } }
;                     u32x4 w; w.x = pk2(v0[0], v0[1]); w.y = pk2(v0[2], v0[3]); w.z = pk2(v1[0], v1[1]); w.w = pk2(v1[2], v1[3]);
;                     *(u32x4*)(rowp + bj * HALF) = w; } }
.Lkp0_epi:
	s_setprio 0
	s_bfe_u32 vcc_lo, s18, 0x20003
	s_lshl_b32 vcc_lo, vcc_lo, 10
	s_add_i32 vcc_lo, vcc_lo, 0x20010
	v_lshl_add_u32 v236, v153, 2, vcc_lo
	ds_read_b32 v228, v236
	ds_read_b32 v229, v236 offset:64
	ds_read_b32 v230, v236 offset:128
	ds_read_b32 v231, v236 offset:192
	ds_read_b32 v232, v236 offset:512
	ds_read_b32 v233, v236 offset:576
	ds_read_b32 v234, v236 offset:640
	ds_read_b32 v235, v236 offset:704
	s_waitcnt lgkmcnt(0)
	v_lshl_add_u32 v162, s18, 8, v153
	v_ashrrev_i32_e32 v163, 31, v162
	v_or_b32_e32 v160, 16, v162
	v_or_b32_e32 v158, 32, v162
	v_or_b32_e32 v156, 48, v162
	v_ashrrev_i32_e32 v161, 31, v160
	v_ashrrev_i32_e32 v159, 31, v158
	v_ashrrev_i32_e32 v157, 31, v156
	v_add_u32_e32 v154, 0x80, v162
	v_add_u32_e32 v150, 0x90, v162
	v_add_u32_e32 v148, 0xa0, v162
	v_add_u32_e32 v146, 0xb0, v162
	v_ashrrev_i32_e32 v155, 31, v154
	v_ashrrev_i32_e32 v151, 31, v150
	v_ashrrev_i32_e32 v149, 31, v148
	v_ashrrev_i32_e32 v147, 31, v146
	s_cmp_lg_u32 s43, 20
	s_mov_b64 s[18:19], -1
	s_cbranch_scc0 .LBB0_208
	s_waitcnt vmcnt(8)
	v_lshl_or_b32 v166, s43, 8, v169
	v_ashrrev_i32_e32 v167, 31, v166
	v_lshlrev_b64 v[166:167], 1, v[166:167]
	v_mov_b32_e32 v186, v228
	v_mov_b64_e32 v[164:165], s[96:97]
	v_mad_i64_i32 v[182:183], s[18:19], v162, s42, v[164:165]
	v_lshl_add_u64 v[188:189], v[182:183], 0, v[166:167]
	v_pk_mul_f32 v[184:185], v[78:79], v[186:187] op_sel_hi:[1,0]
	v_pk_mul_f32 v[182:183], v[76:77], v[186:187] op_sel_hi:[1,0]
	v_pk_mul_f32 v[190:191], v[66:67], v[186:187] op_sel_hi:[1,0]
	v_pk_mul_f32 v[192:193], v[64:65], v[186:187] op_sel_hi:[1,0]
	v_cvt_pk_bf16_f32 v182, v182, v183
	v_cvt_pk_bf16_f32 v183, v184, v185
	v_cvt_pk_bf16_f32 v184, v192, v193
	v_cvt_pk_bf16_f32 v185, v190, v191
	v_pk_mul_f32 v[124:125], v[124:125], v[186:187] op_sel_hi:[1,0]
	global_store_dwordx4 v[188:189], v[182:185], off
	v_pk_mul_f32 v[126:127], v[126:127], v[186:187] op_sel_hi:[1,0]
	s_nop 0
	v_pk_mul_f32 v[182:183], v[122:123], v[186:187] op_sel_hi:[1,0]
	v_pk_mul_f32 v[122:123], v[120:121], v[186:187] op_sel_hi:[1,0]
	v_cvt_pk_bf16_f32 v120, v124, v125
	v_cvt_pk_bf16_f32 v121, v126, v127
	v_cvt_pk_bf16_f32 v122, v122, v123
	v_cvt_pk_bf16_f32 v123, v182, v183
	global_store_dwordx4 v[188:189], v[120:123], off offset:256
	s_nop 1
	v_mov_b32_e32 v124, v229
	v_mad_i64_i32 v[120:121], s[18:19], v160, s42, v[164:165]
	v_lshl_add_u64 v[126:127], v[120:121], 0, v[166:167]
	v_pk_mul_f32 v[122:123], v[62:63], v[124:125] op_sel_hi:[1,0]
	v_pk_mul_f32 v[120:121], v[60:61], v[124:125] op_sel_hi:[1,0]
	v_pk_mul_f32 v[182:183], v[58:59], v[124:125] op_sel_hi:[1,0]
	v_pk_mul_f32 v[184:185], v[56:57], v[124:125] op_sel_hi:[1,0]
	v_cvt_pk_bf16_f32 v120, v120, v121
	v_cvt_pk_bf16_f32 v121, v122, v123
	v_cvt_pk_bf16_f32 v122, v184, v185
	v_cvt_pk_bf16_f32 v123, v182, v183
	v_pk_mul_f32 v[116:117], v[116:117], v[124:125] op_sel_hi:[1,0]
	global_store_dwordx4 v[126:127], v[120:123], off
	v_pk_mul_f32 v[118:119], v[118:119], v[124:125] op_sel_hi:[1,0]
	s_nop 0
	v_pk_mul_f32 v[120:121], v[114:115], v[124:125] op_sel_hi:[1,0]
	v_pk_mul_f32 v[114:115], v[112:113], v[124:125] op_sel_hi:[1,0]
	v_cvt_pk_bf16_f32 v112, v116, v117
	v_cvt_pk_bf16_f32 v113, v118, v119
	v_cvt_pk_bf16_f32 v114, v114, v115
	v_cvt_pk_bf16_f32 v115, v120, v121
	global_store_dwordx4 v[126:127], v[112:115], off offset:256
	s_nop 1
	v_mov_b32_e32 v116, v230
	v_mad_i64_i32 v[112:113], s[18:19], v158, s42, v[164:165]
	v_lshl_add_u64 v[118:119], v[112:113], 0, v[166:167]
	v_pk_mul_f32 v[114:115], v[50:51], v[116:117] op_sel_hi:[1,0]
	v_pk_mul_f32 v[112:113], v[48:49], v[116:117] op_sel_hi:[1,0]
	v_pk_mul_f32 v[120:121], v[42:43], v[116:117] op_sel_hi:[1,0]
	v_pk_mul_f32 v[122:123], v[40:41], v[116:117] op_sel_hi:[1,0]
	v_cvt_pk_bf16_f32 v112, v112, v113
	v_cvt_pk_bf16_f32 v113, v114, v115
	v_cvt_pk_bf16_f32 v114, v122, v123
	v_cvt_pk_bf16_f32 v115, v120, v121
	v_pk_mul_f32 v[108:109], v[108:109], v[116:117] op_sel_hi:[1,0]
	global_store_dwordx4 v[118:119], v[112:115], off
	v_pk_mul_f32 v[110:111], v[110:111], v[116:117] op_sel_hi:[1,0]
	s_nop 0
	v_pk_mul_f32 v[112:113], v[106:107], v[116:117] op_sel_hi:[1,0]
	v_pk_mul_f32 v[106:107], v[104:105], v[116:117] op_sel_hi:[1,0]
	v_cvt_pk_bf16_f32 v104, v108, v109
	v_cvt_pk_bf16_f32 v105, v110, v111
	v_cvt_pk_bf16_f32 v106, v106, v107
	v_cvt_pk_bf16_f32 v107, v112, v113
	global_store_dwordx4 v[118:119], v[104:107], off offset:256
	s_nop 1
	v_mov_b32_e32 v108, v231
	v_mad_i64_i32 v[104:105], s[18:19], v156, s42, v[164:165]
	v_lshl_add_u64 v[110:111], v[104:105], 0, v[166:167]
	v_pk_mul_f32 v[106:107], v[38:39], v[108:109] op_sel_hi:[1,0]
	v_pk_mul_f32 v[104:105], v[36:37], v[108:109] op_sel_hi:[1,0]
	v_pk_mul_f32 v[112:113], v[34:35], v[108:109] op_sel_hi:[1,0]
; __device__ __forceinline__ unsigned pk2(float lo, float hi) { const f32x2 v = (f32x2){lo, hi}; const bf16x2_t b = __builtin_convertvector(v, bf16x2_t); return __builtin_bit_cast(unsigned, b); }
;     __device__ __forceinline__ void operator()(const f32x4 (&acc)[2][2][4][2], const Unit& u, int wr, int wc, int fr, int fq, const float (&)[8]) const {
;     ...
;             for (int m = 0; m < 4; ++m) { const int row = row0 + ai * HALF + m * 16; const float rs = rsqrtf(ep[ai * 4 + m] * (1.0f / 1024.0f) + EPS);
;                 u16* rowp = O + (size_t)row * ldc + col0;
; #pragma unroll
;                 for (int bj = 0; bj < 2; ++bj) { f32x4 v0 = acc[ai][bj][m][0] * rs, v1 = acc[ai][bj][m][1] * rs;
;                     if (ACT == 1) {
; #pragma unroll
;                         for (int j = 0; j < 4; ++j) { const float a0 = fmaxf(v0[j], 0.f), a1 = fmaxf(v1[j], 0.f); v0[j] = a0 * a0; v1[j] = a1 * a1; } }
;                     u32x4 w; w.x = pk2(v0[0], v0[1]); w.y = pk2(v0[2], v0[3]); w.z = pk2(v1[0], v1[1]); w.w = pk2(v1[2], v1[3]);
;                     *(u32x4*)(rowp + bj * HALF) = w; } }
	v_pk_mul_f32 v[114:115], v[32:33], v[108:109] op_sel_hi:[1,0]
	v_cvt_pk_bf16_f32 v104, v104, v105
	v_cvt_pk_bf16_f32 v105, v106, v107
	v_cvt_pk_bf16_f32 v106, v114, v115
	v_cvt_pk_bf16_f32 v107, v112, v113
	v_pk_mul_f32 v[100:101], v[100:101], v[108:109] op_sel_hi:[1,0]
	global_store_dwordx4 v[110:111], v[104:107], off
	v_pk_mul_f32 v[102:103], v[102:103], v[108:109] op_sel_hi:[1,0]
	s_nop 0
	v_pk_mul_f32 v[104:105], v[98:99], v[108:109] op_sel_hi:[1,0]
	v_pk_mul_f32 v[98:99], v[96:97], v[108:109] op_sel_hi:[1,0]
	v_cvt_pk_bf16_f32 v96, v100, v101
	v_cvt_pk_bf16_f32 v97, v102, v103
	v_cvt_pk_bf16_f32 v98, v98, v99
	v_cvt_pk_bf16_f32 v99, v104, v105
	global_store_dwordx4 v[110:111], v[96:99], off offset:256
	s_nop 1
	v_mov_b32_e32 v100, v232
	v_mad_i64_i32 v[96:97], s[18:19], v154, s42, v[164:165]
	v_lshl_add_u64 v[102:103], v[96:97], 0, v[166:167]
	v_pk_mul_f32 v[98:99], v[30:31], v[100:101] op_sel_hi:[1,0]
	v_pk_mul_f32 v[96:97], v[28:29], v[100:101] op_sel_hi:[1,0]
	v_pk_mul_f32 v[104:105], v[26:27], v[100:101] op_sel_hi:[1,0]
	v_pk_mul_f32 v[106:107], v[24:25], v[100:101] op_sel_hi:[1,0]
	v_cvt_pk_bf16_f32 v96, v96, v97
	v_cvt_pk_bf16_f32 v97, v98, v99
	v_cvt_pk_bf16_f32 v98, v106, v107
	v_cvt_pk_bf16_f32 v99, v104, v105
	v_pk_mul_f32 v[92:93], v[92:93], v[100:101] op_sel_hi:[1,0]
	global_store_dwordx4 v[102:103], v[96:99], off
	v_pk_mul_f32 v[94:95], v[94:95], v[100:101] op_sel_hi:[1,0]
	s_nop 0
	v_pk_mul_f32 v[96:97], v[90:91], v[100:101] op_sel_hi:[1,0]
	v_pk_mul_f32 v[90:91], v[88:89], v[100:101] op_sel_hi:[1,0]
	v_cvt_pk_bf16_f32 v88, v92, v93
	v_cvt_pk_bf16_f32 v89, v94, v95
	v_cvt_pk_bf16_f32 v90, v90, v91
	v_cvt_pk_bf16_f32 v91, v96, v97
	global_store_dwordx4 v[102:103], v[88:91], off offset:256
	s_nop 1
	v_mov_b32_e32 v92, v233
	v_mad_i64_i32 v[88:89], s[18:19], v150, s42, v[164:165]
	v_lshl_add_u64 v[94:95], v[88:89], 0, v[166:167]
	v_pk_mul_f32 v[90:91], v[22:23], v[92:93] op_sel_hi:[1,0]
	v_pk_mul_f32 v[88:89], v[20:21], v[92:93] op_sel_hi:[1,0]
	v_pk_mul_f32 v[96:97], v[18:19], v[92:93] op_sel_hi:[1,0]
	v_pk_mul_f32 v[98:99], v[16:17], v[92:93] op_sel_hi:[1,0]
	v_cvt_pk_bf16_f32 v88, v88, v89
	v_cvt_pk_bf16_f32 v89, v90, v91
	v_cvt_pk_bf16_f32 v90, v98, v99
	v_cvt_pk_bf16_f32 v91, v96, v97
	v_pk_mul_f32 v[84:85], v[84:85], v[92:93] op_sel_hi:[1,0]
	global_store_dwordx4 v[94:95], v[88:91], off
	v_pk_mul_f32 v[86:87], v[86:87], v[92:93] op_sel_hi:[1,0]
	s_nop 0
	v_pk_mul_f32 v[88:89], v[82:83], v[92:93] op_sel_hi:[1,0]
	v_pk_mul_f32 v[82:83], v[80:81], v[92:93] op_sel_hi:[1,0]
	v_cvt_pk_bf16_f32 v80, v84, v85
	v_cvt_pk_bf16_f32 v81, v86, v87
	v_cvt_pk_bf16_f32 v82, v82, v83
	v_cvt_pk_bf16_f32 v83, v88, v89
	global_store_dwordx4 v[94:95], v[80:83], off offset:256
	s_nop 1
	v_mov_b32_e32 v84, v234
	v_mad_i64_i32 v[80:81], s[18:19], v148, s42, v[164:165]
	v_lshl_add_u64 v[86:87], v[80:81], 0, v[166:167]
	v_pk_mul_f32 v[82:83], v[14:15], v[84:85] op_sel_hi:[1,0]
	v_pk_mul_f32 v[80:81], v[12:13], v[84:85] op_sel_hi:[1,0]
	v_pk_mul_f32 v[88:89], v[10:11], v[84:85] op_sel_hi:[1,0]
	v_pk_mul_f32 v[90:91], v[8:9], v[84:85] op_sel_hi:[1,0]
	v_cvt_pk_bf16_f32 v80, v80, v81
	v_cvt_pk_bf16_f32 v81, v82, v83
	v_cvt_pk_bf16_f32 v82, v90, v91
	v_cvt_pk_bf16_f32 v83, v88, v89
	v_pk_mul_f32 v[72:73], v[72:73], v[84:85] op_sel_hi:[1,0]
	global_store_dwordx4 v[86:87], v[80:83], off
	v_pk_mul_f32 v[74:75], v[74:75], v[84:85] op_sel_hi:[1,0]
	s_nop 0
	v_pk_mul_f32 v[80:81], v[70:71], v[84:85] op_sel_hi:[1,0]
	v_pk_mul_f32 v[70:71], v[68:69], v[84:85] op_sel_hi:[1,0]
	v_cvt_pk_bf16_f32 v68, v72, v73
	v_cvt_pk_bf16_f32 v69, v74, v75
	v_cvt_pk_bf16_f32 v70, v70, v71
	v_cvt_pk_bf16_f32 v71, v80, v81
	global_store_dwordx4 v[86:87], v[68:71], off offset:256
	s_nop 1
	v_mov_b32_e32 v72, v235
	v_mad_i64_i32 v[68:69], s[18:19], v146, s42, v[164:165]
	v_lshl_add_u64 v[74:75], v[68:69], 0, v[166:167]
	v_pk_mul_f32 v[70:71], v[6:7], v[72:73] op_sel_hi:[1,0]
	v_pk_mul_f32 v[68:69], v[4:5], v[72:73] op_sel_hi:[1,0]
	v_pk_mul_f32 v[80:81], v[2:3], v[72:73] op_sel_hi:[1,0]
	v_pk_mul_f32 v[82:83], v[0:1], v[72:73] op_sel_hi:[1,0]
	v_cvt_pk_bf16_f32 v68, v68, v69
	v_cvt_pk_bf16_f32 v69, v70, v71
	v_cvt_pk_bf16_f32 v70, v82, v83
	v_cvt_pk_bf16_f32 v71, v80, v81
	global_store_dwordx4 v[74:75], v[68:71], off
	v_pk_mul_f32 v[54:55], v[54:55], v[72:73] op_sel_hi:[1,0]
	v_pk_mul_f32 v[52:53], v[52:53], v[72:73] op_sel_hi:[1,0]
	v_pk_mul_f32 v[68:69], v[46:47], v[72:73] op_sel_hi:[1,0]
	v_pk_mul_f32 v[46:47], v[44:45], v[72:73] op_sel_hi:[1,0]
	v_cvt_pk_bf16_f32 v44, v52, v53
	v_cvt_pk_bf16_f32 v45, v54, v55
	v_cvt_pk_bf16_f32 v46, v46, v47
	v_cvt_pk_bf16_f32 v47, v68, v69
	global_store_dwordx4 v[74:75], v[44:47], off offset:256
	s_mov_b64 s[18:19], 0

; template <class Epi>
; __device__ __forceinline__ void gemm_phase(LAS unsigned char* lds, const Gemm g, const StaticOrder& S, const Epi& E) {
;     ...
;     for (;;) {
;         const bool has_next = S.next(ui + 1, nxt);
;         const char* nA = has_next ? (const char*)g.A + (size_t)nxt.pm * tstepA : cA; const char* nB = has_next ? (const char*)g.Bt + (size_t)nxt.pn * tstepB : cB;
;     ...
;         cur = nxt; cA = nA; cB = nB; ++ui;
.LBB0_674:
	s_or_b64 exec, exec, s[4:5]
	s_and_b64 vcc, exec, s[2:3]
	s_mov_b32 s10, s16
	s_mov_b32 s12, s44
	s_mov_b64 s[22:23], s[20:21]
	s_mov_b64 s[24:25], s[18:19]
	s_cbranch_vccnz .LBB0_701
	s_branch .LBB0_675

; #define PG8_STAGE(bufoff, gbase, voff) do { _Pragma("unroll") for (int _i = 0; _i < 2; ++_i) \
;         __builtin_amdgcn_global_load_lds((const unsigned*)((const char*)(gbase) + (voff)[_i]), (LAS unsigned*)(lds + (bufoff) + ldsw + _i * 8192), 16, 0, 0); } while (0)
; #define PG8_LDA(dst, b, h) do { _Pragma("unroll") for (int m = 0; m < 4; ++m) _Pragma("unroll") for (int k = 0; k < 2; ++k) dst[m][k] = *(const LAS bf16x8*)(lds + PG8_SA(b, h) + aoff + m * 2048 + k * 1024); } while (0)
; #define PG8_LDB(dst, b, h) do { _Pragma("unroll") for (int n = 0; n < 2; ++n) _Pragma("unroll") for (int k = 0; k < 2; ++k) dst[n][k] = *(const LAS bf16x8*)(lds + PG8_SB(b, h) + boff + n * 2048 + k * 1024); } while (0)
; #define PG8_WAIT_V(n) asm volatile("s_waitcnt vmcnt(" #n ")" ::: "memory")
; #define PG8_WAIT_L(n) asm volatile("s_waitcnt lgkmcnt(" #n ")" ::: "memory")
; #define PG8_BAR __builtin_amdgcn_s_barrier()
; #define PG8_SCHED __builtin_amdgcn_sched_barrier(0)
; template <class Epi>
; __device__ __forceinline__ void gemm_phase(LAS unsigned char* lds, const Gemm g, const StaticOrder& S, const Epi& E) {
;     ...
;         const char* nA = has_next ? (const char*)g.A + (size_t)nxt.pm * tstepA : cA; const char* nB = has_next ? (const char*)g.Bt + (size_t)nxt.pn * tstepB : cB;
;         for (int t = 0; t < nt; t += 2) {
;             const bool last = (t == nt - 2);
;             const char* a1 = cA + (size_t)(t + 1) * kstep;
;             const char* a2 = last ? nA : cA + (size_t)(t + 2) * kstep; const char* b2 = last ? nB : cB + (size_t)(t + 2) * kstep;
;             const char* a3 = a2 + kstep; const char* b3 = b2 + kstep;
;             if (last) E.pre(cur, wr, fr, epre);
;             PG8_LDB(B0, 0, 0); PG8_SCHED; PG8_LDA(At, 0, 0); PG8_STAGE(PG8_SA(1, 1), a1 + hstepA, voffA);
;             PG8_WAIT_L(8); PG8_BAR; PG8_WAIT_L(0); PG8_MMA(0, 0, At, B0); PG8_BAR; PG8_SCHED;
;             PG8_LDB(B1, 0, 1); PG8_STAGE(PG8_SB(0, 0), b2, voffB);
;             PG8_BAR; PG8_WAIT_L(0); PG8_MMA(0, 1, At, B1); PG8_BAR;
;             PG8_LDA(At, 0, 1); PG8_STAGE(PG8_SA(0, 0), a2, voffA);
;             PG8_BAR; PG8_WAIT_L(0); PG8_MMA(1, 0, At, B0); PG8_BAR; PG8_SCHED;
;             PG8_STAGE(PG8_SB(0, 1), b2 + hstepB, voffB);
;             PG8_WAIT_V(6); PG8_BAR; PG8_MMA(1, 1, At, B1); PG8_BAR;
.Lkp1_683:
	s_ashr_i32 s17, s16, 31
	s_lshl_b64 s[20:21], s[16:17], 20
	s_add_u32 s20, s29, s20
	s_addc_u32 s21, s30, s21
	s_and_b64 s[4:5], s[4:5], exec
	s_cselect_b32 s17, s21, s23
	s_cselect_b32 s45, s20, s22
	s_add_u32 s4, s24, 0x140080
	s_addc_u32 s5, s25, 0
	s_add_u32 s46, s22, 0x100
	s_addc_u32 s47, s23, 0
	s_mov_b32 s48, -2
	s_waitcnt lgkmcnt(0)
	ds_read_b128 v[128:131], v191
	ds_read_b128 v[132:135], v191 offset:1024
	ds_read_b128 v[136:139], v191 offset:2048
	ds_read_b128 v[140:143], v191 offset:3072
	s_add_u32 s22, s4, 0xffec0080
	s_addc_u32 s23, s5, -1
	s_cmp_eq_u32 s48, 28
	s_cselect_b32 s25, s19, s23
	s_cselect_b32 s24, s18, s22
	s_cselect_b32 s23, s17, s47
	s_cselect_b32 s22, s45, s46
	v_lshl_add_u64 v[186:187], s[4:5], 0, v[162:163]
	s_add_i32 m0, s11, 0xc000
	ds_read_b128 v[144:147], v192
	ds_read_b128 v[148:151], v192 offset:1024
	ds_read_b128 v[170:173], v192 offset:2048
	ds_read_b128 v[174:177], v192 offset:3072
	ds_read_b128 v[178:181], v192 offset:4096
	ds_read_b128 v[182:185], v192 offset:5120
	ds_read_b128 v[196:199], v192 offset:6144
	ds_read_b128 v[200:203], v192 offset:7168
	global_load_lds_dwordx4 v[186:187], off
	v_lshl_add_u64 v[186:187], s[4:5], 0, v[164:165]
	s_add_i32 m0, s11, 0xe000
	s_nop 0
	global_load_lds_dwordx4 v[186:187], off
	s_waitcnt lgkmcnt(8)
	s_barrier
	s_waitcnt lgkmcnt(0)
	s_setprio 2
	s_waitcnt lgkmcnt(0)
	v_mfma_f32_16x16x32_bf16 v[124:127], v[128:131], v[144:147], 0
	v_mfma_f32_16x16x32_bf16 v[120:123], v[136:139], v[144:147], 0
	v_mfma_f32_16x16x32_bf16 v[108:111], v[128:131], v[170:173], 0
	v_mfma_f32_16x16x32_bf16 v[104:107], v[136:139], v[170:173], 0
	v_mfma_f32_16x16x32_bf16 v[92:95], v[128:131], v[178:181], 0
	v_mfma_f32_16x16x32_bf16 v[88:91], v[136:139], v[178:181], 0
	v_mfma_f32_16x16x32_bf16 v[76:79], v[128:131], v[196:199], 0
	v_mfma_f32_16x16x32_bf16 v[72:75], v[136:139], v[196:199], 0
	v_mfma_f32_16x16x32_bf16 v[124:127], v[132:135], v[148:151], v[124:127]
	v_mfma_f32_16x16x32_bf16 v[120:123], v[140:143], v[148:151], v[120:123]
	v_mfma_f32_16x16x32_bf16 v[108:111], v[132:135], v[174:177], v[108:111]
	v_mfma_f32_16x16x32_bf16 v[104:107], v[140:143], v[174:177], v[104:107]
	v_mfma_f32_16x16x32_bf16 v[92:95], v[132:135], v[182:185], v[92:95]
	v_mfma_f32_16x16x32_bf16 v[88:91], v[140:143], v[182:185], v[88:91]
	v_mfma_f32_16x16x32_bf16 v[76:79], v[132:135], v[200:203], v[76:79]
	v_mfma_f32_16x16x32_bf16 v[72:75], v[140:143], v[200:203], v[72:75]
	s_setprio 1
	s_barrier
	s_add_i32 s49, s42, s31
	v_lshl_add_u64 v[186:187], s[22:23], 0, v[156:157]
	s_mov_b32 m0, s49
	ds_read_b128 v[204:207], v193
	ds_read_b128 v[208:211], v193 offset:1024
	ds_read_b128 v[212:215], v193 offset:2048
	ds_read_b128 v[216:219], v193 offset:3072
	global_load_lds_dwordx4 v[186:187], off
	v_lshl_add_u64 v[220:221], s[22:23], 0, v[160:161]
	s_add_i32 m0, s49, 0x2000
	s_nop 0
	global_load_lds_dwordx4 v[220:221], off
	s_barrier
	s_waitcnt lgkmcnt(0)
	s_setprio 2
	s_waitcnt lgkmcnt(0)
	v_mfma_f32_16x16x32_bf16 v[116:119], v[204:207], v[144:147], 0
	v_mfma_f32_16x16x32_bf16 v[112:115], v[212:215], v[144:147], 0
	v_mfma_f32_16x16x32_bf16 v[100:103], v[204:207], v[170:173], 0
	v_mfma_f32_16x16x32_bf16 v[96:99], v[212:215], v[170:173], 0
	v_mfma_f32_16x16x32_bf16 v[84:87], v[204:207], v[178:181], 0
	v_mfma_f32_16x16x32_bf16 v[80:83], v[212:215], v[178:181], 0
	v_mfma_f32_16x16x32_bf16 v[68:71], v[204:207], v[196:199], 0
	v_mfma_f32_16x16x32_bf16 v[64:67], v[212:215], v[196:199], 0
	v_mfma_f32_16x16x32_bf16 v[116:119], v[208:211], v[148:151], v[116:119]
	v_mfma_f32_16x16x32_bf16 v[112:115], v[216:219], v[148:151], v[112:115]
	v_mfma_f32_16x16x32_bf16 v[100:103], v[208:211], v[174:177], v[100:103]
	v_mfma_f32_16x16x32_bf16 v[96:99], v[216:219], v[174:177], v[96:99]
	v_mfma_f32_16x16x32_bf16 v[84:87], v[208:211], v[182:185], v[84:87]
	v_mfma_f32_16x16x32_bf16 v[80:83], v[216:219], v[182:185], v[80:83]
	v_mfma_f32_16x16x32_bf16 v[68:71], v[208:211], v[200:203], v[68:71]
	v_mfma_f32_16x16x32_bf16 v[64:67], v[216:219], v[200:203], v[64:67]
	s_setprio 1
	s_mov_b32 m0, s11
	v_lshl_add_u64 v[222:223], s[24:25], 0, v[154:155]
	s_barrier
	ds_read_b128 v[144:147], v192 offset:16384
	ds_read_b128 v[148:151], v192 offset:17408
	ds_read_b128 v[170:173], v192 offset:18432
	ds_read_b128 v[174:177], v192 offset:19456
	ds_read_b128 v[178:181], v192 offset:20480
	ds_read_b128 v[182:185], v192 offset:21504
	ds_read_b128 v[196:199], v192 offset:22528
	ds_read_b128 v[200:203], v192 offset:23552
	global_load_lds_dwordx4 v[222:223], off
	v_lshl_add_u64 v[224:225], s[24:25], 0, v[158:159]
	s_mov_b32 m0, s34
	s_nop 0
	global_load_lds_dwordx4 v[224:225], off
	s_barrier
	s_waitcnt lgkmcnt(0)
	s_setprio 2
	s_waitcnt lgkmcnt(0)
	v_mfma_f32_16x16x32_bf16 v[60:63], v[128:131], v[144:147], 0
	v_mfma_f32_16x16x32_bf16 v[56:59], v[136:139], v[144:147], 0
	v_mfma_f32_16x16x32_bf16 v[44:47], v[128:131], v[170:173], 0
	v_mfma_f32_16x16x32_bf16 v[40:43], v[136:139], v[170:173], 0
	v_mfma_f32_16x16x32_bf16 v[28:31], v[128:131], v[178:181], 0
	v_mfma_f32_16x16x32_bf16 v[24:27], v[136:139], v[178:181], 0
	v_mfma_f32_16x16x32_bf16 v[12:15], v[128:131], v[196:199], 0
	v_mfma_f32_16x16x32_bf16 v[8:11], v[136:139], v[196:199], 0
	v_mfma_f32_16x16x32_bf16 v[60:63], v[132:135], v[148:151], v[60:63]
	v_mfma_f32_16x16x32_bf16 v[56:59], v[140:143], v[148:151], v[56:59]
	v_mfma_f32_16x16x32_bf16 v[44:47], v[132:135], v[174:177], v[44:47]
	v_mfma_f32_16x16x32_bf16 v[40:43], v[140:143], v[174:177], v[40:43]
	v_mfma_f32_16x16x32_bf16 v[28:31], v[132:135], v[182:185], v[28:31]
	v_mfma_f32_16x16x32_bf16 v[24:27], v[140:143], v[182:185], v[24:27]
	v_mfma_f32_16x16x32_bf16 v[12:15], v[132:135], v[200:203], v[12:15]
	v_mfma_f32_16x16x32_bf16 v[8:11], v[140:143], v[200:203], v[8:11]
	s_setprio 1
	s_barrier
; #define PG8_STAGE(bufoff, gbase, voff) do { _Pragma("unroll") for (int _i = 0; _i < 2; ++_i) \
;         __builtin_amdgcn_global_load_lds((const unsigned*)((const char*)(gbase) + (voff)[_i]), (LAS unsigned*)(lds + (bufoff) + ldsw + _i * 8192), 16, 0, 0); } while (0)
; #define PG8_LDA(dst, b, h) do { _Pragma("unroll") for (int m = 0; m < 4; ++m) _Pragma("unroll") for (int k = 0; k < 2; ++k) dst[m][k] = *(const LAS bf16x8*)(lds + PG8_SA(b, h) + aoff + m * 2048 + k * 1024); } while (0)
; #define PG8_LDB(dst, b, h) do { _Pragma("unroll") for (int n = 0; n < 2; ++n) _Pragma("unroll") for (int k = 0; k < 2; ++k) dst[n][k] = *(const LAS bf16x8*)(lds + PG8_SB(b, h) + boff + n * 2048 + k * 1024); } while (0)
; #define PG8_MMA(ai, bj, At, Bt) do { __builtin_amdgcn_s_setprio(1); _Pragma("unroll") for (int m = 0; m < 4; ++m) _Pragma("unroll") for (int n = 0; n < 2; ++n) _Pragma("unroll") for (int k = 0; k < 2; ++k) \
;         acc[ai][bj][m][n] = __builtin_amdgcn_mfma_f32_16x16x32_bf16(Bt[n][k], At[m][k], acc[ai][bj][m][n], 0, 0, 0); __builtin_amdgcn_s_setprio(0); } while (0)
; #define PG8_WAIT_V(n) asm volatile("s_waitcnt vmcnt(" #n ")" ::: "memory")
; #define PG8_WAIT_L(n) asm volatile("s_waitcnt lgkmcnt(" #n ")" ::: "memory")
; #define PG8_BAR __builtin_amdgcn_s_barrier()
; #define PG8_SCHED __builtin_amdgcn_sched_barrier(0)
; template <class Epi>
; __device__ __forceinline__ void gemm_phase(LAS unsigned char* lds, const Gemm g, const StaticOrder& S, const Epi& E) {
;     ...
;             PG8_STAGE(PG8_SB(0, 1), b2 + hstepB, voffB);
;             PG8_WAIT_V(6); PG8_BAR; PG8_MMA(1, 1, At, B1); PG8_BAR;
;             PG8_LDB(B0, 1, 0); PG8_SCHED; PG8_LDA(At, 1, 0); PG8_STAGE(PG8_SA(0, 1), a2 + hstepA, voffA);
;             PG8_WAIT_L(8); PG8_BAR; PG8_WAIT_L(0); PG8_MMA(0, 0, At, B0); PG8_BAR; PG8_SCHED;
;             PG8_LDB(B1, 1, 1); PG8_STAGE(PG8_SB(1, 0), b3, voffB);
;             PG8_BAR; PG8_WAIT_L(0); PG8_MMA(0, 1, At, B1); PG8_BAR;
;             PG8_LDA(At, 1, 1); PG8_STAGE(PG8_SA(1, 0), a3, voffA);
;             PG8_BAR; PG8_WAIT_L(0); PG8_MMA(1, 0, At, B0); PG8_BAR; PG8_SCHED;
;             PG8_STAGE(PG8_SB(1, 1), b3 + hstepB, voffB);
;             PG8_WAIT_V(6); PG8_BAR; PG8_MMA(1, 1, At, B1); PG8_BAR;
	s_add_u32 s50, s22, 0x80000
	s_addc_u32 s51, s23, 0
	s_add_i32 s49, s43, s31
	v_lshl_add_u64 v[128:129], s[50:51], 0, v[156:157]
	s_mov_b32 m0, s49
	s_nop 0
	global_load_lds_dwordx4 v[128:129], off
	v_lshl_add_u64 v[128:129], s[50:51], 0, v[160:161]
	s_add_i32 m0, s49, 0x2000
	s_nop 0
	global_load_lds_dwordx4 v[128:129], off
	s_waitcnt vmcnt(6)
	s_barrier
	s_setprio 2
	v_mfma_f32_16x16x32_bf16 v[52:55], v[204:207], v[144:147], 0
	v_mfma_f32_16x16x32_bf16 v[48:51], v[212:215], v[144:147], 0
	v_mfma_f32_16x16x32_bf16 v[36:39], v[204:207], v[170:173], 0
	v_mfma_f32_16x16x32_bf16 v[32:35], v[212:215], v[170:173], 0
	v_mfma_f32_16x16x32_bf16 v[20:23], v[204:207], v[178:181], 0
	v_mfma_f32_16x16x32_bf16 v[16:19], v[212:215], v[178:181], 0
	v_mfma_f32_16x16x32_bf16 v[4:7], v[204:207], v[196:199], 0
	v_mfma_f32_16x16x32_bf16 v[0:3], v[212:215], v[196:199], 0
	v_mfma_f32_16x16x32_bf16 v[52:55], v[208:211], v[148:151], v[52:55]
	v_mfma_f32_16x16x32_bf16 v[48:51], v[216:219], v[148:151], v[48:51]
	v_mfma_f32_16x16x32_bf16 v[36:39], v[208:211], v[174:177], v[36:39]
	v_mfma_f32_16x16x32_bf16 v[32:35], v[216:219], v[174:177], v[32:35]
	v_mfma_f32_16x16x32_bf16 v[20:23], v[208:211], v[182:185], v[20:23]
	v_mfma_f32_16x16x32_bf16 v[16:19], v[216:219], v[182:185], v[16:19]
	v_mfma_f32_16x16x32_bf16 v[4:7], v[208:211], v[200:203], v[4:7]
	v_mfma_f32_16x16x32_bf16 v[0:3], v[216:219], v[200:203], v[0:3]
	s_setprio 1
	s_add_i32 s49, 0, 0x18000
	v_add_u32_e32 v140, s49, v189
	s_barrier
	ds_read_b128 v[128:131], v140
	ds_read_b128 v[132:135], v140 offset:1024
	ds_read_b128 v[136:139], v140 offset:2048
	ds_read_b128 v[140:143], v140 offset:3072
	s_add_u32 s24, s24, 0x140000
	s_addc_u32 s25, s25, 0
	s_mov_b32 m0, s35
	v_lshl_add_u64 v[204:205], s[24:25], 0, v[154:155]
	ds_read_b128 v[144:147], v192 offset:32768
	ds_read_b128 v[148:151], v192 offset:33792
	ds_read_b128 v[170:173], v192 offset:34816
	ds_read_b128 v[174:177], v192 offset:35840
	ds_read_b128 v[178:181], v192 offset:36864
	ds_read_b128 v[182:185], v192 offset:37888
	ds_read_b128 v[196:199], v192 offset:38912
	ds_read_b128 v[200:203], v192 offset:39936
	global_load_lds_dwordx4 v[204:205], off
	v_lshl_add_u64 v[204:205], s[24:25], 0, v[158:159]
	s_mov_b32 m0, s36
	s_nop 0
	global_load_lds_dwordx4 v[204:205], off
	s_waitcnt lgkmcnt(8)
	s_barrier
	s_waitcnt lgkmcnt(0)
	s_setprio 2
	s_waitcnt lgkmcnt(0)
	v_mfma_f32_16x16x32_bf16 v[124:127], v[128:131], v[144:147], v[124:127]
	v_mfma_f32_16x16x32_bf16 v[120:123], v[136:139], v[144:147], v[120:123]
	v_mfma_f32_16x16x32_bf16 v[108:111], v[128:131], v[170:173], v[108:111]
	v_mfma_f32_16x16x32_bf16 v[104:107], v[136:139], v[170:173], v[104:107]
	v_mfma_f32_16x16x32_bf16 v[92:95], v[128:131], v[178:181], v[92:95]
	v_mfma_f32_16x16x32_bf16 v[88:91], v[136:139], v[178:181], v[88:91]
	v_mfma_f32_16x16x32_bf16 v[76:79], v[128:131], v[196:199], v[76:79]
	v_mfma_f32_16x16x32_bf16 v[72:75], v[136:139], v[196:199], v[72:75]
	v_mfma_f32_16x16x32_bf16 v[124:127], v[132:135], v[148:151], v[124:127]
	v_mfma_f32_16x16x32_bf16 v[120:123], v[140:143], v[148:151], v[120:123]
	v_mfma_f32_16x16x32_bf16 v[108:111], v[132:135], v[174:177], v[108:111]
	v_mfma_f32_16x16x32_bf16 v[104:107], v[140:143], v[174:177], v[104:107]
	v_mfma_f32_16x16x32_bf16 v[92:95], v[132:135], v[182:185], v[92:95]
	v_mfma_f32_16x16x32_bf16 v[88:91], v[140:143], v[182:185], v[88:91]
	v_mfma_f32_16x16x32_bf16 v[76:79], v[132:135], v[200:203], v[76:79]
	v_mfma_f32_16x16x32_bf16 v[72:75], v[140:143], v[200:203], v[72:75]
	s_setprio 1
	s_barrier
	s_add_i32 s24, 0, 0x1c000
	s_add_i32 s25, s49, s31
	v_add_u32_e32 v195, s24, v189
	v_lshl_add_u64 v[186:187], v[186:187], 0, s[14:15]
	s_mov_b32 m0, s25
	ds_read_b128 v[204:207], v195
	ds_read_b128 v[208:211], v195 offset:1024
	ds_read_b128 v[212:215], v195 offset:2048
	ds_read_b128 v[216:219], v195 offset:3072
	global_load_lds_dwordx4 v[186:187], off
	v_lshl_add_u64 v[186:187], v[220:221], 0, s[14:15]
	s_add_i32 m0, s25, 0x2000
	s_nop 0
	global_load_lds_dwordx4 v[186:187], off
	s_barrier
	s_waitcnt lgkmcnt(0)
	s_setprio 2
	s_waitcnt lgkmcnt(0)
	v_mfma_f32_16x16x32_bf16 v[116:119], v[204:207], v[144:147], v[116:119]
	v_mfma_f32_16x16x32_bf16 v[112:115], v[212:215], v[144:147], v[112:115]
	v_mfma_f32_16x16x32_bf16 v[100:103], v[204:207], v[170:173], v[100:103]
	v_mfma_f32_16x16x32_bf16 v[96:99], v[212:215], v[170:173], v[96:99]
	v_mfma_f32_16x16x32_bf16 v[84:87], v[204:207], v[178:181], v[84:87]
	v_mfma_f32_16x16x32_bf16 v[80:83], v[212:215], v[178:181], v[80:83]
	v_mfma_f32_16x16x32_bf16 v[68:71], v[204:207], v[196:199], v[68:71]
	v_mfma_f32_16x16x32_bf16 v[64:67], v[212:215], v[196:199], v[64:67]
	v_mfma_f32_16x16x32_bf16 v[116:119], v[208:211], v[148:151], v[116:119]
	v_mfma_f32_16x16x32_bf16 v[112:115], v[216:219], v[148:151], v[112:115]
	v_mfma_f32_16x16x32_bf16 v[100:103], v[208:211], v[174:177], v[100:103]
	v_mfma_f32_16x16x32_bf16 v[96:99], v[216:219], v[174:177], v[96:99]
	v_mfma_f32_16x16x32_bf16 v[84:87], v[208:211], v[182:185], v[84:87]
	v_mfma_f32_16x16x32_bf16 v[80:83], v[216:219], v[182:185], v[80:83]
	v_mfma_f32_16x16x32_bf16 v[68:71], v[208:211], v[200:203], v[68:71]
	v_mfma_f32_16x16x32_bf16 v[64:67], v[216:219], v[200:203], v[64:67]
	s_setprio 1
	s_mov_b32 m0, s38
	v_lshl_add_u64 v[186:187], v[222:223], 0, s[14:15]
	s_barrier
	ds_read_b128 v[144:147], v192 offset:49152
	ds_read_b128 v[148:151], v192 offset:50176
	ds_read_b128 v[170:173], v192 offset:51200
	ds_read_b128 v[174:177], v192 offset:52224
	ds_read_b128 v[178:181], v192 offset:53248
	ds_read_b128 v[182:185], v192 offset:54272
	ds_read_b128 v[196:199], v192 offset:55296
	ds_read_b128 v[200:203], v192 offset:56320
	global_load_lds_dwordx4 v[186:187], off
	v_lshl_add_u64 v[186:187], v[224:225], 0, s[14:15]
	s_mov_b32 m0, s39
	s_nop 0
	global_load_lds_dwordx4 v[186:187], off
	s_barrier
; #define PG8_STAGE(bufoff, gbase, voff) do { _Pragma("unroll") for (int _i = 0; _i < 2; ++_i) \
;         __builtin_amdgcn_global_load_lds((const unsigned*)((const char*)(gbase) + (voff)[_i]), (LAS unsigned*)(lds + (bufoff) + ldsw + _i * 8192), 16, 0, 0); } while (0)
; #define PG8_LDA(dst, b, h) do { _Pragma("unroll") for (int m = 0; m < 4; ++m) _Pragma("unroll") for (int k = 0; k < 2; ++k) dst[m][k] = *(const LAS bf16x8*)(lds + PG8_SA(b, h) + aoff + m * 2048 + k * 1024); } while (0)
; #define PG8_WAIT_V(n) asm volatile("s_waitcnt vmcnt(" #n ")" ::: "memory")
; template <class Epi>
; __device__ __forceinline__ void gemm_phase(LAS unsigned char* lds, const Gemm g, const StaticOrder& S, const Epi& E) {
;     ...
;         for (int t = 0; t < nt; t += 2) {
;             const bool last = (t == nt - 2);
;             const char* a1 = cA + (size_t)(t + 1) * kstep;
;             const char* a2 = last ? nA : cA + (size_t)(t + 2) * kstep; const char* b2 = last ? nB : cB + (size_t)(t + 2) * kstep;
;             const char* a3 = a2 + kstep; const char* b3 = b2 + kstep;
;             if (last) E.pre(cur, wr, fr, epre);
;             PG8_LDB(B0, 0, 0); PG8_SCHED; PG8_LDA(At, 0, 0); PG8_STAGE(PG8_SA(1, 1), a1 + hstepA, voffA);
;             PG8_WAIT_L(8); PG8_BAR; PG8_WAIT_L(0); PG8_MMA(0, 0, At, B0); PG8_BAR; PG8_SCHED;
;             PG8_LDB(B1, 0, 1); PG8_STAGE(PG8_SB(0, 0), b2, voffB);
;             PG8_BAR; PG8_WAIT_L(0); PG8_MMA(0, 1, At, B1); PG8_BAR;
;             PG8_LDA(At, 0, 1); PG8_STAGE(PG8_SA(0, 0), a2, voffA);
;             PG8_BAR; PG8_WAIT_L(0); PG8_MMA(1, 0, At, B0); PG8_BAR; PG8_SCHED;
;             PG8_STAGE(PG8_SB(0, 1), b2 + hstepB, voffB);
;             PG8_WAIT_V(6); PG8_BAR; PG8_MMA(1, 1, At, B1); PG8_BAR;
;             PG8_LDB(B0, 1, 0); PG8_SCHED; PG8_LDA(At, 1, 0); PG8_STAGE(PG8_SA(0, 1), a2 + hstepA, voffA);
;             PG8_WAIT_L(8); PG8_BAR; PG8_WAIT_L(0); PG8_MMA(0, 0, At, B0); PG8_BAR; PG8_SCHED;
;             PG8_LDB(B1, 1, 1); PG8_STAGE(PG8_SB(1, 0), b3, voffB);
;             PG8_BAR; PG8_WAIT_L(0); PG8_MMA(0, 1, At, B1); PG8_BAR;
;             PG8_LDA(At, 1, 1); PG8_STAGE(PG8_SA(1, 0), a3, voffA);
;             PG8_BAR; PG8_WAIT_L(0); PG8_MMA(1, 0, At, B0); PG8_BAR; PG8_SCHED;
;             PG8_STAGE(PG8_SB(1, 1), b3 + hstepB, voffB);
;             PG8_WAIT_V(6); PG8_BAR; PG8_MMA(1, 1, At, B1); PG8_BAR;
	s_waitcnt lgkmcnt(0)
	s_setprio 2
	s_waitcnt lgkmcnt(0)
	v_mfma_f32_16x16x32_bf16 v[60:63], v[128:131], v[144:147], v[60:63]
	v_mfma_f32_16x16x32_bf16 v[56:59], v[136:139], v[144:147], v[56:59]
	v_mfma_f32_16x16x32_bf16 v[44:47], v[128:131], v[170:173], v[44:47]
	v_mfma_f32_16x16x32_bf16 v[40:43], v[136:139], v[170:173], v[40:43]
	v_mfma_f32_16x16x32_bf16 v[28:31], v[128:131], v[178:181], v[28:31]
	v_mfma_f32_16x16x32_bf16 v[24:27], v[136:139], v[178:181], v[24:27]
	v_mfma_f32_16x16x32_bf16 v[12:15], v[128:131], v[196:199], v[12:15]
	v_mfma_f32_16x16x32_bf16 v[8:11], v[136:139], v[196:199], v[8:11]
	v_mfma_f32_16x16x32_bf16 v[60:63], v[132:135], v[148:151], v[60:63]
	v_mfma_f32_16x16x32_bf16 v[56:59], v[140:143], v[148:151], v[56:59]
	v_mfma_f32_16x16x32_bf16 v[44:47], v[132:135], v[174:177], v[44:47]
	v_mfma_f32_16x16x32_bf16 v[40:43], v[140:143], v[174:177], v[40:43]
	v_mfma_f32_16x16x32_bf16 v[28:31], v[132:135], v[182:185], v[28:31]
	v_mfma_f32_16x16x32_bf16 v[24:27], v[140:143], v[182:185], v[24:27]
	v_mfma_f32_16x16x32_bf16 v[12:15], v[132:135], v[200:203], v[12:15]
	v_mfma_f32_16x16x32_bf16 v[8:11], v[140:143], v[200:203], v[8:11]
	s_setprio 1
	s_barrier
	s_add_u32 s22, s22, 0x80080
	s_addc_u32 s23, s23, 0
	s_add_i32 s24, s24, s31
	v_lshl_add_u64 v[128:129], s[22:23], 0, v[156:157]
	s_mov_b32 m0, s24
	s_nop 0
	global_load_lds_dwordx4 v[128:129], off
	v_lshl_add_u64 v[128:129], s[22:23], 0, v[160:161]
	s_add_i32 m0, s24, 0x2000
	s_nop 0
	global_load_lds_dwordx4 v[128:129], off
	s_waitcnt vmcnt(6)
	s_barrier
	s_setprio 2
	v_mfma_f32_16x16x32_bf16 v[52:55], v[204:207], v[144:147], v[52:55]
	v_mfma_f32_16x16x32_bf16 v[48:51], v[212:215], v[144:147], v[48:51]
	v_mfma_f32_16x16x32_bf16 v[36:39], v[204:207], v[170:173], v[36:39]
	v_mfma_f32_16x16x32_bf16 v[32:35], v[212:215], v[170:173], v[32:35]
	v_mfma_f32_16x16x32_bf16 v[20:23], v[204:207], v[178:181], v[20:23]
	v_mfma_f32_16x16x32_bf16 v[16:19], v[212:215], v[178:181], v[16:19]
	v_mfma_f32_16x16x32_bf16 v[4:7], v[204:207], v[196:199], v[4:7]
	v_mfma_f32_16x16x32_bf16 v[0:3], v[212:215], v[196:199], v[0:3]
	v_mfma_f32_16x16x32_bf16 v[52:55], v[208:211], v[148:151], v[52:55]
	v_mfma_f32_16x16x32_bf16 v[48:51], v[216:219], v[148:151], v[48:51]
	v_mfma_f32_16x16x32_bf16 v[36:39], v[208:211], v[174:177], v[36:39]
	v_mfma_f32_16x16x32_bf16 v[32:35], v[216:219], v[174:177], v[32:35]
	v_mfma_f32_16x16x32_bf16 v[20:23], v[208:211], v[182:185], v[20:23]
	v_mfma_f32_16x16x32_bf16 v[16:19], v[216:219], v[182:185], v[16:19]
	v_mfma_f32_16x16x32_bf16 v[4:7], v[208:211], v[200:203], v[4:7]
	v_mfma_f32_16x16x32_bf16 v[0:3], v[216:219], v[200:203], v[0:3]
	s_setprio 1
	s_add_i32 s48, s48, 2
	s_add_u32 s4, s4, 0x100
	s_addc_u32 s5, s5, 0
	s_add_u32 s46, s46, 0x100
	s_addc_u32 s47, s47, 0
	s_cmp_gt_u32 s48, 29
	s_barrier
.Lkp1_684:
	ds_read_b128 v[128:131], v191
	ds_read_b128 v[132:135], v191 offset:1024
	ds_read_b128 v[136:139], v191 offset:2048
	ds_read_b128 v[140:143], v191 offset:3072
	s_add_u32 s22, s4, 0xffec0080
	s_addc_u32 s23, s5, -1
	s_cmp_eq_u32 s48, 28
	s_cselect_b32 s25, s19, s23
	s_cselect_b32 s24, s18, s22
	s_cselect_b32 s23, s17, s47
	s_cselect_b32 s22, s45, s46
	v_lshl_add_u64 v[186:187], s[4:5], 0, v[162:163]
	s_add_i32 m0, s11, 0xc000
	ds_read_b128 v[144:147], v192
	ds_read_b128 v[148:151], v192 offset:1024
	ds_read_b128 v[170:173], v192 offset:2048
	ds_read_b128 v[174:177], v192 offset:3072
	ds_read_b128 v[178:181], v192 offset:4096
	ds_read_b128 v[182:185], v192 offset:5120
	ds_read_b128 v[196:199], v192 offset:6144
	ds_read_b128 v[200:203], v192 offset:7168
	global_load_lds_dwordx4 v[186:187], off
	v_lshl_add_u64 v[186:187], s[4:5], 0, v[164:165]
	s_add_i32 m0, s11, 0xe000
	s_nop 0
	global_load_lds_dwordx4 v[186:187], off
	s_waitcnt lgkmcnt(8)
	s_barrier
	s_waitcnt lgkmcnt(0)
	s_setprio 2
	s_waitcnt lgkmcnt(0)
	v_mfma_f32_16x16x32_bf16 v[124:127], v[128:131], v[144:147], v[124:127]
	v_mfma_f32_16x16x32_bf16 v[120:123], v[136:139], v[144:147], v[120:123]
	v_mfma_f32_16x16x32_bf16 v[108:111], v[128:131], v[170:173], v[108:111]
	v_mfma_f32_16x16x32_bf16 v[104:107], v[136:139], v[170:173], v[104:107]
	v_mfma_f32_16x16x32_bf16 v[92:95], v[128:131], v[178:181], v[92:95]
	v_mfma_f32_16x16x32_bf16 v[88:91], v[136:139], v[178:181], v[88:91]
	v_mfma_f32_16x16x32_bf16 v[76:79], v[128:131], v[196:199], v[76:79]
	v_mfma_f32_16x16x32_bf16 v[72:75], v[136:139], v[196:199], v[72:75]
	v_mfma_f32_16x16x32_bf16 v[124:127], v[132:135], v[148:151], v[124:127]
	v_mfma_f32_16x16x32_bf16 v[120:123], v[140:143], v[148:151], v[120:123]
	v_mfma_f32_16x16x32_bf16 v[108:111], v[132:135], v[174:177], v[108:111]
	v_mfma_f32_16x16x32_bf16 v[104:107], v[140:143], v[174:177], v[104:107]
	v_mfma_f32_16x16x32_bf16 v[92:95], v[132:135], v[182:185], v[92:95]
	v_mfma_f32_16x16x32_bf16 v[88:91], v[140:143], v[182:185], v[88:91]
	v_mfma_f32_16x16x32_bf16 v[76:79], v[132:135], v[200:203], v[76:79]
	v_mfma_f32_16x16x32_bf16 v[72:75], v[140:143], v[200:203], v[72:75]
	s_setprio 1
	s_barrier
	s_add_i32 s49, s42, s31
	v_lshl_add_u64 v[186:187], s[22:23], 0, v[156:157]
	s_mov_b32 m0, s49
	ds_read_b128 v[204:207], v193
	ds_read_b128 v[208:211], v193 offset:1024
	ds_read_b128 v[212:215], v193 offset:2048
	ds_read_b128 v[216:219], v193 offset:3072
	global_load_lds_dwordx4 v[186:187], off
	v_lshl_add_u64 v[220:221], s[22:23], 0, v[160:161]
	s_add_i32 m0, s49, 0x2000
	s_nop 0
	global_load_lds_dwordx4 v[220:221], off
	s_barrier
; #define PG8_STAGE(bufoff, gbase, voff) do { _Pragma("unroll") for (int _i = 0; _i < 2; ++_i) \
;         __builtin_amdgcn_global_load_lds((const unsigned*)((const char*)(gbase) + (voff)[_i]), (LAS unsigned*)(lds + (bufoff) + ldsw + _i * 8192), 16, 0, 0); } while (0)
; #define PG8_LDA(dst, b, h) do { _Pragma("unroll") for (int m = 0; m < 4; ++m) _Pragma("unroll") for (int k = 0; k < 2; ++k) dst[m][k] = *(const LAS bf16x8*)(lds + PG8_SA(b, h) + aoff + m * 2048 + k * 1024); } while (0)
; #define PG8_LDB(dst, b, h) do { _Pragma("unroll") for (int n = 0; n < 2; ++n) _Pragma("unroll") for (int k = 0; k < 2; ++k) dst[n][k] = *(const LAS bf16x8*)(lds + PG8_SB(b, h) + boff + n * 2048 + k * 1024); } while (0)
; #define PG8_MMA(ai, bj, At, Bt) do { __builtin_amdgcn_s_setprio(1); _Pragma("unroll") for (int m = 0; m < 4; ++m) _Pragma("unroll") for (int n = 0; n < 2; ++n) _Pragma("unroll") for (int k = 0; k < 2; ++k) \
;         acc[ai][bj][m][n] = __builtin_amdgcn_mfma_f32_16x16x32_bf16(Bt[n][k], At[m][k], acc[ai][bj][m][n], 0, 0, 0); __builtin_amdgcn_s_setprio(0); } while (0)
; #define PG8_WAIT_V(n) asm volatile("s_waitcnt vmcnt(" #n ")" ::: "memory")
; #define PG8_WAIT_L(n) asm volatile("s_waitcnt lgkmcnt(" #n ")" ::: "memory")
; #define PG8_BAR __builtin_amdgcn_s_barrier()
; #define PG8_SCHED __builtin_amdgcn_sched_barrier(0)
; template <class Epi>
; __device__ __forceinline__ void gemm_phase(LAS unsigned char* lds, const Gemm g, const StaticOrder& S, const Epi& E) {
;     ...
;             PG8_BAR; PG8_WAIT_L(0); PG8_MMA(0, 1, At, B1); PG8_BAR;
;             PG8_LDA(At, 0, 1); PG8_STAGE(PG8_SA(0, 0), a2, voffA);
;             PG8_BAR; PG8_WAIT_L(0); PG8_MMA(1, 0, At, B0); PG8_BAR; PG8_SCHED;
;             PG8_STAGE(PG8_SB(0, 1), b2 + hstepB, voffB);
;             PG8_WAIT_V(6); PG8_BAR; PG8_MMA(1, 1, At, B1); PG8_BAR;
;             PG8_LDB(B0, 1, 0); PG8_SCHED; PG8_LDA(At, 1, 0); PG8_STAGE(PG8_SA(0, 1), a2 + hstepA, voffA);
	s_waitcnt lgkmcnt(0)
	s_setprio 2
	s_waitcnt lgkmcnt(0)
	v_mfma_f32_16x16x32_bf16 v[116:119], v[204:207], v[144:147], v[116:119]
	v_mfma_f32_16x16x32_bf16 v[112:115], v[212:215], v[144:147], v[112:115]
	v_mfma_f32_16x16x32_bf16 v[100:103], v[204:207], v[170:173], v[100:103]
	v_mfma_f32_16x16x32_bf16 v[96:99], v[212:215], v[170:173], v[96:99]
	v_mfma_f32_16x16x32_bf16 v[84:87], v[204:207], v[178:181], v[84:87]
	v_mfma_f32_16x16x32_bf16 v[80:83], v[212:215], v[178:181], v[80:83]
	v_mfma_f32_16x16x32_bf16 v[68:71], v[204:207], v[196:199], v[68:71]
	v_mfma_f32_16x16x32_bf16 v[64:67], v[212:215], v[196:199], v[64:67]
	v_mfma_f32_16x16x32_bf16 v[116:119], v[208:211], v[148:151], v[116:119]
	v_mfma_f32_16x16x32_bf16 v[112:115], v[216:219], v[148:151], v[112:115]
	v_mfma_f32_16x16x32_bf16 v[100:103], v[208:211], v[174:177], v[100:103]
	v_mfma_f32_16x16x32_bf16 v[96:99], v[216:219], v[174:177], v[96:99]
	v_mfma_f32_16x16x32_bf16 v[84:87], v[208:211], v[182:185], v[84:87]
	v_mfma_f32_16x16x32_bf16 v[80:83], v[216:219], v[182:185], v[80:83]
	v_mfma_f32_16x16x32_bf16 v[68:71], v[208:211], v[200:203], v[68:71]
	v_mfma_f32_16x16x32_bf16 v[64:67], v[216:219], v[200:203], v[64:67]
	s_setprio 1
	s_mov_b32 m0, s11
	v_lshl_add_u64 v[222:223], s[24:25], 0, v[154:155]
	s_barrier
	ds_read_b128 v[144:147], v192 offset:16384
	ds_read_b128 v[148:151], v192 offset:17408
	ds_read_b128 v[170:173], v192 offset:18432
	ds_read_b128 v[174:177], v192 offset:19456
	ds_read_b128 v[178:181], v192 offset:20480
	ds_read_b128 v[182:185], v192 offset:21504
	ds_read_b128 v[196:199], v192 offset:22528
	ds_read_b128 v[200:203], v192 offset:23552
	global_load_lds_dwordx4 v[222:223], off
	v_lshl_add_u64 v[224:225], s[24:25], 0, v[158:159]
	s_mov_b32 m0, s34
	s_nop 0
	global_load_lds_dwordx4 v[224:225], off
	s_barrier
	s_waitcnt lgkmcnt(0)
	s_setprio 2
	s_waitcnt lgkmcnt(0)
	v_mfma_f32_16x16x32_bf16 v[60:63], v[128:131], v[144:147], v[60:63]
	v_mfma_f32_16x16x32_bf16 v[56:59], v[136:139], v[144:147], v[56:59]
	v_mfma_f32_16x16x32_bf16 v[44:47], v[128:131], v[170:173], v[44:47]
	v_mfma_f32_16x16x32_bf16 v[40:43], v[136:139], v[170:173], v[40:43]
	v_mfma_f32_16x16x32_bf16 v[28:31], v[128:131], v[178:181], v[28:31]
	v_mfma_f32_16x16x32_bf16 v[24:27], v[136:139], v[178:181], v[24:27]
	v_mfma_f32_16x16x32_bf16 v[12:15], v[128:131], v[196:199], v[12:15]
	v_mfma_f32_16x16x32_bf16 v[8:11], v[136:139], v[196:199], v[8:11]
	v_mfma_f32_16x16x32_bf16 v[60:63], v[132:135], v[148:151], v[60:63]
	v_mfma_f32_16x16x32_bf16 v[56:59], v[140:143], v[148:151], v[56:59]
	v_mfma_f32_16x16x32_bf16 v[44:47], v[132:135], v[174:177], v[44:47]
	v_mfma_f32_16x16x32_bf16 v[40:43], v[140:143], v[174:177], v[40:43]
	v_mfma_f32_16x16x32_bf16 v[28:31], v[132:135], v[182:185], v[28:31]
	v_mfma_f32_16x16x32_bf16 v[24:27], v[140:143], v[182:185], v[24:27]
	v_mfma_f32_16x16x32_bf16 v[12:15], v[132:135], v[200:203], v[12:15]
	v_mfma_f32_16x16x32_bf16 v[8:11], v[140:143], v[200:203], v[8:11]
	s_setprio 1
	s_barrier
	s_add_u32 s50, s22, 0x80000
	s_addc_u32 s51, s23, 0
	s_add_i32 s49, s43, s31
	v_lshl_add_u64 v[128:129], s[50:51], 0, v[156:157]
	s_mov_b32 m0, s49
	s_nop 0
	global_load_lds_dwordx4 v[128:129], off
	v_lshl_add_u64 v[128:129], s[50:51], 0, v[160:161]
	s_add_i32 m0, s49, 0x2000
	s_nop 0
	global_load_lds_dwordx4 v[128:129], off
	s_waitcnt vmcnt(6)
	s_barrier
	s_setprio 2
	v_mfma_f32_16x16x32_bf16 v[52:55], v[204:207], v[144:147], v[52:55]
	v_mfma_f32_16x16x32_bf16 v[48:51], v[212:215], v[144:147], v[48:51]
	v_mfma_f32_16x16x32_bf16 v[36:39], v[204:207], v[170:173], v[36:39]
	v_mfma_f32_16x16x32_bf16 v[32:35], v[212:215], v[170:173], v[32:35]
	v_mfma_f32_16x16x32_bf16 v[20:23], v[204:207], v[178:181], v[20:23]
	v_mfma_f32_16x16x32_bf16 v[16:19], v[212:215], v[178:181], v[16:19]
	v_mfma_f32_16x16x32_bf16 v[4:7], v[204:207], v[196:199], v[4:7]
	v_mfma_f32_16x16x32_bf16 v[0:3], v[212:215], v[196:199], v[0:3]
	v_mfma_f32_16x16x32_bf16 v[52:55], v[208:211], v[148:151], v[52:55]
	v_mfma_f32_16x16x32_bf16 v[48:51], v[216:219], v[148:151], v[48:51]
	v_mfma_f32_16x16x32_bf16 v[36:39], v[208:211], v[174:177], v[36:39]
	v_mfma_f32_16x16x32_bf16 v[32:35], v[216:219], v[174:177], v[32:35]
	v_mfma_f32_16x16x32_bf16 v[20:23], v[208:211], v[182:185], v[20:23]
	v_mfma_f32_16x16x32_bf16 v[16:19], v[216:219], v[182:185], v[16:19]
	v_mfma_f32_16x16x32_bf16 v[4:7], v[208:211], v[200:203], v[4:7]
	v_mfma_f32_16x16x32_bf16 v[0:3], v[216:219], v[200:203], v[0:3]
	s_setprio 1
	s_add_i32 s49, 0, 0x18000
	v_add_u32_e32 v140, s49, v189
	s_barrier
	ds_read_b128 v[128:131], v140
	ds_read_b128 v[132:135], v140 offset:1024
	ds_read_b128 v[136:139], v140 offset:2048
	ds_read_b128 v[140:143], v140 offset:3072
	s_add_u32 s24, s24, 0x140000
	s_addc_u32 s25, s25, 0
	s_mov_b32 m0, s35
	v_lshl_add_u64 v[204:205], s[24:25], 0, v[154:155]
	ds_read_b128 v[144:147], v192 offset:32768
	ds_read_b128 v[148:151], v192 offset:33792
	ds_read_b128 v[170:173], v192 offset:34816
	ds_read_b128 v[174:177], v192 offset:35840
	ds_read_b128 v[178:181], v192 offset:36864
	ds_read_b128 v[182:185], v192 offset:37888
	ds_read_b128 v[196:199], v192 offset:38912
	ds_read_b128 v[200:203], v192 offset:39936
	global_load_lds_dwordx4 v[204:205], off
	v_lshl_add_u64 v[204:205], s[24:25], 0, v[158:159]
	s_mov_b32 m0, s36
	s_nop 0
	global_load_lds_dwordx4 v[204:205], off
	s_waitcnt lgkmcnt(8)
	s_barrier
; #define PG8_STAGE(bufoff, gbase, voff) do { _Pragma("unroll") for (int _i = 0; _i < 2; ++_i) \
;         __builtin_amdgcn_global_load_lds((const unsigned*)((const char*)(gbase) + (voff)[_i]), (LAS unsigned*)(lds + (bufoff) + ldsw + _i * 8192), 16, 0, 0); } while (0)
; #define PG8_LDA(dst, b, h) do { _Pragma("unroll") for (int m = 0; m < 4; ++m) _Pragma("unroll") for (int k = 0; k < 2; ++k) dst[m][k] = *(const LAS bf16x8*)(lds + PG8_SA(b, h) + aoff + m * 2048 + k * 1024); } while (0)
; #define PG8_LDB(dst, b, h) do { _Pragma("unroll") for (int n = 0; n < 2; ++n) _Pragma("unroll") for (int k = 0; k < 2; ++k) dst[n][k] = *(const LAS bf16x8*)(lds + PG8_SB(b, h) + boff + n * 2048 + k * 1024); } while (0)
; #define PG8_MMA(ai, bj, At, Bt) do { __builtin_amdgcn_s_setprio(1); _Pragma("unroll") for (int m = 0; m < 4; ++m) _Pragma("unroll") for (int n = 0; n < 2; ++n) _Pragma("unroll") for (int k = 0; k < 2; ++k) \
;         acc[ai][bj][m][n] = __builtin_amdgcn_mfma_f32_16x16x32_bf16(Bt[n][k], At[m][k], acc[ai][bj][m][n], 0, 0, 0); __builtin_amdgcn_s_setprio(0); } while (0)
; #define PG8_WAIT_V(n) asm volatile("s_waitcnt vmcnt(" #n ")" ::: "memory")
; #define PG8_BAR __builtin_amdgcn_s_barrier()
;     __device__ bool next(int i, Unit& u) const {
;         const long L = (long)i * G + c; if (L >= nwg) return false;
;         int wgid = (int)L; { const int q = nwg / NXCD, r = nwg % NXCD, xcd = wgid % NXCD, off = wgid / NXCD; wgid = (xcd < r ? xcd * (q + 1) : r * (q + 1) + (xcd - r) * q) + off; }
;         const int nig = WGM * nN, gid = wgid / nig, fm = gid * WGM, gsz = (nM - fm) < WGM ? (nM - fm) : WGM;
;         u.pm = fm + ((wgid % nig) % gsz); u.pn = (wgid % nig) / gsz; return true;
; template <class Epi>
; __device__ __forceinline__ void gemm_phase(LAS unsigned char* lds, const Gemm g, const StaticOrder& S, const Epi& E) {
;     ...
;             PG8_WAIT_L(8); PG8_BAR; PG8_WAIT_L(0); PG8_MMA(0, 0, At, B0); PG8_BAR; PG8_SCHED;
;             PG8_LDB(B1, 1, 1); PG8_STAGE(PG8_SB(1, 0), b3, voffB);
;             PG8_BAR; PG8_WAIT_L(0); PG8_MMA(0, 1, At, B1); PG8_BAR;
;             PG8_LDA(At, 1, 1); PG8_STAGE(PG8_SA(1, 0), a3, voffA);
;             PG8_BAR; PG8_WAIT_L(0); PG8_MMA(1, 0, At, B0); PG8_BAR; PG8_SCHED;
;             PG8_STAGE(PG8_SB(1, 1), b3 + hstepB, voffB);
;             PG8_WAIT_V(6); PG8_BAR; PG8_MMA(1, 1, At, B1); PG8_BAR;
;         }
	s_waitcnt lgkmcnt(0)
	s_setprio 2
	s_waitcnt lgkmcnt(0)
	v_mfma_f32_16x16x32_bf16 v[124:127], v[128:131], v[144:147], v[124:127]
	v_mfma_f32_16x16x32_bf16 v[120:123], v[136:139], v[144:147], v[120:123]
	v_mfma_f32_16x16x32_bf16 v[108:111], v[128:131], v[170:173], v[108:111]
	v_mfma_f32_16x16x32_bf16 v[104:107], v[136:139], v[170:173], v[104:107]
	v_mfma_f32_16x16x32_bf16 v[92:95], v[128:131], v[178:181], v[92:95]
	v_mfma_f32_16x16x32_bf16 v[88:91], v[136:139], v[178:181], v[88:91]
	v_mfma_f32_16x16x32_bf16 v[76:79], v[128:131], v[196:199], v[76:79]
	v_mfma_f32_16x16x32_bf16 v[72:75], v[136:139], v[196:199], v[72:75]
	v_mfma_f32_16x16x32_bf16 v[124:127], v[132:135], v[148:151], v[124:127]
	v_mfma_f32_16x16x32_bf16 v[120:123], v[140:143], v[148:151], v[120:123]
	v_mfma_f32_16x16x32_bf16 v[108:111], v[132:135], v[174:177], v[108:111]
	v_mfma_f32_16x16x32_bf16 v[104:107], v[140:143], v[174:177], v[104:107]
	v_mfma_f32_16x16x32_bf16 v[92:95], v[132:135], v[182:185], v[92:95]
	v_mfma_f32_16x16x32_bf16 v[88:91], v[140:143], v[182:185], v[88:91]
	v_mfma_f32_16x16x32_bf16 v[76:79], v[132:135], v[200:203], v[76:79]
	v_mfma_f32_16x16x32_bf16 v[72:75], v[140:143], v[200:203], v[72:75]
	s_setprio 1
	s_barrier
	s_add_i32 s24, 0, 0x1c000
	s_add_i32 s25, s49, s31
	v_add_u32_e32 v195, s24, v189
	v_lshl_add_u64 v[186:187], v[186:187], 0, s[14:15]
	s_mov_b32 m0, s25
	ds_read_b128 v[204:207], v195
	ds_read_b128 v[208:211], v195 offset:1024
	ds_read_b128 v[212:215], v195 offset:2048
	ds_read_b128 v[216:219], v195 offset:3072
	global_load_lds_dwordx4 v[186:187], off
	v_lshl_add_u64 v[186:187], v[220:221], 0, s[14:15]
	s_add_i32 m0, s25, 0x2000
	s_nop 0
	global_load_lds_dwordx4 v[186:187], off
	s_barrier
	s_waitcnt lgkmcnt(0)
	s_setprio 2
	s_waitcnt lgkmcnt(0)
	v_mfma_f32_16x16x32_bf16 v[116:119], v[204:207], v[144:147], v[116:119]
	v_mfma_f32_16x16x32_bf16 v[112:115], v[212:215], v[144:147], v[112:115]
	v_mfma_f32_16x16x32_bf16 v[100:103], v[204:207], v[170:173], v[100:103]
	v_mfma_f32_16x16x32_bf16 v[96:99], v[212:215], v[170:173], v[96:99]
	v_mfma_f32_16x16x32_bf16 v[84:87], v[204:207], v[178:181], v[84:87]
	v_mfma_f32_16x16x32_bf16 v[80:83], v[212:215], v[178:181], v[80:83]
	v_mfma_f32_16x16x32_bf16 v[68:71], v[204:207], v[196:199], v[68:71]
	v_mfma_f32_16x16x32_bf16 v[64:67], v[212:215], v[196:199], v[64:67]
	v_mfma_f32_16x16x32_bf16 v[116:119], v[208:211], v[148:151], v[116:119]
	v_mfma_f32_16x16x32_bf16 v[112:115], v[216:219], v[148:151], v[112:115]
	v_mfma_f32_16x16x32_bf16 v[100:103], v[208:211], v[174:177], v[100:103]
	v_mfma_f32_16x16x32_bf16 v[96:99], v[216:219], v[174:177], v[96:99]
	v_mfma_f32_16x16x32_bf16 v[84:87], v[208:211], v[182:185], v[84:87]
	v_mfma_f32_16x16x32_bf16 v[80:83], v[216:219], v[182:185], v[80:83]
	v_mfma_f32_16x16x32_bf16 v[68:71], v[208:211], v[200:203], v[68:71]
	v_mfma_f32_16x16x32_bf16 v[64:67], v[216:219], v[200:203], v[64:67]
	s_setprio 1
	s_mov_b32 m0, s38
	v_lshl_add_u64 v[186:187], v[222:223], 0, s[14:15]
	s_barrier
	ds_read_b128 v[144:147], v192 offset:49152
	ds_read_b128 v[148:151], v192 offset:50176
	ds_read_b128 v[170:173], v192 offset:51200
	ds_read_b128 v[174:177], v192 offset:52224
	ds_read_b128 v[178:181], v192 offset:53248
	ds_read_b128 v[182:185], v192 offset:54272
	ds_read_b128 v[196:199], v192 offset:55296
	ds_read_b128 v[200:203], v192 offset:56320
	global_load_lds_dwordx4 v[186:187], off
	v_lshl_add_u64 v[186:187], v[224:225], 0, s[14:15]
	s_mov_b32 m0, s39
	s_nop 0
	global_load_lds_dwordx4 v[186:187], off
	s_barrier
	s_waitcnt lgkmcnt(0)
	s_setprio 2
	s_waitcnt lgkmcnt(0)
	v_mfma_f32_16x16x32_bf16 v[60:63], v[128:131], v[144:147], v[60:63]
	v_mfma_f32_16x16x32_bf16 v[56:59], v[136:139], v[144:147], v[56:59]
	v_mfma_f32_16x16x32_bf16 v[44:47], v[128:131], v[170:173], v[44:47]
	v_mfma_f32_16x16x32_bf16 v[40:43], v[136:139], v[170:173], v[40:43]
	v_mfma_f32_16x16x32_bf16 v[28:31], v[128:131], v[178:181], v[28:31]
	v_mfma_f32_16x16x32_bf16 v[24:27], v[136:139], v[178:181], v[24:27]
	v_mfma_f32_16x16x32_bf16 v[12:15], v[128:131], v[196:199], v[12:15]
	v_mfma_f32_16x16x32_bf16 v[8:11], v[136:139], v[196:199], v[8:11]
	v_mfma_f32_16x16x32_bf16 v[60:63], v[132:135], v[148:151], v[60:63]
	v_mfma_f32_16x16x32_bf16 v[56:59], v[140:143], v[148:151], v[56:59]
	v_mfma_f32_16x16x32_bf16 v[44:47], v[132:135], v[174:177], v[44:47]
	v_mfma_f32_16x16x32_bf16 v[40:43], v[140:143], v[174:177], v[40:43]
	v_mfma_f32_16x16x32_bf16 v[28:31], v[132:135], v[182:185], v[28:31]
	v_mfma_f32_16x16x32_bf16 v[24:27], v[140:143], v[182:185], v[24:27]
	v_mfma_f32_16x16x32_bf16 v[12:15], v[132:135], v[200:203], v[12:15]
	v_mfma_f32_16x16x32_bf16 v[8:11], v[140:143], v[200:203], v[8:11]
	s_setprio 1
	s_barrier
	s_add_u32 s22, s22, 0x80080
	s_addc_u32 s23, s23, 0
	s_add_i32 s24, s24, s31
	v_lshl_add_u64 v[128:129], s[22:23], 0, v[156:157]
	s_mov_b32 m0, s24
	s_nop 0
	global_load_lds_dwordx4 v[128:129], off
	v_lshl_add_u64 v[128:129], s[22:23], 0, v[160:161]
	s_add_i32 m0, s24, 0x2000
	s_nop 0
	global_load_lds_dwordx4 v[128:129], off
	s_waitcnt vmcnt(6)
	s_barrier
	s_setprio 2
	v_mfma_f32_16x16x32_bf16 v[52:55], v[204:207], v[144:147], v[52:55]
	v_mfma_f32_16x16x32_bf16 v[48:51], v[212:215], v[144:147], v[48:51]
	v_mfma_f32_16x16x32_bf16 v[36:39], v[204:207], v[170:173], v[36:39]
	v_mfma_f32_16x16x32_bf16 v[32:35], v[212:215], v[170:173], v[32:35]
	v_mfma_f32_16x16x32_bf16 v[20:23], v[204:207], v[178:181], v[20:23]
	v_mfma_f32_16x16x32_bf16 v[16:19], v[212:215], v[178:181], v[16:19]
	v_mfma_f32_16x16x32_bf16 v[4:7], v[204:207], v[196:199], v[4:7]
	v_mfma_f32_16x16x32_bf16 v[0:3], v[212:215], v[196:199], v[0:3]
	v_mfma_f32_16x16x32_bf16 v[52:55], v[208:211], v[148:151], v[52:55]
	v_mfma_f32_16x16x32_bf16 v[48:51], v[216:219], v[148:151], v[48:51]
	v_mfma_f32_16x16x32_bf16 v[36:39], v[208:211], v[174:177], v[36:39]
	v_mfma_f32_16x16x32_bf16 v[32:35], v[216:219], v[174:177], v[32:35]
	v_mfma_f32_16x16x32_bf16 v[20:23], v[208:211], v[182:185], v[20:23]
	v_mfma_f32_16x16x32_bf16 v[16:19], v[216:219], v[182:185], v[16:19]
	v_mfma_f32_16x16x32_bf16 v[4:7], v[208:211], v[200:203], v[4:7]
	v_mfma_f32_16x16x32_bf16 v[0:3], v[216:219], v[200:203], v[0:3]
	s_setprio 1
	s_add_i32 s48, s48, 2
	s_add_u32 s4, s4, 0x100
	s_addc_u32 s5, s5, 0
	s_add_u32 s46, s46, 0x100
	s_addc_u32 s47, s47, 0
	s_cmp_gt_u32 s48, 29
	s_barrier
	s_cbranch_scc0 .Lkp1_684
	s_branch .Lkp1_epi
.LBB0_675:
	v_readfirstlane_b32 s98, v152
	s_nop 3
	s_cmp_ge_u32 s98, 0x100
	s_cbranch_scc1 .Lkp1_head
	s_add_i32 s33, s33, 1
	s_mul_i32 s2, s33, s40
	s_mul_hi_u32 s3, s33, s92
	s_add_i32 s3, s3, s2
	s_mul_i32 s2, s33, s92
	s_add_u32 s18, s2, s93
	s_addc_u32 s19, s3, s41
	v_cmp_gt_i64_e64 s[2:3], s[18:19], v[168:169]
	v_cmp_lt_i64_e64 s[4:5], s[18:19], v[166:167]
	s_and_b64 vcc, exec, s[2:3]
	s_cbranch_vccnz .LBB0_681
	s_ashr_i32 s16, s18, 31
	s_lshr_b32 s16, s16, 29
	s_add_i32 s19, s18, s16
	s_and_b32 s16, s19, -8
	s_sub_i32 s18, s18, s16
	s_cmp_gt_i32 s18, -1
	s_mov_b64 s[16:17], -1
	s_cbranch_scc0 .LBB0_678
	s_lshl_b32 s20, s18, 7
	s_mov_b64 s[16:17], 0

; __device__ __forceinline__ unsigned pk2(float lo, float hi) { const f32x2 v = (f32x2){lo, hi}; const bf16x2_t b = __builtin_convertvector(v, bf16x2_t); return __builtin_bit_cast(unsigned, b); }
; __device__ __forceinline__ void unpack8(const u32x4 v, float* f) { f[0] = bf_lo(v.x); f[1] = bf_hi(v.x); f[2] = bf_lo(v.y); f[3] = bf_hi(v.y); f[4] = bf_lo(v.z); f[5] = bf_hi(v.z); f[6] = bf_lo(v.w); f[7] = bf_hi(v.w); }
;     __device__ __forceinline__ void operator()(const f32x4 (&acc)[2][2][4][2], const Unit& u, int wr, int wc, int fr, int fq, const float (&)[8]) const {
;         const int row0 = u.pm * BM + wr * 64 + fr, col0 = u.pn * BM + wc * 32 + 8 * fq;
; #pragma unroll
;         for (int ai = 0; ai < 2; ++ai) {
;             u32x4 bv[4][2];
; #pragma unroll
;             for (int m = 0; m < 4; ++m)
; #pragma unroll
;                 for (int bj = 0; bj < 2; ++bj) bv[m][bj] = *(const u32x4*)(xb + (size_t)(row0 + ai * HALF + m * 16) * DM + col0 + bj * HALF);
; #pragma unroll
;             for (int m = 0; m < 4; ++m) { const int row = row0 + ai * HALF + m * 16; const size_t ro = (size_t)row * DM + col0; float s = 0.f;
; #pragma unroll
;                 for (int bj = 0; bj < 2; ++bj) { float b8[8]; unpack8(bv[m][bj], b8);
;                     const f32x4 v0 = (f32x4){b8[0], b8[1], b8[2], b8[3]} + acc[ai][bj][m][0], v1 = (f32x4){b8[4], b8[5], b8[6], b8[7]} + acc[ai][bj][m][1];
;                     s += v0[0] * v0[0] + v0[1] * v0[1] + v0[2] * v0[2] + v0[3] * v0[3] + v1[0] * v1[0] + v1[1] * v1[1] + v1[2] * v1[2] + v1[3] * v1[3];
;                     if (LAST) { *(f32x4*)(out + ro + bj * HALF) = v0; *(f32x4*)(out + ro + bj * HALF + 4) = v1; }
;                     else { u32x4 w; w.x = pk2(v0[0], v0[1]); w.y = pk2(v0[2], v0[3]); w.z = pk2(v1[0], v1[1]); w.w = pk2(v1[2], v1[3]); *(u32x4*)(xb + ro + bj * HALF) = w; } }
;                 s += __shfl_xor(s, 16); s += __shfl_xor(s, 32);
;                 if (fq == 0) ss[(size_t)row * 16 + u.pn * 4 + wc] = s; }
.Lkp1_epi:
	s_setprio 0
	v_lshl_or_b32 v170, s10, 8, v190
	v_lshl_add_u32 v172, s12, 8, v188
	v_ashrrev_i32_e32 v171, 31, v170
	v_lshlrev_b64 v[206:207], 1, v[170:171]
	v_ashrrev_i32_e32 v173, 31, v172
	v_lshl_add_u64 v[174:175], s[76:77], 0, v[206:207]
	v_lshlrev_b64 v[208:209], 11, v[172:173]
	v_lshl_add_u64 v[128:129], v[174:175], 0, v[208:209]
	global_load_dwordx4 v[198:201], v[128:129], off
	global_load_dwordx4 v[202:205], v[128:129], off offset:256
	v_or_b32_e32 v184, 16, v172
	v_or_b32_e32 v180, 32, v172
	v_or_b32_e32 v176, 48, v172
	v_ashrrev_i32_e32 v185, 31, v184
	v_ashrrev_i32_e32 v181, 31, v180
	v_ashrrev_i32_e32 v177, 31, v176
	v_lshlrev_b64 v[186:187], 11, v[184:185]
	v_lshlrev_b64 v[182:183], 11, v[180:181]
	v_lshlrev_b64 v[178:179], 11, v[176:177]
	v_lshl_add_u64 v[128:129], v[174:175], 0, v[186:187]
	v_lshl_add_u64 v[130:131], v[174:175], 0, v[182:183]
	v_lshl_add_u64 v[196:197], v[174:175], 0, v[178:179]
	global_load_dwordx4 v[148:151], v[128:129], off
	global_load_dwordx4 v[144:147], v[128:129], off offset:256
	global_load_dwordx4 v[140:143], v[130:131], off
	global_load_dwordx4 v[136:139], v[130:131], off offset:256
	global_load_dwordx4 v[132:135], v[196:197], off
	s_nop 0
	global_load_dwordx4 v[128:131], v[196:197], off offset:256
	v_add_u32_e32 v218, 0x80, v172
	v_ashrrev_i32_e32 v219, 31, v218
	v_lshlrev_b64 v[218:219], 11, v[218:219]
	v_lshl_add_u64 v[218:219], v[174:175], 0, v[218:219]
	global_load_dwordx4 v[220:223], v[218:219], off
	global_load_dwordx4 v[224:227], v[218:219], off offset:256
	v_add_u32_e32 v218, 0x90, v172
	v_ashrrev_i32_e32 v219, 31, v218
	v_lshlrev_b64 v[218:219], 11, v[218:219]
	v_lshl_add_u64 v[218:219], v[174:175], 0, v[218:219]
	global_load_dwordx4 v[228:231], v[218:219], off
	global_load_dwordx4 v[232:235], v[218:219], off offset:256
	v_add_u32_e32 v218, 0xa0, v172
	v_ashrrev_i32_e32 v219, 31, v218
	v_lshlrev_b64 v[218:219], 11, v[218:219]
	v_lshl_add_u64 v[218:219], v[174:175], 0, v[218:219]
	global_load_dwordx4 v[236:239], v[218:219], off
	global_load_dwordx4 v[240:243], v[218:219], off offset:256
	v_add_u32_e32 v218, 0xb0, v172
	v_ashrrev_i32_e32 v219, 31, v218
	v_lshlrev_b64 v[218:219], 11, v[218:219]
	v_lshl_add_u64 v[218:219], v[174:175], 0, v[218:219]
	global_load_dwordx4 v[244:247], v[218:219], off
	global_load_dwordx4 v[252:255], v[218:219], off offset:256
	v_and_b32_e32 v196, 64, v194
	v_xor_b32_e32 v195, 16, v194
	v_add_u32_e32 v196, 64, v196
	v_xor_b32_e32 v197, 32, v194
	v_cmp_lt_i32_e32 vcc, v195, v196
	s_waitcnt vmcnt(15)
	v_lshlrev_b32_e32 v210, 16, v198
	v_cndmask_b32_e32 v195, v194, v195, vcc
	v_cmp_lt_i32_e32 vcc, v197, v196
	v_and_b32_e32 v211, 0xffff0000, v198
	s_waitcnt vmcnt(14)
	v_lshlrev_b32_e32 v214, 16, v202
	v_and_b32_e32 v215, 0xffff0000, v202
	v_cndmask_b32_e32 v197, v194, v197, vcc
	v_lshlrev_b32_e32 v212, 16, v200
	v_and_b32_e32 v213, 0xffff0000, v200
	v_lshlrev_b32_e32 v200, 16, v201
	v_and_b32_e32 v201, 0xffff0000, v201
	v_lshlrev_b32_e32 v216, 16, v204
	v_and_b32_e32 v217, 0xffff0000, v204
	v_pk_add_f32 v[124:125], v[124:125], v[210:211]
	v_pk_add_f32 v[116:117], v[116:117], v[214:215]
	v_lshlrev_b32_e32 v196, 2, v195
	v_lshlrev_b32_e32 v195, 2, v197
	v_lshlrev_b32_e32 v198, 16, v199
	v_and_b32_e32 v199, 0xffff0000, v199
	v_lshlrev_b32_e32 v202, 16, v203
	v_and_b32_e32 v203, 0xffff0000, v203
	v_pk_add_f32 v[122:123], v[122:123], v[200:201]
	v_pk_add_f32 v[200:201], v[112:113], v[216:217]
	v_mul_f32_e32 v197, v125, v125
	v_cvt_pk_bf16_f32 v112, v124, v125
	v_mul_f32_e32 v125, v117, v117
	v_pk_add_f32 v[126:127], v[126:127], v[198:199]
	v_pk_add_f32 v[118:119], v[118:119], v[202:203]
	v_fmac_f32_e32 v197, v124, v124
	v_fmac_f32_e32 v125, v116, v116
	v_fmac_f32_e32 v197, v126, v126
	v_fmac_f32_e32 v125, v118, v118
	v_pk_add_f32 v[120:121], v[120:121], v[212:213]
	v_fmac_f32_e32 v197, v127, v127
	v_fmac_f32_e32 v125, v119, v119
	v_lshlrev_b32_e32 v204, 16, v205
	v_and_b32_e32 v205, 0xffff0000, v205
	v_fmac_f32_e32 v197, v120, v120
	v_fmac_f32_e32 v125, v200, v200
	v_pk_add_f32 v[198:199], v[114:115], v[204:205]
	v_fmac_f32_e32 v197, v121, v121
	v_fmac_f32_e32 v125, v201, v201
	v_fmac_f32_e32 v197, v122, v122
	v_fmac_f32_e32 v125, v198, v198
	v_fmac_f32_e32 v197, v123, v123
	v_fmac_f32_e32 v125, v199, v199
	v_cvt_pk_bf16_f32 v115, v122, v123
	v_add_f32_e32 v122, v197, v125
	ds_bpermute_b32 v123, v196, v122
	v_cvt_pk_bf16_f32 v114, v120, v121
	v_lshl_add_u64 v[120:121], s[76:77], 0, v[208:209]
	v_cvt_pk_bf16_f32 v113, v126, v127
	v_lshl_add_u64 v[120:121], v[120:121], 0, v[206:207]
	global_store_dwordx4 v[120:121], v[112:115], off
	s_waitcnt lgkmcnt(0)
	s_nop 0
	v_add_f32_e32 v112, v122, v123
	ds_bpermute_b32 v113, v195, v112
	v_cvt_pk_bf16_f32 v114, v116, v117
	v_cvt_pk_bf16_f32 v115, v118, v119
	v_cvt_pk_bf16_f32 v116, v200, v201
	v_cvt_pk_bf16_f32 v117, v198, v199
	global_store_dwordx4 v[120:121], v[114:117], off offset:256
	s_and_saveexec_b64 s[4:5], s[0:1]
	s_cbranch_execz .LBB0_687
	s_waitcnt lgkmcnt(0)
	v_add_f32_e32 v114, v112, v113
	s_lshl_b32 s22, s10, 2
	v_lshlrev_b64 v[112:113], 6, v[172:173]
	s_ashr_i32 s23, s22, 31
	v_lshl_add_u64 v[112:113], s[6:7], 0, v[112:113]
	v_lshl_add_u64 v[112:113], s[22:23], 2, v[112:113]
	s_lshl_b32 s12, s37, 2
	v_lshl_add_u64 v[112:113], v[112:113], 0, s[12:13]
	global_store_dword v[112:113], v114, off

; #define PG8_STAGE(bufoff, gbase, voff) do { _Pragma("unroll") for (int _i = 0; _i < 2; ++_i) \
;         __builtin_amdgcn_global_load_lds((const unsigned*)((const char*)(gbase) + (voff)[_i]), (LAS unsigned*)(lds + (bufoff) + ldsw + _i * 8192), 16, 0, 0); } while (0)
; #define PG8_WAIT_V(n) asm volatile("s_waitcnt vmcnt(" #n ")" ::: "memory")
; #define PG8_BAR __builtin_amdgcn_s_barrier()
; template <class Epi>
; __device__ __forceinline__ void gemm_phase(LAS unsigned char* lds, const Gemm g, const StaticOrder& S, const Epi& E) {
;     const int tid = threadIdx.x, wid = __builtin_amdgcn_readfirstlane(tid >> 6), lane = tid & 63, wr = wid >> 2, wc = wid & 3, fr = lane & 15, fq = lane >> 4;
;     const int K = g.K, nt = K / BK, lda = g.lda;
;     unsigned voffA[2], voffB[2];
; #pragma unroll
;     for (int i = 0; i < 2; ++i) { int R, C; stage_rc(tid * 16 + i * 8192, R, C); const int Rb = Epi::PERM ? ((R & ~31) + perm32(R & 31)) : R;
;         voffA[i] = (unsigned)(R * lda + C) * 2u; voffB[i] = (unsigned)(Rb * K + C) * 2u; }
;     const size_t kstep = (size_t)(BK * 2);
;     const size_t hstepA = (size_t)HALF * lda * 2, hstepB = (size_t)HALF * K * 2;
;     const size_t tstepA = 2 * hstepA, tstepB = 2 * hstepB;
;     const unsigned ldsw = (unsigned)wid * 1024u;
;     const int aoff = lds_byte(wr * 64 + fr, fq * 8), boff = lds_byte(wc * 32 + fr, fq * 8);
;     ...
;     PG8_STAGE(PG8_SB(0, 0), cB, voffB); PG8_STAGE(PG8_SA(0, 0), cA, voffA); PG8_STAGE(PG8_SB(0, 1), cB + hstepB, voffB); PG8_STAGE(PG8_SA(0, 1), cA + hstepA, voffA);
;     if (wr == 1) PG8_BAR;
;     PG8_WAIT_V(4); PG8_BAR;
;     PG8_STAGE(PG8_SB(1, 0), cB + kstep, voffB); PG8_STAGE(PG8_SA(1, 0), cA + kstep, voffA); PG8_STAGE(PG8_SB(1, 1), cB + hstepB + kstep, voffB);
;     PG8_WAIT_V(6); PG8_BAR;
.LBB0_762:
	s_lshl_b32 s4, s4, 5
	s_and_b32 s12, s4, 0x60
	s_mov_b64 s[4:5], 0x80
	s_add_i32 m0, s19, 0x18000
	v_lshl_add_u64 v[6:7], v[6:7], 0, s[4:5]
	s_lshl_b32 s8, s1, 13
	s_lshl_b32 s13, s12, 7
	s_waitcnt vmcnt(4)
	s_barrier
	global_load_lds_dwordx4 v[6:7], off
	v_lshl_add_u64 v[4:5], v[4:5], 0, s[4:5]
	s_add_i32 m0, s19, 0x1a000
	s_add_i32 s35, s19, 0x8000
	s_add_i32 s36, s19, 0xa000
	global_load_lds_dwordx4 v[4:5], off
	v_lshl_add_u64 v[2:3], v[2:3], 0, s[4:5]
	s_mov_b32 m0, s35
	s_add_u32 s10, s22, 0x40080
	global_load_lds_dwordx4 v[2:3], off
	v_lshl_add_u64 v[0:1], v[0:1], 0, s[4:5]
	s_mov_b32 m0, s36
	s_addc_u32 s11, s23, 0
	global_load_lds_dwordx4 v[0:1], off
	s_add_i32 m0, s19, 0x1c000
	v_lshl_add_u64 v[0:1], s[10:11], 0, v[130:131]
	global_load_lds_dwordx4 v[0:1], off
	v_lshl_add_u64 v[0:1], s[10:11], 0, v[134:135]
	s_add_i32 m0, s19, 0x1e000
	v_bfe_u32 v2, v152, 4, 2
	global_load_lds_dwordx4 v[0:1], off
	v_and_b32_e32 v1, 15, v152
	v_lshlrev_b32_e32 v0, 4, v2
	v_lshlrev_b32_e32 v3, 2, v152
	v_lshl_or_b32 v174, s1, 6, v1
	v_lshl_or_b32 v1, v1, 6, v0
	v_and_b32_e32 v3, 32, v3
	s_sext_i32_i8 s40, s0
	v_bitop3_b32 v4, v1, s8, v3 bitop3:0xde
	v_lshlrev_b32_e32 v1, 6, v152
	s_movk_i32 s0, 0x3c0
	v_and_or_b32 v1, v1, s0, v0
	v_bitop3_b32 v175, s13, v1, v3 bitop3:0xf6
	v_mov_b32_e32 v1, v131
	v_lshl_add_u64 v[136:137], s[6:7], 0, v[0:1]
	v_lshlrev_b32_e32 v0, 8, v152
	v_and_b32_e32 v0, 0x38000, v0
	v_lshlrev_b32_e32 v1, 11, v10
	v_or3_b32 v0, v8, v0, v1
	v_add_u32_e32 v138, v0, v9
	v_lshlrev_b32_e32 v0, 4, v11
	v_and_b32_e32 v0, 0x78000, v0
	s_waitcnt vmcnt(6)
	v_or3_b32 v0, v8, v0, v1
	v_add_u32_e32 v140, v0, v9
	s_add_i32 s7, 0, 0x10000
	s_add_i32 s38, 0, 0x14000
	v_mbcnt_lo_u32_b32 v0, -1, 0
	s_ashr_i32 s37, s92, 31
	v_lshl_or_b32 v176, v2, 3, s12
	v_mov_b32_e32 v139, v131
	v_mov_b32_e32 v141, v131
	v_mov_b64_e32 v[142:143], 0x1000
	v_mov_b64_e32 v[144:145], 0xfff
	v_add_u32_e32 v177, s7, v175
	v_add_u32_e32 v178, 0, v4
	v_add_u32_e32 v179, s38, v175
	v_mbcnt_hi_u32_b32 v180, -1, v0
	s_mov_b32 s6, 0x3a800000
	s_mov_b32 s8, 0x358637bd
	s_mov_b32 s39, 0x800000
	s_barrier
	s_branch .LBB0_763

; #define PG8_STAGE(bufoff, gbase, voff) do { _Pragma("unroll") for (int _i = 0; _i < 2; ++_i) \
;         __builtin_amdgcn_global_load_lds((const unsigned*)((const char*)(gbase) + (voff)[_i]), (LAS unsigned*)(lds + (bufoff) + ldsw + _i * 8192), 16, 0, 0); } while (0)
; #define PG8_LDA(dst, b, h) do { _Pragma("unroll") for (int m = 0; m < 4; ++m) _Pragma("unroll") for (int k = 0; k < 2; ++k) dst[m][k] = *(const LAS bf16x8*)(lds + PG8_SA(b, h) + aoff + m * 2048 + k * 1024); } while (0)
; #define PG8_LDB(dst, b, h) do { _Pragma("unroll") for (int n = 0; n < 2; ++n) _Pragma("unroll") for (int k = 0; k < 2; ++k) dst[n][k] = *(const LAS bf16x8*)(lds + PG8_SB(b, h) + boff + n * 2048 + k * 1024); } while (0)
; #define PG8_WAIT_V(n) asm volatile("s_waitcnt vmcnt(" #n ")" ::: "memory")
; #define PG8_WAIT_L(n) asm volatile("s_waitcnt lgkmcnt(" #n ")" ::: "memory")
; #define PG8_BAR __builtin_amdgcn_s_barrier()
; #define PG8_SCHED __builtin_amdgcn_sched_barrier(0)
; template <class Epi>
; __device__ __forceinline__ void gemm_phase(LAS unsigned char* lds, const Gemm g, const StaticOrder& S, const Epi& E) {
;     ...
;         const char* nA = has_next ? (const char*)g.A + (size_t)nxt.pm * tstepA : cA; const char* nB = has_next ? (const char*)g.Bt + (size_t)nxt.pn * tstepB : cB;
;         for (int t = 0; t < nt; t += 2) {
;             const bool last = (t == nt - 2);
;             const char* a1 = cA + (size_t)(t + 1) * kstep;
;             const char* a2 = last ? nA : cA + (size_t)(t + 2) * kstep; const char* b2 = last ? nB : cB + (size_t)(t + 2) * kstep;
;             const char* a3 = a2 + kstep; const char* b3 = b2 + kstep;
;             if (last) E.pre(cur, wr, fr, epre);
;             PG8_LDB(B0, 0, 0); PG8_SCHED; PG8_LDA(At, 0, 0); PG8_STAGE(PG8_SA(1, 1), a1 + hstepA, voffA);
;             PG8_WAIT_L(8); PG8_BAR; PG8_WAIT_L(0); PG8_MMA(0, 0, At, B0); PG8_BAR; PG8_SCHED;
;             PG8_LDB(B1, 0, 1); PG8_STAGE(PG8_SB(0, 0), b2, voffB);
;             PG8_BAR; PG8_WAIT_L(0); PG8_MMA(0, 1, At, B1); PG8_BAR;
;             PG8_LDA(At, 0, 1); PG8_STAGE(PG8_SA(0, 0), a2, voffA);
;             PG8_BAR; PG8_WAIT_L(0); PG8_MMA(1, 0, At, B0); PG8_BAR; PG8_SCHED;
;             PG8_STAGE(PG8_SB(0, 1), b2 + hstepB, voffB);
;             PG8_WAIT_V(6); PG8_BAR; PG8_MMA(1, 1, At, B1); PG8_BAR;
.Lkp2_769:
	s_ashr_i32 s13, s12, 31
	v_cmp_lt_i64_e32 vcc, s[14:15], v[142:143]
	s_lshl_b64 s[14:15], s[12:13], 19
	s_add_u32 s14, s76, s14
	s_addc_u32 s15, s77, s15
	s_and_b64 s[16:17], vcc, exec
	s_cselect_b32 s13, s15, s21
	s_cselect_b32 s41, s14, s20
	s_ashr_i32 s11, s10, 31
	s_lshl_b64 s[16:17], s[10:11], 19
	s_add_u32 s16, s27, s16
	s_addc_u32 s17, s28, s17
	s_and_b64 s[24:25], vcc, exec
	s_cselect_b32 s11, s17, s23
	s_cselect_b32 s42, s16, s22
	s_add_u32 s20, s20, 0x40080
	s_addc_u32 s21, s21, 0
	s_add_u32 s43, s22, 0x100
	s_addc_u32 s44, s23, 0
	s_mov_b32 s45, -2
	ds_read_b128 v[146:149], v177
	ds_read_b128 v[154:157], v177 offset:1024
	ds_read_b128 v[158:161], v177 offset:2048
	ds_read_b128 v[162:165], v177 offset:3072
	s_add_u32 s22, s20, 0xfffc0080
	s_addc_u32 s23, s21, -1
	s_cmp_eq_u32 s45, 12
	s_cselect_b32 s25, s13, s23
	s_cselect_b32 s24, s41, s22
	s_cselect_b32 s23, s11, s44
	s_cselect_b32 s22, s42, s43
	v_lshl_add_u64 v[150:151], s[20:21], 0, v[138:139]
	s_add_i32 m0, s19, 0xc000
	ds_read_b128 v[166:169], v178
	ds_read_b128 v[170:173], v178 offset:1024
	ds_read_b128 v[182:185], v178 offset:2048
	ds_read_b128 v[186:189], v178 offset:3072
	ds_read_b128 v[190:193], v178 offset:4096
	ds_read_b128 v[194:197], v178 offset:5120
	ds_read_b128 v[198:201], v178 offset:6144
	ds_read_b128 v[202:205], v178 offset:7168
	global_load_lds_dwordx4 v[150:151], off
	v_lshl_add_u64 v[150:151], s[20:21], 0, v[140:141]
	s_add_i32 m0, s19, 0xe000
	s_nop 0
	global_load_lds_dwordx4 v[150:151], off
	s_waitcnt lgkmcnt(8)
	s_barrier
	s_waitcnt lgkmcnt(0)
	s_setprio 2
	s_waitcnt lgkmcnt(0)
	v_mfma_f32_16x16x32_bf16 v[124:127], v[146:149], v[166:169], 0
	v_mfma_f32_16x16x32_bf16 v[120:123], v[158:161], v[166:169], 0
	v_mfma_f32_16x16x32_bf16 v[108:111], v[146:149], v[182:185], 0
	v_mfma_f32_16x16x32_bf16 v[104:107], v[158:161], v[182:185], 0
	v_mfma_f32_16x16x32_bf16 v[92:95], v[146:149], v[190:193], 0
	v_mfma_f32_16x16x32_bf16 v[88:91], v[158:161], v[190:193], 0
	v_mfma_f32_16x16x32_bf16 v[76:79], v[146:149], v[198:201], 0
	v_mfma_f32_16x16x32_bf16 v[72:75], v[158:161], v[198:201], 0
	v_mfma_f32_16x16x32_bf16 v[124:127], v[154:157], v[170:173], v[124:127]
	v_mfma_f32_16x16x32_bf16 v[120:123], v[162:165], v[170:173], v[120:123]
	v_mfma_f32_16x16x32_bf16 v[108:111], v[154:157], v[186:189], v[108:111]
	v_mfma_f32_16x16x32_bf16 v[104:107], v[162:165], v[186:189], v[104:107]
	v_mfma_f32_16x16x32_bf16 v[92:95], v[154:157], v[194:197], v[92:95]
	v_mfma_f32_16x16x32_bf16 v[88:91], v[162:165], v[194:197], v[88:91]
	v_mfma_f32_16x16x32_bf16 v[76:79], v[154:157], v[202:205], v[76:79]
	v_mfma_f32_16x16x32_bf16 v[72:75], v[162:165], v[202:205], v[72:75]
	s_setprio 1
	s_barrier
	s_add_i32 s46, s7, s29
	v_lshl_add_u64 v[150:151], s[22:23], 0, v[130:131]
	s_mov_b32 m0, s46
	ds_read_b128 v[206:209], v179
	ds_read_b128 v[210:213], v179 offset:1024
	ds_read_b128 v[214:217], v179 offset:2048
	ds_read_b128 v[218:221], v179 offset:3072
	global_load_lds_dwordx4 v[150:151], off
	v_lshl_add_u64 v[222:223], s[22:23], 0, v[134:135]
	s_add_i32 m0, s46, 0x2000
	s_nop 0
	global_load_lds_dwordx4 v[222:223], off
	s_barrier
	s_waitcnt lgkmcnt(0)
	s_setprio 2
	s_waitcnt lgkmcnt(0)
	v_mfma_f32_16x16x32_bf16 v[116:119], v[206:209], v[166:169], 0
	v_mfma_f32_16x16x32_bf16 v[112:115], v[214:217], v[166:169], 0
	v_mfma_f32_16x16x32_bf16 v[100:103], v[206:209], v[182:185], 0
	v_mfma_f32_16x16x32_bf16 v[96:99], v[214:217], v[182:185], 0
	v_mfma_f32_16x16x32_bf16 v[84:87], v[206:209], v[190:193], 0
	v_mfma_f32_16x16x32_bf16 v[80:83], v[214:217], v[190:193], 0
	v_mfma_f32_16x16x32_bf16 v[68:71], v[206:209], v[198:201], 0
	v_mfma_f32_16x16x32_bf16 v[64:67], v[214:217], v[198:201], 0
	v_mfma_f32_16x16x32_bf16 v[116:119], v[210:213], v[170:173], v[116:119]
	v_mfma_f32_16x16x32_bf16 v[112:115], v[218:221], v[170:173], v[112:115]
	v_mfma_f32_16x16x32_bf16 v[100:103], v[210:213], v[186:189], v[100:103]
	v_mfma_f32_16x16x32_bf16 v[96:99], v[218:221], v[186:189], v[96:99]
	v_mfma_f32_16x16x32_bf16 v[84:87], v[210:213], v[194:197], v[84:87]
	v_mfma_f32_16x16x32_bf16 v[80:83], v[218:221], v[194:197], v[80:83]
	v_mfma_f32_16x16x32_bf16 v[68:71], v[210:213], v[202:205], v[68:71]
	v_mfma_f32_16x16x32_bf16 v[64:67], v[218:221], v[202:205], v[64:67]
	s_setprio 1
	s_mov_b32 m0, s19
	v_lshl_add_u64 v[224:225], s[24:25], 0, v[128:129]
	s_barrier
	ds_read_b128 v[166:169], v178 offset:16384
	ds_read_b128 v[170:173], v178 offset:17408
	ds_read_b128 v[182:185], v178 offset:18432
	ds_read_b128 v[186:189], v178 offset:19456
	ds_read_b128 v[190:193], v178 offset:20480
	ds_read_b128 v[194:197], v178 offset:21504
	ds_read_b128 v[198:201], v178 offset:22528
	ds_read_b128 v[202:205], v178 offset:23552
	global_load_lds_dwordx4 v[224:225], off
	v_lshl_add_u64 v[226:227], s[24:25], 0, v[132:133]
	s_mov_b32 m0, s30
	s_nop 0
	global_load_lds_dwordx4 v[226:227], off
	s_barrier
	s_waitcnt lgkmcnt(0)
	s_setprio 2
	s_waitcnt lgkmcnt(0)
	v_mfma_f32_16x16x32_bf16 v[60:63], v[146:149], v[166:169], 0
	v_mfma_f32_16x16x32_bf16 v[56:59], v[158:161], v[166:169], 0
	v_mfma_f32_16x16x32_bf16 v[44:47], v[146:149], v[182:185], 0
	v_mfma_f32_16x16x32_bf16 v[40:43], v[158:161], v[182:185], 0
	v_mfma_f32_16x16x32_bf16 v[28:31], v[146:149], v[190:193], 0
	v_mfma_f32_16x16x32_bf16 v[24:27], v[158:161], v[190:193], 0
	v_mfma_f32_16x16x32_bf16 v[12:15], v[146:149], v[198:201], 0
	v_mfma_f32_16x16x32_bf16 v[8:11], v[158:161], v[198:201], 0
	v_mfma_f32_16x16x32_bf16 v[60:63], v[154:157], v[170:173], v[60:63]
	v_mfma_f32_16x16x32_bf16 v[56:59], v[162:165], v[170:173], v[56:59]
	v_mfma_f32_16x16x32_bf16 v[44:47], v[154:157], v[186:189], v[44:47]
	v_mfma_f32_16x16x32_bf16 v[40:43], v[162:165], v[186:189], v[40:43]
	v_mfma_f32_16x16x32_bf16 v[28:31], v[154:157], v[194:197], v[28:31]
	v_mfma_f32_16x16x32_bf16 v[24:27], v[162:165], v[194:197], v[24:27]
	v_mfma_f32_16x16x32_bf16 v[12:15], v[154:157], v[202:205], v[12:15]
	v_mfma_f32_16x16x32_bf16 v[8:11], v[162:165], v[202:205], v[8:11]
	s_setprio 1
	s_barrier
; #define PG8_STAGE(bufoff, gbase, voff) do { _Pragma("unroll") for (int _i = 0; _i < 2; ++_i) \
;         __builtin_amdgcn_global_load_lds((const unsigned*)((const char*)(gbase) + (voff)[_i]), (LAS unsigned*)(lds + (bufoff) + ldsw + _i * 8192), 16, 0, 0); } while (0)
; #define PG8_LDA(dst, b, h) do { _Pragma("unroll") for (int m = 0; m < 4; ++m) _Pragma("unroll") for (int k = 0; k < 2; ++k) dst[m][k] = *(const LAS bf16x8*)(lds + PG8_SA(b, h) + aoff + m * 2048 + k * 1024); } while (0)
; #define PG8_LDB(dst, b, h) do { _Pragma("unroll") for (int n = 0; n < 2; ++n) _Pragma("unroll") for (int k = 0; k < 2; ++k) dst[n][k] = *(const LAS bf16x8*)(lds + PG8_SB(b, h) + boff + n * 2048 + k * 1024); } while (0)
; #define PG8_MMA(ai, bj, At, Bt) do { __builtin_amdgcn_s_setprio(1); _Pragma("unroll") for (int m = 0; m < 4; ++m) _Pragma("unroll") for (int n = 0; n < 2; ++n) _Pragma("unroll") for (int k = 0; k < 2; ++k) \
;         acc[ai][bj][m][n] = __builtin_amdgcn_mfma_f32_16x16x32_bf16(Bt[n][k], At[m][k], acc[ai][bj][m][n], 0, 0, 0); __builtin_amdgcn_s_setprio(0); } while (0)
; #define PG8_WAIT_V(n) asm volatile("s_waitcnt vmcnt(" #n ")" ::: "memory")
; #define PG8_WAIT_L(n) asm volatile("s_waitcnt lgkmcnt(" #n ")" ::: "memory")
; #define PG8_BAR __builtin_amdgcn_s_barrier()
; #define PG8_SCHED __builtin_amdgcn_sched_barrier(0)
; template <class Epi>
; __device__ __forceinline__ void gemm_phase(LAS unsigned char* lds, const Gemm g, const StaticOrder& S, const Epi& E) {
;     ...
;             PG8_STAGE(PG8_SB(0, 1), b2 + hstepB, voffB);
;             PG8_WAIT_V(6); PG8_BAR; PG8_MMA(1, 1, At, B1); PG8_BAR;
;             PG8_LDB(B0, 1, 0); PG8_SCHED; PG8_LDA(At, 1, 0); PG8_STAGE(PG8_SA(0, 1), a2 + hstepA, voffA);
;             PG8_WAIT_L(8); PG8_BAR; PG8_WAIT_L(0); PG8_MMA(0, 0, At, B0); PG8_BAR; PG8_SCHED;
;             PG8_LDB(B1, 1, 1); PG8_STAGE(PG8_SB(1, 0), b3, voffB);
;             PG8_BAR; PG8_WAIT_L(0); PG8_MMA(0, 1, At, B1); PG8_BAR;
;             PG8_LDA(At, 1, 1); PG8_STAGE(PG8_SA(1, 0), a3, voffA);
;             PG8_BAR; PG8_WAIT_L(0); PG8_MMA(1, 0, At, B0); PG8_BAR; PG8_SCHED;
;             PG8_STAGE(PG8_SB(1, 1), b3 + hstepB, voffB);
;             PG8_WAIT_V(6); PG8_BAR; PG8_MMA(1, 1, At, B1); PG8_BAR;
	s_add_u32 s46, s22, 0x40000
	s_addc_u32 s47, s23, 0
	s_add_i32 s48, s38, s29
	v_lshl_add_u64 v[146:147], s[46:47], 0, v[130:131]
	s_mov_b32 m0, s48
	s_nop 0
	global_load_lds_dwordx4 v[146:147], off
	v_lshl_add_u64 v[146:147], s[46:47], 0, v[134:135]
	s_add_i32 m0, s48, 0x2000
	s_nop 0
	global_load_lds_dwordx4 v[146:147], off
	s_waitcnt vmcnt(6)
	s_barrier
	s_setprio 2
	v_mfma_f32_16x16x32_bf16 v[52:55], v[206:209], v[166:169], 0
	v_mfma_f32_16x16x32_bf16 v[48:51], v[214:217], v[166:169], 0
	v_mfma_f32_16x16x32_bf16 v[36:39], v[206:209], v[182:185], 0
	v_mfma_f32_16x16x32_bf16 v[32:35], v[214:217], v[182:185], 0
	v_mfma_f32_16x16x32_bf16 v[20:23], v[206:209], v[190:193], 0
	v_mfma_f32_16x16x32_bf16 v[16:19], v[214:217], v[190:193], 0
	v_mfma_f32_16x16x32_bf16 v[4:7], v[206:209], v[198:201], 0
	v_mfma_f32_16x16x32_bf16 v[0:3], v[214:217], v[198:201], 0
	v_mfma_f32_16x16x32_bf16 v[52:55], v[210:213], v[170:173], v[52:55]
	v_mfma_f32_16x16x32_bf16 v[48:51], v[218:221], v[170:173], v[48:51]
	v_mfma_f32_16x16x32_bf16 v[36:39], v[210:213], v[186:189], v[36:39]
	v_mfma_f32_16x16x32_bf16 v[32:35], v[218:221], v[186:189], v[32:35]
	v_mfma_f32_16x16x32_bf16 v[20:23], v[210:213], v[194:197], v[20:23]
	v_mfma_f32_16x16x32_bf16 v[16:19], v[218:221], v[194:197], v[16:19]
	v_mfma_f32_16x16x32_bf16 v[4:7], v[210:213], v[202:205], v[4:7]
	v_mfma_f32_16x16x32_bf16 v[0:3], v[218:221], v[202:205], v[0:3]
	s_setprio 1
	s_add_i32 s46, 0, 0x18000
	v_add_u32_e32 v162, s46, v175
	s_barrier
	ds_read_b128 v[146:149], v162
	ds_read_b128 v[154:157], v162 offset:1024
	ds_read_b128 v[158:161], v162 offset:2048
	ds_read_b128 v[162:165], v162 offset:3072
	s_add_u32 s24, s24, 0x40000
	s_addc_u32 s25, s25, 0
	s_mov_b32 m0, s31
	v_lshl_add_u64 v[206:207], s[24:25], 0, v[128:129]
	ds_read_b128 v[166:169], v178 offset:32768
	ds_read_b128 v[170:173], v178 offset:33792
	ds_read_b128 v[182:185], v178 offset:34816
	ds_read_b128 v[186:189], v178 offset:35840
	ds_read_b128 v[190:193], v178 offset:36864
	ds_read_b128 v[194:197], v178 offset:37888
	ds_read_b128 v[198:201], v178 offset:38912
	ds_read_b128 v[202:205], v178 offset:39936
	global_load_lds_dwordx4 v[206:207], off
	v_lshl_add_u64 v[206:207], s[24:25], 0, v[132:133]
	s_mov_b32 m0, s33
	s_nop 0
	global_load_lds_dwordx4 v[206:207], off
	s_waitcnt lgkmcnt(8)
	s_barrier
	s_waitcnt lgkmcnt(0)
	s_setprio 2
	s_waitcnt lgkmcnt(0)
	v_mfma_f32_16x16x32_bf16 v[124:127], v[146:149], v[166:169], v[124:127]
	v_mfma_f32_16x16x32_bf16 v[120:123], v[158:161], v[166:169], v[120:123]
	v_mfma_f32_16x16x32_bf16 v[108:111], v[146:149], v[182:185], v[108:111]
	v_mfma_f32_16x16x32_bf16 v[104:107], v[158:161], v[182:185], v[104:107]
	v_mfma_f32_16x16x32_bf16 v[92:95], v[146:149], v[190:193], v[92:95]
	v_mfma_f32_16x16x32_bf16 v[88:91], v[158:161], v[190:193], v[88:91]
	v_mfma_f32_16x16x32_bf16 v[76:79], v[146:149], v[198:201], v[76:79]
	v_mfma_f32_16x16x32_bf16 v[72:75], v[158:161], v[198:201], v[72:75]
	v_mfma_f32_16x16x32_bf16 v[124:127], v[154:157], v[170:173], v[124:127]
	v_mfma_f32_16x16x32_bf16 v[120:123], v[162:165], v[170:173], v[120:123]
	v_mfma_f32_16x16x32_bf16 v[108:111], v[154:157], v[186:189], v[108:111]
	v_mfma_f32_16x16x32_bf16 v[104:107], v[162:165], v[186:189], v[104:107]
	v_mfma_f32_16x16x32_bf16 v[92:95], v[154:157], v[194:197], v[92:95]
	v_mfma_f32_16x16x32_bf16 v[88:91], v[162:165], v[194:197], v[88:91]
	v_mfma_f32_16x16x32_bf16 v[76:79], v[154:157], v[202:205], v[76:79]
	v_mfma_f32_16x16x32_bf16 v[72:75], v[162:165], v[202:205], v[72:75]
	s_setprio 1
	s_barrier
	s_add_i32 s24, 0, 0x1c000
	s_add_i32 s25, s46, s29
	v_add_u32_e32 v181, s24, v175
	v_lshl_add_u64 v[150:151], v[150:151], 0, s[4:5]
	s_mov_b32 m0, s25
	ds_read_b128 v[206:209], v181
	ds_read_b128 v[210:213], v181 offset:1024
	ds_read_b128 v[214:217], v181 offset:2048
	ds_read_b128 v[218:221], v181 offset:3072
	global_load_lds_dwordx4 v[150:151], off
	v_lshl_add_u64 v[150:151], v[222:223], 0, s[4:5]
	s_add_i32 m0, s25, 0x2000
	s_nop 0
	global_load_lds_dwordx4 v[150:151], off
	s_barrier
	s_waitcnt lgkmcnt(0)
	s_setprio 2
	s_waitcnt lgkmcnt(0)
	v_mfma_f32_16x16x32_bf16 v[116:119], v[206:209], v[166:169], v[116:119]
	v_mfma_f32_16x16x32_bf16 v[112:115], v[214:217], v[166:169], v[112:115]
	v_mfma_f32_16x16x32_bf16 v[100:103], v[206:209], v[182:185], v[100:103]
	v_mfma_f32_16x16x32_bf16 v[96:99], v[214:217], v[182:185], v[96:99]
	v_mfma_f32_16x16x32_bf16 v[84:87], v[206:209], v[190:193], v[84:87]
	v_mfma_f32_16x16x32_bf16 v[80:83], v[214:217], v[190:193], v[80:83]
	v_mfma_f32_16x16x32_bf16 v[68:71], v[206:209], v[198:201], v[68:71]
	v_mfma_f32_16x16x32_bf16 v[64:67], v[214:217], v[198:201], v[64:67]
	v_mfma_f32_16x16x32_bf16 v[116:119], v[210:213], v[170:173], v[116:119]
	v_mfma_f32_16x16x32_bf16 v[112:115], v[218:221], v[170:173], v[112:115]
	v_mfma_f32_16x16x32_bf16 v[100:103], v[210:213], v[186:189], v[100:103]
	v_mfma_f32_16x16x32_bf16 v[96:99], v[218:221], v[186:189], v[96:99]
	v_mfma_f32_16x16x32_bf16 v[84:87], v[210:213], v[194:197], v[84:87]
	v_mfma_f32_16x16x32_bf16 v[80:83], v[218:221], v[194:197], v[80:83]
	v_mfma_f32_16x16x32_bf16 v[68:71], v[210:213], v[202:205], v[68:71]
	v_mfma_f32_16x16x32_bf16 v[64:67], v[218:221], v[202:205], v[64:67]
	s_setprio 1
	s_mov_b32 m0, s35
	v_lshl_add_u64 v[150:151], v[224:225], 0, s[4:5]
	s_barrier
	ds_read_b128 v[166:169], v178 offset:49152
	ds_read_b128 v[170:173], v178 offset:50176
	ds_read_b128 v[182:185], v178 offset:51200
	ds_read_b128 v[186:189], v178 offset:52224
	ds_read_b128 v[190:193], v178 offset:53248
	ds_read_b128 v[194:197], v178 offset:54272
	ds_read_b128 v[198:201], v178 offset:55296
	ds_read_b128 v[202:205], v178 offset:56320
	global_load_lds_dwordx4 v[150:151], off
	v_lshl_add_u64 v[150:151], v[226:227], 0, s[4:5]
	s_mov_b32 m0, s36
	s_nop 0
	global_load_lds_dwordx4 v[150:151], off
	s_barrier
; #define PG8_STAGE(bufoff, gbase, voff) do { _Pragma("unroll") for (int _i = 0; _i < 2; ++_i) \
;         __builtin_amdgcn_global_load_lds((const unsigned*)((const char*)(gbase) + (voff)[_i]), (LAS unsigned*)(lds + (bufoff) + ldsw + _i * 8192), 16, 0, 0); } while (0)
; #define PG8_LDA(dst, b, h) do { _Pragma("unroll") for (int m = 0; m < 4; ++m) _Pragma("unroll") for (int k = 0; k < 2; ++k) dst[m][k] = *(const LAS bf16x8*)(lds + PG8_SA(b, h) + aoff + m * 2048 + k * 1024); } while (0)
; #define PG8_WAIT_V(n) asm volatile("s_waitcnt vmcnt(" #n ")" ::: "memory")
; template <class Epi>
; __device__ __forceinline__ void gemm_phase(LAS unsigned char* lds, const Gemm g, const StaticOrder& S, const Epi& E) {
;     ...
;         for (int t = 0; t < nt; t += 2) {
;             const bool last = (t == nt - 2);
;             const char* a1 = cA + (size_t)(t + 1) * kstep;
;             const char* a2 = last ? nA : cA + (size_t)(t + 2) * kstep; const char* b2 = last ? nB : cB + (size_t)(t + 2) * kstep;
;             const char* a3 = a2 + kstep; const char* b3 = b2 + kstep;
;             if (last) E.pre(cur, wr, fr, epre);
;             PG8_LDB(B0, 0, 0); PG8_SCHED; PG8_LDA(At, 0, 0); PG8_STAGE(PG8_SA(1, 1), a1 + hstepA, voffA);
;             PG8_WAIT_L(8); PG8_BAR; PG8_WAIT_L(0); PG8_MMA(0, 0, At, B0); PG8_BAR; PG8_SCHED;
;             PG8_LDB(B1, 0, 1); PG8_STAGE(PG8_SB(0, 0), b2, voffB);
;             PG8_BAR; PG8_WAIT_L(0); PG8_MMA(0, 1, At, B1); PG8_BAR;
;             PG8_LDA(At, 0, 1); PG8_STAGE(PG8_SA(0, 0), a2, voffA);
;             PG8_BAR; PG8_WAIT_L(0); PG8_MMA(1, 0, At, B0); PG8_BAR; PG8_SCHED;
;             PG8_STAGE(PG8_SB(0, 1), b2 + hstepB, voffB);
;             PG8_WAIT_V(6); PG8_BAR; PG8_MMA(1, 1, At, B1); PG8_BAR;
;             PG8_LDB(B0, 1, 0); PG8_SCHED; PG8_LDA(At, 1, 0); PG8_STAGE(PG8_SA(0, 1), a2 + hstepA, voffA);
;             PG8_WAIT_L(8); PG8_BAR; PG8_WAIT_L(0); PG8_MMA(0, 0, At, B0); PG8_BAR; PG8_SCHED;
;             PG8_LDB(B1, 1, 1); PG8_STAGE(PG8_SB(1, 0), b3, voffB);
;             PG8_BAR; PG8_WAIT_L(0); PG8_MMA(0, 1, At, B1); PG8_BAR;
;             PG8_LDA(At, 1, 1); PG8_STAGE(PG8_SA(1, 0), a3, voffA);
;             PG8_BAR; PG8_WAIT_L(0); PG8_MMA(1, 0, At, B0); PG8_BAR; PG8_SCHED;
;             PG8_STAGE(PG8_SB(1, 1), b3 + hstepB, voffB);
;             PG8_WAIT_V(6); PG8_BAR; PG8_MMA(1, 1, At, B1); PG8_BAR;
	s_waitcnt lgkmcnt(0)
	s_setprio 2
	s_waitcnt lgkmcnt(0)
	v_mfma_f32_16x16x32_bf16 v[60:63], v[146:149], v[166:169], v[60:63]
	v_mfma_f32_16x16x32_bf16 v[56:59], v[158:161], v[166:169], v[56:59]
	v_mfma_f32_16x16x32_bf16 v[44:47], v[146:149], v[182:185], v[44:47]
	v_mfma_f32_16x16x32_bf16 v[40:43], v[158:161], v[182:185], v[40:43]
	v_mfma_f32_16x16x32_bf16 v[28:31], v[146:149], v[190:193], v[28:31]
	v_mfma_f32_16x16x32_bf16 v[24:27], v[158:161], v[190:193], v[24:27]
	v_mfma_f32_16x16x32_bf16 v[12:15], v[146:149], v[198:201], v[12:15]
	v_mfma_f32_16x16x32_bf16 v[8:11], v[158:161], v[198:201], v[8:11]
	v_mfma_f32_16x16x32_bf16 v[60:63], v[154:157], v[170:173], v[60:63]
	v_mfma_f32_16x16x32_bf16 v[56:59], v[162:165], v[170:173], v[56:59]
	v_mfma_f32_16x16x32_bf16 v[44:47], v[154:157], v[186:189], v[44:47]
	v_mfma_f32_16x16x32_bf16 v[40:43], v[162:165], v[186:189], v[40:43]
	v_mfma_f32_16x16x32_bf16 v[28:31], v[154:157], v[194:197], v[28:31]
	v_mfma_f32_16x16x32_bf16 v[24:27], v[162:165], v[194:197], v[24:27]
	v_mfma_f32_16x16x32_bf16 v[12:15], v[154:157], v[202:205], v[12:15]
	v_mfma_f32_16x16x32_bf16 v[8:11], v[162:165], v[202:205], v[8:11]
	s_setprio 1
	s_barrier
	s_add_u32 s22, s22, 0x40080
	s_addc_u32 s23, s23, 0
	s_add_i32 s24, s24, s29
	v_lshl_add_u64 v[146:147], s[22:23], 0, v[130:131]
	s_mov_b32 m0, s24
	s_nop 0
	global_load_lds_dwordx4 v[146:147], off
	v_lshl_add_u64 v[146:147], s[22:23], 0, v[134:135]
	s_add_i32 m0, s24, 0x2000
	s_nop 0
	global_load_lds_dwordx4 v[146:147], off
	s_waitcnt vmcnt(6)
	s_barrier
	s_setprio 2
	v_mfma_f32_16x16x32_bf16 v[52:55], v[206:209], v[166:169], v[52:55]
	v_mfma_f32_16x16x32_bf16 v[48:51], v[214:217], v[166:169], v[48:51]
	v_mfma_f32_16x16x32_bf16 v[36:39], v[206:209], v[182:185], v[36:39]
	v_mfma_f32_16x16x32_bf16 v[32:35], v[214:217], v[182:185], v[32:35]
	v_mfma_f32_16x16x32_bf16 v[20:23], v[206:209], v[190:193], v[20:23]
	v_mfma_f32_16x16x32_bf16 v[16:19], v[214:217], v[190:193], v[16:19]
	v_mfma_f32_16x16x32_bf16 v[4:7], v[206:209], v[198:201], v[4:7]
	v_mfma_f32_16x16x32_bf16 v[0:3], v[214:217], v[198:201], v[0:3]
	v_mfma_f32_16x16x32_bf16 v[52:55], v[210:213], v[170:173], v[52:55]
	v_mfma_f32_16x16x32_bf16 v[48:51], v[218:221], v[170:173], v[48:51]
	v_mfma_f32_16x16x32_bf16 v[36:39], v[210:213], v[186:189], v[36:39]
	v_mfma_f32_16x16x32_bf16 v[32:35], v[218:221], v[186:189], v[32:35]
	v_mfma_f32_16x16x32_bf16 v[20:23], v[210:213], v[194:197], v[20:23]
	v_mfma_f32_16x16x32_bf16 v[16:19], v[218:221], v[194:197], v[16:19]
	v_mfma_f32_16x16x32_bf16 v[4:7], v[210:213], v[202:205], v[4:7]
	v_mfma_f32_16x16x32_bf16 v[0:3], v[218:221], v[202:205], v[0:3]
	s_setprio 1
	s_add_i32 s45, s45, 2
	s_add_u32 s20, s20, 0x100
	s_addc_u32 s21, s21, 0
	s_add_u32 s43, s43, 0x100
	s_addc_u32 s44, s44, 0
	s_cmp_gt_u32 s45, 13
	s_barrier
.Lkp2_770:
	ds_read_b128 v[146:149], v177
	ds_read_b128 v[154:157], v177 offset:1024
	ds_read_b128 v[158:161], v177 offset:2048
	ds_read_b128 v[162:165], v177 offset:3072
	s_add_u32 s22, s20, 0xfffc0080
	s_addc_u32 s23, s21, -1
	s_cmp_eq_u32 s45, 12
	s_cselect_b32 s25, s13, s23
	s_cselect_b32 s24, s41, s22
	s_cselect_b32 s23, s11, s44
	s_cselect_b32 s22, s42, s43
	v_lshl_add_u64 v[150:151], s[20:21], 0, v[138:139]
	s_add_i32 m0, s19, 0xc000
	ds_read_b128 v[166:169], v178
	ds_read_b128 v[170:173], v178 offset:1024
	ds_read_b128 v[182:185], v178 offset:2048
	ds_read_b128 v[186:189], v178 offset:3072
	ds_read_b128 v[190:193], v178 offset:4096
	ds_read_b128 v[194:197], v178 offset:5120
	ds_read_b128 v[198:201], v178 offset:6144
	ds_read_b128 v[202:205], v178 offset:7168
	global_load_lds_dwordx4 v[150:151], off
	v_lshl_add_u64 v[150:151], s[20:21], 0, v[140:141]
	s_add_i32 m0, s19, 0xe000
	s_nop 0
	global_load_lds_dwordx4 v[150:151], off
	s_waitcnt lgkmcnt(8)
	s_barrier
	s_waitcnt lgkmcnt(0)
	s_setprio 2
	s_waitcnt lgkmcnt(0)
	v_mfma_f32_16x16x32_bf16 v[124:127], v[146:149], v[166:169], v[124:127]
	v_mfma_f32_16x16x32_bf16 v[120:123], v[158:161], v[166:169], v[120:123]
	v_mfma_f32_16x16x32_bf16 v[108:111], v[146:149], v[182:185], v[108:111]
	v_mfma_f32_16x16x32_bf16 v[104:107], v[158:161], v[182:185], v[104:107]
	v_mfma_f32_16x16x32_bf16 v[92:95], v[146:149], v[190:193], v[92:95]
	v_mfma_f32_16x16x32_bf16 v[88:91], v[158:161], v[190:193], v[88:91]
	v_mfma_f32_16x16x32_bf16 v[76:79], v[146:149], v[198:201], v[76:79]
	v_mfma_f32_16x16x32_bf16 v[72:75], v[158:161], v[198:201], v[72:75]
	v_mfma_f32_16x16x32_bf16 v[124:127], v[154:157], v[170:173], v[124:127]
	v_mfma_f32_16x16x32_bf16 v[120:123], v[162:165], v[170:173], v[120:123]
	v_mfma_f32_16x16x32_bf16 v[108:111], v[154:157], v[186:189], v[108:111]
	v_mfma_f32_16x16x32_bf16 v[104:107], v[162:165], v[186:189], v[104:107]
	v_mfma_f32_16x16x32_bf16 v[92:95], v[154:157], v[194:197], v[92:95]
	v_mfma_f32_16x16x32_bf16 v[88:91], v[162:165], v[194:197], v[88:91]
	v_mfma_f32_16x16x32_bf16 v[76:79], v[154:157], v[202:205], v[76:79]
	v_mfma_f32_16x16x32_bf16 v[72:75], v[162:165], v[202:205], v[72:75]
	s_setprio 1
	s_barrier
	s_add_i32 s46, s7, s29
	v_lshl_add_u64 v[150:151], s[22:23], 0, v[130:131]
	s_mov_b32 m0, s46
	ds_read_b128 v[206:209], v179
	ds_read_b128 v[210:213], v179 offset:1024
	ds_read_b128 v[214:217], v179 offset:2048
	ds_read_b128 v[218:221], v179 offset:3072
	global_load_lds_dwordx4 v[150:151], off
	v_lshl_add_u64 v[222:223], s[22:23], 0, v[134:135]
	s_add_i32 m0, s46, 0x2000
	s_nop 0
	global_load_lds_dwordx4 v[222:223], off
	s_barrier
; #define PG8_STAGE(bufoff, gbase, voff) do { _Pragma("unroll") for (int _i = 0; _i < 2; ++_i) \
;         __builtin_amdgcn_global_load_lds((const unsigned*)((const char*)(gbase) + (voff)[_i]), (LAS unsigned*)(lds + (bufoff) + ldsw + _i * 8192), 16, 0, 0); } while (0)
; #define PG8_LDA(dst, b, h) do { _Pragma("unroll") for (int m = 0; m < 4; ++m) _Pragma("unroll") for (int k = 0; k < 2; ++k) dst[m][k] = *(const LAS bf16x8*)(lds + PG8_SA(b, h) + aoff + m * 2048 + k * 1024); } while (0)
; #define PG8_LDB(dst, b, h) do { _Pragma("unroll") for (int n = 0; n < 2; ++n) _Pragma("unroll") for (int k = 0; k < 2; ++k) dst[n][k] = *(const LAS bf16x8*)(lds + PG8_SB(b, h) + boff + n * 2048 + k * 1024); } while (0)
; #define PG8_MMA(ai, bj, At, Bt) do { __builtin_amdgcn_s_setprio(1); _Pragma("unroll") for (int m = 0; m < 4; ++m) _Pragma("unroll") for (int n = 0; n < 2; ++n) _Pragma("unroll") for (int k = 0; k < 2; ++k) \
;         acc[ai][bj][m][n] = __builtin_amdgcn_mfma_f32_16x16x32_bf16(Bt[n][k], At[m][k], acc[ai][bj][m][n], 0, 0, 0); __builtin_amdgcn_s_setprio(0); } while (0)
; #define PG8_WAIT_V(n) asm volatile("s_waitcnt vmcnt(" #n ")" ::: "memory")
; #define PG8_WAIT_L(n) asm volatile("s_waitcnt lgkmcnt(" #n ")" ::: "memory")
; #define PG8_BAR __builtin_amdgcn_s_barrier()
; #define PG8_SCHED __builtin_amdgcn_sched_barrier(0)
; template <class Epi>
; __device__ __forceinline__ void gemm_phase(LAS unsigned char* lds, const Gemm g, const StaticOrder& S, const Epi& E) {
;     ...
;             PG8_BAR; PG8_WAIT_L(0); PG8_MMA(0, 1, At, B1); PG8_BAR;
;             PG8_LDA(At, 0, 1); PG8_STAGE(PG8_SA(0, 0), a2, voffA);
;             PG8_BAR; PG8_WAIT_L(0); PG8_MMA(1, 0, At, B0); PG8_BAR; PG8_SCHED;
;             PG8_STAGE(PG8_SB(0, 1), b2 + hstepB, voffB);
;             PG8_WAIT_V(6); PG8_BAR; PG8_MMA(1, 1, At, B1); PG8_BAR;
;             PG8_LDB(B0, 1, 0); PG8_SCHED; PG8_LDA(At, 1, 0); PG8_STAGE(PG8_SA(0, 1), a2 + hstepA, voffA);
	s_waitcnt lgkmcnt(0)
	s_setprio 2
	s_waitcnt lgkmcnt(0)
	v_mfma_f32_16x16x32_bf16 v[116:119], v[206:209], v[166:169], v[116:119]
	v_mfma_f32_16x16x32_bf16 v[112:115], v[214:217], v[166:169], v[112:115]
	v_mfma_f32_16x16x32_bf16 v[100:103], v[206:209], v[182:185], v[100:103]
	v_mfma_f32_16x16x32_bf16 v[96:99], v[214:217], v[182:185], v[96:99]
	v_mfma_f32_16x16x32_bf16 v[84:87], v[206:209], v[190:193], v[84:87]
	v_mfma_f32_16x16x32_bf16 v[80:83], v[214:217], v[190:193], v[80:83]
	v_mfma_f32_16x16x32_bf16 v[68:71], v[206:209], v[198:201], v[68:71]
	v_mfma_f32_16x16x32_bf16 v[64:67], v[214:217], v[198:201], v[64:67]
	v_mfma_f32_16x16x32_bf16 v[116:119], v[210:213], v[170:173], v[116:119]
	v_mfma_f32_16x16x32_bf16 v[112:115], v[218:221], v[170:173], v[112:115]
	v_mfma_f32_16x16x32_bf16 v[100:103], v[210:213], v[186:189], v[100:103]
	v_mfma_f32_16x16x32_bf16 v[96:99], v[218:221], v[186:189], v[96:99]
	v_mfma_f32_16x16x32_bf16 v[84:87], v[210:213], v[194:197], v[84:87]
	v_mfma_f32_16x16x32_bf16 v[80:83], v[218:221], v[194:197], v[80:83]
	v_mfma_f32_16x16x32_bf16 v[68:71], v[210:213], v[202:205], v[68:71]
	v_mfma_f32_16x16x32_bf16 v[64:67], v[218:221], v[202:205], v[64:67]
	s_setprio 1
	s_mov_b32 m0, s19
	v_lshl_add_u64 v[224:225], s[24:25], 0, v[128:129]
	s_barrier
	ds_read_b128 v[166:169], v178 offset:16384
	ds_read_b128 v[170:173], v178 offset:17408
	ds_read_b128 v[182:185], v178 offset:18432
	ds_read_b128 v[186:189], v178 offset:19456
	ds_read_b128 v[190:193], v178 offset:20480
	ds_read_b128 v[194:197], v178 offset:21504
	ds_read_b128 v[198:201], v178 offset:22528
	ds_read_b128 v[202:205], v178 offset:23552
	global_load_lds_dwordx4 v[224:225], off
	v_lshl_add_u64 v[226:227], s[24:25], 0, v[132:133]
	s_mov_b32 m0, s30
	s_nop 0
	global_load_lds_dwordx4 v[226:227], off
	s_barrier
	s_waitcnt lgkmcnt(0)
	s_setprio 2
	s_waitcnt lgkmcnt(0)
	v_mfma_f32_16x16x32_bf16 v[60:63], v[146:149], v[166:169], v[60:63]
	v_mfma_f32_16x16x32_bf16 v[56:59], v[158:161], v[166:169], v[56:59]
	v_mfma_f32_16x16x32_bf16 v[44:47], v[146:149], v[182:185], v[44:47]
	v_mfma_f32_16x16x32_bf16 v[40:43], v[158:161], v[182:185], v[40:43]
	v_mfma_f32_16x16x32_bf16 v[28:31], v[146:149], v[190:193], v[28:31]
	v_mfma_f32_16x16x32_bf16 v[24:27], v[158:161], v[190:193], v[24:27]
	v_mfma_f32_16x16x32_bf16 v[12:15], v[146:149], v[198:201], v[12:15]
	v_mfma_f32_16x16x32_bf16 v[8:11], v[158:161], v[198:201], v[8:11]
	v_mfma_f32_16x16x32_bf16 v[60:63], v[154:157], v[170:173], v[60:63]
	v_mfma_f32_16x16x32_bf16 v[56:59], v[162:165], v[170:173], v[56:59]
	v_mfma_f32_16x16x32_bf16 v[44:47], v[154:157], v[186:189], v[44:47]
	v_mfma_f32_16x16x32_bf16 v[40:43], v[162:165], v[186:189], v[40:43]
	v_mfma_f32_16x16x32_bf16 v[28:31], v[154:157], v[194:197], v[28:31]
	v_mfma_f32_16x16x32_bf16 v[24:27], v[162:165], v[194:197], v[24:27]
	v_mfma_f32_16x16x32_bf16 v[12:15], v[154:157], v[202:205], v[12:15]
	v_mfma_f32_16x16x32_bf16 v[8:11], v[162:165], v[202:205], v[8:11]
	s_setprio 1
	s_barrier
	s_add_u32 s46, s22, 0x40000
	s_addc_u32 s47, s23, 0
	s_add_i32 s48, s38, s29
	v_lshl_add_u64 v[146:147], s[46:47], 0, v[130:131]
	s_mov_b32 m0, s48
	s_nop 0
	global_load_lds_dwordx4 v[146:147], off
	v_lshl_add_u64 v[146:147], s[46:47], 0, v[134:135]
	s_add_i32 m0, s48, 0x2000
	s_nop 0
	global_load_lds_dwordx4 v[146:147], off
	s_waitcnt vmcnt(6)
	s_barrier
	s_setprio 2
	v_mfma_f32_16x16x32_bf16 v[52:55], v[206:209], v[166:169], v[52:55]
	v_mfma_f32_16x16x32_bf16 v[48:51], v[214:217], v[166:169], v[48:51]
	v_mfma_f32_16x16x32_bf16 v[36:39], v[206:209], v[182:185], v[36:39]
	v_mfma_f32_16x16x32_bf16 v[32:35], v[214:217], v[182:185], v[32:35]
	v_mfma_f32_16x16x32_bf16 v[20:23], v[206:209], v[190:193], v[20:23]
	v_mfma_f32_16x16x32_bf16 v[16:19], v[214:217], v[190:193], v[16:19]
	v_mfma_f32_16x16x32_bf16 v[4:7], v[206:209], v[198:201], v[4:7]
	v_mfma_f32_16x16x32_bf16 v[0:3], v[214:217], v[198:201], v[0:3]
	v_mfma_f32_16x16x32_bf16 v[52:55], v[210:213], v[170:173], v[52:55]
	v_mfma_f32_16x16x32_bf16 v[48:51], v[218:221], v[170:173], v[48:51]
	v_mfma_f32_16x16x32_bf16 v[36:39], v[210:213], v[186:189], v[36:39]
	v_mfma_f32_16x16x32_bf16 v[32:35], v[218:221], v[186:189], v[32:35]
	v_mfma_f32_16x16x32_bf16 v[20:23], v[210:213], v[194:197], v[20:23]
	v_mfma_f32_16x16x32_bf16 v[16:19], v[218:221], v[194:197], v[16:19]
	v_mfma_f32_16x16x32_bf16 v[4:7], v[210:213], v[202:205], v[4:7]
	v_mfma_f32_16x16x32_bf16 v[0:3], v[218:221], v[202:205], v[0:3]
	s_setprio 1
	s_add_i32 s46, 0, 0x18000
	v_add_u32_e32 v162, s46, v175
	s_barrier
	ds_read_b128 v[146:149], v162
	ds_read_b128 v[154:157], v162 offset:1024
	ds_read_b128 v[158:161], v162 offset:2048
	ds_read_b128 v[162:165], v162 offset:3072
	s_add_u32 s24, s24, 0x40000
	s_addc_u32 s25, s25, 0
	s_mov_b32 m0, s31
	v_lshl_add_u64 v[206:207], s[24:25], 0, v[128:129]
	ds_read_b128 v[166:169], v178 offset:32768
	ds_read_b128 v[170:173], v178 offset:33792
	ds_read_b128 v[182:185], v178 offset:34816
	ds_read_b128 v[186:189], v178 offset:35840
	ds_read_b128 v[190:193], v178 offset:36864
	ds_read_b128 v[194:197], v178 offset:37888
	ds_read_b128 v[198:201], v178 offset:38912
	ds_read_b128 v[202:205], v178 offset:39936
	global_load_lds_dwordx4 v[206:207], off
	v_lshl_add_u64 v[206:207], s[24:25], 0, v[132:133]
	s_mov_b32 m0, s33
	s_nop 0
	global_load_lds_dwordx4 v[206:207], off
	s_waitcnt lgkmcnt(8)
	s_barrier
; #define PG8_STAGE(bufoff, gbase, voff) do { _Pragma("unroll") for (int _i = 0; _i < 2; ++_i) \
;         __builtin_amdgcn_global_load_lds((const unsigned*)((const char*)(gbase) + (voff)[_i]), (LAS unsigned*)(lds + (bufoff) + ldsw + _i * 8192), 16, 0, 0); } while (0)
; #define PG8_LDA(dst, b, h) do { _Pragma("unroll") for (int m = 0; m < 4; ++m) _Pragma("unroll") for (int k = 0; k < 2; ++k) dst[m][k] = *(const LAS bf16x8*)(lds + PG8_SA(b, h) + aoff + m * 2048 + k * 1024); } while (0)
; #define PG8_LDB(dst, b, h) do { _Pragma("unroll") for (int n = 0; n < 2; ++n) _Pragma("unroll") for (int k = 0; k < 2; ++k) dst[n][k] = *(const LAS bf16x8*)(lds + PG8_SB(b, h) + boff + n * 2048 + k * 1024); } while (0)
; #define PG8_MMA(ai, bj, At, Bt) do { __builtin_amdgcn_s_setprio(1); _Pragma("unroll") for (int m = 0; m < 4; ++m) _Pragma("unroll") for (int n = 0; n < 2; ++n) _Pragma("unroll") for (int k = 0; k < 2; ++k) \
;         acc[ai][bj][m][n] = __builtin_amdgcn_mfma_f32_16x16x32_bf16(Bt[n][k], At[m][k], acc[ai][bj][m][n], 0, 0, 0); __builtin_amdgcn_s_setprio(0); } while (0)
; #define PG8_WAIT_V(n) asm volatile("s_waitcnt vmcnt(" #n ")" ::: "memory")
; #define PG8_WAIT_L(n) asm volatile("s_waitcnt lgkmcnt(" #n ")" ::: "memory")
; #define PG8_BAR __builtin_amdgcn_s_barrier()
; #define PG8_SCHED __builtin_amdgcn_sched_barrier(0)
; template <class Epi>
; __device__ __forceinline__ void gemm_phase(LAS unsigned char* lds, const Gemm g, const StaticOrder& S, const Epi& E) {
;     ...
;             PG8_WAIT_L(8); PG8_BAR; PG8_WAIT_L(0); PG8_MMA(0, 0, At, B0); PG8_BAR; PG8_SCHED;
;             PG8_LDB(B1, 1, 1); PG8_STAGE(PG8_SB(1, 0), b3, voffB);
;             PG8_BAR; PG8_WAIT_L(0); PG8_MMA(0, 1, At, B1); PG8_BAR;
;             PG8_LDA(At, 1, 1); PG8_STAGE(PG8_SA(1, 0), a3, voffA);
;             PG8_BAR; PG8_WAIT_L(0); PG8_MMA(1, 0, At, B0); PG8_BAR; PG8_SCHED;
;             PG8_STAGE(PG8_SB(1, 1), b3 + hstepB, voffB);
;             PG8_WAIT_V(6); PG8_BAR; PG8_MMA(1, 1, At, B1); PG8_BAR;
;         }
	s_waitcnt lgkmcnt(0)
	s_setprio 2
	s_waitcnt lgkmcnt(0)
	v_mfma_f32_16x16x32_bf16 v[124:127], v[146:149], v[166:169], v[124:127]
	v_mfma_f32_16x16x32_bf16 v[120:123], v[158:161], v[166:169], v[120:123]
	v_mfma_f32_16x16x32_bf16 v[108:111], v[146:149], v[182:185], v[108:111]
	v_mfma_f32_16x16x32_bf16 v[104:107], v[158:161], v[182:185], v[104:107]
	v_mfma_f32_16x16x32_bf16 v[92:95], v[146:149], v[190:193], v[92:95]
	v_mfma_f32_16x16x32_bf16 v[88:91], v[158:161], v[190:193], v[88:91]
	v_mfma_f32_16x16x32_bf16 v[76:79], v[146:149], v[198:201], v[76:79]
	v_mfma_f32_16x16x32_bf16 v[72:75], v[158:161], v[198:201], v[72:75]
	v_mfma_f32_16x16x32_bf16 v[124:127], v[154:157], v[170:173], v[124:127]
	v_mfma_f32_16x16x32_bf16 v[120:123], v[162:165], v[170:173], v[120:123]
	v_mfma_f32_16x16x32_bf16 v[108:111], v[154:157], v[186:189], v[108:111]
	v_mfma_f32_16x16x32_bf16 v[104:107], v[162:165], v[186:189], v[104:107]
	v_mfma_f32_16x16x32_bf16 v[92:95], v[154:157], v[194:197], v[92:95]
	v_mfma_f32_16x16x32_bf16 v[88:91], v[162:165], v[194:197], v[88:91]
	v_mfma_f32_16x16x32_bf16 v[76:79], v[154:157], v[202:205], v[76:79]
	v_mfma_f32_16x16x32_bf16 v[72:75], v[162:165], v[202:205], v[72:75]
	s_setprio 1
	s_barrier
	s_add_i32 s24, 0, 0x1c000
	s_add_i32 s25, s46, s29
	v_add_u32_e32 v181, s24, v175
	v_lshl_add_u64 v[150:151], v[150:151], 0, s[4:5]
	s_mov_b32 m0, s25
	ds_read_b128 v[206:209], v181
	ds_read_b128 v[210:213], v181 offset:1024
	ds_read_b128 v[214:217], v181 offset:2048
	ds_read_b128 v[218:221], v181 offset:3072
	global_load_lds_dwordx4 v[150:151], off
	v_lshl_add_u64 v[150:151], v[222:223], 0, s[4:5]
	s_add_i32 m0, s25, 0x2000
	s_nop 0
	global_load_lds_dwordx4 v[150:151], off
	s_barrier
	s_waitcnt lgkmcnt(0)
	s_setprio 2
	s_waitcnt lgkmcnt(0)
	v_mfma_f32_16x16x32_bf16 v[116:119], v[206:209], v[166:169], v[116:119]
	v_mfma_f32_16x16x32_bf16 v[112:115], v[214:217], v[166:169], v[112:115]
	v_mfma_f32_16x16x32_bf16 v[100:103], v[206:209], v[182:185], v[100:103]
	v_mfma_f32_16x16x32_bf16 v[96:99], v[214:217], v[182:185], v[96:99]
	v_mfma_f32_16x16x32_bf16 v[84:87], v[206:209], v[190:193], v[84:87]
	v_mfma_f32_16x16x32_bf16 v[80:83], v[214:217], v[190:193], v[80:83]
	v_mfma_f32_16x16x32_bf16 v[68:71], v[206:209], v[198:201], v[68:71]
	v_mfma_f32_16x16x32_bf16 v[64:67], v[214:217], v[198:201], v[64:67]
	v_mfma_f32_16x16x32_bf16 v[116:119], v[210:213], v[170:173], v[116:119]
	v_mfma_f32_16x16x32_bf16 v[112:115], v[218:221], v[170:173], v[112:115]
	v_mfma_f32_16x16x32_bf16 v[100:103], v[210:213], v[186:189], v[100:103]
	v_mfma_f32_16x16x32_bf16 v[96:99], v[218:221], v[186:189], v[96:99]
	v_mfma_f32_16x16x32_bf16 v[84:87], v[210:213], v[194:197], v[84:87]
	v_mfma_f32_16x16x32_bf16 v[80:83], v[218:221], v[194:197], v[80:83]
	v_mfma_f32_16x16x32_bf16 v[68:71], v[210:213], v[202:205], v[68:71]
	v_mfma_f32_16x16x32_bf16 v[64:67], v[218:221], v[202:205], v[64:67]
	s_setprio 1
	s_mov_b32 m0, s35
	v_lshl_add_u64 v[150:151], v[224:225], 0, s[4:5]
	s_barrier
	ds_read_b128 v[166:169], v178 offset:49152
	ds_read_b128 v[170:173], v178 offset:50176
	ds_read_b128 v[182:185], v178 offset:51200
	ds_read_b128 v[186:189], v178 offset:52224
	ds_read_b128 v[190:193], v178 offset:53248
	ds_read_b128 v[194:197], v178 offset:54272
	ds_read_b128 v[198:201], v178 offset:55296
	ds_read_b128 v[202:205], v178 offset:56320
	global_load_lds_dwordx4 v[150:151], off
	v_lshl_add_u64 v[150:151], v[226:227], 0, s[4:5]
	s_mov_b32 m0, s36
	s_nop 0
	global_load_lds_dwordx4 v[150:151], off
	s_barrier
	s_waitcnt lgkmcnt(0)
	s_setprio 2
	s_waitcnt lgkmcnt(0)
	v_mfma_f32_16x16x32_bf16 v[60:63], v[146:149], v[166:169], v[60:63]
	v_mfma_f32_16x16x32_bf16 v[56:59], v[158:161], v[166:169], v[56:59]
	v_mfma_f32_16x16x32_bf16 v[44:47], v[146:149], v[182:185], v[44:47]
	v_mfma_f32_16x16x32_bf16 v[40:43], v[158:161], v[182:185], v[40:43]
	v_mfma_f32_16x16x32_bf16 v[28:31], v[146:149], v[190:193], v[28:31]
	v_mfma_f32_16x16x32_bf16 v[24:27], v[158:161], v[190:193], v[24:27]
	v_mfma_f32_16x16x32_bf16 v[12:15], v[146:149], v[198:201], v[12:15]
	v_mfma_f32_16x16x32_bf16 v[8:11], v[158:161], v[198:201], v[8:11]
	v_mfma_f32_16x16x32_bf16 v[60:63], v[154:157], v[170:173], v[60:63]
	v_mfma_f32_16x16x32_bf16 v[56:59], v[162:165], v[170:173], v[56:59]
	v_mfma_f32_16x16x32_bf16 v[44:47], v[154:157], v[186:189], v[44:47]
	v_mfma_f32_16x16x32_bf16 v[40:43], v[162:165], v[186:189], v[40:43]
	v_mfma_f32_16x16x32_bf16 v[28:31], v[154:157], v[194:197], v[28:31]
	v_mfma_f32_16x16x32_bf16 v[24:27], v[162:165], v[194:197], v[24:27]
	v_mfma_f32_16x16x32_bf16 v[12:15], v[154:157], v[202:205], v[12:15]
	v_mfma_f32_16x16x32_bf16 v[8:11], v[162:165], v[202:205], v[8:11]
	s_setprio 1
	s_barrier
	s_add_u32 s22, s22, 0x40080
	s_addc_u32 s23, s23, 0
	s_add_i32 s24, s24, s29
	v_lshl_add_u64 v[146:147], s[22:23], 0, v[130:131]
	s_mov_b32 m0, s24
	s_nop 0
	global_load_lds_dwordx4 v[146:147], off
	v_lshl_add_u64 v[146:147], s[22:23], 0, v[134:135]
	s_add_i32 m0, s24, 0x2000
	s_nop 0
	global_load_lds_dwordx4 v[146:147], off
	s_waitcnt vmcnt(6)
	s_barrier
	s_setprio 2
	v_mfma_f32_16x16x32_bf16 v[52:55], v[206:209], v[166:169], v[52:55]
	v_mfma_f32_16x16x32_bf16 v[48:51], v[214:217], v[166:169], v[48:51]
	v_mfma_f32_16x16x32_bf16 v[36:39], v[206:209], v[182:185], v[36:39]
	v_mfma_f32_16x16x32_bf16 v[32:35], v[214:217], v[182:185], v[32:35]
	v_mfma_f32_16x16x32_bf16 v[20:23], v[206:209], v[190:193], v[20:23]
	v_mfma_f32_16x16x32_bf16 v[16:19], v[214:217], v[190:193], v[16:19]
	v_mfma_f32_16x16x32_bf16 v[4:7], v[206:209], v[198:201], v[4:7]
	v_mfma_f32_16x16x32_bf16 v[0:3], v[214:217], v[198:201], v[0:3]
	v_mfma_f32_16x16x32_bf16 v[52:55], v[210:213], v[170:173], v[52:55]
	v_mfma_f32_16x16x32_bf16 v[48:51], v[218:221], v[170:173], v[48:51]
	v_mfma_f32_16x16x32_bf16 v[36:39], v[210:213], v[186:189], v[36:39]
	v_mfma_f32_16x16x32_bf16 v[32:35], v[218:221], v[186:189], v[32:35]
	v_mfma_f32_16x16x32_bf16 v[20:23], v[210:213], v[194:197], v[20:23]
	v_mfma_f32_16x16x32_bf16 v[16:19], v[218:221], v[194:197], v[16:19]
	v_mfma_f32_16x16x32_bf16 v[4:7], v[210:213], v[202:205], v[4:7]
	v_mfma_f32_16x16x32_bf16 v[0:3], v[218:221], v[202:205], v[0:3]
	s_setprio 1
	s_add_i32 s45, s45, 2
	s_add_u32 s20, s20, 0x100
	s_addc_u32 s21, s21, 0
	s_add_u32 s43, s43, 0x100
	s_addc_u32 s44, s44, 0
	s_cmp_gt_u32 s45, 13
	s_barrier
	s_cbranch_scc0 .Lkp2_770
	s_branch .Lkp2_epi
;     __device__ bool next(int i, Unit& u) const {
;         const long L = (long)i * G + c; if (L >= nwg) return false;
;         int wgid = (int)L; { const int q = nwg / NXCD, r = nwg % NXCD, xcd = wgid % NXCD, off = wgid / NXCD; wgid = (xcd < r ? xcd * (q + 1) : r * (q + 1) + (xcd - r) * q) + off; }
;         const int nig = WGM * nN, gid = wgid / nig, fm = gid * WGM, gsz = (nM - fm) < WGM ? (nM - fm) : WGM;
;         u.pm = fm + ((wgid % nig) % gsz); u.pn = (wgid % nig) / gsz; return true;
; template <class Epi>
; __device__ __forceinline__ void gemm_phase(LAS unsigned char* lds, const Gemm g, const StaticOrder& S, const Epi& E) {
;     ...
;         const bool has_next = S.next(ui + 1, nxt);
;         const char* nA = has_next ? (const char*)g.A + (size_t)nxt.pm * tstepA : cA; const char* nB = has_next ? (const char*)g.Bt + (size_t)nxt.pn * tstepB : cB;
.LBB0_763:
	v_readfirstlane_b32 s98, v152
	s_nop 3
	s_cmp_ge_u32 s98, 0x100
	s_cbranch_scc1 .Lkp2_head
	s_add_i32 s34, s34, 1
	s_mul_i32 s0, s34, s37
	s_mul_hi_u32 s1, s34, s92
	s_add_i32 s1, s1, s0
	s_mul_i32 s0, s34, s92
	s_add_u32 s14, s0, s93
	s_addc_u32 s15, s1, s26
	v_cmp_gt_i64_e64 s[0:1], s[14:15], v[144:145]
	s_and_b64 vcc, exec, s[0:1]
	s_cbranch_vccnz .LBB0_769
	s_lshr_b32 s10, s14, 3
	s_mov_b32 s13, 0
	s_sub_u32 s11, s10, 0x80
	s_cmp_ge_u32 s10, 0x80
	s_cselect_b32 s10, s11, s10
	s_addc_u32 s13, s13, 0
	s_sub_u32 s11, s10, 0x80
	s_cmp_ge_u32 s10, 0x80
	s_cselect_b32 s10, s11, s10
	s_addc_u32 s13, s13, 0
	s_sub_u32 s11, s10, 0x80
	s_cmp_ge_u32 s10, 0x80
	s_cselect_b32 s10, s11, s10
	s_addc_u32 s13, s13, 0
	s_and_b32 s12, s14, 7
	s_lshl_b32 s12, s12, 2
	s_add_i32 s12, s12, s13
	s_lshl_b32 s12, s12, 3
	s_and_b32 s13, s10, 7
	s_add_i32 s12, s12, s13
	s_lshr_b32 s10, s10, 3

; __device__ __forceinline__ unsigned pk2(float lo, float hi) { const f32x2 v = (f32x2){lo, hi}; const bf16x2_t b = __builtin_convertvector(v, bf16x2_t); return __builtin_bit_cast(unsigned, b); }
;     __device__ __forceinline__ void operator()(const f32x4 (&acc)[2][2][4][2], const Unit& u, int wr, int wc, int fr, int fq, const float (&)[8]) const {
;     ...
;         const int col0 = u.pn * BM + wc * 32 + 8 * fq;
; #pragma unroll
;         for (int ai = 0; ai < 2; ++ai)
; #pragma unroll
;             for (int m = 0; m < 4; ++m) { const int row = row0 + ai * HALF + m * 16; const float rs = rsqrtf(ep[ai * 4 + m] * (1.0f / 1024.0f) + EPS);
;                 u16* rowp = O + (size_t)row * ldc + col0;
; #pragma unroll
;                 for (int bj = 0; bj < 2; ++bj) { f32x4 v0 = acc[ai][bj][m][0] * rs, v1 = acc[ai][bj][m][1] * rs;
;                     if (ACT == 1) {
; #pragma unroll
;                         for (int j = 0; j < 4; ++j) { const float a0 = fmaxf(v0[j], 0.f), a1 = fmaxf(v1[j], 0.f); v0[j] = a0 * a0; v1[j] = a1 * a1; } }
;                     u32x4 w; w.x = pk2(v0[0], v0[1]); w.y = pk2(v0[2], v0[3]); w.z = pk2(v1[0], v1[1]); w.w = pk2(v1[2], v1[3]);
;                     *(u32x4*)(rowp + bj * HALF) = w; } }
.Lkp2_epi:
	s_setprio 0
	s_bfe_u32 vcc_lo, s18, 0x20003
	s_lshl_b32 vcc_lo, vcc_lo, 10
	s_add_i32 vcc_lo, vcc_lo, 0x20010
	v_lshl_add_u32 v236, v174, 2, vcc_lo
	ds_read_b32 v228, v236
	ds_read_b32 v229, v236 offset:64
	ds_read_b32 v230, v236 offset:128
	ds_read_b32 v231, v236 offset:192
	ds_read_b32 v232, v236 offset:512
	ds_read_b32 v233, v236 offset:576
	ds_read_b32 v234, v236 offset:640
	ds_read_b32 v235, v236 offset:704
	s_waitcnt lgkmcnt(0)
	v_lshl_add_u32 v148, s18, 8, v174
	v_ashrrev_i32_e32 v149, 31, v148
	v_or_b32_e32 v172, 16, v148
	v_ashrrev_i32_e32 v173, 31, v172
	v_or_b32_e32 v168, 32, v148
	v_or_b32_e32 v164, 48, v148
	v_ashrrev_i32_e32 v169, 31, v168
	v_ashrrev_i32_e32 v165, 31, v164
	v_add_u32_e32 v162, 0x80, v148
	v_add_u32_e32 v156, 0x90, v148
	v_ashrrev_i32_e32 v163, 31, v162
	v_ashrrev_i32_e32 v157, 31, v156
	v_add_u32_e32 v150, 0xa0, v148
	v_ashrrev_i32_e32 v151, 31, v150
	v_add_u32_e32 v146, 0xb0, v148
	v_ashrrev_i32_e32 v147, 31, v146
	v_lshl_or_b32 v166, s40, 8, v176
	v_ashrrev_i32_e32 v167, 31, v166
	v_lshlrev_b64 v[170:171], 13, v[148:149]
	v_lshlrev_b64 v[148:149], 1, v[166:167]
	v_lshl_add_u64 v[166:167], s[96:97], 0, v[170:171]
	v_lshl_add_u64 v[212:213], v[166:167], 0, v[148:149]
	s_mov_b32 s40, s10
	s_mov_b32 s18, s12
	s_mov_b64 s[22:23], s[16:17]
	s_mov_b64 s[20:21], s[14:15]
	s_waitcnt vmcnt(8)
	s_waitcnt lgkmcnt(0)
	s_waitcnt lgkmcnt(0)
	v_mov_b32_e32 v184, v228
	v_pk_mul_f32 v[120:121], v[120:121], v[184:185] op_sel_hi:[1,0]
	v_pk_mul_f32 v[126:127], v[126:127], v[184:185] op_sel_hi:[1,0]
	v_pk_mul_f32 v[124:125], v[124:125], v[184:185] op_sel_hi:[1,0]
	v_pk_mul_f32 v[122:123], v[122:123], v[184:185] op_sel_hi:[1,0]
	v_max_f32_e32 v120, 0, v120
	v_max_f32_e32 v121, 0, v121
	v_max_f32_e32 v124, 0, v124
	v_max_f32_e32 v125, 0, v125
	v_pk_mul_f32 v[190:191], v[120:121], v[120:121]
	v_max_f32_e32 v120, 0, v126
	v_max_f32_e32 v122, 0, v122
	v_max_f32_e32 v121, 0, v127
	v_max_f32_e32 v123, 0, v123
	v_pk_mul_f32 v[124:125], v[124:125], v[124:125]
	v_pk_mul_f32 v[126:127], v[120:121], v[120:121]
	v_pk_mul_f32 v[194:195], v[122:123], v[122:123]
	v_pk_mul_f32 v[114:115], v[114:115], v[184:185] op_sel_hi:[1,0]
	v_cvt_pk_bf16_f32 v120, v124, v125
	v_cvt_pk_bf16_f32 v121, v126, v127
	v_cvt_pk_bf16_f32 v122, v190, v191
	v_cvt_pk_bf16_f32 v123, v194, v195
	v_pk_mul_f32 v[116:117], v[116:117], v[184:185] op_sel_hi:[1,0]
	v_pk_mul_f32 v[112:113], v[112:113], v[184:185] op_sel_hi:[1,0]
	v_max_f32_e32 v114, 0, v114
	v_max_f32_e32 v115, 0, v115
	global_store_dwordx4 v[212:213], v[120:123], off
	v_pk_mul_f32 v[118:119], v[118:119], v[184:185] op_sel_hi:[1,0]
	v_max_f32_e32 v116, 0, v116
	v_max_f32_e32 v112, 0, v112
	v_max_f32_e32 v117, 0, v117
	v_max_f32_e32 v113, 0, v113
	v_pk_mul_f32 v[122:123], v[114:115], v[114:115]
	v_pk_mul_f32 v[116:117], v[116:117], v[116:117]
	v_pk_mul_f32 v[120:121], v[112:113], v[112:113]
	v_max_f32_e32 v112, 0, v118
	v_max_f32_e32 v113, 0, v119
	v_pk_mul_f32 v[118:119], v[112:113], v[112:113]
	v_cvt_pk_bf16_f32 v112, v116, v117
	v_cvt_pk_bf16_f32 v113, v118, v119
	v_cvt_pk_bf16_f32 v114, v120, v121
	v_cvt_pk_bf16_f32 v115, v122, v123
	global_store_dwordx4 v[212:213], v[112:115], off offset:256
	s_nop 1
	v_mov_b32_e32 v112, v229
	v_pk_mul_f32 v[104:105], v[104:105], v[112:113] op_sel_hi:[1,0]
	v_pk_mul_f32 v[110:111], v[110:111], v[112:113] op_sel_hi:[1,0]
	v_pk_mul_f32 v[108:109], v[108:109], v[112:113] op_sel_hi:[1,0]
	v_pk_mul_f32 v[106:107], v[106:107], v[112:113] op_sel_hi:[1,0]
	v_max_f32_e32 v104, 0, v104
	v_max_f32_e32 v105, 0, v105
	v_lshlrev_b64 v[114:115], 13, v[172:173]
	v_max_f32_e32 v108, 0, v108
	v_max_f32_e32 v109, 0, v109
	v_pk_mul_f32 v[116:117], v[104:105], v[104:105]
	v_max_f32_e32 v104, 0, v110
	v_max_f32_e32 v106, 0, v106
	v_max_f32_e32 v105, 0, v111
	v_max_f32_e32 v107, 0, v107
	v_lshl_add_u64 v[114:115], s[96:97], 0, v[114:115]
	v_pk_mul_f32 v[108:109], v[108:109], v[108:109]
	v_pk_mul_f32 v[110:111], v[104:105], v[104:105]
	v_pk_mul_f32 v[118:119], v[106:107], v[106:107]
	v_pk_mul_f32 v[96:97], v[96:97], v[112:113] op_sel_hi:[1,0]
	v_lshl_add_u64 v[114:115], v[114:115], 0, v[148:149]
	v_cvt_pk_bf16_f32 v104, v108, v109
	v_cvt_pk_bf16_f32 v105, v110, v111
	v_cvt_pk_bf16_f32 v106, v116, v117
	v_cvt_pk_bf16_f32 v107, v118, v119
	v_pk_mul_f32 v[102:103], v[102:103], v[112:113] op_sel_hi:[1,0]
	v_max_f32_e32 v96, 0, v96
	v_max_f32_e32 v97, 0, v97
	global_store_dwordx4 v[114:115], v[104:107], off
	v_pk_mul_f32 v[100:101], v[100:101], v[112:113] op_sel_hi:[1,0]
	v_pk_mul_f32 v[98:99], v[98:99], v[112:113] op_sel_hi:[1,0]
	v_pk_mul_f32 v[104:105], v[96:97], v[96:97]
	v_max_f32_e32 v96, 0, v102
	v_max_f32_e32 v97, 0, v103
	v_max_f32_e32 v100, 0, v100
	v_max_f32_e32 v101, 0, v101
	v_pk_mul_f32 v[100:101], v[100:101], v[100:101]
	v_pk_mul_f32 v[108:109], v[96:97], v[96:97]
	v_cvt_pk_bf16_f32 v96, v100, v101
	s_waitcnt lgkmcnt(0)
	v_max_f32_e32 v98, 0, v98
	v_max_f32_e32 v99, 0, v99
	v_pk_mul_f32 v[110:111], v[98:99], v[98:99]
	v_cvt_pk_bf16_f32 v97, v108, v109
	v_cvt_pk_bf16_f32 v98, v104, v105
	v_cvt_pk_bf16_f32 v99, v110, v111
	global_store_dwordx4 v[114:115], v[96:99], off offset:256
	s_waitcnt lgkmcnt(0)
; __device__ __forceinline__ unsigned pk2(float lo, float hi) { const f32x2 v = (f32x2){lo, hi}; const bf16x2_t b = __builtin_convertvector(v, bf16x2_t); return __builtin_bit_cast(unsigned, b); }
;     __device__ __forceinline__ void operator()(const f32x4 (&acc)[2][2][4][2], const Unit& u, int wr, int wc, int fr, int fq, const float (&)[8]) const {
;     ...
;         const int col0 = u.pn * BM + wc * 32 + 8 * fq;
; #pragma unroll
;         for (int ai = 0; ai < 2; ++ai)
; #pragma unroll
;             for (int m = 0; m < 4; ++m) { const int row = row0 + ai * HALF + m * 16; const float rs = rsqrtf(ep[ai * 4 + m] * (1.0f / 1024.0f) + EPS);
;                 u16* rowp = O + (size_t)row * ldc + col0;
; #pragma unroll
;                 for (int bj = 0; bj < 2; ++bj) { f32x4 v0 = acc[ai][bj][m][0] * rs, v1 = acc[ai][bj][m][1] * rs;
;                     if (ACT == 1) {
; #pragma unroll
;                         for (int j = 0; j < 4; ++j) { const float a0 = fmaxf(v0[j], 0.f), a1 = fmaxf(v1[j], 0.f); v0[j] = a0 * a0; v1[j] = a1 * a1; } }
;                     u32x4 w; w.x = pk2(v0[0], v0[1]); w.y = pk2(v0[2], v0[3]); w.z = pk2(v1[0], v1[1]); w.w = pk2(v1[2], v1[3]);
;                     *(u32x4*)(rowp + bj * HALF) = w; } }
	s_nop 0
	s_nop 0
	s_nop 0
	s_nop 1
	v_lshlrev_b64 v[98:99], 13, v[168:169]
	v_lshl_add_u64 v[98:99], s[96:97], 0, v[98:99]
	v_lshl_add_u64 v[98:99], v[98:99], 0, v[148:149]
	v_mov_b32_e32 v100, v230
	v_pk_mul_f32 v[88:89], v[88:89], v[100:101] op_sel_hi:[1,0]
	v_pk_mul_f32 v[94:95], v[94:95], v[100:101] op_sel_hi:[1,0]
	v_pk_mul_f32 v[92:93], v[92:93], v[100:101] op_sel_hi:[1,0]
	v_pk_mul_f32 v[90:91], v[90:91], v[100:101] op_sel_hi:[1,0]
	v_max_f32_e32 v88, 0, v88
	v_max_f32_e32 v89, 0, v89
	v_max_f32_e32 v92, 0, v92
	v_max_f32_e32 v93, 0, v93
	v_pk_mul_f32 v[102:103], v[88:89], v[88:89]
	v_max_f32_e32 v88, 0, v94
	v_max_f32_e32 v90, 0, v90
	v_max_f32_e32 v89, 0, v95
	v_max_f32_e32 v91, 0, v91
	v_pk_mul_f32 v[92:93], v[92:93], v[92:93]
	v_pk_mul_f32 v[94:95], v[88:89], v[88:89]
	v_pk_mul_f32 v[104:105], v[90:91], v[90:91]
	v_pk_mul_f32 v[82:83], v[82:83], v[100:101] op_sel_hi:[1,0]
	v_cvt_pk_bf16_f32 v88, v92, v93
	v_cvt_pk_bf16_f32 v89, v94, v95
	v_cvt_pk_bf16_f32 v90, v102, v103
	v_cvt_pk_bf16_f32 v91, v104, v105
	v_pk_mul_f32 v[84:85], v[84:85], v[100:101] op_sel_hi:[1,0]
	v_pk_mul_f32 v[80:81], v[80:81], v[100:101] op_sel_hi:[1,0]
	v_max_f32_e32 v82, 0, v82
	v_max_f32_e32 v83, 0, v83
	global_store_dwordx4 v[98:99], v[88:91], off
	v_pk_mul_f32 v[86:87], v[86:87], v[100:101] op_sel_hi:[1,0]
	v_max_f32_e32 v84, 0, v84
	v_max_f32_e32 v80, 0, v80
	v_max_f32_e32 v85, 0, v85
	v_max_f32_e32 v81, 0, v81
	v_pk_mul_f32 v[90:91], v[82:83], v[82:83]
	v_pk_mul_f32 v[84:85], v[84:85], v[84:85]
	v_pk_mul_f32 v[88:89], v[80:81], v[80:81]
	v_max_f32_e32 v80, 0, v86
	v_max_f32_e32 v81, 0, v87
	v_pk_mul_f32 v[86:87], v[80:81], v[80:81]
	v_cvt_pk_bf16_f32 v80, v84, v85
	v_cvt_pk_bf16_f32 v81, v86, v87
	v_cvt_pk_bf16_f32 v82, v88, v89
	v_cvt_pk_bf16_f32 v83, v90, v91
	global_store_dwordx4 v[98:99], v[80:83], off offset:256
	s_nop 1
	v_mov_b32_e32 v80, v231
	v_pk_mul_f32 v[72:73], v[72:73], v[80:81] op_sel_hi:[1,0]
	v_pk_mul_f32 v[78:79], v[78:79], v[80:81] op_sel_hi:[1,0]
	v_pk_mul_f32 v[76:77], v[76:77], v[80:81] op_sel_hi:[1,0]
	v_pk_mul_f32 v[74:75], v[74:75], v[80:81] op_sel_hi:[1,0]
	v_max_f32_e32 v72, 0, v72
	v_max_f32_e32 v73, 0, v73
	v_lshlrev_b64 v[82:83], 13, v[164:165]
	v_max_f32_e32 v76, 0, v76
	v_max_f32_e32 v77, 0, v77
	v_pk_mul_f32 v[84:85], v[72:73], v[72:73]
	v_max_f32_e32 v72, 0, v78
	v_max_f32_e32 v74, 0, v74
	v_max_f32_e32 v73, 0, v79
	v_max_f32_e32 v75, 0, v75
	v_lshl_add_u64 v[82:83], s[96:97], 0, v[82:83]
	v_pk_mul_f32 v[76:77], v[76:77], v[76:77]
	v_pk_mul_f32 v[78:79], v[72:73], v[72:73]
	v_pk_mul_f32 v[86:87], v[74:75], v[74:75]
	v_pk_mul_f32 v[64:65], v[64:65], v[80:81] op_sel_hi:[1,0]
	v_lshl_add_u64 v[82:83], v[82:83], 0, v[148:149]
	v_cvt_pk_bf16_f32 v72, v76, v77
	v_cvt_pk_bf16_f32 v73, v78, v79
	v_cvt_pk_bf16_f32 v74, v84, v85
	v_cvt_pk_bf16_f32 v75, v86, v87
	v_pk_mul_f32 v[70:71], v[70:71], v[80:81] op_sel_hi:[1,0]
	v_max_f32_e32 v64, 0, v64
	v_max_f32_e32 v65, 0, v65
	global_store_dwordx4 v[82:83], v[72:75], off
	v_pk_mul_f32 v[68:69], v[68:69], v[80:81] op_sel_hi:[1,0]
	v_pk_mul_f32 v[66:67], v[66:67], v[80:81] op_sel_hi:[1,0]
	v_pk_mul_f32 v[72:73], v[64:65], v[64:65]
	v_max_f32_e32 v64, 0, v70
	v_max_f32_e32 v65, 0, v71
	v_max_f32_e32 v68, 0, v68
	v_max_f32_e32 v69, 0, v69
	v_pk_mul_f32 v[68:69], v[68:69], v[68:69]
	v_pk_mul_f32 v[76:77], v[64:65], v[64:65]
	v_cvt_pk_bf16_f32 v64, v68, v69
	s_waitcnt lgkmcnt(0)
	v_max_f32_e32 v66, 0, v66
	v_max_f32_e32 v67, 0, v67
	v_pk_mul_f32 v[78:79], v[66:67], v[66:67]
	v_cvt_pk_bf16_f32 v65, v76, v77
	v_cvt_pk_bf16_f32 v66, v72, v73
	v_cvt_pk_bf16_f32 v67, v78, v79
	global_store_dwordx4 v[82:83], v[64:67], off offset:256
	s_waitcnt lgkmcnt(0)
	s_nop 0
	s_nop 0
	s_nop 0
	s_nop 1
	v_lshlrev_b64 v[66:67], 13, v[162:163]
	v_lshl_add_u64 v[66:67], s[96:97], 0, v[66:67]
	v_lshl_add_u64 v[66:67], v[66:67], 0, v[148:149]
	v_mov_b32_e32 v68, v232
	v_pk_mul_f32 v[56:57], v[56:57], v[68:69] op_sel_hi:[1,0]
	v_pk_mul_f32 v[62:63], v[62:63], v[68:69] op_sel_hi:[1,0]
	v_pk_mul_f32 v[60:61], v[60:61], v[68:69] op_sel_hi:[1,0]
	v_pk_mul_f32 v[58:59], v[58:59], v[68:69] op_sel_hi:[1,0]
	v_max_f32_e32 v56, 0, v56
	v_max_f32_e32 v57, 0, v57
	v_max_f32_e32 v60, 0, v60
	v_max_f32_e32 v61, 0, v61
	v_pk_mul_f32 v[70:71], v[56:57], v[56:57]
	v_max_f32_e32 v56, 0, v62
	v_max_f32_e32 v58, 0, v58
	v_max_f32_e32 v57, 0, v63
	v_max_f32_e32 v59, 0, v59
	v_pk_mul_f32 v[60:61], v[60:61], v[60:61]
	v_pk_mul_f32 v[62:63], v[56:57], v[56:57]
	v_pk_mul_f32 v[72:73], v[58:59], v[58:59]
	v_pk_mul_f32 v[50:51], v[50:51], v[68:69] op_sel_hi:[1,0]
	v_cvt_pk_bf16_f32 v56, v60, v61
	v_cvt_pk_bf16_f32 v57, v62, v63
	v_cvt_pk_bf16_f32 v58, v70, v71
	v_cvt_pk_bf16_f32 v59, v72, v73
	v_pk_mul_f32 v[52:53], v[52:53], v[68:69] op_sel_hi:[1,0]
	v_pk_mul_f32 v[48:49], v[48:49], v[68:69] op_sel_hi:[1,0]
	v_max_f32_e32 v50, 0, v50
	v_max_f32_e32 v51, 0, v51
	global_store_dwordx4 v[66:67], v[56:59], off
	v_pk_mul_f32 v[54:55], v[54:55], v[68:69] op_sel_hi:[1,0]
	v_max_f32_e32 v52, 0, v52
	v_max_f32_e32 v48, 0, v48
	v_max_f32_e32 v53, 0, v53
	v_max_f32_e32 v49, 0, v49
	v_pk_mul_f32 v[58:59], v[50:51], v[50:51]
	v_pk_mul_f32 v[52:53], v[52:53], v[52:53]
	v_pk_mul_f32 v[56:57], v[48:49], v[48:49]
	v_max_f32_e32 v48, 0, v54
	v_max_f32_e32 v49, 0, v55
	v_pk_mul_f32 v[54:55], v[48:49], v[48:49]
	v_cvt_pk_bf16_f32 v48, v52, v53
	v_cvt_pk_bf16_f32 v49, v54, v55
	v_cvt_pk_bf16_f32 v50, v56, v57
	v_cvt_pk_bf16_f32 v51, v58, v59
	global_store_dwordx4 v[66:67], v[48:51], off offset:256
	s_nop 1
	v_mov_b32_e32 v48, v233
	v_pk_mul_f32 v[40:41], v[40:41], v[48:49] op_sel_hi:[1,0]
	v_pk_mul_f32 v[46:47], v[46:47], v[48:49] op_sel_hi:[1,0]
	v_pk_mul_f32 v[44:45], v[44:45], v[48:49] op_sel_hi:[1,0]
	v_pk_mul_f32 v[42:43], v[42:43], v[48:49] op_sel_hi:[1,0]
	v_max_f32_e32 v40, 0, v40
	v_max_f32_e32 v41, 0, v41
	v_lshlrev_b64 v[50:51], 13, v[156:157]
	v_max_f32_e32 v44, 0, v44
	v_max_f32_e32 v45, 0, v45
	v_pk_mul_f32 v[52:53], v[40:41], v[40:41]
	v_max_f32_e32 v40, 0, v46
	v_max_f32_e32 v42, 0, v42
	v_max_f32_e32 v41, 0, v47
	v_max_f32_e32 v43, 0, v43
	v_lshl_add_u64 v[50:51], s[96:97], 0, v[50:51]
	v_pk_mul_f32 v[44:45], v[44:45], v[44:45]
	v_pk_mul_f32 v[46:47], v[40:41], v[40:41]
	v_pk_mul_f32 v[54:55], v[42:43], v[42:43]
	v_pk_mul_f32 v[32:33], v[32:33], v[48:49] op_sel_hi:[1,0]
	v_lshl_add_u64 v[50:51], v[50:51], 0, v[148:149]
	v_cvt_pk_bf16_f32 v40, v44, v45
	v_cvt_pk_bf16_f32 v41, v46, v47
	v_cvt_pk_bf16_f32 v42, v52, v53
	v_cvt_pk_bf16_f32 v43, v54, v55
	v_pk_mul_f32 v[38:39], v[38:39], v[48:49] op_sel_hi:[1,0]
	v_max_f32_e32 v32, 0, v32
	v_max_f32_e32 v33, 0, v33
	global_store_dwordx4 v[50:51], v[40:43], off
	v_pk_mul_f32 v[36:37], v[36:37], v[48:49] op_sel_hi:[1,0]
	v_pk_mul_f32 v[34:35], v[34:35], v[48:49] op_sel_hi:[1,0]
	v_pk_mul_f32 v[40:41], v[32:33], v[32:33]
	v_max_f32_e32 v32, 0, v38
	v_max_f32_e32 v33, 0, v39
	v_max_f32_e32 v36, 0, v36
	v_max_f32_e32 v37, 0, v37
	v_pk_mul_f32 v[36:37], v[36:37], v[36:37]
	v_pk_mul_f32 v[44:45], v[32:33], v[32:33]
	v_cvt_pk_bf16_f32 v32, v36, v37
	s_waitcnt lgkmcnt(0)
; __device__ __forceinline__ unsigned pk2(float lo, float hi) { const f32x2 v = (f32x2){lo, hi}; const bf16x2_t b = __builtin_convertvector(v, bf16x2_t); return __builtin_bit_cast(unsigned, b); }
; #define PG8_WAIT_V(n) asm volatile("s_waitcnt vmcnt(" #n ")" ::: "memory")
; #define PG8_BAR __builtin_amdgcn_s_barrier()
;     __device__ __forceinline__ void operator()(const f32x4 (&acc)[2][2][4][2], const Unit& u, int wr, int wc, int fr, int fq, const float (&)[8]) const {
;     ...
;             for (int m = 0; m < 4; ++m) { const int row = row0 + ai * HALF + m * 16; const float rs = rsqrtf(ep[ai * 4 + m] * (1.0f / 1024.0f) + EPS);
;                 u16* rowp = O + (size_t)row * ldc + col0;
; #pragma unroll
;                 for (int bj = 0; bj < 2; ++bj) { f32x4 v0 = acc[ai][bj][m][0] * rs, v1 = acc[ai][bj][m][1] * rs;
;                     if (ACT == 1) {
; #pragma unroll
;                         for (int j = 0; j < 4; ++j) { const float a0 = fmaxf(v0[j], 0.f), a1 = fmaxf(v1[j], 0.f); v0[j] = a0 * a0; v1[j] = a1 * a1; } }
;                     u32x4 w; w.x = pk2(v0[0], v0[1]); w.y = pk2(v0[2], v0[3]); w.z = pk2(v1[0], v1[1]); w.w = pk2(v1[2], v1[3]);
;                     *(u32x4*)(rowp + bj * HALF) = w; } }
; template <class Epi>
; __device__ __forceinline__ void gemm_phase(LAS unsigned char* lds, const Gemm g, const StaticOrder& S, const Epi& E) {
;     ...
;         E(acc, cur, wr, wc, fr, fq, epre);
;         if (!has_next) break;
; #pragma unroll
;         for (int a = 0; a < 2; ++a)
; #pragma unroll
;             for (int b = 0; b < 2; ++b)
; #pragma unroll
;                 for (int m = 0; m < 4; ++m)
; #pragma unroll
;                     for (int n = 0; n < 2; ++n) acc[a][b][m][n] = (f32x4){0.f, 0.f, 0.f, 0.f};
;         cur = nxt; cA = nA; cB = nB; ++ui;
;     }
;     PG8_WAIT_V(0);
;     if (wr == 0) PG8_BAR;
;     PG8_BAR;
	v_max_f32_e32 v34, 0, v34
	v_max_f32_e32 v35, 0, v35
	v_pk_mul_f32 v[46:47], v[34:35], v[34:35]
	v_cvt_pk_bf16_f32 v33, v44, v45
	v_cvt_pk_bf16_f32 v34, v40, v41
	v_cvt_pk_bf16_f32 v35, v46, v47
	global_store_dwordx4 v[50:51], v[32:35], off offset:256
	s_waitcnt lgkmcnt(0)
	s_nop 0
	s_nop 0
	s_nop 0
	s_nop 1
	v_lshlrev_b64 v[34:35], 13, v[150:151]
	v_lshl_add_u64 v[34:35], s[96:97], 0, v[34:35]
	v_lshl_add_u64 v[34:35], v[34:35], 0, v[148:149]
	v_mov_b32_e32 v36, v234
	v_pk_mul_f32 v[24:25], v[24:25], v[36:37] op_sel_hi:[1,0]
	v_pk_mul_f32 v[30:31], v[30:31], v[36:37] op_sel_hi:[1,0]
	v_pk_mul_f32 v[28:29], v[28:29], v[36:37] op_sel_hi:[1,0]
	v_pk_mul_f32 v[26:27], v[26:27], v[36:37] op_sel_hi:[1,0]
	v_max_f32_e32 v24, 0, v24
	v_max_f32_e32 v25, 0, v25
	v_max_f32_e32 v28, 0, v28
	v_max_f32_e32 v29, 0, v29
	v_pk_mul_f32 v[38:39], v[24:25], v[24:25]
	v_max_f32_e32 v24, 0, v30
	v_max_f32_e32 v26, 0, v26
	v_max_f32_e32 v25, 0, v31
	v_max_f32_e32 v27, 0, v27
	v_pk_mul_f32 v[28:29], v[28:29], v[28:29]
	v_pk_mul_f32 v[30:31], v[24:25], v[24:25]
	v_pk_mul_f32 v[40:41], v[26:27], v[26:27]
	v_pk_mul_f32 v[18:19], v[18:19], v[36:37] op_sel_hi:[1,0]
	v_cvt_pk_bf16_f32 v24, v28, v29
	v_cvt_pk_bf16_f32 v25, v30, v31
	v_cvt_pk_bf16_f32 v26, v38, v39
	v_cvt_pk_bf16_f32 v27, v40, v41
	v_pk_mul_f32 v[20:21], v[20:21], v[36:37] op_sel_hi:[1,0]
	v_pk_mul_f32 v[16:17], v[16:17], v[36:37] op_sel_hi:[1,0]
	v_max_f32_e32 v18, 0, v18
	v_max_f32_e32 v19, 0, v19
	global_store_dwordx4 v[34:35], v[24:27], off
	v_pk_mul_f32 v[22:23], v[22:23], v[36:37] op_sel_hi:[1,0]
	v_max_f32_e32 v20, 0, v20
	v_max_f32_e32 v16, 0, v16
	v_max_f32_e32 v21, 0, v21
	v_max_f32_e32 v17, 0, v17
	v_pk_mul_f32 v[26:27], v[18:19], v[18:19]
	v_pk_mul_f32 v[20:21], v[20:21], v[20:21]
	v_pk_mul_f32 v[24:25], v[16:17], v[16:17]
	v_max_f32_e32 v16, 0, v22
	v_max_f32_e32 v17, 0, v23
	v_pk_mul_f32 v[22:23], v[16:17], v[16:17]
	v_cvt_pk_bf16_f32 v16, v20, v21
	v_cvt_pk_bf16_f32 v17, v22, v23
	v_cvt_pk_bf16_f32 v18, v24, v25
	v_cvt_pk_bf16_f32 v19, v26, v27
	global_store_dwordx4 v[34:35], v[16:19], off offset:256
	s_nop 1
	v_mov_b32_e32 v16, v235
	v_pk_mul_f32 v[8:9], v[8:9], v[16:17] op_sel_hi:[1,0]
	v_pk_mul_f32 v[14:15], v[14:15], v[16:17] op_sel_hi:[1,0]
	v_pk_mul_f32 v[12:13], v[12:13], v[16:17] op_sel_hi:[1,0]
	v_pk_mul_f32 v[10:11], v[10:11], v[16:17] op_sel_hi:[1,0]
	v_max_f32_e32 v8, 0, v8
	v_max_f32_e32 v9, 0, v9
	v_lshlrev_b64 v[18:19], 13, v[146:147]
	v_max_f32_e32 v12, 0, v12
	v_max_f32_e32 v13, 0, v13
	v_pk_mul_f32 v[20:21], v[8:9], v[8:9]
	v_max_f32_e32 v8, 0, v14
	v_max_f32_e32 v10, 0, v10
	v_max_f32_e32 v9, 0, v15
	v_max_f32_e32 v11, 0, v11
	v_lshl_add_u64 v[18:19], s[96:97], 0, v[18:19]
	v_pk_mul_f32 v[12:13], v[12:13], v[12:13]
	v_pk_mul_f32 v[14:15], v[8:9], v[8:9]
	v_pk_mul_f32 v[22:23], v[10:11], v[10:11]
	v_pk_mul_f32 v[0:1], v[0:1], v[16:17] op_sel_hi:[1,0]
	v_lshl_add_u64 v[18:19], v[18:19], 0, v[148:149]
	v_cvt_pk_bf16_f32 v8, v12, v13
	v_cvt_pk_bf16_f32 v9, v14, v15
	v_cvt_pk_bf16_f32 v10, v20, v21
	v_cvt_pk_bf16_f32 v11, v22, v23
	v_pk_mul_f32 v[6:7], v[6:7], v[16:17] op_sel_hi:[1,0]
	v_pk_mul_f32 v[4:5], v[4:5], v[16:17] op_sel_hi:[1,0]
	v_pk_mul_f32 v[2:3], v[2:3], v[16:17] op_sel_hi:[1,0]
	v_max_f32_e32 v0, 0, v0
	v_max_f32_e32 v1, 0, v1
	global_store_dwordx4 v[18:19], v[8:11], off
	v_max_f32_e32 v4, 0, v4
	v_max_f32_e32 v5, 0, v5
	v_pk_mul_f32 v[8:9], v[0:1], v[0:1]
	v_max_f32_e32 v0, 0, v6
	v_max_f32_e32 v2, 0, v2
	v_max_f32_e32 v1, 0, v7
	v_max_f32_e32 v3, 0, v3
	v_pk_mul_f32 v[4:5], v[4:5], v[4:5]
	v_pk_mul_f32 v[6:7], v[0:1], v[0:1]
	v_pk_mul_f32 v[10:11], v[2:3], v[2:3]
	v_cvt_pk_bf16_f32 v0, v4, v5
	v_cvt_pk_bf16_f32 v1, v6, v7
	v_cvt_pk_bf16_f32 v2, v8, v9
	v_cvt_pk_bf16_f32 v3, v10, v11
	s_and_b64 vcc, exec, s[0:1]
	global_store_dwordx4 v[18:19], v[0:3], off offset:256
	s_cbranch_vccz .LBB0_763
	s_waitcnt vmcnt(0)
	s_cmpk_gt_u32 s9, 0xff
	s_cbranch_scc1 .LBB0_774
	s_barrier

; template <class Epi>
; __device__ __forceinline__ void gemm_phase(LAS unsigned char* lds, const Gemm g, const StaticOrder& S, const Epi& E) {
;     ...
;         E(acc, cur, wr, wc, fr, fq, epre);
;         if (!has_next) break;
; #pragma unroll
;         for (int a = 0; a < 2; ++a)
; #pragma unroll
;             for (int b = 0; b < 2; ++b)
; #pragma unroll
;                 for (int m = 0; m < 4; ++m)
; #pragma unroll
;                     for (int n = 0; n < 2; ++n) acc[a][b][m][n] = (f32x4){0.f, 0.f, 0.f, 0.f};
;         cur = nxt; cA = nA; cB = nB; ++ui;
.LBB0_836:
	s_or_b64 exec, exec, s[22:23]
	s_and_b64 vcc, exec, s[2:3]
	s_mov_b32 s6, s14
	s_mov_b32 s8, s16
	s_mov_b64 s[24:25], s[20:21]
	s_mov_b64 s[22:23], s[18:19]
	s_cbranch_vccnz .LBB0_861
	s_branch .LBB0_837

; #define PG8_STAGE(bufoff, gbase, voff) do { _Pragma("unroll") for (int _i = 0; _i < 2; ++_i) \
;         __builtin_amdgcn_global_load_lds((const unsigned*)((const char*)(gbase) + (voff)[_i]), (LAS unsigned*)(lds + (bufoff) + ldsw + _i * 8192), 16, 0, 0); } while (0)
; #define PG8_LDA(dst, b, h) do { _Pragma("unroll") for (int m = 0; m < 4; ++m) _Pragma("unroll") for (int k = 0; k < 2; ++k) dst[m][k] = *(const LAS bf16x8*)(lds + PG8_SA(b, h) + aoff + m * 2048 + k * 1024); } while (0)
; #define PG8_LDB(dst, b, h) do { _Pragma("unroll") for (int n = 0; n < 2; ++n) _Pragma("unroll") for (int k = 0; k < 2; ++k) dst[n][k] = *(const LAS bf16x8*)(lds + PG8_SB(b, h) + boff + n * 2048 + k * 1024); } while (0)
; #define PG8_WAIT_V(n) asm volatile("s_waitcnt vmcnt(" #n ")" ::: "memory")
; #define PG8_WAIT_L(n) asm volatile("s_waitcnt lgkmcnt(" #n ")" ::: "memory")
; #define PG8_BAR __builtin_amdgcn_s_barrier()
; #define PG8_SCHED __builtin_amdgcn_sched_barrier(0)
; template <class Epi>
; __device__ __forceinline__ void gemm_phase(LAS unsigned char* lds, const Gemm g, const StaticOrder& S, const Epi& E) {
;     ...
;         const char* nA = has_next ? (const char*)g.A + (size_t)nxt.pm * tstepA : cA; const char* nB = has_next ? (const char*)g.Bt + (size_t)nxt.pn * tstepB : cB;
;         for (int t = 0; t < nt; t += 2) {
;             const bool last = (t == nt - 2);
;             const char* a1 = cA + (size_t)(t + 1) * kstep;
;             const char* a2 = last ? nA : cA + (size_t)(t + 2) * kstep; const char* b2 = last ? nB : cB + (size_t)(t + 2) * kstep;
;             const char* a3 = a2 + kstep; const char* b3 = b2 + kstep;
;             if (last) E.pre(cur, wr, fr, epre);
;             PG8_LDB(B0, 0, 0); PG8_SCHED; PG8_LDA(At, 0, 0); PG8_STAGE(PG8_SA(1, 1), a1 + hstepA, voffA);
;             PG8_WAIT_L(8); PG8_BAR; PG8_WAIT_L(0); PG8_MMA(0, 0, At, B0); PG8_BAR; PG8_SCHED;
;             PG8_LDB(B1, 0, 1); PG8_STAGE(PG8_SB(0, 0), b2, voffB);
;             PG8_BAR; PG8_WAIT_L(0); PG8_MMA(0, 1, At, B1); PG8_BAR;
;             PG8_LDA(At, 0, 1); PG8_STAGE(PG8_SA(0, 0), a2, voffA);
;             PG8_BAR; PG8_WAIT_L(0); PG8_MMA(1, 0, At, B0); PG8_BAR; PG8_SCHED;
;             PG8_STAGE(PG8_SB(0, 1), b2 + hstepB, voffB);
;             PG8_WAIT_V(6); PG8_BAR; PG8_MMA(1, 1, At, B1); PG8_BAR;
.Lkp3_843:
	s_ashr_i32 s17, s16, 31
	v_cmp_lt_i64_e32 vcc, s[18:19], v[166:167]
	s_lshl_b64 s[18:19], s[16:17], 21
	s_add_u32 s18, s96, s18
	s_addc_u32 s19, s97, s19
	s_and_b64 s[20:21], vcc, exec
	s_cselect_b32 s17, s19, s23
	s_cselect_b32 s44, s18, s22
	s_ashr_i32 s15, s14, 31
	s_lshl_b64 s[20:21], s[14:15], 21
	s_add_u32 s20, s29, s20
	s_addc_u32 s21, s30, s21
	s_and_b64 s[26:27], vcc, exec
	s_cselect_b32 s15, s21, s25
	s_cselect_b32 s45, s20, s24
	s_add_u32 s22, s22, 0x100080
	s_addc_u32 s23, s23, 0
	s_add_u32 s46, s24, 0x100
	s_addc_u32 s47, s25, 0
	s_mov_b32 s48, -2
	s_waitcnt lgkmcnt(0)
	ds_read_b128 v[128:131], v191
	ds_read_b128 v[132:135], v191 offset:1024
	ds_read_b128 v[136:139], v191 offset:2048
	ds_read_b128 v[140:143], v191 offset:3072
	s_add_u32 s24, s22, 0xfff00080
	s_addc_u32 s25, s23, -1
	s_cmp_eq_u32 s48, 60
	s_cselect_b32 s27, s17, s25
	s_cselect_b32 s26, s44, s24
	s_cselect_b32 s25, s15, s47
	s_cselect_b32 s24, s45, s46
	v_lshl_add_u64 v[186:187], s[22:23], 0, v[162:163]
	s_add_i32 m0, s7, 0xc000
	ds_read_b128 v[144:147], v192
	ds_read_b128 v[148:151], v192 offset:1024
	ds_read_b128 v[170:173], v192 offset:2048
	ds_read_b128 v[174:177], v192 offset:3072
	ds_read_b128 v[178:181], v192 offset:4096
	ds_read_b128 v[182:185], v192 offset:5120
	ds_read_b128 v[196:199], v192 offset:6144
	ds_read_b128 v[200:203], v192 offset:7168
	global_load_lds_dwordx4 v[186:187], off
	v_lshl_add_u64 v[186:187], s[22:23], 0, v[164:165]
	s_add_i32 m0, s7, 0xe000
	s_nop 0
	global_load_lds_dwordx4 v[186:187], off
	s_waitcnt lgkmcnt(8)
	s_barrier
	s_waitcnt lgkmcnt(0)
	s_setprio 2
	s_waitcnt lgkmcnt(0)
	v_mfma_f32_16x16x32_bf16 v[124:127], v[128:131], v[144:147], 0
	v_mfma_f32_16x16x32_bf16 v[120:123], v[136:139], v[144:147], 0
	v_mfma_f32_16x16x32_bf16 v[108:111], v[128:131], v[170:173], 0
	v_mfma_f32_16x16x32_bf16 v[104:107], v[136:139], v[170:173], 0
	v_mfma_f32_16x16x32_bf16 v[92:95], v[128:131], v[178:181], 0
	v_mfma_f32_16x16x32_bf16 v[88:91], v[136:139], v[178:181], 0
	v_mfma_f32_16x16x32_bf16 v[76:79], v[128:131], v[196:199], 0
	v_mfma_f32_16x16x32_bf16 v[72:75], v[136:139], v[196:199], 0
	v_mfma_f32_16x16x32_bf16 v[124:127], v[132:135], v[148:151], v[124:127]
	v_mfma_f32_16x16x32_bf16 v[120:123], v[140:143], v[148:151], v[120:123]
	v_mfma_f32_16x16x32_bf16 v[108:111], v[132:135], v[174:177], v[108:111]
	v_mfma_f32_16x16x32_bf16 v[104:107], v[140:143], v[174:177], v[104:107]
	v_mfma_f32_16x16x32_bf16 v[92:95], v[132:135], v[182:185], v[92:95]
	v_mfma_f32_16x16x32_bf16 v[88:91], v[140:143], v[182:185], v[88:91]
	v_mfma_f32_16x16x32_bf16 v[76:79], v[132:135], v[200:203], v[76:79]
	v_mfma_f32_16x16x32_bf16 v[72:75], v[140:143], v[200:203], v[72:75]
	s_setprio 1
	s_barrier
	s_add_i32 s49, s42, s31
	v_lshl_add_u64 v[186:187], s[24:25], 0, v[156:157]
	s_mov_b32 m0, s49
	ds_read_b128 v[204:207], v193
	ds_read_b128 v[208:211], v193 offset:1024
	ds_read_b128 v[212:215], v193 offset:2048
	ds_read_b128 v[216:219], v193 offset:3072
	global_load_lds_dwordx4 v[186:187], off
	v_lshl_add_u64 v[220:221], s[24:25], 0, v[160:161]
	s_add_i32 m0, s49, 0x2000
	s_nop 0
	global_load_lds_dwordx4 v[220:221], off
	s_barrier
	s_waitcnt lgkmcnt(0)
	s_setprio 2
	s_waitcnt lgkmcnt(0)
	v_mfma_f32_16x16x32_bf16 v[116:119], v[204:207], v[144:147], 0
	v_mfma_f32_16x16x32_bf16 v[112:115], v[212:215], v[144:147], 0
	v_mfma_f32_16x16x32_bf16 v[100:103], v[204:207], v[170:173], 0
	v_mfma_f32_16x16x32_bf16 v[96:99], v[212:215], v[170:173], 0
	v_mfma_f32_16x16x32_bf16 v[84:87], v[204:207], v[178:181], 0
	v_mfma_f32_16x16x32_bf16 v[80:83], v[212:215], v[178:181], 0
	v_mfma_f32_16x16x32_bf16 v[68:71], v[204:207], v[196:199], 0
	v_mfma_f32_16x16x32_bf16 v[64:67], v[212:215], v[196:199], 0
	v_mfma_f32_16x16x32_bf16 v[116:119], v[208:211], v[148:151], v[116:119]
	v_mfma_f32_16x16x32_bf16 v[112:115], v[216:219], v[148:151], v[112:115]
	v_mfma_f32_16x16x32_bf16 v[100:103], v[208:211], v[174:177], v[100:103]
	v_mfma_f32_16x16x32_bf16 v[96:99], v[216:219], v[174:177], v[96:99]
	v_mfma_f32_16x16x32_bf16 v[84:87], v[208:211], v[182:185], v[84:87]
	v_mfma_f32_16x16x32_bf16 v[80:83], v[216:219], v[182:185], v[80:83]
	v_mfma_f32_16x16x32_bf16 v[68:71], v[208:211], v[200:203], v[68:71]
	v_mfma_f32_16x16x32_bf16 v[64:67], v[216:219], v[200:203], v[64:67]
	s_setprio 1
	s_mov_b32 m0, s7
	v_lshl_add_u64 v[222:223], s[26:27], 0, v[154:155]
	s_barrier
	ds_read_b128 v[144:147], v192 offset:16384
	ds_read_b128 v[148:151], v192 offset:17408
	ds_read_b128 v[170:173], v192 offset:18432
	ds_read_b128 v[174:177], v192 offset:19456
	ds_read_b128 v[178:181], v192 offset:20480
	ds_read_b128 v[182:185], v192 offset:21504
	ds_read_b128 v[196:199], v192 offset:22528
	ds_read_b128 v[200:203], v192 offset:23552
	global_load_lds_dwordx4 v[222:223], off
	v_lshl_add_u64 v[224:225], s[26:27], 0, v[158:159]
	s_mov_b32 m0, s34
	s_nop 0
	global_load_lds_dwordx4 v[224:225], off
	s_barrier
	s_waitcnt lgkmcnt(0)
	s_setprio 2
	s_waitcnt lgkmcnt(0)
	v_mfma_f32_16x16x32_bf16 v[60:63], v[128:131], v[144:147], 0
	v_mfma_f32_16x16x32_bf16 v[56:59], v[136:139], v[144:147], 0
	v_mfma_f32_16x16x32_bf16 v[44:47], v[128:131], v[170:173], 0
	v_mfma_f32_16x16x32_bf16 v[40:43], v[136:139], v[170:173], 0
	v_mfma_f32_16x16x32_bf16 v[28:31], v[128:131], v[178:181], 0
	v_mfma_f32_16x16x32_bf16 v[24:27], v[136:139], v[178:181], 0
	v_mfma_f32_16x16x32_bf16 v[12:15], v[128:131], v[196:199], 0
	v_mfma_f32_16x16x32_bf16 v[8:11], v[136:139], v[196:199], 0
	v_mfma_f32_16x16x32_bf16 v[60:63], v[132:135], v[148:151], v[60:63]
	v_mfma_f32_16x16x32_bf16 v[56:59], v[140:143], v[148:151], v[56:59]
	v_mfma_f32_16x16x32_bf16 v[44:47], v[132:135], v[174:177], v[44:47]
	v_mfma_f32_16x16x32_bf16 v[40:43], v[140:143], v[174:177], v[40:43]
	v_mfma_f32_16x16x32_bf16 v[28:31], v[132:135], v[182:185], v[28:31]
	v_mfma_f32_16x16x32_bf16 v[24:27], v[140:143], v[182:185], v[24:27]
	v_mfma_f32_16x16x32_bf16 v[12:15], v[132:135], v[200:203], v[12:15]
	v_mfma_f32_16x16x32_bf16 v[8:11], v[140:143], v[200:203], v[8:11]
	s_setprio 1
	s_barrier
; #define PG8_STAGE(bufoff, gbase, voff) do { _Pragma("unroll") for (int _i = 0; _i < 2; ++_i) \
;         __builtin_amdgcn_global_load_lds((const unsigned*)((const char*)(gbase) + (voff)[_i]), (LAS unsigned*)(lds + (bufoff) + ldsw + _i * 8192), 16, 0, 0); } while (0)
; #define PG8_LDA(dst, b, h) do { _Pragma("unroll") for (int m = 0; m < 4; ++m) _Pragma("unroll") for (int k = 0; k < 2; ++k) dst[m][k] = *(const LAS bf16x8*)(lds + PG8_SA(b, h) + aoff + m * 2048 + k * 1024); } while (0)
; #define PG8_LDB(dst, b, h) do { _Pragma("unroll") for (int n = 0; n < 2; ++n) _Pragma("unroll") for (int k = 0; k < 2; ++k) dst[n][k] = *(const LAS bf16x8*)(lds + PG8_SB(b, h) + boff + n * 2048 + k * 1024); } while (0)
; #define PG8_MMA(ai, bj, At, Bt) do { __builtin_amdgcn_s_setprio(1); _Pragma("unroll") for (int m = 0; m < 4; ++m) _Pragma("unroll") for (int n = 0; n < 2; ++n) _Pragma("unroll") for (int k = 0; k < 2; ++k) \
;         acc[ai][bj][m][n] = __builtin_amdgcn_mfma_f32_16x16x32_bf16(Bt[n][k], At[m][k], acc[ai][bj][m][n], 0, 0, 0); __builtin_amdgcn_s_setprio(0); } while (0)
; #define PG8_WAIT_V(n) asm volatile("s_waitcnt vmcnt(" #n ")" ::: "memory")
; #define PG8_WAIT_L(n) asm volatile("s_waitcnt lgkmcnt(" #n ")" ::: "memory")
; #define PG8_BAR __builtin_amdgcn_s_barrier()
; #define PG8_SCHED __builtin_amdgcn_sched_barrier(0)
; template <class Epi>
; __device__ __forceinline__ void gemm_phase(LAS unsigned char* lds, const Gemm g, const StaticOrder& S, const Epi& E) {
;     ...
;             PG8_STAGE(PG8_SB(0, 1), b2 + hstepB, voffB);
;             PG8_WAIT_V(6); PG8_BAR; PG8_MMA(1, 1, At, B1); PG8_BAR;
;             PG8_LDB(B0, 1, 0); PG8_SCHED; PG8_LDA(At, 1, 0); PG8_STAGE(PG8_SA(0, 1), a2 + hstepA, voffA);
;             PG8_WAIT_L(8); PG8_BAR; PG8_WAIT_L(0); PG8_MMA(0, 0, At, B0); PG8_BAR; PG8_SCHED;
;             PG8_LDB(B1, 1, 1); PG8_STAGE(PG8_SB(1, 0), b3, voffB);
;             PG8_BAR; PG8_WAIT_L(0); PG8_MMA(0, 1, At, B1); PG8_BAR;
;             PG8_LDA(At, 1, 1); PG8_STAGE(PG8_SA(1, 0), a3, voffA);
	s_add_u32 s50, s24, 0x100000
	s_addc_u32 s51, s25, 0
	s_add_i32 s49, s43, s31
	v_lshl_add_u64 v[128:129], s[50:51], 0, v[156:157]
	s_mov_b32 m0, s49
	s_nop 0
	global_load_lds_dwordx4 v[128:129], off
	v_lshl_add_u64 v[128:129], s[50:51], 0, v[160:161]
	s_add_i32 m0, s49, 0x2000
	s_nop 0
	global_load_lds_dwordx4 v[128:129], off
	s_waitcnt vmcnt(6)
	s_barrier
	s_setprio 2
	v_mfma_f32_16x16x32_bf16 v[52:55], v[204:207], v[144:147], 0
	v_mfma_f32_16x16x32_bf16 v[48:51], v[212:215], v[144:147], 0
	v_mfma_f32_16x16x32_bf16 v[36:39], v[204:207], v[170:173], 0
	v_mfma_f32_16x16x32_bf16 v[32:35], v[212:215], v[170:173], 0
	v_mfma_f32_16x16x32_bf16 v[20:23], v[204:207], v[178:181], 0
	v_mfma_f32_16x16x32_bf16 v[16:19], v[212:215], v[178:181], 0
	v_mfma_f32_16x16x32_bf16 v[4:7], v[204:207], v[196:199], 0
	v_mfma_f32_16x16x32_bf16 v[0:3], v[212:215], v[196:199], 0
	v_mfma_f32_16x16x32_bf16 v[52:55], v[208:211], v[148:151], v[52:55]
	v_mfma_f32_16x16x32_bf16 v[48:51], v[216:219], v[148:151], v[48:51]
	v_mfma_f32_16x16x32_bf16 v[36:39], v[208:211], v[174:177], v[36:39]
	v_mfma_f32_16x16x32_bf16 v[32:35], v[216:219], v[174:177], v[32:35]
	v_mfma_f32_16x16x32_bf16 v[20:23], v[208:211], v[182:185], v[20:23]
	v_mfma_f32_16x16x32_bf16 v[16:19], v[216:219], v[182:185], v[16:19]
	v_mfma_f32_16x16x32_bf16 v[4:7], v[208:211], v[200:203], v[4:7]
	v_mfma_f32_16x16x32_bf16 v[0:3], v[216:219], v[200:203], v[0:3]
	s_setprio 1
	s_add_i32 s49, 0, 0x18000
	v_add_u32_e32 v140, s49, v189
	s_barrier
	ds_read_b128 v[128:131], v140
	ds_read_b128 v[132:135], v140 offset:1024
	ds_read_b128 v[136:139], v140 offset:2048
	ds_read_b128 v[140:143], v140 offset:3072
	s_add_u32 s26, s26, 0x100000
	s_addc_u32 s27, s27, 0
	s_mov_b32 m0, s35
	v_lshl_add_u64 v[204:205], s[26:27], 0, v[154:155]
	ds_read_b128 v[144:147], v192 offset:32768
	ds_read_b128 v[148:151], v192 offset:33792
	ds_read_b128 v[170:173], v192 offset:34816
	ds_read_b128 v[174:177], v192 offset:35840
	ds_read_b128 v[178:181], v192 offset:36864
	ds_read_b128 v[182:185], v192 offset:37888
	ds_read_b128 v[196:199], v192 offset:38912
	ds_read_b128 v[200:203], v192 offset:39936
	global_load_lds_dwordx4 v[204:205], off
	v_lshl_add_u64 v[204:205], s[26:27], 0, v[158:159]
	s_mov_b32 m0, s36
	s_nop 0
	global_load_lds_dwordx4 v[204:205], off
	s_waitcnt lgkmcnt(8)
	s_barrier
	s_waitcnt lgkmcnt(0)
	s_setprio 2
	s_waitcnt lgkmcnt(0)
	v_mfma_f32_16x16x32_bf16 v[124:127], v[128:131], v[144:147], v[124:127]
	v_mfma_f32_16x16x32_bf16 v[120:123], v[136:139], v[144:147], v[120:123]
	v_mfma_f32_16x16x32_bf16 v[108:111], v[128:131], v[170:173], v[108:111]
	v_mfma_f32_16x16x32_bf16 v[104:107], v[136:139], v[170:173], v[104:107]
	v_mfma_f32_16x16x32_bf16 v[92:95], v[128:131], v[178:181], v[92:95]
	v_mfma_f32_16x16x32_bf16 v[88:91], v[136:139], v[178:181], v[88:91]
	v_mfma_f32_16x16x32_bf16 v[76:79], v[128:131], v[196:199], v[76:79]
	v_mfma_f32_16x16x32_bf16 v[72:75], v[136:139], v[196:199], v[72:75]
	v_mfma_f32_16x16x32_bf16 v[124:127], v[132:135], v[148:151], v[124:127]
	v_mfma_f32_16x16x32_bf16 v[120:123], v[140:143], v[148:151], v[120:123]
	v_mfma_f32_16x16x32_bf16 v[108:111], v[132:135], v[174:177], v[108:111]
	v_mfma_f32_16x16x32_bf16 v[104:107], v[140:143], v[174:177], v[104:107]
	v_mfma_f32_16x16x32_bf16 v[92:95], v[132:135], v[182:185], v[92:95]
	v_mfma_f32_16x16x32_bf16 v[88:91], v[140:143], v[182:185], v[88:91]
	v_mfma_f32_16x16x32_bf16 v[76:79], v[132:135], v[200:203], v[76:79]
	v_mfma_f32_16x16x32_bf16 v[72:75], v[140:143], v[200:203], v[72:75]
	s_setprio 1
	s_barrier
	s_add_i32 s26, 0, 0x1c000
	s_add_i32 s27, s49, s31
	v_add_u32_e32 v195, s26, v189
	v_lshl_add_u64 v[186:187], v[186:187], 0, s[12:13]
	s_mov_b32 m0, s27
	ds_read_b128 v[204:207], v195
	ds_read_b128 v[208:211], v195 offset:1024
	ds_read_b128 v[212:215], v195 offset:2048
	ds_read_b128 v[216:219], v195 offset:3072
	global_load_lds_dwordx4 v[186:187], off
	v_lshl_add_u64 v[186:187], v[220:221], 0, s[12:13]
	s_add_i32 m0, s27, 0x2000
	s_nop 0
	global_load_lds_dwordx4 v[186:187], off
	s_barrier
	s_waitcnt lgkmcnt(0)
	s_setprio 2
	s_waitcnt lgkmcnt(0)
	v_mfma_f32_16x16x32_bf16 v[116:119], v[204:207], v[144:147], v[116:119]
	v_mfma_f32_16x16x32_bf16 v[112:115], v[212:215], v[144:147], v[112:115]
	v_mfma_f32_16x16x32_bf16 v[100:103], v[204:207], v[170:173], v[100:103]
	v_mfma_f32_16x16x32_bf16 v[96:99], v[212:215], v[170:173], v[96:99]
	v_mfma_f32_16x16x32_bf16 v[84:87], v[204:207], v[178:181], v[84:87]
	v_mfma_f32_16x16x32_bf16 v[80:83], v[212:215], v[178:181], v[80:83]
	v_mfma_f32_16x16x32_bf16 v[68:71], v[204:207], v[196:199], v[68:71]
	v_mfma_f32_16x16x32_bf16 v[64:67], v[212:215], v[196:199], v[64:67]
	v_mfma_f32_16x16x32_bf16 v[116:119], v[208:211], v[148:151], v[116:119]
	v_mfma_f32_16x16x32_bf16 v[112:115], v[216:219], v[148:151], v[112:115]
	v_mfma_f32_16x16x32_bf16 v[100:103], v[208:211], v[174:177], v[100:103]
	v_mfma_f32_16x16x32_bf16 v[96:99], v[216:219], v[174:177], v[96:99]
	v_mfma_f32_16x16x32_bf16 v[84:87], v[208:211], v[182:185], v[84:87]
	v_mfma_f32_16x16x32_bf16 v[80:83], v[216:219], v[182:185], v[80:83]
	v_mfma_f32_16x16x32_bf16 v[68:71], v[208:211], v[200:203], v[68:71]
	v_mfma_f32_16x16x32_bf16 v[64:67], v[216:219], v[200:203], v[64:67]
	s_setprio 1
	s_mov_b32 m0, s38
	v_lshl_add_u64 v[186:187], v[222:223], 0, s[12:13]
	s_barrier
	ds_read_b128 v[144:147], v192 offset:49152
	ds_read_b128 v[148:151], v192 offset:50176
	ds_read_b128 v[170:173], v192 offset:51200
	ds_read_b128 v[174:177], v192 offset:52224
	ds_read_b128 v[178:181], v192 offset:53248
	ds_read_b128 v[182:185], v192 offset:54272
	ds_read_b128 v[196:199], v192 offset:55296
	ds_read_b128 v[200:203], v192 offset:56320
	global_load_lds_dwordx4 v[186:187], off
	v_lshl_add_u64 v[186:187], v[224:225], 0, s[12:13]
	s_mov_b32 m0, s39
	s_nop 0
	global_load_lds_dwordx4 v[186:187], off
	s_barrier
; #define PG8_STAGE(bufoff, gbase, voff) do { _Pragma("unroll") for (int _i = 0; _i < 2; ++_i) \
;         __builtin_amdgcn_global_load_lds((const unsigned*)((const char*)(gbase) + (voff)[_i]), (LAS unsigned*)(lds + (bufoff) + ldsw + _i * 8192), 16, 0, 0); } while (0)
; #define PG8_LDA(dst, b, h) do { _Pragma("unroll") for (int m = 0; m < 4; ++m) _Pragma("unroll") for (int k = 0; k < 2; ++k) dst[m][k] = *(const LAS bf16x8*)(lds + PG8_SA(b, h) + aoff + m * 2048 + k * 1024); } while (0)
; #define PG8_LDB(dst, b, h) do { _Pragma("unroll") for (int n = 0; n < 2; ++n) _Pragma("unroll") for (int k = 0; k < 2; ++k) dst[n][k] = *(const LAS bf16x8*)(lds + PG8_SB(b, h) + boff + n * 2048 + k * 1024); } while (0)
; #define PG8_MMA(ai, bj, At, Bt) do { __builtin_amdgcn_s_setprio(1); _Pragma("unroll") for (int m = 0; m < 4; ++m) _Pragma("unroll") for (int n = 0; n < 2; ++n) _Pragma("unroll") for (int k = 0; k < 2; ++k) \
;         acc[ai][bj][m][n] = __builtin_amdgcn_mfma_f32_16x16x32_bf16(Bt[n][k], At[m][k], acc[ai][bj][m][n], 0, 0, 0); __builtin_amdgcn_s_setprio(0); } while (0)
; #define PG8_WAIT_V(n) asm volatile("s_waitcnt vmcnt(" #n ")" ::: "memory")
; #define PG8_WAIT_L(n) asm volatile("s_waitcnt lgkmcnt(" #n ")" ::: "memory")
; #define PG8_BAR __builtin_amdgcn_s_barrier()
; #define PG8_SCHED __builtin_amdgcn_sched_barrier(0)
; template <class Epi>
; __device__ __forceinline__ void gemm_phase(LAS unsigned char* lds, const Gemm g, const StaticOrder& S, const Epi& E) {
;     ...
;             PG8_LDB(B0, 0, 0); PG8_SCHED; PG8_LDA(At, 0, 0); PG8_STAGE(PG8_SA(1, 1), a1 + hstepA, voffA);
;             PG8_WAIT_L(8); PG8_BAR; PG8_WAIT_L(0); PG8_MMA(0, 0, At, B0); PG8_BAR; PG8_SCHED;
;             PG8_LDB(B1, 0, 1); PG8_STAGE(PG8_SB(0, 0), b2, voffB);
;             PG8_BAR; PG8_WAIT_L(0); PG8_MMA(0, 1, At, B1); PG8_BAR;
;     ...
;             PG8_BAR; PG8_WAIT_L(0); PG8_MMA(1, 0, At, B0); PG8_BAR; PG8_SCHED;
;             PG8_STAGE(PG8_SB(1, 1), b3 + hstepB, voffB);
;             PG8_WAIT_V(6); PG8_BAR; PG8_MMA(1, 1, At, B1); PG8_BAR;
	s_waitcnt lgkmcnt(0)
	s_setprio 2
	s_waitcnt lgkmcnt(0)
	v_mfma_f32_16x16x32_bf16 v[60:63], v[128:131], v[144:147], v[60:63]
	v_mfma_f32_16x16x32_bf16 v[56:59], v[136:139], v[144:147], v[56:59]
	v_mfma_f32_16x16x32_bf16 v[44:47], v[128:131], v[170:173], v[44:47]
	v_mfma_f32_16x16x32_bf16 v[40:43], v[136:139], v[170:173], v[40:43]
	v_mfma_f32_16x16x32_bf16 v[28:31], v[128:131], v[178:181], v[28:31]
	v_mfma_f32_16x16x32_bf16 v[24:27], v[136:139], v[178:181], v[24:27]
	v_mfma_f32_16x16x32_bf16 v[12:15], v[128:131], v[196:199], v[12:15]
	v_mfma_f32_16x16x32_bf16 v[8:11], v[136:139], v[196:199], v[8:11]
	v_mfma_f32_16x16x32_bf16 v[60:63], v[132:135], v[148:151], v[60:63]
	v_mfma_f32_16x16x32_bf16 v[56:59], v[140:143], v[148:151], v[56:59]
	v_mfma_f32_16x16x32_bf16 v[44:47], v[132:135], v[174:177], v[44:47]
	v_mfma_f32_16x16x32_bf16 v[40:43], v[140:143], v[174:177], v[40:43]
	v_mfma_f32_16x16x32_bf16 v[28:31], v[132:135], v[182:185], v[28:31]
	v_mfma_f32_16x16x32_bf16 v[24:27], v[140:143], v[182:185], v[24:27]
	v_mfma_f32_16x16x32_bf16 v[12:15], v[132:135], v[200:203], v[12:15]
	v_mfma_f32_16x16x32_bf16 v[8:11], v[140:143], v[200:203], v[8:11]
	s_setprio 1
	s_barrier
	s_add_u32 s24, s24, 0x100080
	s_addc_u32 s25, s25, 0
	s_add_i32 s26, s26, s31
	v_lshl_add_u64 v[128:129], s[24:25], 0, v[156:157]
	s_mov_b32 m0, s26
	s_nop 0
	global_load_lds_dwordx4 v[128:129], off
	v_lshl_add_u64 v[128:129], s[24:25], 0, v[160:161]
	s_add_i32 m0, s26, 0x2000
	s_nop 0
	global_load_lds_dwordx4 v[128:129], off
	s_waitcnt vmcnt(6)
	s_barrier
	s_setprio 2
	v_mfma_f32_16x16x32_bf16 v[52:55], v[204:207], v[144:147], v[52:55]
	v_mfma_f32_16x16x32_bf16 v[48:51], v[212:215], v[144:147], v[48:51]
	v_mfma_f32_16x16x32_bf16 v[36:39], v[204:207], v[170:173], v[36:39]
	v_mfma_f32_16x16x32_bf16 v[32:35], v[212:215], v[170:173], v[32:35]
	v_mfma_f32_16x16x32_bf16 v[20:23], v[204:207], v[178:181], v[20:23]
	v_mfma_f32_16x16x32_bf16 v[16:19], v[212:215], v[178:181], v[16:19]
	v_mfma_f32_16x16x32_bf16 v[4:7], v[204:207], v[196:199], v[4:7]
	v_mfma_f32_16x16x32_bf16 v[0:3], v[212:215], v[196:199], v[0:3]
	v_mfma_f32_16x16x32_bf16 v[52:55], v[208:211], v[148:151], v[52:55]
	v_mfma_f32_16x16x32_bf16 v[48:51], v[216:219], v[148:151], v[48:51]
	v_mfma_f32_16x16x32_bf16 v[36:39], v[208:211], v[174:177], v[36:39]
	v_mfma_f32_16x16x32_bf16 v[32:35], v[216:219], v[174:177], v[32:35]
	v_mfma_f32_16x16x32_bf16 v[20:23], v[208:211], v[182:185], v[20:23]
	v_mfma_f32_16x16x32_bf16 v[16:19], v[216:219], v[182:185], v[16:19]
	v_mfma_f32_16x16x32_bf16 v[4:7], v[208:211], v[200:203], v[4:7]
	v_mfma_f32_16x16x32_bf16 v[0:3], v[216:219], v[200:203], v[0:3]
	s_setprio 1
	s_add_i32 s48, s48, 2
	s_add_u32 s22, s22, 0x100
	s_addc_u32 s23, s23, 0
	s_add_u32 s46, s46, 0x100
	s_addc_u32 s47, s47, 0
	s_cmp_gt_u32 s48, 61
	s_barrier
.Lkp3_844:
	ds_read_b128 v[128:131], v191
	ds_read_b128 v[132:135], v191 offset:1024
	ds_read_b128 v[136:139], v191 offset:2048
	ds_read_b128 v[140:143], v191 offset:3072
	s_add_u32 s24, s22, 0xfff00080
	s_addc_u32 s25, s23, -1
	s_cmp_eq_u32 s48, 60
	s_cselect_b32 s27, s17, s25
	s_cselect_b32 s26, s44, s24
	s_cselect_b32 s25, s15, s47
	s_cselect_b32 s24, s45, s46
	v_lshl_add_u64 v[186:187], s[22:23], 0, v[162:163]
	s_add_i32 m0, s7, 0xc000
	ds_read_b128 v[144:147], v192
	ds_read_b128 v[148:151], v192 offset:1024
	ds_read_b128 v[170:173], v192 offset:2048
	ds_read_b128 v[174:177], v192 offset:3072
	ds_read_b128 v[178:181], v192 offset:4096
	ds_read_b128 v[182:185], v192 offset:5120
	ds_read_b128 v[196:199], v192 offset:6144
	ds_read_b128 v[200:203], v192 offset:7168
	global_load_lds_dwordx4 v[186:187], off
	v_lshl_add_u64 v[186:187], s[22:23], 0, v[164:165]
	s_add_i32 m0, s7, 0xe000
	s_nop 0
	global_load_lds_dwordx4 v[186:187], off
	s_waitcnt lgkmcnt(8)
	s_barrier
	s_waitcnt lgkmcnt(0)
	s_setprio 2
	s_waitcnt lgkmcnt(0)
	v_mfma_f32_16x16x32_bf16 v[124:127], v[128:131], v[144:147], v[124:127]
	v_mfma_f32_16x16x32_bf16 v[120:123], v[136:139], v[144:147], v[120:123]
	v_mfma_f32_16x16x32_bf16 v[108:111], v[128:131], v[170:173], v[108:111]
	v_mfma_f32_16x16x32_bf16 v[104:107], v[136:139], v[170:173], v[104:107]
	v_mfma_f32_16x16x32_bf16 v[92:95], v[128:131], v[178:181], v[92:95]
	v_mfma_f32_16x16x32_bf16 v[88:91], v[136:139], v[178:181], v[88:91]
	v_mfma_f32_16x16x32_bf16 v[76:79], v[128:131], v[196:199], v[76:79]
	v_mfma_f32_16x16x32_bf16 v[72:75], v[136:139], v[196:199], v[72:75]
	v_mfma_f32_16x16x32_bf16 v[124:127], v[132:135], v[148:151], v[124:127]
	v_mfma_f32_16x16x32_bf16 v[120:123], v[140:143], v[148:151], v[120:123]
	v_mfma_f32_16x16x32_bf16 v[108:111], v[132:135], v[174:177], v[108:111]
	v_mfma_f32_16x16x32_bf16 v[104:107], v[140:143], v[174:177], v[104:107]
	v_mfma_f32_16x16x32_bf16 v[92:95], v[132:135], v[182:185], v[92:95]
	v_mfma_f32_16x16x32_bf16 v[88:91], v[140:143], v[182:185], v[88:91]
	v_mfma_f32_16x16x32_bf16 v[76:79], v[132:135], v[200:203], v[76:79]
	v_mfma_f32_16x16x32_bf16 v[72:75], v[140:143], v[200:203], v[72:75]
	s_setprio 1
	s_barrier
	s_add_i32 s49, s42, s31
	v_lshl_add_u64 v[186:187], s[24:25], 0, v[156:157]
	s_mov_b32 m0, s49
	ds_read_b128 v[204:207], v193
	ds_read_b128 v[208:211], v193 offset:1024
	ds_read_b128 v[212:215], v193 offset:2048
	ds_read_b128 v[216:219], v193 offset:3072
	global_load_lds_dwordx4 v[186:187], off
	v_lshl_add_u64 v[220:221], s[24:25], 0, v[160:161]
	s_add_i32 m0, s49, 0x2000
	s_nop 0
	global_load_lds_dwordx4 v[220:221], off
	s_barrier
; #define PG8_STAGE(bufoff, gbase, voff) do { _Pragma("unroll") for (int _i = 0; _i < 2; ++_i) \
;         __builtin_amdgcn_global_load_lds((const unsigned*)((const char*)(gbase) + (voff)[_i]), (LAS unsigned*)(lds + (bufoff) + ldsw + _i * 8192), 16, 0, 0); } while (0)
; #define PG8_LDA(dst, b, h) do { _Pragma("unroll") for (int m = 0; m < 4; ++m) _Pragma("unroll") for (int k = 0; k < 2; ++k) dst[m][k] = *(const LAS bf16x8*)(lds + PG8_SA(b, h) + aoff + m * 2048 + k * 1024); } while (0)
; #define PG8_LDB(dst, b, h) do { _Pragma("unroll") for (int n = 0; n < 2; ++n) _Pragma("unroll") for (int k = 0; k < 2; ++k) dst[n][k] = *(const LAS bf16x8*)(lds + PG8_SB(b, h) + boff + n * 2048 + k * 1024); } while (0)
; #define PG8_MMA(ai, bj, At, Bt) do { __builtin_amdgcn_s_setprio(1); _Pragma("unroll") for (int m = 0; m < 4; ++m) _Pragma("unroll") for (int n = 0; n < 2; ++n) _Pragma("unroll") for (int k = 0; k < 2; ++k) \
;         acc[ai][bj][m][n] = __builtin_amdgcn_mfma_f32_16x16x32_bf16(Bt[n][k], At[m][k], acc[ai][bj][m][n], 0, 0, 0); __builtin_amdgcn_s_setprio(0); } while (0)
; #define PG8_WAIT_V(n) asm volatile("s_waitcnt vmcnt(" #n ")" ::: "memory")
; #define PG8_WAIT_L(n) asm volatile("s_waitcnt lgkmcnt(" #n ")" ::: "memory")
; #define PG8_BAR __builtin_amdgcn_s_barrier()
; #define PG8_SCHED __builtin_amdgcn_sched_barrier(0)
; template <class Epi>
; __device__ __forceinline__ void gemm_phase(LAS unsigned char* lds, const Gemm g, const StaticOrder& S, const Epi& E) {
;     ...
;             PG8_BAR; PG8_WAIT_L(0); PG8_MMA(0, 1, At, B1); PG8_BAR;
;             PG8_LDA(At, 0, 1); PG8_STAGE(PG8_SA(0, 0), a2, voffA);
;             PG8_BAR; PG8_WAIT_L(0); PG8_MMA(1, 0, At, B0); PG8_BAR; PG8_SCHED;
;             PG8_STAGE(PG8_SB(0, 1), b2 + hstepB, voffB);
;             PG8_WAIT_V(6); PG8_BAR; PG8_MMA(1, 1, At, B1); PG8_BAR;
;             PG8_LDB(B0, 1, 0); PG8_SCHED; PG8_LDA(At, 1, 0); PG8_STAGE(PG8_SA(0, 1), a2 + hstepA, voffA);
;             PG8_WAIT_L(8); PG8_BAR; PG8_WAIT_L(0); PG8_MMA(0, 0, At, B0); PG8_BAR; PG8_SCHED;
;             PG8_LDB(B1, 1, 1); PG8_STAGE(PG8_SB(1, 0), b3, voffB);
;             PG8_BAR; PG8_WAIT_L(0); PG8_MMA(0, 1, At, B1); PG8_BAR;
;             PG8_LDA(At, 1, 1); PG8_STAGE(PG8_SA(1, 0), a3, voffA);
	s_waitcnt lgkmcnt(0)
	s_setprio 2
	s_waitcnt lgkmcnt(0)
	v_mfma_f32_16x16x32_bf16 v[116:119], v[204:207], v[144:147], v[116:119]
	v_mfma_f32_16x16x32_bf16 v[112:115], v[212:215], v[144:147], v[112:115]
	v_mfma_f32_16x16x32_bf16 v[100:103], v[204:207], v[170:173], v[100:103]
	v_mfma_f32_16x16x32_bf16 v[96:99], v[212:215], v[170:173], v[96:99]
	v_mfma_f32_16x16x32_bf16 v[84:87], v[204:207], v[178:181], v[84:87]
	v_mfma_f32_16x16x32_bf16 v[80:83], v[212:215], v[178:181], v[80:83]
	v_mfma_f32_16x16x32_bf16 v[68:71], v[204:207], v[196:199], v[68:71]
	v_mfma_f32_16x16x32_bf16 v[64:67], v[212:215], v[196:199], v[64:67]
	v_mfma_f32_16x16x32_bf16 v[116:119], v[208:211], v[148:151], v[116:119]
	v_mfma_f32_16x16x32_bf16 v[112:115], v[216:219], v[148:151], v[112:115]
	v_mfma_f32_16x16x32_bf16 v[100:103], v[208:211], v[174:177], v[100:103]
	v_mfma_f32_16x16x32_bf16 v[96:99], v[216:219], v[174:177], v[96:99]
	v_mfma_f32_16x16x32_bf16 v[84:87], v[208:211], v[182:185], v[84:87]
	v_mfma_f32_16x16x32_bf16 v[80:83], v[216:219], v[182:185], v[80:83]
	v_mfma_f32_16x16x32_bf16 v[68:71], v[208:211], v[200:203], v[68:71]
	v_mfma_f32_16x16x32_bf16 v[64:67], v[216:219], v[200:203], v[64:67]
	s_setprio 1
	s_mov_b32 m0, s7
	v_lshl_add_u64 v[222:223], s[26:27], 0, v[154:155]
	s_barrier
	ds_read_b128 v[144:147], v192 offset:16384
	ds_read_b128 v[148:151], v192 offset:17408
	ds_read_b128 v[170:173], v192 offset:18432
	ds_read_b128 v[174:177], v192 offset:19456
	ds_read_b128 v[178:181], v192 offset:20480
	ds_read_b128 v[182:185], v192 offset:21504
	ds_read_b128 v[196:199], v192 offset:22528
	ds_read_b128 v[200:203], v192 offset:23552
	global_load_lds_dwordx4 v[222:223], off
	v_lshl_add_u64 v[224:225], s[26:27], 0, v[158:159]
	s_mov_b32 m0, s34
	s_nop 0
	global_load_lds_dwordx4 v[224:225], off
	s_barrier
	s_waitcnt lgkmcnt(0)
	s_setprio 2
	s_waitcnt lgkmcnt(0)
	v_mfma_f32_16x16x32_bf16 v[60:63], v[128:131], v[144:147], v[60:63]
	v_mfma_f32_16x16x32_bf16 v[56:59], v[136:139], v[144:147], v[56:59]
	v_mfma_f32_16x16x32_bf16 v[44:47], v[128:131], v[170:173], v[44:47]
	v_mfma_f32_16x16x32_bf16 v[40:43], v[136:139], v[170:173], v[40:43]
	v_mfma_f32_16x16x32_bf16 v[28:31], v[128:131], v[178:181], v[28:31]
	v_mfma_f32_16x16x32_bf16 v[24:27], v[136:139], v[178:181], v[24:27]
	v_mfma_f32_16x16x32_bf16 v[12:15], v[128:131], v[196:199], v[12:15]
	v_mfma_f32_16x16x32_bf16 v[8:11], v[136:139], v[196:199], v[8:11]
	v_mfma_f32_16x16x32_bf16 v[60:63], v[132:135], v[148:151], v[60:63]
	v_mfma_f32_16x16x32_bf16 v[56:59], v[140:143], v[148:151], v[56:59]
	v_mfma_f32_16x16x32_bf16 v[44:47], v[132:135], v[174:177], v[44:47]
	v_mfma_f32_16x16x32_bf16 v[40:43], v[140:143], v[174:177], v[40:43]
	v_mfma_f32_16x16x32_bf16 v[28:31], v[132:135], v[182:185], v[28:31]
	v_mfma_f32_16x16x32_bf16 v[24:27], v[140:143], v[182:185], v[24:27]
	v_mfma_f32_16x16x32_bf16 v[12:15], v[132:135], v[200:203], v[12:15]
	v_mfma_f32_16x16x32_bf16 v[8:11], v[140:143], v[200:203], v[8:11]
	s_setprio 1
	s_barrier
	s_add_u32 s50, s24, 0x100000
	s_addc_u32 s51, s25, 0
	s_add_i32 s49, s43, s31
	v_lshl_add_u64 v[128:129], s[50:51], 0, v[156:157]
	s_mov_b32 m0, s49
	s_nop 0
	global_load_lds_dwordx4 v[128:129], off
	v_lshl_add_u64 v[128:129], s[50:51], 0, v[160:161]
	s_add_i32 m0, s49, 0x2000
	s_nop 0
	global_load_lds_dwordx4 v[128:129], off
	s_waitcnt vmcnt(6)
	s_barrier
	s_setprio 2
	v_mfma_f32_16x16x32_bf16 v[52:55], v[204:207], v[144:147], v[52:55]
	v_mfma_f32_16x16x32_bf16 v[48:51], v[212:215], v[144:147], v[48:51]
	v_mfma_f32_16x16x32_bf16 v[36:39], v[204:207], v[170:173], v[36:39]
	v_mfma_f32_16x16x32_bf16 v[32:35], v[212:215], v[170:173], v[32:35]
	v_mfma_f32_16x16x32_bf16 v[20:23], v[204:207], v[178:181], v[20:23]
	v_mfma_f32_16x16x32_bf16 v[16:19], v[212:215], v[178:181], v[16:19]
	v_mfma_f32_16x16x32_bf16 v[4:7], v[204:207], v[196:199], v[4:7]
	v_mfma_f32_16x16x32_bf16 v[0:3], v[212:215], v[196:199], v[0:3]
	v_mfma_f32_16x16x32_bf16 v[52:55], v[208:211], v[148:151], v[52:55]
	v_mfma_f32_16x16x32_bf16 v[48:51], v[216:219], v[148:151], v[48:51]
	v_mfma_f32_16x16x32_bf16 v[36:39], v[208:211], v[174:177], v[36:39]
	v_mfma_f32_16x16x32_bf16 v[32:35], v[216:219], v[174:177], v[32:35]
	v_mfma_f32_16x16x32_bf16 v[20:23], v[208:211], v[182:185], v[20:23]
	v_mfma_f32_16x16x32_bf16 v[16:19], v[216:219], v[182:185], v[16:19]
	v_mfma_f32_16x16x32_bf16 v[4:7], v[208:211], v[200:203], v[4:7]
	v_mfma_f32_16x16x32_bf16 v[0:3], v[216:219], v[200:203], v[0:3]
	s_setprio 1
	s_add_i32 s49, 0, 0x18000
	v_add_u32_e32 v140, s49, v189
	s_barrier
	ds_read_b128 v[128:131], v140
	ds_read_b128 v[132:135], v140 offset:1024
	ds_read_b128 v[136:139], v140 offset:2048
	ds_read_b128 v[140:143], v140 offset:3072
	s_add_u32 s26, s26, 0x100000
	s_addc_u32 s27, s27, 0
	s_mov_b32 m0, s35
	v_lshl_add_u64 v[204:205], s[26:27], 0, v[154:155]
	ds_read_b128 v[144:147], v192 offset:32768
	ds_read_b128 v[148:151], v192 offset:33792
	ds_read_b128 v[170:173], v192 offset:34816
	ds_read_b128 v[174:177], v192 offset:35840
	ds_read_b128 v[178:181], v192 offset:36864
	ds_read_b128 v[182:185], v192 offset:37888
	ds_read_b128 v[196:199], v192 offset:38912
	ds_read_b128 v[200:203], v192 offset:39936
	global_load_lds_dwordx4 v[204:205], off
	v_lshl_add_u64 v[204:205], s[26:27], 0, v[158:159]
	s_mov_b32 m0, s36
	s_nop 0
	global_load_lds_dwordx4 v[204:205], off
	s_waitcnt lgkmcnt(8)
	s_barrier
; #define PG8_STAGE(bufoff, gbase, voff) do { _Pragma("unroll") for (int _i = 0; _i < 2; ++_i) \
;         __builtin_amdgcn_global_load_lds((const unsigned*)((const char*)(gbase) + (voff)[_i]), (LAS unsigned*)(lds + (bufoff) + ldsw + _i * 8192), 16, 0, 0); } while (0)
; #define PG8_LDA(dst, b, h) do { _Pragma("unroll") for (int m = 0; m < 4; ++m) _Pragma("unroll") for (int k = 0; k < 2; ++k) dst[m][k] = *(const LAS bf16x8*)(lds + PG8_SA(b, h) + aoff + m * 2048 + k * 1024); } while (0)
; #define PG8_LDB(dst, b, h) do { _Pragma("unroll") for (int n = 0; n < 2; ++n) _Pragma("unroll") for (int k = 0; k < 2; ++k) dst[n][k] = *(const LAS bf16x8*)(lds + PG8_SB(b, h) + boff + n * 2048 + k * 1024); } while (0)
; #define PG8_MMA(ai, bj, At, Bt) do { __builtin_amdgcn_s_setprio(1); _Pragma("unroll") for (int m = 0; m < 4; ++m) _Pragma("unroll") for (int n = 0; n < 2; ++n) _Pragma("unroll") for (int k = 0; k < 2; ++k) \
;         acc[ai][bj][m][n] = __builtin_amdgcn_mfma_f32_16x16x32_bf16(Bt[n][k], At[m][k], acc[ai][bj][m][n], 0, 0, 0); __builtin_amdgcn_s_setprio(0); } while (0)
; #define PG8_WAIT_V(n) asm volatile("s_waitcnt vmcnt(" #n ")" ::: "memory")
; #define PG8_WAIT_L(n) asm volatile("s_waitcnt lgkmcnt(" #n ")" ::: "memory")
; #define PG8_BAR __builtin_amdgcn_s_barrier()
; #define PG8_SCHED __builtin_amdgcn_sched_barrier(0)
; template <class Epi>
; __device__ __forceinline__ void gemm_phase(LAS unsigned char* lds, const Gemm g, const StaticOrder& S, const Epi& E) {
;     ...
;             PG8_WAIT_L(8); PG8_BAR; PG8_WAIT_L(0); PG8_MMA(0, 0, At, B0); PG8_BAR; PG8_SCHED;
;             PG8_LDB(B1, 1, 1); PG8_STAGE(PG8_SB(1, 0), b3, voffB);
;             PG8_BAR; PG8_WAIT_L(0); PG8_MMA(0, 1, At, B1); PG8_BAR;
;             PG8_LDA(At, 1, 1); PG8_STAGE(PG8_SA(1, 0), a3, voffA);
;             PG8_BAR; PG8_WAIT_L(0); PG8_MMA(1, 0, At, B0); PG8_BAR; PG8_SCHED;
;             PG8_STAGE(PG8_SB(1, 1), b3 + hstepB, voffB);
;             PG8_WAIT_V(6); PG8_BAR; PG8_MMA(1, 1, At, B1); PG8_BAR;
;         }
	s_waitcnt lgkmcnt(0)
	s_setprio 2
	s_waitcnt lgkmcnt(0)
	v_mfma_f32_16x16x32_bf16 v[124:127], v[128:131], v[144:147], v[124:127]
	v_mfma_f32_16x16x32_bf16 v[120:123], v[136:139], v[144:147], v[120:123]
	v_mfma_f32_16x16x32_bf16 v[108:111], v[128:131], v[170:173], v[108:111]
	v_mfma_f32_16x16x32_bf16 v[104:107], v[136:139], v[170:173], v[104:107]
	v_mfma_f32_16x16x32_bf16 v[92:95], v[128:131], v[178:181], v[92:95]
	v_mfma_f32_16x16x32_bf16 v[88:91], v[136:139], v[178:181], v[88:91]
	v_mfma_f32_16x16x32_bf16 v[76:79], v[128:131], v[196:199], v[76:79]
	v_mfma_f32_16x16x32_bf16 v[72:75], v[136:139], v[196:199], v[72:75]
	v_mfma_f32_16x16x32_bf16 v[124:127], v[132:135], v[148:151], v[124:127]
	v_mfma_f32_16x16x32_bf16 v[120:123], v[140:143], v[148:151], v[120:123]
	v_mfma_f32_16x16x32_bf16 v[108:111], v[132:135], v[174:177], v[108:111]
	v_mfma_f32_16x16x32_bf16 v[104:107], v[140:143], v[174:177], v[104:107]
	v_mfma_f32_16x16x32_bf16 v[92:95], v[132:135], v[182:185], v[92:95]
	v_mfma_f32_16x16x32_bf16 v[88:91], v[140:143], v[182:185], v[88:91]
	v_mfma_f32_16x16x32_bf16 v[76:79], v[132:135], v[200:203], v[76:79]
	v_mfma_f32_16x16x32_bf16 v[72:75], v[140:143], v[200:203], v[72:75]
	s_setprio 1
	s_barrier
	s_add_i32 s26, 0, 0x1c000
	s_add_i32 s27, s49, s31
	v_add_u32_e32 v195, s26, v189
	v_lshl_add_u64 v[186:187], v[186:187], 0, s[12:13]
	s_mov_b32 m0, s27
	ds_read_b128 v[204:207], v195
	ds_read_b128 v[208:211], v195 offset:1024
	ds_read_b128 v[212:215], v195 offset:2048
	ds_read_b128 v[216:219], v195 offset:3072
	global_load_lds_dwordx4 v[186:187], off
	v_lshl_add_u64 v[186:187], v[220:221], 0, s[12:13]
	s_add_i32 m0, s27, 0x2000
	s_nop 0
	global_load_lds_dwordx4 v[186:187], off
	s_barrier
	s_waitcnt lgkmcnt(0)
	s_setprio 2
	s_waitcnt lgkmcnt(0)
	v_mfma_f32_16x16x32_bf16 v[116:119], v[204:207], v[144:147], v[116:119]
	v_mfma_f32_16x16x32_bf16 v[112:115], v[212:215], v[144:147], v[112:115]
	v_mfma_f32_16x16x32_bf16 v[100:103], v[204:207], v[170:173], v[100:103]
	v_mfma_f32_16x16x32_bf16 v[96:99], v[212:215], v[170:173], v[96:99]
	v_mfma_f32_16x16x32_bf16 v[84:87], v[204:207], v[178:181], v[84:87]
	v_mfma_f32_16x16x32_bf16 v[80:83], v[212:215], v[178:181], v[80:83]
	v_mfma_f32_16x16x32_bf16 v[68:71], v[204:207], v[196:199], v[68:71]
	v_mfma_f32_16x16x32_bf16 v[64:67], v[212:215], v[196:199], v[64:67]
	v_mfma_f32_16x16x32_bf16 v[116:119], v[208:211], v[148:151], v[116:119]
	v_mfma_f32_16x16x32_bf16 v[112:115], v[216:219], v[148:151], v[112:115]
	v_mfma_f32_16x16x32_bf16 v[100:103], v[208:211], v[174:177], v[100:103]
	v_mfma_f32_16x16x32_bf16 v[96:99], v[216:219], v[174:177], v[96:99]
	v_mfma_f32_16x16x32_bf16 v[84:87], v[208:211], v[182:185], v[84:87]
	v_mfma_f32_16x16x32_bf16 v[80:83], v[216:219], v[182:185], v[80:83]
	v_mfma_f32_16x16x32_bf16 v[68:71], v[208:211], v[200:203], v[68:71]
	v_mfma_f32_16x16x32_bf16 v[64:67], v[216:219], v[200:203], v[64:67]
	s_setprio 1
	s_mov_b32 m0, s38
	v_lshl_add_u64 v[186:187], v[222:223], 0, s[12:13]
	s_barrier
	ds_read_b128 v[144:147], v192 offset:49152
	ds_read_b128 v[148:151], v192 offset:50176
	ds_read_b128 v[170:173], v192 offset:51200
	ds_read_b128 v[174:177], v192 offset:52224
	ds_read_b128 v[178:181], v192 offset:53248
	ds_read_b128 v[182:185], v192 offset:54272
	ds_read_b128 v[196:199], v192 offset:55296
	ds_read_b128 v[200:203], v192 offset:56320
	global_load_lds_dwordx4 v[186:187], off
	v_lshl_add_u64 v[186:187], v[224:225], 0, s[12:13]
	s_mov_b32 m0, s39
	s_nop 0
	global_load_lds_dwordx4 v[186:187], off
	s_barrier
	s_waitcnt lgkmcnt(0)
	s_setprio 2
	s_waitcnt lgkmcnt(0)
	v_mfma_f32_16x16x32_bf16 v[60:63], v[128:131], v[144:147], v[60:63]
	v_mfma_f32_16x16x32_bf16 v[56:59], v[136:139], v[144:147], v[56:59]
	v_mfma_f32_16x16x32_bf16 v[44:47], v[128:131], v[170:173], v[44:47]
	v_mfma_f32_16x16x32_bf16 v[40:43], v[136:139], v[170:173], v[40:43]
	v_mfma_f32_16x16x32_bf16 v[28:31], v[128:131], v[178:181], v[28:31]
	v_mfma_f32_16x16x32_bf16 v[24:27], v[136:139], v[178:181], v[24:27]
	v_mfma_f32_16x16x32_bf16 v[12:15], v[128:131], v[196:199], v[12:15]
	v_mfma_f32_16x16x32_bf16 v[8:11], v[136:139], v[196:199], v[8:11]
	v_mfma_f32_16x16x32_bf16 v[60:63], v[132:135], v[148:151], v[60:63]
	v_mfma_f32_16x16x32_bf16 v[56:59], v[140:143], v[148:151], v[56:59]
	v_mfma_f32_16x16x32_bf16 v[44:47], v[132:135], v[174:177], v[44:47]
	v_mfma_f32_16x16x32_bf16 v[40:43], v[140:143], v[174:177], v[40:43]
	v_mfma_f32_16x16x32_bf16 v[28:31], v[132:135], v[182:185], v[28:31]
	v_mfma_f32_16x16x32_bf16 v[24:27], v[140:143], v[182:185], v[24:27]
	v_mfma_f32_16x16x32_bf16 v[12:15], v[132:135], v[200:203], v[12:15]
	v_mfma_f32_16x16x32_bf16 v[8:11], v[140:143], v[200:203], v[8:11]
	s_setprio 1
	s_barrier
	s_add_u32 s24, s24, 0x100080
	s_addc_u32 s25, s25, 0
	s_add_i32 s26, s26, s31
	v_lshl_add_u64 v[128:129], s[24:25], 0, v[156:157]
	s_mov_b32 m0, s26
	s_nop 0
	global_load_lds_dwordx4 v[128:129], off
	v_lshl_add_u64 v[128:129], s[24:25], 0, v[160:161]
	s_add_i32 m0, s26, 0x2000
	s_nop 0
	global_load_lds_dwordx4 v[128:129], off
	s_waitcnt vmcnt(6)
	s_barrier
	s_setprio 2
	v_mfma_f32_16x16x32_bf16 v[52:55], v[204:207], v[144:147], v[52:55]
	v_mfma_f32_16x16x32_bf16 v[48:51], v[212:215], v[144:147], v[48:51]
	v_mfma_f32_16x16x32_bf16 v[36:39], v[204:207], v[170:173], v[36:39]
	v_mfma_f32_16x16x32_bf16 v[32:35], v[212:215], v[170:173], v[32:35]
	v_mfma_f32_16x16x32_bf16 v[20:23], v[204:207], v[178:181], v[20:23]
	v_mfma_f32_16x16x32_bf16 v[16:19], v[212:215], v[178:181], v[16:19]
	v_mfma_f32_16x16x32_bf16 v[4:7], v[204:207], v[196:199], v[4:7]
	v_mfma_f32_16x16x32_bf16 v[0:3], v[212:215], v[196:199], v[0:3]
	v_mfma_f32_16x16x32_bf16 v[52:55], v[208:211], v[148:151], v[52:55]
	v_mfma_f32_16x16x32_bf16 v[48:51], v[216:219], v[148:151], v[48:51]
	v_mfma_f32_16x16x32_bf16 v[36:39], v[208:211], v[174:177], v[36:39]
	v_mfma_f32_16x16x32_bf16 v[32:35], v[216:219], v[174:177], v[32:35]
	v_mfma_f32_16x16x32_bf16 v[20:23], v[208:211], v[182:185], v[20:23]
	v_mfma_f32_16x16x32_bf16 v[16:19], v[216:219], v[182:185], v[16:19]
	v_mfma_f32_16x16x32_bf16 v[4:7], v[208:211], v[200:203], v[4:7]
	v_mfma_f32_16x16x32_bf16 v[0:3], v[216:219], v[200:203], v[0:3]
	s_setprio 1
	s_add_i32 s48, s48, 2
	s_add_u32 s22, s22, 0x100
	s_addc_u32 s23, s23, 0
	s_add_u32 s46, s46, 0x100
	s_addc_u32 s47, s47, 0
	s_cmp_gt_u32 s48, 61
	s_barrier
	s_cbranch_scc0 .Lkp3_844
	s_branch .Lkp3_epi
;     __device__ bool next(int i, Unit& u) const {
;         const long L = (long)i * G + c; if (L >= nwg) return false;
;         int wgid = (int)L; { const int q = nwg / NXCD, r = nwg % NXCD, xcd = wgid % NXCD, off = wgid / NXCD; wgid = (xcd < r ? xcd * (q + 1) : r * (q + 1) + (xcd - r) * q) + off; }
;         const int nig = WGM * nN, gid = wgid / nig, fm = gid * WGM, gsz = (nM - fm) < WGM ? (nM - fm) : WGM;
;         u.pm = fm + ((wgid % nig) % gsz); u.pn = (wgid % nig) / gsz; return true;
; template <class Epi>
; __device__ __forceinline__ void gemm_phase(LAS unsigned char* lds, const Gemm g, const StaticOrder& S, const Epi& E) {
;     ...
;         const bool has_next = S.next(ui + 1, nxt);
.LBB0_837:
	v_readfirstlane_b32 s98, v152
	s_nop 3
	s_cmp_ge_u32 s98, 0x100
	s_cbranch_scc1 .Lkp3_head
	s_add_i32 s33, s33, 1
	s_mul_i32 s2, s33, s40
	s_mul_hi_u32 s3, s33, s92
	s_add_i32 s3, s3, s2
	s_mul_i32 s2, s33, s92
	s_add_u32 s18, s2, s93
	s_addc_u32 s19, s3, s41
	v_cmp_gt_i64_e64 s[2:3], s[18:19], v[168:169]
	s_and_b64 vcc, exec, s[2:3]
	s_cbranch_vccnz .LBB0_843
	s_lshr_b32 s14, s18, 3
	s_mov_b32 s17, 0
	s_sub_u32 s15, s14, 0x20
	s_cmp_ge_u32 s14, 0x20
	s_cselect_b32 s14, s15, s14
	s_addc_u32 s17, s17, 0
	s_sub_u32 s15, s14, 0x20
	s_cmp_ge_u32 s14, 0x20
	s_cselect_b32 s14, s15, s14
	s_addc_u32 s17, s17, 0
	s_sub_u32 s15, s14, 0x20
	s_cmp_ge_u32 s14, 0x20
	s_cselect_b32 s14, s15, s14
	s_addc_u32 s17, s17, 0
	s_and_b32 s16, s18, 7
	s_lshl_b32 s16, s16, 2
	s_add_i32 s16, s16, s17
	s_lshl_b32 s16, s16, 3
	s_and_b32 s17, s14, 7
	s_add_i32 s16, s16, s17
	s_lshr_b32 s14, s14, 3

; __device__ __forceinline__ unsigned pk2(float lo, float hi) { const f32x2 v = (f32x2){lo, hi}; const bf16x2_t b = __builtin_convertvector(v, bf16x2_t); return __builtin_bit_cast(unsigned, b); }
; __device__ __forceinline__ void unpack8(const u32x4 v, float* f) { f[0] = bf_lo(v.x); f[1] = bf_hi(v.x); f[2] = bf_lo(v.y); f[3] = bf_hi(v.y); f[4] = bf_lo(v.z); f[5] = bf_hi(v.z); f[6] = bf_lo(v.w); f[7] = bf_hi(v.w); }
;     __device__ __forceinline__ void operator()(const f32x4 (&acc)[2][2][4][2], const Unit& u, int wr, int wc, int fr, int fq, const float (&)[8]) const {
;         const int row0 = u.pm * BM + wr * 64 + fr, col0 = u.pn * BM + wc * 32 + 8 * fq;
; #pragma unroll
;         for (int ai = 0; ai < 2; ++ai) {
;             u32x4 bv[4][2];
; #pragma unroll
;             for (int m = 0; m < 4; ++m)
; #pragma unroll
;                 for (int bj = 0; bj < 2; ++bj) bv[m][bj] = *(const u32x4*)(xb + (size_t)(row0 + ai * HALF + m * 16) * DM + col0 + bj * HALF);
; #pragma unroll
;             for (int m = 0; m < 4; ++m) { const int row = row0 + ai * HALF + m * 16; const size_t ro = (size_t)row * DM + col0; float s = 0.f;
; #pragma unroll
;                 for (int bj = 0; bj < 2; ++bj) { float b8[8]; unpack8(bv[m][bj], b8);
;                     const f32x4 v0 = (f32x4){b8[0], b8[1], b8[2], b8[3]} + acc[ai][bj][m][0], v1 = (f32x4){b8[4], b8[5], b8[6], b8[7]} + acc[ai][bj][m][1];
;                     s += v0[0] * v0[0] + v0[1] * v0[1] + v0[2] * v0[2] + v0[3] * v0[3] + v1[0] * v1[0] + v1[1] * v1[1] + v1[2] * v1[2] + v1[3] * v1[3];
;                     if (LAST) { *(f32x4*)(out + ro + bj * HALF) = v0; *(f32x4*)(out + ro + bj * HALF + 4) = v1; }
;                     else { u32x4 w; w.x = pk2(v0[0], v0[1]); w.y = pk2(v0[2], v0[3]); w.z = pk2(v1[0], v1[1]); w.w = pk2(v1[2], v1[3]); *(u32x4*)(xb + ro + bj * HALF) = w; } }
;                 s += __shfl_xor(s, 16); s += __shfl_xor(s, 32);
;                 if (fq == 0) ss[(size_t)row * 16 + u.pn * 4 + wc] = s; }
.Lkp3_epi:
	s_setprio 0
	v_lshl_or_b32 v170, s6, 8, v190
	v_lshl_add_u32 v172, s8, 8, v188
	v_ashrrev_i32_e32 v171, 31, v170
	v_lshlrev_b64 v[206:207], 1, v[170:171]
	v_ashrrev_i32_e32 v173, 31, v172
	v_lshl_add_u64 v[174:175], s[76:77], 0, v[206:207]
	v_lshlrev_b64 v[208:209], 11, v[172:173]
	v_lshl_add_u64 v[128:129], v[174:175], 0, v[208:209]
	global_load_dwordx4 v[198:201], v[128:129], off
	global_load_dwordx4 v[202:205], v[128:129], off offset:256
	v_or_b32_e32 v184, 16, v172
	v_or_b32_e32 v180, 32, v172
	v_or_b32_e32 v176, 48, v172
	v_ashrrev_i32_e32 v185, 31, v184
	v_ashrrev_i32_e32 v181, 31, v180
	v_ashrrev_i32_e32 v177, 31, v176
	v_lshlrev_b64 v[186:187], 11, v[184:185]
	v_lshlrev_b64 v[182:183], 11, v[180:181]
	v_lshlrev_b64 v[178:179], 11, v[176:177]
	v_lshl_add_u64 v[128:129], v[174:175], 0, v[186:187]
	v_lshl_add_u64 v[130:131], v[174:175], 0, v[182:183]
	v_lshl_add_u64 v[196:197], v[174:175], 0, v[178:179]
	global_load_dwordx4 v[148:151], v[128:129], off
	global_load_dwordx4 v[144:147], v[128:129], off offset:256
	global_load_dwordx4 v[140:143], v[130:131], off
	global_load_dwordx4 v[136:139], v[130:131], off offset:256
	global_load_dwordx4 v[132:135], v[196:197], off
	s_nop 0
	global_load_dwordx4 v[128:131], v[196:197], off offset:256
	v_add_u32_e32 v218, 0x80, v172
	v_ashrrev_i32_e32 v219, 31, v218
	v_lshlrev_b64 v[218:219], 11, v[218:219]
	v_lshl_add_u64 v[218:219], v[174:175], 0, v[218:219]
	global_load_dwordx4 v[220:223], v[218:219], off
	global_load_dwordx4 v[224:227], v[218:219], off offset:256
	v_add_u32_e32 v218, 0x90, v172
	v_ashrrev_i32_e32 v219, 31, v218
	v_lshlrev_b64 v[218:219], 11, v[218:219]
	v_lshl_add_u64 v[218:219], v[174:175], 0, v[218:219]
	global_load_dwordx4 v[228:231], v[218:219], off
	global_load_dwordx4 v[232:235], v[218:219], off offset:256
	v_add_u32_e32 v218, 0xa0, v172
	v_ashrrev_i32_e32 v219, 31, v218
	v_lshlrev_b64 v[218:219], 11, v[218:219]
	v_lshl_add_u64 v[218:219], v[174:175], 0, v[218:219]
	global_load_dwordx4 v[236:239], v[218:219], off
	global_load_dwordx4 v[240:243], v[218:219], off offset:256
	v_add_u32_e32 v218, 0xb0, v172
	v_ashrrev_i32_e32 v219, 31, v218
	v_lshlrev_b64 v[218:219], 11, v[218:219]
	v_lshl_add_u64 v[218:219], v[174:175], 0, v[218:219]
	global_load_dwordx4 v[244:247], v[218:219], off
	global_load_dwordx4 v[252:255], v[218:219], off offset:256
	v_and_b32_e32 v196, 64, v194
	v_xor_b32_e32 v195, 16, v194
	v_add_u32_e32 v196, 64, v196
	v_xor_b32_e32 v197, 32, v194
	v_cmp_lt_i32_e32 vcc, v195, v196
	s_waitcnt vmcnt(15)
	v_lshlrev_b32_e32 v210, 16, v198
	v_cndmask_b32_e32 v195, v194, v195, vcc
	v_cmp_lt_i32_e32 vcc, v197, v196
	v_and_b32_e32 v211, 0xffff0000, v198
	s_waitcnt vmcnt(14)
	v_lshlrev_b32_e32 v214, 16, v202
	v_and_b32_e32 v215, 0xffff0000, v202
	v_cndmask_b32_e32 v197, v194, v197, vcc
	v_lshlrev_b32_e32 v212, 16, v200
	v_and_b32_e32 v213, 0xffff0000, v200
	v_lshlrev_b32_e32 v200, 16, v201
	v_and_b32_e32 v201, 0xffff0000, v201
	v_lshlrev_b32_e32 v216, 16, v204
	v_and_b32_e32 v217, 0xffff0000, v204
	v_pk_add_f32 v[124:125], v[124:125], v[210:211]
	v_pk_add_f32 v[116:117], v[116:117], v[214:215]
	v_lshlrev_b32_e32 v196, 2, v195
	v_lshlrev_b32_e32 v195, 2, v197
	v_lshlrev_b32_e32 v198, 16, v199
	v_and_b32_e32 v199, 0xffff0000, v199
	v_lshlrev_b32_e32 v202, 16, v203
	v_and_b32_e32 v203, 0xffff0000, v203
	v_pk_add_f32 v[122:123], v[122:123], v[200:201]
	v_pk_add_f32 v[200:201], v[112:113], v[216:217]
	v_mul_f32_e32 v197, v125, v125
	v_cvt_pk_bf16_f32 v112, v124, v125
	v_mul_f32_e32 v125, v117, v117
	v_pk_add_f32 v[126:127], v[126:127], v[198:199]
	v_pk_add_f32 v[118:119], v[118:119], v[202:203]
	v_fmac_f32_e32 v197, v124, v124
	v_fmac_f32_e32 v125, v116, v116
	v_fmac_f32_e32 v197, v126, v126
	v_fmac_f32_e32 v125, v118, v118
	v_pk_add_f32 v[120:121], v[120:121], v[212:213]
	v_fmac_f32_e32 v197, v127, v127
	v_fmac_f32_e32 v125, v119, v119
	v_lshlrev_b32_e32 v204, 16, v205
	v_and_b32_e32 v205, 0xffff0000, v205
	v_fmac_f32_e32 v197, v120, v120
	v_fmac_f32_e32 v125, v200, v200
	v_pk_add_f32 v[198:199], v[114:115], v[204:205]
	v_fmac_f32_e32 v197, v121, v121
	v_fmac_f32_e32 v125, v201, v201
	v_fmac_f32_e32 v197, v122, v122
	v_fmac_f32_e32 v125, v198, v198
	v_fmac_f32_e32 v197, v123, v123
	v_fmac_f32_e32 v125, v199, v199
	v_cvt_pk_bf16_f32 v115, v122, v123
	v_add_f32_e32 v122, v197, v125
	ds_bpermute_b32 v123, v196, v122
	v_cvt_pk_bf16_f32 v114, v120, v121
	v_lshl_add_u64 v[120:121], s[76:77], 0, v[208:209]
	v_cvt_pk_bf16_f32 v113, v126, v127
	v_lshl_add_u64 v[120:121], v[120:121], 0, v[206:207]
	global_store_dwordx4 v[120:121], v[112:115], off
	s_waitcnt lgkmcnt(0)
	s_nop 0
	v_add_f32_e32 v112, v122, v123
	ds_bpermute_b32 v113, v195, v112
	v_cvt_pk_bf16_f32 v114, v116, v117
	v_cvt_pk_bf16_f32 v115, v118, v119
	v_cvt_pk_bf16_f32 v116, v200, v201
	v_cvt_pk_bf16_f32 v117, v198, v199
	global_store_dwordx4 v[120:121], v[114:117], off offset:256
	s_and_saveexec_b64 s[22:23], s[0:1]
	s_cbranch_execz .LBB0_847
	s_waitcnt lgkmcnt(0)
	v_add_f32_e32 v114, v112, v113
	s_lshl_b32 s24, s6, 2
	v_lshlrev_b64 v[112:113], 6, v[172:173]
	s_ashr_i32 s25, s24, 31
	v_lshl_add_u64 v[112:113], s[10:11], 0, v[112:113]
	v_lshl_add_u64 v[112:113], s[24:25], 2, v[112:113]
	s_lshl_b32 s8, s37, 2
	v_lshl_add_u64 v[112:113], v[112:113], 0, s[8:9]
	global_store_dword v[112:113], v114, off

; #define PG8_STAGE(bufoff, gbase, voff) do { _Pragma("unroll") for (int _i = 0; _i < 2; ++_i) \
;         __builtin_amdgcn_global_load_lds((const unsigned*)((const char*)(gbase) + (voff)[_i]), (LAS unsigned*)(lds + (bufoff) + ldsw + _i * 8192), 16, 0, 0); } while (0)
; #define PG8_WAIT_V(n) asm volatile("s_waitcnt vmcnt(" #n ")" ::: "memory")
; #define PG8_BAR __builtin_amdgcn_s_barrier()
; template <class Epi>
; __device__ __forceinline__ void gemm_phase(LAS unsigned char* lds, const Gemm g, const StaticOrder& S, const Epi& E) {
;     const int tid = threadIdx.x, wid = __builtin_amdgcn_readfirstlane(tid >> 6), lane = tid & 63, wr = wid >> 2, wc = wid & 3, fr = lane & 15, fq = lane >> 4;
;     const int K = g.K, nt = K / BK, lda = g.lda;
;     unsigned voffA[2], voffB[2];
; #pragma unroll
;     for (int i = 0; i < 2; ++i) { int R, C; stage_rc(tid * 16 + i * 8192, R, C); const int Rb = Epi::PERM ? ((R & ~31) + perm32(R & 31)) : R;
;         voffA[i] = (unsigned)(R * lda + C) * 2u; voffB[i] = (unsigned)(Rb * K + C) * 2u; }
;     const size_t kstep = (size_t)(BK * 2);
;     const size_t hstepA = (size_t)HALF * lda * 2, hstepB = (size_t)HALF * K * 2;
;     const size_t tstepA = 2 * hstepA, tstepB = 2 * hstepB;
;     const unsigned ldsw = (unsigned)wid * 1024u;
;     const int aoff = lds_byte(wr * 64 + fr, fq * 8), boff = lds_byte(wc * 32 + fr, fq * 8);
;     ...
;     PG8_STAGE(PG8_SB(0, 0), cB, voffB); PG8_STAGE(PG8_SA(0, 0), cA, voffA); PG8_STAGE(PG8_SB(0, 1), cB + hstepB, voffB); PG8_STAGE(PG8_SA(0, 1), cA + hstepA, voffA);
;     if (wr == 1) PG8_BAR;
;     PG8_WAIT_V(4); PG8_BAR;
;     PG8_STAGE(PG8_SB(1, 0), cB + kstep, voffB); PG8_STAGE(PG8_SA(1, 0), cA + kstep, voffA); PG8_STAGE(PG8_SB(1, 1), cB + hstepB + kstep, voffB);
;     PG8_WAIT_V(6); PG8_BAR;
.LBB0_918:
	s_lshl_b32 s4, s4, 5
	s_and_b32 s8, s4, 0x60
	s_mov_b64 s[4:5], 0x80
	s_add_i32 m0, s19, 0x18000
	v_lshl_add_u64 v[6:7], v[6:7], 0, s[4:5]
	s_lshl_b32 s6, s1, 13
	s_lshl_b32 s12, s8, 7
	s_waitcnt vmcnt(4)
	s_barrier
	global_load_lds_dwordx4 v[6:7], off
	v_lshl_add_u64 v[4:5], v[4:5], 0, s[4:5]
	s_add_i32 m0, s19, 0x1a000
	s_add_i32 s35, s19, 0x8000
	s_add_i32 s36, s19, 0xa000
	global_load_lds_dwordx4 v[4:5], off
	v_lshl_add_u64 v[2:3], v[2:3], 0, s[4:5]
	s_mov_b32 m0, s35
	s_add_u32 s10, s22, 0x40080
	global_load_lds_dwordx4 v[2:3], off
	v_lshl_add_u64 v[0:1], v[0:1], 0, s[4:5]
	s_mov_b32 m0, s36
	s_addc_u32 s11, s23, 0
	global_load_lds_dwordx4 v[0:1], off
	s_add_i32 m0, s19, 0x1c000
	v_lshl_add_u64 v[0:1], s[10:11], 0, v[132:133]
	global_load_lds_dwordx4 v[0:1], off
	v_lshl_add_u64 v[0:1], s[10:11], 0, v[128:129]
	s_add_i32 m0, s19, 0x1e000
	v_bfe_u32 v2, v152, 4, 2
	global_load_lds_dwordx4 v[0:1], off
	v_and_b32_e32 v1, 15, v152
	v_lshlrev_b32_e32 v0, 4, v2
	v_lshlrev_b32_e32 v3, 2, v152
	v_lshl_or_b32 v170, s1, 6, v1
	v_lshl_or_b32 v1, v1, 6, v0
	v_and_b32_e32 v3, 32, v3
	s_sext_i32_i16 s42, s0
	v_bitop3_b32 v4, v1, s6, v3 bitop3:0xde
	v_lshlrev_b32_e32 v1, 6, v152
	s_movk_i32 s0, 0x3c0
	v_and_or_b32 v1, v1, s0, v0
	v_bitop3_b32 v171, s12, v1, v3 bitop3:0xf6
	v_mov_b32_e32 v1, v133
	v_lshl_add_u64 v[0:1], s[74:75], 0, v[0:1]
	s_mov_b64 s[0:1], 0x3c7c4000
	v_lshl_add_u64 v[136:137], v[0:1], 0, s[0:1]
	v_lshlrev_b32_e32 v0, 8, v152
	v_and_b32_e32 v0, 0x38000, v0
	v_lshlrev_b32_e32 v1, 11, v11
	v_or3_b32 v0, v9, v0, v1
	v_add_u32_e32 v138, v0, v10
	v_lshlrev_b32_e32 v0, 4, v8
	v_and_b32_e32 v0, 0x78000, v0
	s_waitcnt vmcnt(6)
	v_or3_b32 v0, v9, v0, v1
	v_add_u32_e32 v140, v0, v10
	s_add_i32 s38, 0, 0x10000
	s_add_i32 s39, 0, 0x14000
	v_mbcnt_lo_u32_b32 v0, -1, 0
	s_ashr_i32 s37, s92, 31
	v_lshl_or_b32 v172, v2, 3, s8
	v_mov_b32_e32 v139, v133
	v_mov_b32_e32 v141, v133
	v_mov_b64_e32 v[142:143], 0x1400
	v_mov_b64_e32 v[144:145], 0x13ff
	v_add_u32_e32 v173, s38, v171
	v_add_u32_e32 v174, 0, v4
	v_add_u32_e32 v175, s39, v171
	v_mbcnt_hi_u32_b32 v176, -1, v0
	s_movk_i32 s40, 0x2800
	s_mov_b32 s6, 0x3a800000
	s_mov_b32 s8, 0x358637bd
	s_mov_b32 s41, 0x800000
	s_barrier
	s_branch .LBB0_919

; #define PG8_STAGE(bufoff, gbase, voff) do { _Pragma("unroll") for (int _i = 0; _i < 2; ++_i) \
;         __builtin_amdgcn_global_load_lds((const unsigned*)((const char*)(gbase) + (voff)[_i]), (LAS unsigned*)(lds + (bufoff) + ldsw + _i * 8192), 16, 0, 0); } while (0)
; #define PG8_LDA(dst, b, h) do { _Pragma("unroll") for (int m = 0; m < 4; ++m) _Pragma("unroll") for (int k = 0; k < 2; ++k) dst[m][k] = *(const LAS bf16x8*)(lds + PG8_SA(b, h) + aoff + m * 2048 + k * 1024); } while (0)
; #define PG8_LDB(dst, b, h) do { _Pragma("unroll") for (int n = 0; n < 2; ++n) _Pragma("unroll") for (int k = 0; k < 2; ++k) dst[n][k] = *(const LAS bf16x8*)(lds + PG8_SB(b, h) + boff + n * 2048 + k * 1024); } while (0)
; #define PG8_WAIT_V(n) asm volatile("s_waitcnt vmcnt(" #n ")" ::: "memory")
; #define PG8_WAIT_L(n) asm volatile("s_waitcnt lgkmcnt(" #n ")" ::: "memory")
; #define PG8_BAR __builtin_amdgcn_s_barrier()
; #define PG8_SCHED __builtin_amdgcn_sched_barrier(0)
; template <class Epi>
; __device__ __forceinline__ void gemm_phase(LAS unsigned char* lds, const Gemm g, const StaticOrder& S, const Epi& E) {
;     ...
;         const char* nA = has_next ? (const char*)g.A + (size_t)nxt.pm * tstepA : cA; const char* nB = has_next ? (const char*)g.Bt + (size_t)nxt.pn * tstepB : cB;
;         for (int t = 0; t < nt; t += 2) {
;             const bool last = (t == nt - 2);
;             const char* a1 = cA + (size_t)(t + 1) * kstep;
;             const char* a2 = last ? nA : cA + (size_t)(t + 2) * kstep; const char* b2 = last ? nB : cB + (size_t)(t + 2) * kstep;
;             const char* a3 = a2 + kstep; const char* b3 = b2 + kstep;
;             if (last) E.pre(cur, wr, fr, epre);
;             PG8_LDB(B0, 0, 0); PG8_SCHED; PG8_LDA(At, 0, 0); PG8_STAGE(PG8_SA(1, 1), a1 + hstepA, voffA);
;             PG8_WAIT_L(8); PG8_BAR; PG8_WAIT_L(0); PG8_MMA(0, 0, At, B0); PG8_BAR; PG8_SCHED;
;             PG8_LDB(B1, 0, 1); PG8_STAGE(PG8_SB(0, 0), b2, voffB);
;             PG8_BAR; PG8_WAIT_L(0); PG8_MMA(0, 1, At, B1); PG8_BAR;
;             PG8_LDA(At, 0, 1); PG8_STAGE(PG8_SA(0, 0), a2, voffA);
;             PG8_BAR; PG8_WAIT_L(0); PG8_MMA(1, 0, At, B0); PG8_BAR; PG8_SCHED;
;             PG8_STAGE(PG8_SB(0, 1), b2 + hstepB, voffB);
;             PG8_WAIT_V(6); PG8_BAR; PG8_MMA(1, 1, At, B1); PG8_BAR;
.Lkp4_921:
	s_ashr_i32 s13, s12, 31
	v_cmp_lt_i64_e32 vcc, s[14:15], v[142:143]
	s_lshl_b64 s[14:15], s[12:13], 19
	s_add_u32 s14, s76, s14
	s_addc_u32 s15, s77, s15
	s_and_b64 s[16:17], vcc, exec
	s_cselect_b32 s13, s15, s21
	s_cselect_b32 s43, s14, s20
	s_ashr_i32 s11, s10, 31
	s_lshl_b64 s[16:17], s[10:11], 19
	s_add_u32 s16, s9, s16
	s_addc_u32 s17, s26, s17
	s_and_b64 s[24:25], vcc, exec
	s_cselect_b32 s11, s17, s23
	s_cselect_b32 s44, s16, s22
	s_add_u32 s20, s20, 0x40080
	s_addc_u32 s21, s21, 0
	s_add_u32 s45, s22, 0x100
	s_addc_u32 s46, s23, 0
	s_mov_b32 s47, -2
	ds_read_b128 v[146:149], v173
	ds_read_b128 v[154:157], v173 offset:1024
	ds_read_b128 v[158:161], v173 offset:2048
	ds_read_b128 v[162:165], v173 offset:3072
	s_add_u32 s22, s20, 0xfffc0080
	s_addc_u32 s23, s21, -1
	s_cmp_eq_u32 s47, 12
	s_cselect_b32 s25, s13, s23
	s_cselect_b32 s24, s43, s22
	s_cselect_b32 s23, s11, s46
	s_cselect_b32 s22, s44, s45
	v_lshl_add_u64 v[150:151], s[20:21], 0, v[138:139]
	s_add_i32 m0, s19, 0xc000
	ds_read_b128 v[166:169], v174
	ds_read_b128 v[178:181], v174 offset:1024
	ds_read_b128 v[182:185], v174 offset:2048
	ds_read_b128 v[186:189], v174 offset:3072
	ds_read_b128 v[190:193], v174 offset:4096
	ds_read_b128 v[194:197], v174 offset:5120
	ds_read_b128 v[198:201], v174 offset:6144
	ds_read_b128 v[202:205], v174 offset:7168
	global_load_lds_dwordx4 v[150:151], off
	v_lshl_add_u64 v[150:151], s[20:21], 0, v[140:141]
	s_add_i32 m0, s19, 0xe000
	s_nop 0
	global_load_lds_dwordx4 v[150:151], off
	s_waitcnt lgkmcnt(8)
	s_barrier
	s_waitcnt lgkmcnt(0)
	s_setprio 2
	s_waitcnt lgkmcnt(0)
	v_mfma_f32_16x16x32_bf16 v[124:127], v[146:149], v[166:169], 0
	v_mfma_f32_16x16x32_bf16 v[120:123], v[158:161], v[166:169], 0
	v_mfma_f32_16x16x32_bf16 v[112:115], v[146:149], v[182:185], 0
	v_mfma_f32_16x16x32_bf16 v[104:107], v[158:161], v[182:185], 0
	v_mfma_f32_16x16x32_bf16 v[92:95], v[146:149], v[190:193], 0
	v_mfma_f32_16x16x32_bf16 v[88:91], v[158:161], v[190:193], 0
	v_mfma_f32_16x16x32_bf16 v[80:83], v[146:149], v[198:201], 0
	v_mfma_f32_16x16x32_bf16 v[72:75], v[158:161], v[198:201], 0
	v_mfma_f32_16x16x32_bf16 v[124:127], v[154:157], v[178:181], v[124:127]
	v_mfma_f32_16x16x32_bf16 v[120:123], v[162:165], v[178:181], v[120:123]
	v_mfma_f32_16x16x32_bf16 v[112:115], v[154:157], v[186:189], v[112:115]
	v_mfma_f32_16x16x32_bf16 v[104:107], v[162:165], v[186:189], v[104:107]
	v_mfma_f32_16x16x32_bf16 v[92:95], v[154:157], v[194:197], v[92:95]
	v_mfma_f32_16x16x32_bf16 v[88:91], v[162:165], v[194:197], v[88:91]
	v_mfma_f32_16x16x32_bf16 v[80:83], v[154:157], v[202:205], v[80:83]
	v_mfma_f32_16x16x32_bf16 v[72:75], v[162:165], v[202:205], v[72:75]
	s_setprio 1
	s_barrier
	s_add_i32 s48, s38, s27
	v_lshl_add_u64 v[150:151], s[22:23], 0, v[132:133]
	s_mov_b32 m0, s48
	ds_read_b128 v[206:209], v175
	ds_read_b128 v[210:213], v175 offset:1024
	ds_read_b128 v[214:217], v175 offset:2048
	ds_read_b128 v[218:221], v175 offset:3072
	global_load_lds_dwordx4 v[150:151], off
	v_lshl_add_u64 v[222:223], s[22:23], 0, v[128:129]
	s_add_i32 m0, s48, 0x2000
	s_nop 0
	global_load_lds_dwordx4 v[222:223], off
	s_barrier
	s_waitcnt lgkmcnt(0)
	s_setprio 2
	s_waitcnt lgkmcnt(0)
	v_mfma_f32_16x16x32_bf16 v[116:119], v[206:209], v[166:169], 0
	v_mfma_f32_16x16x32_bf16 v[108:111], v[214:217], v[166:169], 0
	v_mfma_f32_16x16x32_bf16 v[100:103], v[206:209], v[182:185], 0
	v_mfma_f32_16x16x32_bf16 v[96:99], v[214:217], v[182:185], 0
	v_mfma_f32_16x16x32_bf16 v[84:87], v[206:209], v[190:193], 0
	v_mfma_f32_16x16x32_bf16 v[76:79], v[214:217], v[190:193], 0
	v_mfma_f32_16x16x32_bf16 v[68:71], v[206:209], v[198:201], 0
	v_mfma_f32_16x16x32_bf16 v[64:67], v[214:217], v[198:201], 0
	v_mfma_f32_16x16x32_bf16 v[116:119], v[210:213], v[178:181], v[116:119]
	v_mfma_f32_16x16x32_bf16 v[108:111], v[218:221], v[178:181], v[108:111]
	v_mfma_f32_16x16x32_bf16 v[100:103], v[210:213], v[186:189], v[100:103]
	v_mfma_f32_16x16x32_bf16 v[96:99], v[218:221], v[186:189], v[96:99]
	v_mfma_f32_16x16x32_bf16 v[84:87], v[210:213], v[194:197], v[84:87]
	v_mfma_f32_16x16x32_bf16 v[76:79], v[218:221], v[194:197], v[76:79]
	v_mfma_f32_16x16x32_bf16 v[68:71], v[210:213], v[202:205], v[68:71]
	v_mfma_f32_16x16x32_bf16 v[64:67], v[218:221], v[202:205], v[64:67]
	s_setprio 1
	s_mov_b32 m0, s19
	v_lshl_add_u64 v[224:225], s[24:25], 0, v[134:135]
	s_barrier
	ds_read_b128 v[166:169], v174 offset:16384
	ds_read_b128 v[178:181], v174 offset:17408
	ds_read_b128 v[182:185], v174 offset:18432
	ds_read_b128 v[186:189], v174 offset:19456
	ds_read_b128 v[190:193], v174 offset:20480
	ds_read_b128 v[194:197], v174 offset:21504
	ds_read_b128 v[198:201], v174 offset:22528
	ds_read_b128 v[202:205], v174 offset:23552
	global_load_lds_dwordx4 v[224:225], off
	v_lshl_add_u64 v[226:227], s[24:25], 0, v[130:131]
	s_mov_b32 m0, s30
	s_nop 0
	global_load_lds_dwordx4 v[226:227], off
	s_barrier
	s_waitcnt lgkmcnt(0)
	s_setprio 2
	s_waitcnt lgkmcnt(0)
	v_mfma_f32_16x16x32_bf16 v[60:63], v[146:149], v[166:169], 0
	v_mfma_f32_16x16x32_bf16 v[56:59], v[158:161], v[166:169], 0
	v_mfma_f32_16x16x32_bf16 v[48:51], v[146:149], v[182:185], 0
	v_mfma_f32_16x16x32_bf16 v[40:43], v[158:161], v[182:185], 0
	v_mfma_f32_16x16x32_bf16 v[32:35], v[146:149], v[190:193], 0
	v_mfma_f32_16x16x32_bf16 v[24:27], v[158:161], v[190:193], 0
	v_mfma_f32_16x16x32_bf16 v[16:19], v[146:149], v[198:201], 0
	v_mfma_f32_16x16x32_bf16 v[8:11], v[158:161], v[198:201], 0
	v_mfma_f32_16x16x32_bf16 v[60:63], v[154:157], v[178:181], v[60:63]
	v_mfma_f32_16x16x32_bf16 v[56:59], v[162:165], v[178:181], v[56:59]
	v_mfma_f32_16x16x32_bf16 v[48:51], v[154:157], v[186:189], v[48:51]
	v_mfma_f32_16x16x32_bf16 v[40:43], v[162:165], v[186:189], v[40:43]
	v_mfma_f32_16x16x32_bf16 v[32:35], v[154:157], v[194:197], v[32:35]
	v_mfma_f32_16x16x32_bf16 v[24:27], v[162:165], v[194:197], v[24:27]
	v_mfma_f32_16x16x32_bf16 v[16:19], v[154:157], v[202:205], v[16:19]
	v_mfma_f32_16x16x32_bf16 v[8:11], v[162:165], v[202:205], v[8:11]
	s_setprio 1
	s_barrier
; #define PG8_STAGE(bufoff, gbase, voff) do { _Pragma("unroll") for (int _i = 0; _i < 2; ++_i) \
;         __builtin_amdgcn_global_load_lds((const unsigned*)((const char*)(gbase) + (voff)[_i]), (LAS unsigned*)(lds + (bufoff) + ldsw + _i * 8192), 16, 0, 0); } while (0)
; #define PG8_LDA(dst, b, h) do { _Pragma("unroll") for (int m = 0; m < 4; ++m) _Pragma("unroll") for (int k = 0; k < 2; ++k) dst[m][k] = *(const LAS bf16x8*)(lds + PG8_SA(b, h) + aoff + m * 2048 + k * 1024); } while (0)
; #define PG8_LDB(dst, b, h) do { _Pragma("unroll") for (int n = 0; n < 2; ++n) _Pragma("unroll") for (int k = 0; k < 2; ++k) dst[n][k] = *(const LAS bf16x8*)(lds + PG8_SB(b, h) + boff + n * 2048 + k * 1024); } while (0)
; #define PG8_MMA(ai, bj, At, Bt) do { __builtin_amdgcn_s_setprio(1); _Pragma("unroll") for (int m = 0; m < 4; ++m) _Pragma("unroll") for (int n = 0; n < 2; ++n) _Pragma("unroll") for (int k = 0; k < 2; ++k) \
;         acc[ai][bj][m][n] = __builtin_amdgcn_mfma_f32_16x16x32_bf16(Bt[n][k], At[m][k], acc[ai][bj][m][n], 0, 0, 0); __builtin_amdgcn_s_setprio(0); } while (0)
; #define PG8_WAIT_V(n) asm volatile("s_waitcnt vmcnt(" #n ")" ::: "memory")
; #define PG8_WAIT_L(n) asm volatile("s_waitcnt lgkmcnt(" #n ")" ::: "memory")
; #define PG8_BAR __builtin_amdgcn_s_barrier()
; #define PG8_SCHED __builtin_amdgcn_sched_barrier(0)
; template <class Epi>
; __device__ __forceinline__ void gemm_phase(LAS unsigned char* lds, const Gemm g, const StaticOrder& S, const Epi& E) {
;     ...
;             PG8_STAGE(PG8_SB(0, 1), b2 + hstepB, voffB);
;             PG8_WAIT_V(6); PG8_BAR; PG8_MMA(1, 1, At, B1); PG8_BAR;
;             PG8_LDB(B0, 1, 0); PG8_SCHED; PG8_LDA(At, 1, 0); PG8_STAGE(PG8_SA(0, 1), a2 + hstepA, voffA);
;             PG8_WAIT_L(8); PG8_BAR; PG8_WAIT_L(0); PG8_MMA(0, 0, At, B0); PG8_BAR; PG8_SCHED;
;             PG8_LDB(B1, 1, 1); PG8_STAGE(PG8_SB(1, 0), b3, voffB);
;             PG8_BAR; PG8_WAIT_L(0); PG8_MMA(0, 1, At, B1); PG8_BAR;
;             PG8_LDA(At, 1, 1); PG8_STAGE(PG8_SA(1, 0), a3, voffA);
	s_add_u32 s48, s22, 0x40000
	s_addc_u32 s49, s23, 0
	s_add_i32 s50, s39, s27
	v_lshl_add_u64 v[146:147], s[48:49], 0, v[132:133]
	s_mov_b32 m0, s50
	s_nop 0
	global_load_lds_dwordx4 v[146:147], off
	v_lshl_add_u64 v[146:147], s[48:49], 0, v[128:129]
	s_add_i32 m0, s50, 0x2000
	s_nop 0
	global_load_lds_dwordx4 v[146:147], off
	s_waitcnt vmcnt(6)
	s_barrier
	s_setprio 2
	v_mfma_f32_16x16x32_bf16 v[52:55], v[206:209], v[166:169], 0
	v_mfma_f32_16x16x32_bf16 v[44:47], v[214:217], v[166:169], 0
	v_mfma_f32_16x16x32_bf16 v[36:39], v[206:209], v[182:185], 0
	v_mfma_f32_16x16x32_bf16 v[28:31], v[214:217], v[182:185], 0
	v_mfma_f32_16x16x32_bf16 v[20:23], v[206:209], v[190:193], 0
	v_mfma_f32_16x16x32_bf16 v[12:15], v[214:217], v[190:193], 0
	v_mfma_f32_16x16x32_bf16 v[4:7], v[206:209], v[198:201], 0
	v_mfma_f32_16x16x32_bf16 v[0:3], v[214:217], v[198:201], 0
	v_mfma_f32_16x16x32_bf16 v[52:55], v[210:213], v[178:181], v[52:55]
	v_mfma_f32_16x16x32_bf16 v[44:47], v[218:221], v[178:181], v[44:47]
	v_mfma_f32_16x16x32_bf16 v[36:39], v[210:213], v[186:189], v[36:39]
	v_mfma_f32_16x16x32_bf16 v[28:31], v[218:221], v[186:189], v[28:31]
	v_mfma_f32_16x16x32_bf16 v[20:23], v[210:213], v[194:197], v[20:23]
	v_mfma_f32_16x16x32_bf16 v[12:15], v[218:221], v[194:197], v[12:15]
	v_mfma_f32_16x16x32_bf16 v[4:7], v[210:213], v[202:205], v[4:7]
	v_mfma_f32_16x16x32_bf16 v[0:3], v[218:221], v[202:205], v[0:3]
	s_setprio 1
	s_add_i32 s48, 0, 0x18000
	v_add_u32_e32 v162, s48, v171
	s_barrier
	ds_read_b128 v[146:149], v162
	ds_read_b128 v[154:157], v162 offset:1024
	ds_read_b128 v[158:161], v162 offset:2048
	ds_read_b128 v[162:165], v162 offset:3072
	s_add_u32 s24, s24, 0x40000
	s_addc_u32 s25, s25, 0
	s_mov_b32 m0, s31
	v_lshl_add_u64 v[206:207], s[24:25], 0, v[134:135]
	ds_read_b128 v[166:169], v174 offset:32768
	ds_read_b128 v[178:181], v174 offset:33792
	ds_read_b128 v[182:185], v174 offset:34816
	ds_read_b128 v[186:189], v174 offset:35840
	ds_read_b128 v[190:193], v174 offset:36864
	ds_read_b128 v[194:197], v174 offset:37888
	ds_read_b128 v[198:201], v174 offset:38912
	ds_read_b128 v[202:205], v174 offset:39936
	global_load_lds_dwordx4 v[206:207], off
	v_lshl_add_u64 v[206:207], s[24:25], 0, v[130:131]
	s_mov_b32 m0, s33
	s_nop 0
	global_load_lds_dwordx4 v[206:207], off
	s_waitcnt lgkmcnt(8)
	s_barrier
	s_waitcnt lgkmcnt(0)
	s_setprio 2
	s_waitcnt lgkmcnt(0)
	v_mfma_f32_16x16x32_bf16 v[124:127], v[146:149], v[166:169], v[124:127]
	v_mfma_f32_16x16x32_bf16 v[120:123], v[158:161], v[166:169], v[120:123]
	v_mfma_f32_16x16x32_bf16 v[112:115], v[146:149], v[182:185], v[112:115]
	v_mfma_f32_16x16x32_bf16 v[104:107], v[158:161], v[182:185], v[104:107]
	v_mfma_f32_16x16x32_bf16 v[92:95], v[146:149], v[190:193], v[92:95]
	v_mfma_f32_16x16x32_bf16 v[88:91], v[158:161], v[190:193], v[88:91]
	v_mfma_f32_16x16x32_bf16 v[80:83], v[146:149], v[198:201], v[80:83]
	v_mfma_f32_16x16x32_bf16 v[72:75], v[158:161], v[198:201], v[72:75]
	v_mfma_f32_16x16x32_bf16 v[124:127], v[154:157], v[178:181], v[124:127]
	v_mfma_f32_16x16x32_bf16 v[120:123], v[162:165], v[178:181], v[120:123]
	v_mfma_f32_16x16x32_bf16 v[112:115], v[154:157], v[186:189], v[112:115]
	v_mfma_f32_16x16x32_bf16 v[104:107], v[162:165], v[186:189], v[104:107]
	v_mfma_f32_16x16x32_bf16 v[92:95], v[154:157], v[194:197], v[92:95]
	v_mfma_f32_16x16x32_bf16 v[88:91], v[162:165], v[194:197], v[88:91]
	v_mfma_f32_16x16x32_bf16 v[80:83], v[154:157], v[202:205], v[80:83]
	v_mfma_f32_16x16x32_bf16 v[72:75], v[162:165], v[202:205], v[72:75]
	s_setprio 1
	s_barrier
	s_add_i32 s24, 0, 0x1c000
	s_add_i32 s25, s48, s27
	v_add_u32_e32 v177, s24, v171
	v_lshl_add_u64 v[150:151], v[150:151], 0, s[4:5]
	s_mov_b32 m0, s25
	ds_read_b128 v[206:209], v177
	ds_read_b128 v[210:213], v177 offset:1024
	ds_read_b128 v[214:217], v177 offset:2048
	ds_read_b128 v[218:221], v177 offset:3072
	global_load_lds_dwordx4 v[150:151], off
	v_lshl_add_u64 v[150:151], v[222:223], 0, s[4:5]
	s_add_i32 m0, s25, 0x2000
	s_nop 0
	global_load_lds_dwordx4 v[150:151], off
	s_barrier
	s_waitcnt lgkmcnt(0)
	s_setprio 2
	s_waitcnt lgkmcnt(0)
	v_mfma_f32_16x16x32_bf16 v[116:119], v[206:209], v[166:169], v[116:119]
	v_mfma_f32_16x16x32_bf16 v[108:111], v[214:217], v[166:169], v[108:111]
	v_mfma_f32_16x16x32_bf16 v[100:103], v[206:209], v[182:185], v[100:103]
	v_mfma_f32_16x16x32_bf16 v[96:99], v[214:217], v[182:185], v[96:99]
	v_mfma_f32_16x16x32_bf16 v[84:87], v[206:209], v[190:193], v[84:87]
	v_mfma_f32_16x16x32_bf16 v[76:79], v[214:217], v[190:193], v[76:79]
	v_mfma_f32_16x16x32_bf16 v[68:71], v[206:209], v[198:201], v[68:71]
	v_mfma_f32_16x16x32_bf16 v[64:67], v[214:217], v[198:201], v[64:67]
	v_mfma_f32_16x16x32_bf16 v[116:119], v[210:213], v[178:181], v[116:119]
	v_mfma_f32_16x16x32_bf16 v[108:111], v[218:221], v[178:181], v[108:111]
	v_mfma_f32_16x16x32_bf16 v[100:103], v[210:213], v[186:189], v[100:103]
	v_mfma_f32_16x16x32_bf16 v[96:99], v[218:221], v[186:189], v[96:99]
	v_mfma_f32_16x16x32_bf16 v[84:87], v[210:213], v[194:197], v[84:87]
	v_mfma_f32_16x16x32_bf16 v[76:79], v[218:221], v[194:197], v[76:79]
	v_mfma_f32_16x16x32_bf16 v[68:71], v[210:213], v[202:205], v[68:71]
	v_mfma_f32_16x16x32_bf16 v[64:67], v[218:221], v[202:205], v[64:67]
	s_setprio 1
	s_mov_b32 m0, s35
	v_lshl_add_u64 v[150:151], v[224:225], 0, s[4:5]
	s_barrier
	ds_read_b128 v[166:169], v174 offset:49152
	ds_read_b128 v[178:181], v174 offset:50176
	ds_read_b128 v[182:185], v174 offset:51200
	ds_read_b128 v[186:189], v174 offset:52224
	ds_read_b128 v[190:193], v174 offset:53248
	ds_read_b128 v[194:197], v174 offset:54272
	ds_read_b128 v[198:201], v174 offset:55296
	ds_read_b128 v[202:205], v174 offset:56320
	global_load_lds_dwordx4 v[150:151], off
	v_lshl_add_u64 v[150:151], v[226:227], 0, s[4:5]
	s_mov_b32 m0, s36
	s_nop 0
	global_load_lds_dwordx4 v[150:151], off
	s_barrier
; #define PG8_STAGE(bufoff, gbase, voff) do { _Pragma("unroll") for (int _i = 0; _i < 2; ++_i) \
;         __builtin_amdgcn_global_load_lds((const unsigned*)((const char*)(gbase) + (voff)[_i]), (LAS unsigned*)(lds + (bufoff) + ldsw + _i * 8192), 16, 0, 0); } while (0)
; #define PG8_LDA(dst, b, h) do { _Pragma("unroll") for (int m = 0; m < 4; ++m) _Pragma("unroll") for (int k = 0; k < 2; ++k) dst[m][k] = *(const LAS bf16x8*)(lds + PG8_SA(b, h) + aoff + m * 2048 + k * 1024); } while (0)
; #define PG8_LDB(dst, b, h) do { _Pragma("unroll") for (int n = 0; n < 2; ++n) _Pragma("unroll") for (int k = 0; k < 2; ++k) dst[n][k] = *(const LAS bf16x8*)(lds + PG8_SB(b, h) + boff + n * 2048 + k * 1024); } while (0)
; #define PG8_MMA(ai, bj, At, Bt) do { __builtin_amdgcn_s_setprio(1); _Pragma("unroll") for (int m = 0; m < 4; ++m) _Pragma("unroll") for (int n = 0; n < 2; ++n) _Pragma("unroll") for (int k = 0; k < 2; ++k) \
;         acc[ai][bj][m][n] = __builtin_amdgcn_mfma_f32_16x16x32_bf16(Bt[n][k], At[m][k], acc[ai][bj][m][n], 0, 0, 0); __builtin_amdgcn_s_setprio(0); } while (0)
; #define PG8_WAIT_V(n) asm volatile("s_waitcnt vmcnt(" #n ")" ::: "memory")
; #define PG8_WAIT_L(n) asm volatile("s_waitcnt lgkmcnt(" #n ")" ::: "memory")
; #define PG8_BAR __builtin_amdgcn_s_barrier()
; #define PG8_SCHED __builtin_amdgcn_sched_barrier(0)
; template <class Epi>
; __device__ __forceinline__ void gemm_phase(LAS unsigned char* lds, const Gemm g, const StaticOrder& S, const Epi& E) {
;     ...
;             PG8_LDB(B0, 0, 0); PG8_SCHED; PG8_LDA(At, 0, 0); PG8_STAGE(PG8_SA(1, 1), a1 + hstepA, voffA);
;             PG8_WAIT_L(8); PG8_BAR; PG8_WAIT_L(0); PG8_MMA(0, 0, At, B0); PG8_BAR; PG8_SCHED;
;             PG8_LDB(B1, 0, 1); PG8_STAGE(PG8_SB(0, 0), b2, voffB);
;             PG8_BAR; PG8_WAIT_L(0); PG8_MMA(0, 1, At, B1); PG8_BAR;
;     ...
;             PG8_BAR; PG8_WAIT_L(0); PG8_MMA(1, 0, At, B0); PG8_BAR; PG8_SCHED;
;             PG8_STAGE(PG8_SB(1, 1), b3 + hstepB, voffB);
;             PG8_WAIT_V(6); PG8_BAR; PG8_MMA(1, 1, At, B1); PG8_BAR;
	s_waitcnt lgkmcnt(0)
	s_setprio 2
	s_waitcnt lgkmcnt(0)
	v_mfma_f32_16x16x32_bf16 v[60:63], v[146:149], v[166:169], v[60:63]
	v_mfma_f32_16x16x32_bf16 v[56:59], v[158:161], v[166:169], v[56:59]
	v_mfma_f32_16x16x32_bf16 v[48:51], v[146:149], v[182:185], v[48:51]
	v_mfma_f32_16x16x32_bf16 v[40:43], v[158:161], v[182:185], v[40:43]
	v_mfma_f32_16x16x32_bf16 v[32:35], v[146:149], v[190:193], v[32:35]
	v_mfma_f32_16x16x32_bf16 v[24:27], v[158:161], v[190:193], v[24:27]
	v_mfma_f32_16x16x32_bf16 v[16:19], v[146:149], v[198:201], v[16:19]
	v_mfma_f32_16x16x32_bf16 v[8:11], v[158:161], v[198:201], v[8:11]
	v_mfma_f32_16x16x32_bf16 v[60:63], v[154:157], v[178:181], v[60:63]
	v_mfma_f32_16x16x32_bf16 v[56:59], v[162:165], v[178:181], v[56:59]
	v_mfma_f32_16x16x32_bf16 v[48:51], v[154:157], v[186:189], v[48:51]
	v_mfma_f32_16x16x32_bf16 v[40:43], v[162:165], v[186:189], v[40:43]
	v_mfma_f32_16x16x32_bf16 v[32:35], v[154:157], v[194:197], v[32:35]
	v_mfma_f32_16x16x32_bf16 v[24:27], v[162:165], v[194:197], v[24:27]
	v_mfma_f32_16x16x32_bf16 v[16:19], v[154:157], v[202:205], v[16:19]
	v_mfma_f32_16x16x32_bf16 v[8:11], v[162:165], v[202:205], v[8:11]
	s_setprio 1
	s_barrier
	s_add_u32 s22, s22, 0x40080
	s_addc_u32 s23, s23, 0
	s_add_i32 s24, s24, s27
	v_lshl_add_u64 v[146:147], s[22:23], 0, v[132:133]
	s_mov_b32 m0, s24
	s_nop 0
	global_load_lds_dwordx4 v[146:147], off
	v_lshl_add_u64 v[146:147], s[22:23], 0, v[128:129]
	s_add_i32 m0, s24, 0x2000
	s_nop 0
	global_load_lds_dwordx4 v[146:147], off
	s_waitcnt vmcnt(6)
	s_barrier
	s_setprio 2
	v_mfma_f32_16x16x32_bf16 v[52:55], v[206:209], v[166:169], v[52:55]
	v_mfma_f32_16x16x32_bf16 v[44:47], v[214:217], v[166:169], v[44:47]
	v_mfma_f32_16x16x32_bf16 v[36:39], v[206:209], v[182:185], v[36:39]
	v_mfma_f32_16x16x32_bf16 v[28:31], v[214:217], v[182:185], v[28:31]
	v_mfma_f32_16x16x32_bf16 v[20:23], v[206:209], v[190:193], v[20:23]
	v_mfma_f32_16x16x32_bf16 v[12:15], v[214:217], v[190:193], v[12:15]
	v_mfma_f32_16x16x32_bf16 v[4:7], v[206:209], v[198:201], v[4:7]
	v_mfma_f32_16x16x32_bf16 v[0:3], v[214:217], v[198:201], v[0:3]
	v_mfma_f32_16x16x32_bf16 v[52:55], v[210:213], v[178:181], v[52:55]
	v_mfma_f32_16x16x32_bf16 v[44:47], v[218:221], v[178:181], v[44:47]
	v_mfma_f32_16x16x32_bf16 v[36:39], v[210:213], v[186:189], v[36:39]
	v_mfma_f32_16x16x32_bf16 v[28:31], v[218:221], v[186:189], v[28:31]
	v_mfma_f32_16x16x32_bf16 v[20:23], v[210:213], v[194:197], v[20:23]
	v_mfma_f32_16x16x32_bf16 v[12:15], v[218:221], v[194:197], v[12:15]
	v_mfma_f32_16x16x32_bf16 v[4:7], v[210:213], v[202:205], v[4:7]
	v_mfma_f32_16x16x32_bf16 v[0:3], v[218:221], v[202:205], v[0:3]
	s_setprio 1
	s_add_i32 s47, s47, 2
	s_add_u32 s20, s20, 0x100
	s_addc_u32 s21, s21, 0
	s_add_u32 s45, s45, 0x100
	s_addc_u32 s46, s46, 0
	s_cmp_gt_u32 s47, 13
	s_barrier
.Lkp4_922:
	ds_read_b128 v[146:149], v173
	ds_read_b128 v[154:157], v173 offset:1024
	ds_read_b128 v[158:161], v173 offset:2048
	ds_read_b128 v[162:165], v173 offset:3072
	s_add_u32 s22, s20, 0xfffc0080
	s_addc_u32 s23, s21, -1
	s_cmp_eq_u32 s47, 12
	s_cselect_b32 s25, s13, s23
	s_cselect_b32 s24, s43, s22
	s_cselect_b32 s23, s11, s46
	s_cselect_b32 s22, s44, s45
	v_lshl_add_u64 v[150:151], s[20:21], 0, v[138:139]
	s_add_i32 m0, s19, 0xc000
	ds_read_b128 v[166:169], v174
	ds_read_b128 v[178:181], v174 offset:1024
	ds_read_b128 v[182:185], v174 offset:2048
	ds_read_b128 v[186:189], v174 offset:3072
	ds_read_b128 v[190:193], v174 offset:4096
	ds_read_b128 v[194:197], v174 offset:5120
	ds_read_b128 v[198:201], v174 offset:6144
	ds_read_b128 v[202:205], v174 offset:7168
	global_load_lds_dwordx4 v[150:151], off
	v_lshl_add_u64 v[150:151], s[20:21], 0, v[140:141]
	s_add_i32 m0, s19, 0xe000
	s_nop 0
	global_load_lds_dwordx4 v[150:151], off
	s_waitcnt lgkmcnt(8)
	s_barrier
	s_waitcnt lgkmcnt(0)
	s_setprio 2
	s_waitcnt lgkmcnt(0)
	v_mfma_f32_16x16x32_bf16 v[124:127], v[146:149], v[166:169], v[124:127]
	v_mfma_f32_16x16x32_bf16 v[120:123], v[158:161], v[166:169], v[120:123]
	v_mfma_f32_16x16x32_bf16 v[112:115], v[146:149], v[182:185], v[112:115]
	v_mfma_f32_16x16x32_bf16 v[104:107], v[158:161], v[182:185], v[104:107]
	v_mfma_f32_16x16x32_bf16 v[92:95], v[146:149], v[190:193], v[92:95]
	v_mfma_f32_16x16x32_bf16 v[88:91], v[158:161], v[190:193], v[88:91]
	v_mfma_f32_16x16x32_bf16 v[80:83], v[146:149], v[198:201], v[80:83]
	v_mfma_f32_16x16x32_bf16 v[72:75], v[158:161], v[198:201], v[72:75]
	v_mfma_f32_16x16x32_bf16 v[124:127], v[154:157], v[178:181], v[124:127]
	v_mfma_f32_16x16x32_bf16 v[120:123], v[162:165], v[178:181], v[120:123]
	v_mfma_f32_16x16x32_bf16 v[112:115], v[154:157], v[186:189], v[112:115]
	v_mfma_f32_16x16x32_bf16 v[104:107], v[162:165], v[186:189], v[104:107]
	v_mfma_f32_16x16x32_bf16 v[92:95], v[154:157], v[194:197], v[92:95]
	v_mfma_f32_16x16x32_bf16 v[88:91], v[162:165], v[194:197], v[88:91]
	v_mfma_f32_16x16x32_bf16 v[80:83], v[154:157], v[202:205], v[80:83]
	v_mfma_f32_16x16x32_bf16 v[72:75], v[162:165], v[202:205], v[72:75]
	s_setprio 1
	s_barrier
	s_add_i32 s48, s38, s27
	v_lshl_add_u64 v[150:151], s[22:23], 0, v[132:133]
	s_mov_b32 m0, s48
	ds_read_b128 v[206:209], v175
	ds_read_b128 v[210:213], v175 offset:1024
	ds_read_b128 v[214:217], v175 offset:2048
	ds_read_b128 v[218:221], v175 offset:3072
	global_load_lds_dwordx4 v[150:151], off
	v_lshl_add_u64 v[222:223], s[22:23], 0, v[128:129]
	s_add_i32 m0, s48, 0x2000
	s_nop 0
	global_load_lds_dwordx4 v[222:223], off
	s_barrier
; #define PG8_STAGE(bufoff, gbase, voff) do { _Pragma("unroll") for (int _i = 0; _i < 2; ++_i) \
;         __builtin_amdgcn_global_load_lds((const unsigned*)((const char*)(gbase) + (voff)[_i]), (LAS unsigned*)(lds + (bufoff) + ldsw + _i * 8192), 16, 0, 0); } while (0)
; #define PG8_LDA(dst, b, h) do { _Pragma("unroll") for (int m = 0; m < 4; ++m) _Pragma("unroll") for (int k = 0; k < 2; ++k) dst[m][k] = *(const LAS bf16x8*)(lds + PG8_SA(b, h) + aoff + m * 2048 + k * 1024); } while (0)
; #define PG8_LDB(dst, b, h) do { _Pragma("unroll") for (int n = 0; n < 2; ++n) _Pragma("unroll") for (int k = 0; k < 2; ++k) dst[n][k] = *(const LAS bf16x8*)(lds + PG8_SB(b, h) + boff + n * 2048 + k * 1024); } while (0)
; #define PG8_MMA(ai, bj, At, Bt) do { __builtin_amdgcn_s_setprio(1); _Pragma("unroll") for (int m = 0; m < 4; ++m) _Pragma("unroll") for (int n = 0; n < 2; ++n) _Pragma("unroll") for (int k = 0; k < 2; ++k) \
;         acc[ai][bj][m][n] = __builtin_amdgcn_mfma_f32_16x16x32_bf16(Bt[n][k], At[m][k], acc[ai][bj][m][n], 0, 0, 0); __builtin_amdgcn_s_setprio(0); } while (0)
; #define PG8_WAIT_V(n) asm volatile("s_waitcnt vmcnt(" #n ")" ::: "memory")
; #define PG8_WAIT_L(n) asm volatile("s_waitcnt lgkmcnt(" #n ")" ::: "memory")
; #define PG8_BAR __builtin_amdgcn_s_barrier()
; #define PG8_SCHED __builtin_amdgcn_sched_barrier(0)
; template <class Epi>
; __device__ __forceinline__ void gemm_phase(LAS unsigned char* lds, const Gemm g, const StaticOrder& S, const Epi& E) {
;     ...
;             PG8_BAR; PG8_WAIT_L(0); PG8_MMA(0, 1, At, B1); PG8_BAR;
;             PG8_LDA(At, 0, 1); PG8_STAGE(PG8_SA(0, 0), a2, voffA);
;             PG8_BAR; PG8_WAIT_L(0); PG8_MMA(1, 0, At, B0); PG8_BAR; PG8_SCHED;
;             PG8_STAGE(PG8_SB(0, 1), b2 + hstepB, voffB);
;             PG8_WAIT_V(6); PG8_BAR; PG8_MMA(1, 1, At, B1); PG8_BAR;
;             PG8_LDB(B0, 1, 0); PG8_SCHED; PG8_LDA(At, 1, 0); PG8_STAGE(PG8_SA(0, 1), a2 + hstepA, voffA);
;             PG8_WAIT_L(8); PG8_BAR; PG8_WAIT_L(0); PG8_MMA(0, 0, At, B0); PG8_BAR; PG8_SCHED;
;             PG8_LDB(B1, 1, 1); PG8_STAGE(PG8_SB(1, 0), b3, voffB);
;             PG8_BAR; PG8_WAIT_L(0); PG8_MMA(0, 1, At, B1); PG8_BAR;
;             PG8_LDA(At, 1, 1); PG8_STAGE(PG8_SA(1, 0), a3, voffA);
	s_waitcnt lgkmcnt(0)
	s_setprio 2
	s_waitcnt lgkmcnt(0)
	v_mfma_f32_16x16x32_bf16 v[116:119], v[206:209], v[166:169], v[116:119]
	v_mfma_f32_16x16x32_bf16 v[108:111], v[214:217], v[166:169], v[108:111]
	v_mfma_f32_16x16x32_bf16 v[100:103], v[206:209], v[182:185], v[100:103]
	v_mfma_f32_16x16x32_bf16 v[96:99], v[214:217], v[182:185], v[96:99]
	v_mfma_f32_16x16x32_bf16 v[84:87], v[206:209], v[190:193], v[84:87]
	v_mfma_f32_16x16x32_bf16 v[76:79], v[214:217], v[190:193], v[76:79]
	v_mfma_f32_16x16x32_bf16 v[68:71], v[206:209], v[198:201], v[68:71]
	v_mfma_f32_16x16x32_bf16 v[64:67], v[214:217], v[198:201], v[64:67]
	v_mfma_f32_16x16x32_bf16 v[116:119], v[210:213], v[178:181], v[116:119]
	v_mfma_f32_16x16x32_bf16 v[108:111], v[218:221], v[178:181], v[108:111]
	v_mfma_f32_16x16x32_bf16 v[100:103], v[210:213], v[186:189], v[100:103]
	v_mfma_f32_16x16x32_bf16 v[96:99], v[218:221], v[186:189], v[96:99]
	v_mfma_f32_16x16x32_bf16 v[84:87], v[210:213], v[194:197], v[84:87]
	v_mfma_f32_16x16x32_bf16 v[76:79], v[218:221], v[194:197], v[76:79]
	v_mfma_f32_16x16x32_bf16 v[68:71], v[210:213], v[202:205], v[68:71]
	v_mfma_f32_16x16x32_bf16 v[64:67], v[218:221], v[202:205], v[64:67]
	s_setprio 1
	s_mov_b32 m0, s19
	v_lshl_add_u64 v[224:225], s[24:25], 0, v[134:135]
	s_barrier
	ds_read_b128 v[166:169], v174 offset:16384
	ds_read_b128 v[178:181], v174 offset:17408
	ds_read_b128 v[182:185], v174 offset:18432
	ds_read_b128 v[186:189], v174 offset:19456
	ds_read_b128 v[190:193], v174 offset:20480
	ds_read_b128 v[194:197], v174 offset:21504
	ds_read_b128 v[198:201], v174 offset:22528
	ds_read_b128 v[202:205], v174 offset:23552
	global_load_lds_dwordx4 v[224:225], off
	v_lshl_add_u64 v[226:227], s[24:25], 0, v[130:131]
	s_mov_b32 m0, s30
	s_nop 0
	global_load_lds_dwordx4 v[226:227], off
	s_barrier
	s_waitcnt lgkmcnt(0)
	s_setprio 2
	s_waitcnt lgkmcnt(0)
	v_mfma_f32_16x16x32_bf16 v[60:63], v[146:149], v[166:169], v[60:63]
	v_mfma_f32_16x16x32_bf16 v[56:59], v[158:161], v[166:169], v[56:59]
	v_mfma_f32_16x16x32_bf16 v[48:51], v[146:149], v[182:185], v[48:51]
	v_mfma_f32_16x16x32_bf16 v[40:43], v[158:161], v[182:185], v[40:43]
	v_mfma_f32_16x16x32_bf16 v[32:35], v[146:149], v[190:193], v[32:35]
	v_mfma_f32_16x16x32_bf16 v[24:27], v[158:161], v[190:193], v[24:27]
	v_mfma_f32_16x16x32_bf16 v[16:19], v[146:149], v[198:201], v[16:19]
	v_mfma_f32_16x16x32_bf16 v[8:11], v[158:161], v[198:201], v[8:11]
	v_mfma_f32_16x16x32_bf16 v[60:63], v[154:157], v[178:181], v[60:63]
	v_mfma_f32_16x16x32_bf16 v[56:59], v[162:165], v[178:181], v[56:59]
	v_mfma_f32_16x16x32_bf16 v[48:51], v[154:157], v[186:189], v[48:51]
	v_mfma_f32_16x16x32_bf16 v[40:43], v[162:165], v[186:189], v[40:43]
	v_mfma_f32_16x16x32_bf16 v[32:35], v[154:157], v[194:197], v[32:35]
	v_mfma_f32_16x16x32_bf16 v[24:27], v[162:165], v[194:197], v[24:27]
	v_mfma_f32_16x16x32_bf16 v[16:19], v[154:157], v[202:205], v[16:19]
	v_mfma_f32_16x16x32_bf16 v[8:11], v[162:165], v[202:205], v[8:11]
	s_setprio 1
	s_barrier
	s_add_u32 s48, s22, 0x40000
	s_addc_u32 s49, s23, 0
	s_add_i32 s50, s39, s27
	v_lshl_add_u64 v[146:147], s[48:49], 0, v[132:133]
	s_mov_b32 m0, s50
	s_nop 0
	global_load_lds_dwordx4 v[146:147], off
	v_lshl_add_u64 v[146:147], s[48:49], 0, v[128:129]
	s_add_i32 m0, s50, 0x2000
	s_nop 0
	global_load_lds_dwordx4 v[146:147], off
	s_waitcnt vmcnt(6)
	s_barrier
	s_setprio 2
	v_mfma_f32_16x16x32_bf16 v[52:55], v[206:209], v[166:169], v[52:55]
	v_mfma_f32_16x16x32_bf16 v[44:47], v[214:217], v[166:169], v[44:47]
	v_mfma_f32_16x16x32_bf16 v[36:39], v[206:209], v[182:185], v[36:39]
	v_mfma_f32_16x16x32_bf16 v[28:31], v[214:217], v[182:185], v[28:31]
	v_mfma_f32_16x16x32_bf16 v[20:23], v[206:209], v[190:193], v[20:23]
	v_mfma_f32_16x16x32_bf16 v[12:15], v[214:217], v[190:193], v[12:15]
	v_mfma_f32_16x16x32_bf16 v[4:7], v[206:209], v[198:201], v[4:7]
	v_mfma_f32_16x16x32_bf16 v[0:3], v[214:217], v[198:201], v[0:3]
	v_mfma_f32_16x16x32_bf16 v[52:55], v[210:213], v[178:181], v[52:55]
	v_mfma_f32_16x16x32_bf16 v[44:47], v[218:221], v[178:181], v[44:47]
	v_mfma_f32_16x16x32_bf16 v[36:39], v[210:213], v[186:189], v[36:39]
	v_mfma_f32_16x16x32_bf16 v[28:31], v[218:221], v[186:189], v[28:31]
	v_mfma_f32_16x16x32_bf16 v[20:23], v[210:213], v[194:197], v[20:23]
	v_mfma_f32_16x16x32_bf16 v[12:15], v[218:221], v[194:197], v[12:15]
	v_mfma_f32_16x16x32_bf16 v[4:7], v[210:213], v[202:205], v[4:7]
	v_mfma_f32_16x16x32_bf16 v[0:3], v[218:221], v[202:205], v[0:3]
	s_setprio 1
	s_add_i32 s48, 0, 0x18000
	v_add_u32_e32 v162, s48, v171
	s_barrier
	ds_read_b128 v[146:149], v162
	ds_read_b128 v[154:157], v162 offset:1024
	ds_read_b128 v[158:161], v162 offset:2048
	ds_read_b128 v[162:165], v162 offset:3072
	s_add_u32 s24, s24, 0x40000
	s_addc_u32 s25, s25, 0
	s_mov_b32 m0, s31
	v_lshl_add_u64 v[206:207], s[24:25], 0, v[134:135]
	ds_read_b128 v[166:169], v174 offset:32768
	ds_read_b128 v[178:181], v174 offset:33792
	ds_read_b128 v[182:185], v174 offset:34816
	ds_read_b128 v[186:189], v174 offset:35840
	ds_read_b128 v[190:193], v174 offset:36864
	ds_read_b128 v[194:197], v174 offset:37888
	ds_read_b128 v[198:201], v174 offset:38912
	ds_read_b128 v[202:205], v174 offset:39936
	global_load_lds_dwordx4 v[206:207], off
	v_lshl_add_u64 v[206:207], s[24:25], 0, v[130:131]
	s_mov_b32 m0, s33
	s_nop 0
	global_load_lds_dwordx4 v[206:207], off
	s_waitcnt lgkmcnt(8)
	s_barrier
; #define PG8_STAGE(bufoff, gbase, voff) do { _Pragma("unroll") for (int _i = 0; _i < 2; ++_i) \
;         __builtin_amdgcn_global_load_lds((const unsigned*)((const char*)(gbase) + (voff)[_i]), (LAS unsigned*)(lds + (bufoff) + ldsw + _i * 8192), 16, 0, 0); } while (0)
; #define PG8_LDA(dst, b, h) do { _Pragma("unroll") for (int m = 0; m < 4; ++m) _Pragma("unroll") for (int k = 0; k < 2; ++k) dst[m][k] = *(const LAS bf16x8*)(lds + PG8_SA(b, h) + aoff + m * 2048 + k * 1024); } while (0)
; #define PG8_LDB(dst, b, h) do { _Pragma("unroll") for (int n = 0; n < 2; ++n) _Pragma("unroll") for (int k = 0; k < 2; ++k) dst[n][k] = *(const LAS bf16x8*)(lds + PG8_SB(b, h) + boff + n * 2048 + k * 1024); } while (0)
; #define PG8_MMA(ai, bj, At, Bt) do { __builtin_amdgcn_s_setprio(1); _Pragma("unroll") for (int m = 0; m < 4; ++m) _Pragma("unroll") for (int n = 0; n < 2; ++n) _Pragma("unroll") for (int k = 0; k < 2; ++k) \
;         acc[ai][bj][m][n] = __builtin_amdgcn_mfma_f32_16x16x32_bf16(Bt[n][k], At[m][k], acc[ai][bj][m][n], 0, 0, 0); __builtin_amdgcn_s_setprio(0); } while (0)
; #define PG8_WAIT_V(n) asm volatile("s_waitcnt vmcnt(" #n ")" ::: "memory")
; #define PG8_WAIT_L(n) asm volatile("s_waitcnt lgkmcnt(" #n ")" ::: "memory")
; #define PG8_BAR __builtin_amdgcn_s_barrier()
; #define PG8_SCHED __builtin_amdgcn_sched_barrier(0)
; template <class Epi>
; __device__ __forceinline__ void gemm_phase(LAS unsigned char* lds, const Gemm g, const StaticOrder& S, const Epi& E) {
;     ...
;             PG8_WAIT_L(8); PG8_BAR; PG8_WAIT_L(0); PG8_MMA(0, 0, At, B0); PG8_BAR; PG8_SCHED;
;             PG8_LDB(B1, 1, 1); PG8_STAGE(PG8_SB(1, 0), b3, voffB);
;             PG8_BAR; PG8_WAIT_L(0); PG8_MMA(0, 1, At, B1); PG8_BAR;
;             PG8_LDA(At, 1, 1); PG8_STAGE(PG8_SA(1, 0), a3, voffA);
;             PG8_BAR; PG8_WAIT_L(0); PG8_MMA(1, 0, At, B0); PG8_BAR; PG8_SCHED;
;             PG8_STAGE(PG8_SB(1, 1), b3 + hstepB, voffB);
;             PG8_WAIT_V(6); PG8_BAR; PG8_MMA(1, 1, At, B1); PG8_BAR;
;         }
	s_waitcnt lgkmcnt(0)
	s_setprio 2
	s_waitcnt lgkmcnt(0)
	v_mfma_f32_16x16x32_bf16 v[124:127], v[146:149], v[166:169], v[124:127]
	v_mfma_f32_16x16x32_bf16 v[120:123], v[158:161], v[166:169], v[120:123]
	v_mfma_f32_16x16x32_bf16 v[112:115], v[146:149], v[182:185], v[112:115]
	v_mfma_f32_16x16x32_bf16 v[104:107], v[158:161], v[182:185], v[104:107]
	v_mfma_f32_16x16x32_bf16 v[92:95], v[146:149], v[190:193], v[92:95]
	v_mfma_f32_16x16x32_bf16 v[88:91], v[158:161], v[190:193], v[88:91]
	v_mfma_f32_16x16x32_bf16 v[80:83], v[146:149], v[198:201], v[80:83]
	v_mfma_f32_16x16x32_bf16 v[72:75], v[158:161], v[198:201], v[72:75]
	v_mfma_f32_16x16x32_bf16 v[124:127], v[154:157], v[178:181], v[124:127]
	v_mfma_f32_16x16x32_bf16 v[120:123], v[162:165], v[178:181], v[120:123]
	v_mfma_f32_16x16x32_bf16 v[112:115], v[154:157], v[186:189], v[112:115]
	v_mfma_f32_16x16x32_bf16 v[104:107], v[162:165], v[186:189], v[104:107]
	v_mfma_f32_16x16x32_bf16 v[92:95], v[154:157], v[194:197], v[92:95]
	v_mfma_f32_16x16x32_bf16 v[88:91], v[162:165], v[194:197], v[88:91]
	v_mfma_f32_16x16x32_bf16 v[80:83], v[154:157], v[202:205], v[80:83]
	v_mfma_f32_16x16x32_bf16 v[72:75], v[162:165], v[202:205], v[72:75]
	s_setprio 1
	s_barrier
	s_add_i32 s24, 0, 0x1c000
	s_add_i32 s25, s48, s27
	v_add_u32_e32 v177, s24, v171
	v_lshl_add_u64 v[150:151], v[150:151], 0, s[4:5]
	s_mov_b32 m0, s25
	ds_read_b128 v[206:209], v177
	ds_read_b128 v[210:213], v177 offset:1024
	ds_read_b128 v[214:217], v177 offset:2048
	ds_read_b128 v[218:221], v177 offset:3072
	global_load_lds_dwordx4 v[150:151], off
	v_lshl_add_u64 v[150:151], v[222:223], 0, s[4:5]
	s_add_i32 m0, s25, 0x2000
	s_nop 0
	global_load_lds_dwordx4 v[150:151], off
	s_barrier
	s_waitcnt lgkmcnt(0)
	s_setprio 2
	s_waitcnt lgkmcnt(0)
	v_mfma_f32_16x16x32_bf16 v[116:119], v[206:209], v[166:169], v[116:119]
	v_mfma_f32_16x16x32_bf16 v[108:111], v[214:217], v[166:169], v[108:111]
	v_mfma_f32_16x16x32_bf16 v[100:103], v[206:209], v[182:185], v[100:103]
	v_mfma_f32_16x16x32_bf16 v[96:99], v[214:217], v[182:185], v[96:99]
	v_mfma_f32_16x16x32_bf16 v[84:87], v[206:209], v[190:193], v[84:87]
	v_mfma_f32_16x16x32_bf16 v[76:79], v[214:217], v[190:193], v[76:79]
	v_mfma_f32_16x16x32_bf16 v[68:71], v[206:209], v[198:201], v[68:71]
	v_mfma_f32_16x16x32_bf16 v[64:67], v[214:217], v[198:201], v[64:67]
	v_mfma_f32_16x16x32_bf16 v[116:119], v[210:213], v[178:181], v[116:119]
	v_mfma_f32_16x16x32_bf16 v[108:111], v[218:221], v[178:181], v[108:111]
	v_mfma_f32_16x16x32_bf16 v[100:103], v[210:213], v[186:189], v[100:103]
	v_mfma_f32_16x16x32_bf16 v[96:99], v[218:221], v[186:189], v[96:99]
	v_mfma_f32_16x16x32_bf16 v[84:87], v[210:213], v[194:197], v[84:87]
	v_mfma_f32_16x16x32_bf16 v[76:79], v[218:221], v[194:197], v[76:79]
	v_mfma_f32_16x16x32_bf16 v[68:71], v[210:213], v[202:205], v[68:71]
	v_mfma_f32_16x16x32_bf16 v[64:67], v[218:221], v[202:205], v[64:67]
	s_setprio 1
	s_mov_b32 m0, s35
	v_lshl_add_u64 v[150:151], v[224:225], 0, s[4:5]
	s_barrier
	ds_read_b128 v[166:169], v174 offset:49152
	ds_read_b128 v[178:181], v174 offset:50176
	ds_read_b128 v[182:185], v174 offset:51200
	ds_read_b128 v[186:189], v174 offset:52224
	ds_read_b128 v[190:193], v174 offset:53248
	ds_read_b128 v[194:197], v174 offset:54272
	ds_read_b128 v[198:201], v174 offset:55296
	ds_read_b128 v[202:205], v174 offset:56320
	global_load_lds_dwordx4 v[150:151], off
	v_lshl_add_u64 v[150:151], v[226:227], 0, s[4:5]
	s_mov_b32 m0, s36
	s_nop 0
	global_load_lds_dwordx4 v[150:151], off
	s_barrier
	s_waitcnt lgkmcnt(0)
	s_setprio 2
	s_waitcnt lgkmcnt(0)
	v_mfma_f32_16x16x32_bf16 v[60:63], v[146:149], v[166:169], v[60:63]
	v_mfma_f32_16x16x32_bf16 v[56:59], v[158:161], v[166:169], v[56:59]
	v_mfma_f32_16x16x32_bf16 v[48:51], v[146:149], v[182:185], v[48:51]
	v_mfma_f32_16x16x32_bf16 v[40:43], v[158:161], v[182:185], v[40:43]
	v_mfma_f32_16x16x32_bf16 v[32:35], v[146:149], v[190:193], v[32:35]
	v_mfma_f32_16x16x32_bf16 v[24:27], v[158:161], v[190:193], v[24:27]
	v_mfma_f32_16x16x32_bf16 v[16:19], v[146:149], v[198:201], v[16:19]
	v_mfma_f32_16x16x32_bf16 v[8:11], v[158:161], v[198:201], v[8:11]
	v_mfma_f32_16x16x32_bf16 v[60:63], v[154:157], v[178:181], v[60:63]
	v_mfma_f32_16x16x32_bf16 v[56:59], v[162:165], v[178:181], v[56:59]
	v_mfma_f32_16x16x32_bf16 v[48:51], v[154:157], v[186:189], v[48:51]
	v_mfma_f32_16x16x32_bf16 v[40:43], v[162:165], v[186:189], v[40:43]
	v_mfma_f32_16x16x32_bf16 v[32:35], v[154:157], v[194:197], v[32:35]
	v_mfma_f32_16x16x32_bf16 v[24:27], v[162:165], v[194:197], v[24:27]
	v_mfma_f32_16x16x32_bf16 v[16:19], v[154:157], v[202:205], v[16:19]
	v_mfma_f32_16x16x32_bf16 v[8:11], v[162:165], v[202:205], v[8:11]
	s_setprio 1
	s_barrier
	s_add_u32 s22, s22, 0x40080
	s_addc_u32 s23, s23, 0
	s_add_i32 s24, s24, s27
	v_lshl_add_u64 v[146:147], s[22:23], 0, v[132:133]
	s_mov_b32 m0, s24
	s_nop 0
	global_load_lds_dwordx4 v[146:147], off
	v_lshl_add_u64 v[146:147], s[22:23], 0, v[128:129]
	s_add_i32 m0, s24, 0x2000
	s_nop 0
	global_load_lds_dwordx4 v[146:147], off
	s_waitcnt vmcnt(6)
	s_barrier
	s_setprio 2
	v_mfma_f32_16x16x32_bf16 v[52:55], v[206:209], v[166:169], v[52:55]
	v_mfma_f32_16x16x32_bf16 v[44:47], v[214:217], v[166:169], v[44:47]
	v_mfma_f32_16x16x32_bf16 v[36:39], v[206:209], v[182:185], v[36:39]
	v_mfma_f32_16x16x32_bf16 v[28:31], v[214:217], v[182:185], v[28:31]
	v_mfma_f32_16x16x32_bf16 v[20:23], v[206:209], v[190:193], v[20:23]
	v_mfma_f32_16x16x32_bf16 v[12:15], v[214:217], v[190:193], v[12:15]
	v_mfma_f32_16x16x32_bf16 v[4:7], v[206:209], v[198:201], v[4:7]
	v_mfma_f32_16x16x32_bf16 v[0:3], v[214:217], v[198:201], v[0:3]
	v_mfma_f32_16x16x32_bf16 v[52:55], v[210:213], v[178:181], v[52:55]
	v_mfma_f32_16x16x32_bf16 v[44:47], v[218:221], v[178:181], v[44:47]
	v_mfma_f32_16x16x32_bf16 v[36:39], v[210:213], v[186:189], v[36:39]
	v_mfma_f32_16x16x32_bf16 v[28:31], v[218:221], v[186:189], v[28:31]
	v_mfma_f32_16x16x32_bf16 v[20:23], v[210:213], v[194:197], v[20:23]
	v_mfma_f32_16x16x32_bf16 v[12:15], v[218:221], v[194:197], v[12:15]
	v_mfma_f32_16x16x32_bf16 v[4:7], v[210:213], v[202:205], v[4:7]
	v_mfma_f32_16x16x32_bf16 v[0:3], v[218:221], v[202:205], v[0:3]
	s_setprio 1
	s_add_i32 s47, s47, 2
	s_add_u32 s20, s20, 0x100
	s_addc_u32 s21, s21, 0
	s_add_u32 s45, s45, 0x100
	s_addc_u32 s46, s46, 0
	s_cmp_gt_u32 s47, 13
	s_barrier
	s_cbranch_scc0 .Lkp4_922
	s_branch .Lkp4_epi
;     __device__ bool next(int i, Unit& u) const {
;         const long L = (long)i * G + c; if (L >= nwg) return false;
;         int wgid = (int)L; { const int q = nwg / NXCD, r = nwg % NXCD, xcd = wgid % NXCD, off = wgid / NXCD; wgid = (xcd < r ? xcd * (q + 1) : r * (q + 1) + (xcd - r) * q) + off; }
;         const int nig = WGM * nN, gid = wgid / nig, fm = gid * WGM, gsz = (nM - fm) < WGM ? (nM - fm) : WGM;
;         u.pm = fm + ((wgid % nig) % gsz); u.pn = (wgid % nig) / gsz; return true;
; template <class Epi>
; __device__ __forceinline__ void gemm_phase(LAS unsigned char* lds, const Gemm g, const StaticOrder& S, const Epi& E) {
;     ...
;         const bool has_next = S.next(ui + 1, nxt);
.LBB0_919:
	v_readfirstlane_b32 s98, v152
	s_nop 3
	s_cmp_ge_u32 s98, 0x100
	s_cbranch_scc1 .Lkp4_head
	s_add_i32 s34, s34, 1
	s_mul_i32 s0, s34, s37
	s_mul_hi_u32 s1, s34, s92
	s_add_i32 s1, s1, s0
	s_mul_i32 s0, s34, s92
	s_add_u32 s14, s0, s93
	s_addc_u32 s15, s1, s28
	v_cmp_gt_i64_e64 s[0:1], s[14:15], v[144:145]
	s_and_b64 vcc, exec, s[0:1]
	s_cbranch_vccnz .LBB0_921
	s_lshr_b32 s10, s14, 3
	s_mov_b32 s13, 0
	s_sub_u32 s11, s10, 0xa0
	s_cmp_ge_u32 s10, 0xa0
	s_cselect_b32 s10, s11, s10
	s_addc_u32 s13, s13, 0
	s_sub_u32 s11, s10, 0xa0
	s_cmp_ge_u32 s10, 0xa0
	s_cselect_b32 s10, s11, s10
	s_addc_u32 s13, s13, 0
	s_sub_u32 s11, s10, 0xa0
	s_cmp_ge_u32 s10, 0xa0
	s_cselect_b32 s10, s11, s10
	s_addc_u32 s13, s13, 0
	s_and_b32 s12, s14, 7
	s_lshl_b32 s12, s12, 2
	s_add_i32 s12, s12, s13
	s_lshl_b32 s12, s12, 3
	s_and_b32 s13, s10, 7
	s_add_i32 s12, s12, s13
	s_lshr_b32 s10, s10, 3

; __device__ __forceinline__ unsigned pk2(float lo, float hi) { const f32x2 v = (f32x2){lo, hi}; const bf16x2_t b = __builtin_convertvector(v, bf16x2_t); return __builtin_bit_cast(unsigned, b); }
;     __device__ __forceinline__ void operator()(const f32x4 (&acc)[2][2][4][2], const Unit& u, int wr, int wc, int fr, int fq, const float (&)[8]) const {
;     ...
;         const int col0 = u.pn * BM + wc * 32 + 8 * fq;
; #pragma unroll
;         for (int ai = 0; ai < 2; ++ai)
; #pragma unroll
;             for (int m = 0; m < 4; ++m) { const int row = row0 + ai * HALF + m * 16; const float rs = rsqrtf(ep[ai * 4 + m] * (1.0f / 1024.0f) + EPS);
;                 u16* rowp = O + (size_t)row * ldc + col0;
; #pragma unroll
;                 for (int bj = 0; bj < 2; ++bj) { f32x4 v0 = acc[ai][bj][m][0] * rs, v1 = acc[ai][bj][m][1] * rs;
;                     if (ACT == 1) {
; #pragma unroll
;                         for (int j = 0; j < 4; ++j) { const float a0 = fmaxf(v0[j], 0.f), a1 = fmaxf(v1[j], 0.f); v0[j] = a0 * a0; v1[j] = a1 * a1; } }
;                     u32x4 w; w.x = pk2(v0[0], v0[1]); w.y = pk2(v0[2], v0[3]); w.z = pk2(v1[0], v1[1]); w.w = pk2(v1[2], v1[3]);
;                     *(u32x4*)(rowp + bj * HALF) = w; } }
.Lkp4_epi:
	s_setprio 0
	s_bfe_u32 vcc_lo, s18, 0x20003
	s_lshl_b32 vcc_lo, vcc_lo, 10
	s_add_i32 vcc_lo, vcc_lo, 0x20010
	v_lshl_add_u32 v236, v170, 2, vcc_lo
	ds_read_b32 v228, v236
	ds_read_b32 v229, v236 offset:64
	ds_read_b32 v230, v236 offset:128
	ds_read_b32 v231, v236 offset:192
	ds_read_b32 v232, v236 offset:512
	ds_read_b32 v233, v236 offset:576
	ds_read_b32 v234, v236 offset:640
	ds_read_b32 v235, v236 offset:704
	s_waitcnt lgkmcnt(0)
	v_lshl_add_u32 v154, s18, 8, v170
	v_or_b32_e32 v206, 16, v154
	v_or_b32_e32 v168, 32, v154
	v_or_b32_e32 v162, 48, v154
	v_add_u32_e32 v160, 0x80, v154
	v_add_u32_e32 v156, 0x90, v154
	v_add_u32_e32 v150, 0xa0, v154
	v_add_u32_e32 v146, 0xb0, v154
	v_lshl_or_b32 v208, s42, 8, v172
	v_mov_b64_e32 v[148:149], s[96:97]
	v_ashrrev_i32_e32 v209, 31, v208
	v_mad_i64_i32 v[210:211], s[20:21], v154, s40, v[148:149]
	s_nop 0
	v_lshlrev_b64 v[154:155], 1, v[208:209]
	v_lshl_add_u64 v[208:209], v[210:211], 0, v[154:155]
	s_mov_b32 s42, s10
	s_mov_b32 s18, s12
	s_mov_b64 s[22:23], s[16:17]
	s_waitcnt vmcnt(8)
	s_waitcnt lgkmcnt(0)
	s_waitcnt lgkmcnt(0)
	v_mov_b32_e32 v178, v228
	v_pk_mul_f32 v[126:127], v[126:127], v[178:179] op_sel_hi:[1,0]
	v_pk_mul_f32 v[124:125], v[124:125], v[178:179] op_sel_hi:[1,0]
	v_pk_mul_f32 v[190:191], v[122:123], v[178:179] op_sel_hi:[1,0]
	v_pk_mul_f32 v[122:123], v[120:121], v[178:179] op_sel_hi:[1,0]
	v_cvt_pk_bf16_f32 v120, v124, v125
	v_cvt_pk_bf16_f32 v121, v126, v127
	v_cvt_pk_bf16_f32 v122, v122, v123
	v_cvt_pk_bf16_f32 v123, v190, v191
	v_pk_mul_f32 v[116:117], v[116:117], v[178:179] op_sel_hi:[1,0]
	global_store_dwordx4 v[208:209], v[120:123], off
	s_nop 0
	v_pk_mul_f32 v[118:119], v[118:119], v[178:179] op_sel_hi:[1,0]
	v_pk_mul_f32 v[120:121], v[110:111], v[178:179] op_sel_hi:[1,0]
	v_pk_mul_f32 v[110:111], v[108:109], v[178:179] op_sel_hi:[1,0]
	v_cvt_pk_bf16_f32 v108, v116, v117
	v_cvt_pk_bf16_f32 v109, v118, v119
	v_cvt_pk_bf16_f32 v110, v110, v111
	v_cvt_pk_bf16_f32 v111, v120, v121
	global_store_dwordx4 v[208:209], v[108:111], off offset:256
	s_nop 1
	v_mov_b32_e32 v108, v229
	v_mad_i64_i32 v[110:111], s[20:21], v206, s40, v[148:149]
	v_pk_mul_f32 v[114:115], v[114:115], v[108:109] op_sel_hi:[1,0]
	v_pk_mul_f32 v[112:113], v[112:113], v[108:109] op_sel_hi:[1,0]
	v_pk_mul_f32 v[116:117], v[106:107], v[108:109] op_sel_hi:[1,0]
	v_pk_mul_f32 v[106:107], v[104:105], v[108:109] op_sel_hi:[1,0]
	v_lshl_add_u64 v[110:111], v[110:111], 0, v[154:155]
	v_cvt_pk_bf16_f32 v104, v112, v113
	v_cvt_pk_bf16_f32 v105, v114, v115
	v_cvt_pk_bf16_f32 v106, v106, v107
	v_cvt_pk_bf16_f32 v107, v116, v117
	global_store_dwordx4 v[110:111], v[104:107], off
	v_pk_mul_f32 v[100:101], v[100:101], v[108:109] op_sel_hi:[1,0]
	v_pk_mul_f32 v[112:113], v[98:99], v[108:109] op_sel_hi:[1,0]
	v_pk_mul_f32 v[98:99], v[96:97], v[108:109] op_sel_hi:[1,0]
	v_cvt_pk_bf16_f32 v96, v100, v101
	v_pk_mul_f32 v[102:103], v[102:103], v[108:109] op_sel_hi:[1,0]
	v_cvt_pk_bf16_f32 v98, v98, v99
	s_waitcnt lgkmcnt(0)
	v_cvt_pk_bf16_f32 v97, v102, v103
	v_cvt_pk_bf16_f32 v99, v112, v113
	global_store_dwordx4 v[110:111], v[96:99], off offset:256
	s_nop 0
	s_waitcnt lgkmcnt(0)
	v_mad_i64_i32 v[98:99], s[20:21], v168, s40, v[148:149]
	v_lshl_add_u64 v[98:99], v[98:99], 0, v[154:155]
	v_mov_b32_e32 v100, v230
	v_pk_mul_f32 v[94:95], v[94:95], v[100:101] op_sel_hi:[1,0]
	v_pk_mul_f32 v[92:93], v[92:93], v[100:101] op_sel_hi:[1,0]
	v_pk_mul_f32 v[102:103], v[90:91], v[100:101] op_sel_hi:[1,0]
	v_pk_mul_f32 v[90:91], v[88:89], v[100:101] op_sel_hi:[1,0]
	v_cvt_pk_bf16_f32 v88, v92, v93
	v_cvt_pk_bf16_f32 v89, v94, v95
	v_cvt_pk_bf16_f32 v90, v90, v91
	v_cvt_pk_bf16_f32 v91, v102, v103
	v_pk_mul_f32 v[84:85], v[84:85], v[100:101] op_sel_hi:[1,0]
	global_store_dwordx4 v[98:99], v[88:91], off
	s_nop 0
	v_pk_mul_f32 v[86:87], v[86:87], v[100:101] op_sel_hi:[1,0]
	v_pk_mul_f32 v[88:89], v[78:79], v[100:101] op_sel_hi:[1,0]
	v_pk_mul_f32 v[78:79], v[76:77], v[100:101] op_sel_hi:[1,0]
	v_cvt_pk_bf16_f32 v76, v84, v85
	v_cvt_pk_bf16_f32 v77, v86, v87
	v_cvt_pk_bf16_f32 v78, v78, v79
	v_cvt_pk_bf16_f32 v79, v88, v89
	global_store_dwordx4 v[98:99], v[76:79], off offset:256
	s_nop 1
	v_mov_b32_e32 v76, v231
	v_mad_i64_i32 v[78:79], s[20:21], v162, s40, v[148:149]
	v_pk_mul_f32 v[82:83], v[82:83], v[76:77] op_sel_hi:[1,0]
	v_pk_mul_f32 v[80:81], v[80:81], v[76:77] op_sel_hi:[1,0]
	v_pk_mul_f32 v[84:85], v[74:75], v[76:77] op_sel_hi:[1,0]
	v_pk_mul_f32 v[74:75], v[72:73], v[76:77] op_sel_hi:[1,0]
	v_lshl_add_u64 v[78:79], v[78:79], 0, v[154:155]
	v_cvt_pk_bf16_f32 v72, v80, v81
	v_cvt_pk_bf16_f32 v73, v82, v83
	v_cvt_pk_bf16_f32 v74, v74, v75
	v_cvt_pk_bf16_f32 v75, v84, v85
	global_store_dwordx4 v[78:79], v[72:75], off
	v_pk_mul_f32 v[68:69], v[68:69], v[76:77] op_sel_hi:[1,0]
	v_pk_mul_f32 v[80:81], v[66:67], v[76:77] op_sel_hi:[1,0]
	v_pk_mul_f32 v[66:67], v[64:65], v[76:77] op_sel_hi:[1,0]
	v_cvt_pk_bf16_f32 v64, v68, v69
	v_pk_mul_f32 v[70:71], v[70:71], v[76:77] op_sel_hi:[1,0]
	v_cvt_pk_bf16_f32 v66, v66, v67
	s_waitcnt lgkmcnt(0)
; __device__ __forceinline__ unsigned pk2(float lo, float hi) { const f32x2 v = (f32x2){lo, hi}; const bf16x2_t b = __builtin_convertvector(v, bf16x2_t); return __builtin_bit_cast(unsigned, b); }
; #define PG8_WAIT_V(n) asm volatile("s_waitcnt vmcnt(" #n ")" ::: "memory")
; #define PG8_BAR __builtin_amdgcn_s_barrier()
;     __device__ __forceinline__ void operator()(const f32x4 (&acc)[2][2][4][2], const Unit& u, int wr, int wc, int fr, int fq, const float (&)[8]) const {
;     ...
;             for (int m = 0; m < 4; ++m) { const int row = row0 + ai * HALF + m * 16; const float rs = rsqrtf(ep[ai * 4 + m] * (1.0f / 1024.0f) + EPS);
;                 u16* rowp = O + (size_t)row * ldc + col0;
; #pragma unroll
;                 for (int bj = 0; bj < 2; ++bj) { f32x4 v0 = acc[ai][bj][m][0] * rs, v1 = acc[ai][bj][m][1] * rs;
;                     if (ACT == 1) {
; #pragma unroll
;                         for (int j = 0; j < 4; ++j) { const float a0 = fmaxf(v0[j], 0.f), a1 = fmaxf(v1[j], 0.f); v0[j] = a0 * a0; v1[j] = a1 * a1; } }
;                     u32x4 w; w.x = pk2(v0[0], v0[1]); w.y = pk2(v0[2], v0[3]); w.z = pk2(v1[0], v1[1]); w.w = pk2(v1[2], v1[3]);
;                     *(u32x4*)(rowp + bj * HALF) = w; } }
; template <class Epi>
; __device__ __forceinline__ void gemm_phase(LAS unsigned char* lds, const Gemm g, const StaticOrder& S, const Epi& E) {
;     ...
;         E(acc, cur, wr, wc, fr, fq, epre);
;         if (!has_next) break;
; #pragma unroll
;         for (int a = 0; a < 2; ++a)
; #pragma unroll
;             for (int b = 0; b < 2; ++b)
; #pragma unroll
;                 for (int m = 0; m < 4; ++m)
; #pragma unroll
;                     for (int n = 0; n < 2; ++n) acc[a][b][m][n] = (f32x4){0.f, 0.f, 0.f, 0.f};
;         cur = nxt; cA = nA; cB = nB; ++ui;
;     }
;     PG8_WAIT_V(0);
;     if (wr == 0) PG8_BAR;
;     PG8_BAR;
	v_cvt_pk_bf16_f32 v65, v70, v71
	v_cvt_pk_bf16_f32 v67, v80, v81
	global_store_dwordx4 v[78:79], v[64:67], off offset:256
	s_waitcnt lgkmcnt(0)
	s_nop 0
	s_nop 0
	s_nop 0
	s_nop 1
	v_mad_i64_i32 v[66:67], s[20:21], v160, s40, v[148:149]
	v_lshl_add_u64 v[66:67], v[66:67], 0, v[154:155]
	v_mov_b32_e32 v68, v232
	v_pk_mul_f32 v[62:63], v[62:63], v[68:69] op_sel_hi:[1,0]
	v_pk_mul_f32 v[60:61], v[60:61], v[68:69] op_sel_hi:[1,0]
	v_pk_mul_f32 v[70:71], v[58:59], v[68:69] op_sel_hi:[1,0]
	v_pk_mul_f32 v[58:59], v[56:57], v[68:69] op_sel_hi:[1,0]
	v_cvt_pk_bf16_f32 v56, v60, v61
	v_cvt_pk_bf16_f32 v57, v62, v63
	v_cvt_pk_bf16_f32 v58, v58, v59
	v_cvt_pk_bf16_f32 v59, v70, v71
	v_pk_mul_f32 v[52:53], v[52:53], v[68:69] op_sel_hi:[1,0]
	global_store_dwordx4 v[66:67], v[56:59], off
	s_nop 0
	v_pk_mul_f32 v[54:55], v[54:55], v[68:69] op_sel_hi:[1,0]
	v_pk_mul_f32 v[56:57], v[46:47], v[68:69] op_sel_hi:[1,0]
	v_pk_mul_f32 v[46:47], v[44:45], v[68:69] op_sel_hi:[1,0]
	v_cvt_pk_bf16_f32 v44, v52, v53
	v_cvt_pk_bf16_f32 v45, v54, v55
	v_cvt_pk_bf16_f32 v46, v46, v47
	v_cvt_pk_bf16_f32 v47, v56, v57
	global_store_dwordx4 v[66:67], v[44:47], off offset:256
	s_nop 1
	v_mov_b32_e32 v44, v233
	v_mad_i64_i32 v[46:47], s[20:21], v156, s40, v[148:149]
	v_pk_mul_f32 v[50:51], v[50:51], v[44:45] op_sel_hi:[1,0]
	v_pk_mul_f32 v[48:49], v[48:49], v[44:45] op_sel_hi:[1,0]
	v_pk_mul_f32 v[52:53], v[42:43], v[44:45] op_sel_hi:[1,0]
	v_pk_mul_f32 v[42:43], v[40:41], v[44:45] op_sel_hi:[1,0]
	v_lshl_add_u64 v[46:47], v[46:47], 0, v[154:155]
	v_cvt_pk_bf16_f32 v40, v48, v49
	v_cvt_pk_bf16_f32 v41, v50, v51
	v_cvt_pk_bf16_f32 v42, v42, v43
	v_cvt_pk_bf16_f32 v43, v52, v53
	global_store_dwordx4 v[46:47], v[40:43], off
	v_pk_mul_f32 v[36:37], v[36:37], v[44:45] op_sel_hi:[1,0]
	v_pk_mul_f32 v[48:49], v[30:31], v[44:45] op_sel_hi:[1,0]
	v_pk_mul_f32 v[30:31], v[28:29], v[44:45] op_sel_hi:[1,0]
	v_cvt_pk_bf16_f32 v28, v36, v37
	v_pk_mul_f32 v[38:39], v[38:39], v[44:45] op_sel_hi:[1,0]
	v_cvt_pk_bf16_f32 v30, v30, v31
	s_waitcnt lgkmcnt(0)
	v_cvt_pk_bf16_f32 v29, v38, v39
	v_cvt_pk_bf16_f32 v31, v48, v49
	global_store_dwordx4 v[46:47], v[28:31], off offset:256
	s_waitcnt lgkmcnt(0)
	s_nop 0
	s_nop 0
	s_nop 0
	s_nop 1
	v_mad_i64_i32 v[30:31], s[20:21], v150, s40, v[148:149]
	v_lshl_add_u64 v[30:31], v[30:31], 0, v[154:155]
	v_mov_b32_e32 v36, v234
	v_pk_mul_f32 v[34:35], v[34:35], v[36:37] op_sel_hi:[1,0]
	v_pk_mul_f32 v[32:33], v[32:33], v[36:37] op_sel_hi:[1,0]
	v_pk_mul_f32 v[38:39], v[26:27], v[36:37] op_sel_hi:[1,0]
	v_pk_mul_f32 v[26:27], v[24:25], v[36:37] op_sel_hi:[1,0]
	v_cvt_pk_bf16_f32 v24, v32, v33
	v_cvt_pk_bf16_f32 v25, v34, v35
	v_cvt_pk_bf16_f32 v26, v26, v27
	v_cvt_pk_bf16_f32 v27, v38, v39
	v_pk_mul_f32 v[20:21], v[20:21], v[36:37] op_sel_hi:[1,0]
	global_store_dwordx4 v[30:31], v[24:27], off
	s_nop 0
	v_pk_mul_f32 v[22:23], v[22:23], v[36:37] op_sel_hi:[1,0]
	v_pk_mul_f32 v[24:25], v[14:15], v[36:37] op_sel_hi:[1,0]
	v_pk_mul_f32 v[14:15], v[12:13], v[36:37] op_sel_hi:[1,0]
	v_cvt_pk_bf16_f32 v12, v20, v21
	v_cvt_pk_bf16_f32 v13, v22, v23
	v_cvt_pk_bf16_f32 v14, v14, v15
	v_cvt_pk_bf16_f32 v15, v24, v25
	global_store_dwordx4 v[30:31], v[12:15], off offset:256
	s_nop 1
	v_mov_b32_e32 v12, v235
	v_mad_i64_i32 v[14:15], s[20:21], v146, s40, v[148:149]
	v_pk_mul_f32 v[18:19], v[18:19], v[12:13] op_sel_hi:[1,0]
	v_pk_mul_f32 v[16:17], v[16:17], v[12:13] op_sel_hi:[1,0]
	v_pk_mul_f32 v[20:21], v[10:11], v[12:13] op_sel_hi:[1,0]
	v_pk_mul_f32 v[10:11], v[8:9], v[12:13] op_sel_hi:[1,0]
	v_lshl_add_u64 v[14:15], v[14:15], 0, v[154:155]
	v_cvt_pk_bf16_f32 v8, v16, v17
	v_cvt_pk_bf16_f32 v9, v18, v19
	v_cvt_pk_bf16_f32 v10, v10, v11
	v_cvt_pk_bf16_f32 v11, v20, v21
	global_store_dwordx4 v[14:15], v[8:11], off
	v_pk_mul_f32 v[6:7], v[6:7], v[12:13] op_sel_hi:[1,0]
	v_pk_mul_f32 v[4:5], v[4:5], v[12:13] op_sel_hi:[1,0]
	v_pk_mul_f32 v[8:9], v[2:3], v[12:13] op_sel_hi:[1,0]
	v_pk_mul_f32 v[2:3], v[0:1], v[12:13] op_sel_hi:[1,0]
	v_cvt_pk_bf16_f32 v0, v4, v5
	v_cvt_pk_bf16_f32 v1, v6, v7
	v_cvt_pk_bf16_f32 v2, v2, v3
	v_cvt_pk_bf16_f32 v3, v8, v9
	s_and_b64 vcc, exec, s[0:1]
	s_mov_b64 s[20:21], s[14:15]
	global_store_dwordx4 v[14:15], v[0:3], off offset:256
	s_cbranch_vccz .LBB0_919
	s_waitcnt vmcnt(0)
	v_readlane_b32 s40, v251, 54
	s_cmpk_gt_u32 s7, 0xff
	v_readlane_b32 s41, v251, 55
	s_cbranch_scc1 .LBB0_926
	s_barrier

; template <class Epi>
; __device__ __forceinline__ void gemm_phase(LAS unsigned char* lds, const Gemm g, const StaticOrder& S, const Epi& E) {
;     ...
;         E(acc, cur, wr, wc, fr, fq, epre);
;         if (!has_next) break;
; #pragma unroll
;         for (int a = 0; a < 2; ++a)
; #pragma unroll
;             for (int b = 0; b < 2; ++b)
; #pragma unroll
;                 for (int m = 0; m < 4; ++m)
; #pragma unroll
;                     for (int n = 0; n < 2; ++n) acc[a][b][m][n] = (f32x4){0.f, 0.f, 0.f, 0.f};
;         cur = nxt; cA = nA; cB = nB; ++ui;
.LBB0_1108:
	s_or_b64 exec, exec, s[4:5]
	s_and_b64 vcc, exec, s[2:3]
	s_mov_b32 s8, s16
	s_mov_b32 s10, s42
	s_mov_b64 s[22:23], s[20:21]
	s_mov_b64 s[24:25], s[18:19]
	s_cbranch_vccnz .LBB0_1135
	s_branch .LBB0_1109

; #define PG8_STAGE(bufoff, gbase, voff) do { _Pragma("unroll") for (int _i = 0; _i < 2; ++_i) \
;         __builtin_amdgcn_global_load_lds((const unsigned*)((const char*)(gbase) + (voff)[_i]), (LAS unsigned*)(lds + (bufoff) + ldsw + _i * 8192), 16, 0, 0); } while (0)
; #define PG8_LDA(dst, b, h) do { _Pragma("unroll") for (int m = 0; m < 4; ++m) _Pragma("unroll") for (int k = 0; k < 2; ++k) dst[m][k] = *(const LAS bf16x8*)(lds + PG8_SA(b, h) + aoff + m * 2048 + k * 1024); } while (0)
; #define PG8_LDB(dst, b, h) do { _Pragma("unroll") for (int n = 0; n < 2; ++n) _Pragma("unroll") for (int k = 0; k < 2; ++k) dst[n][k] = *(const LAS bf16x8*)(lds + PG8_SB(b, h) + boff + n * 2048 + k * 1024); } while (0)
; #define PG8_WAIT_V(n) asm volatile("s_waitcnt vmcnt(" #n ")" ::: "memory")
; #define PG8_WAIT_L(n) asm volatile("s_waitcnt lgkmcnt(" #n ")" ::: "memory")
; #define PG8_BAR __builtin_amdgcn_s_barrier()
; #define PG8_SCHED __builtin_amdgcn_sched_barrier(0)
; template <class Epi>
; __device__ __forceinline__ void gemm_phase(LAS unsigned char* lds, const Gemm g, const StaticOrder& S, const Epi& E) {
;     ...
;         const char* nA = has_next ? (const char*)g.A + (size_t)nxt.pm * tstepA : cA; const char* nB = has_next ? (const char*)g.Bt + (size_t)nxt.pn * tstepB : cB;
;         for (int t = 0; t < nt; t += 2) {
;             const bool last = (t == nt - 2);
;             const char* a1 = cA + (size_t)(t + 1) * kstep;
;             const char* a2 = last ? nA : cA + (size_t)(t + 2) * kstep; const char* b2 = last ? nB : cB + (size_t)(t + 2) * kstep;
;             const char* a3 = a2 + kstep; const char* b3 = b2 + kstep;
;             if (last) E.pre(cur, wr, fr, epre);
;             PG8_LDB(B0, 0, 0); PG8_SCHED; PG8_LDA(At, 0, 0); PG8_STAGE(PG8_SA(1, 1), a1 + hstepA, voffA);
;             PG8_WAIT_L(8); PG8_BAR; PG8_WAIT_L(0); PG8_MMA(0, 0, At, B0); PG8_BAR; PG8_SCHED;
;             PG8_LDB(B1, 0, 1); PG8_STAGE(PG8_SB(0, 0), b2, voffB);
;             PG8_BAR; PG8_WAIT_L(0); PG8_MMA(0, 1, At, B1); PG8_BAR;
;             PG8_LDA(At, 0, 1); PG8_STAGE(PG8_SA(0, 0), a2, voffA);
;             PG8_BAR; PG8_WAIT_L(0); PG8_MMA(1, 0, At, B0); PG8_BAR; PG8_SCHED;
;             PG8_STAGE(PG8_SB(0, 1), b2 + hstepB, voffB);
;             PG8_WAIT_V(6); PG8_BAR; PG8_MMA(1, 1, At, B1); PG8_BAR;
.Lkp5_1117:
	s_ashr_i32 s17, s16, 31
	s_lshl_b64 s[20:21], s[16:17], 19
	s_add_u32 s20, s27, s20
	s_addc_u32 s21, s28, s21
	s_and_b64 s[4:5], s[4:5], exec
	s_cselect_b32 s17, s21, s23
	s_cselect_b32 s43, s20, s22
	s_add_u32 s4, s24, 0x140080
	s_addc_u32 s5, s25, 0
	s_add_u32 s44, s22, 0x100
	s_addc_u32 s45, s23, 0
	s_mov_b32 s46, -2
	s_waitcnt lgkmcnt(0)
	ds_read_b128 v[128:131], v190
	ds_read_b128 v[132:135], v190 offset:1024
	ds_read_b128 v[136:139], v190 offset:2048
	ds_read_b128 v[140:143], v190 offset:3072
	s_add_u32 s22, s4, 0xffec0080
	s_addc_u32 s23, s5, -1
	s_cmp_eq_u32 s46, 12
	s_cselect_b32 s25, s19, s23
	s_cselect_b32 s24, s18, s22
	s_cselect_b32 s23, s17, s45
	s_cselect_b32 s22, s43, s44
	v_lshl_add_u64 v[186:187], s[4:5], 0, v[162:163]
	s_add_i32 m0, s9, 0xc000
	ds_read_b128 v[144:147], v191
	ds_read_b128 v[148:151], v191 offset:1024
	ds_read_b128 v[170:173], v191 offset:2048
	ds_read_b128 v[174:177], v191 offset:3072
	ds_read_b128 v[178:181], v191 offset:4096
	ds_read_b128 v[182:185], v191 offset:5120
	ds_read_b128 v[194:197], v191 offset:6144
	ds_read_b128 v[198:201], v191 offset:7168
	global_load_lds_dwordx4 v[186:187], off
	v_lshl_add_u64 v[186:187], s[4:5], 0, v[164:165]
	s_add_i32 m0, s9, 0xe000
	s_nop 0
	global_load_lds_dwordx4 v[186:187], off
	s_waitcnt lgkmcnt(8)
	s_barrier
	s_waitcnt lgkmcnt(0)
	s_setprio 2
	s_waitcnt lgkmcnt(0)
	v_mfma_f32_16x16x32_bf16 v[124:127], v[128:131], v[144:147], 0
	v_mfma_f32_16x16x32_bf16 v[120:123], v[136:139], v[144:147], 0
	v_mfma_f32_16x16x32_bf16 v[108:111], v[128:131], v[170:173], 0
	v_mfma_f32_16x16x32_bf16 v[104:107], v[136:139], v[170:173], 0
	v_mfma_f32_16x16x32_bf16 v[92:95], v[128:131], v[178:181], 0
	v_mfma_f32_16x16x32_bf16 v[88:91], v[136:139], v[178:181], 0
	v_mfma_f32_16x16x32_bf16 v[76:79], v[128:131], v[194:197], 0
	v_mfma_f32_16x16x32_bf16 v[72:75], v[136:139], v[194:197], 0
	v_mfma_f32_16x16x32_bf16 v[124:127], v[132:135], v[148:151], v[124:127]
	v_mfma_f32_16x16x32_bf16 v[120:123], v[140:143], v[148:151], v[120:123]
	v_mfma_f32_16x16x32_bf16 v[108:111], v[132:135], v[174:177], v[108:111]
	v_mfma_f32_16x16x32_bf16 v[104:107], v[140:143], v[174:177], v[104:107]
	v_mfma_f32_16x16x32_bf16 v[92:95], v[132:135], v[182:185], v[92:95]
	v_mfma_f32_16x16x32_bf16 v[88:91], v[140:143], v[182:185], v[88:91]
	v_mfma_f32_16x16x32_bf16 v[76:79], v[132:135], v[198:201], v[76:79]
	v_mfma_f32_16x16x32_bf16 v[72:75], v[140:143], v[198:201], v[72:75]
	s_setprio 1
	s_barrier
	s_add_i32 s47, s40, s29
	v_lshl_add_u64 v[186:187], s[22:23], 0, v[156:157]
	s_mov_b32 m0, s47
	ds_read_b128 v[202:205], v192
	ds_read_b128 v[206:209], v192 offset:1024
	ds_read_b128 v[210:213], v192 offset:2048
	ds_read_b128 v[214:217], v192 offset:3072
	global_load_lds_dwordx4 v[186:187], off
	v_lshl_add_u64 v[218:219], s[22:23], 0, v[160:161]
	s_add_i32 m0, s47, 0x2000
	s_nop 0
	global_load_lds_dwordx4 v[218:219], off
	s_barrier
	s_waitcnt lgkmcnt(0)
	s_setprio 2
	s_waitcnt lgkmcnt(0)
	v_mfma_f32_16x16x32_bf16 v[116:119], v[202:205], v[144:147], 0
	v_mfma_f32_16x16x32_bf16 v[112:115], v[210:213], v[144:147], 0
	v_mfma_f32_16x16x32_bf16 v[100:103], v[202:205], v[170:173], 0
	v_mfma_f32_16x16x32_bf16 v[96:99], v[210:213], v[170:173], 0
	v_mfma_f32_16x16x32_bf16 v[84:87], v[202:205], v[178:181], 0
	v_mfma_f32_16x16x32_bf16 v[80:83], v[210:213], v[178:181], 0
	v_mfma_f32_16x16x32_bf16 v[68:71], v[202:205], v[194:197], 0
	v_mfma_f32_16x16x32_bf16 v[64:67], v[210:213], v[194:197], 0
	v_mfma_f32_16x16x32_bf16 v[116:119], v[206:209], v[148:151], v[116:119]
	v_mfma_f32_16x16x32_bf16 v[112:115], v[214:217], v[148:151], v[112:115]
	v_mfma_f32_16x16x32_bf16 v[100:103], v[206:209], v[174:177], v[100:103]
	v_mfma_f32_16x16x32_bf16 v[96:99], v[214:217], v[174:177], v[96:99]
	v_mfma_f32_16x16x32_bf16 v[84:87], v[206:209], v[182:185], v[84:87]
	v_mfma_f32_16x16x32_bf16 v[80:83], v[214:217], v[182:185], v[80:83]
	v_mfma_f32_16x16x32_bf16 v[68:71], v[206:209], v[198:201], v[68:71]
	v_mfma_f32_16x16x32_bf16 v[64:67], v[214:217], v[198:201], v[64:67]
	s_setprio 1
	s_mov_b32 m0, s9
	v_lshl_add_u64 v[220:221], s[24:25], 0, v[154:155]
	s_barrier
	ds_read_b128 v[144:147], v191 offset:16384
	ds_read_b128 v[148:151], v191 offset:17408
	ds_read_b128 v[170:173], v191 offset:18432
	ds_read_b128 v[174:177], v191 offset:19456
	ds_read_b128 v[178:181], v191 offset:20480
	ds_read_b128 v[182:185], v191 offset:21504
	ds_read_b128 v[194:197], v191 offset:22528
	ds_read_b128 v[198:201], v191 offset:23552
	global_load_lds_dwordx4 v[220:221], off
	v_lshl_add_u64 v[222:223], s[24:25], 0, v[158:159]
	s_mov_b32 m0, s30
	s_nop 0
	global_load_lds_dwordx4 v[222:223], off
	s_barrier
	s_waitcnt lgkmcnt(0)
	s_setprio 2
	s_waitcnt lgkmcnt(0)
	v_mfma_f32_16x16x32_bf16 v[60:63], v[128:131], v[144:147], 0
	v_mfma_f32_16x16x32_bf16 v[56:59], v[136:139], v[144:147], 0
	v_mfma_f32_16x16x32_bf16 v[44:47], v[128:131], v[170:173], 0
	v_mfma_f32_16x16x32_bf16 v[40:43], v[136:139], v[170:173], 0
	v_mfma_f32_16x16x32_bf16 v[28:31], v[128:131], v[178:181], 0
	v_mfma_f32_16x16x32_bf16 v[24:27], v[136:139], v[178:181], 0
	v_mfma_f32_16x16x32_bf16 v[12:15], v[128:131], v[194:197], 0
	v_mfma_f32_16x16x32_bf16 v[8:11], v[136:139], v[194:197], 0
	v_mfma_f32_16x16x32_bf16 v[60:63], v[132:135], v[148:151], v[60:63]
	v_mfma_f32_16x16x32_bf16 v[56:59], v[140:143], v[148:151], v[56:59]
	v_mfma_f32_16x16x32_bf16 v[44:47], v[132:135], v[174:177], v[44:47]
	v_mfma_f32_16x16x32_bf16 v[40:43], v[140:143], v[174:177], v[40:43]
	v_mfma_f32_16x16x32_bf16 v[28:31], v[132:135], v[182:185], v[28:31]
	v_mfma_f32_16x16x32_bf16 v[24:27], v[140:143], v[182:185], v[24:27]
	v_mfma_f32_16x16x32_bf16 v[12:15], v[132:135], v[198:201], v[12:15]
	v_mfma_f32_16x16x32_bf16 v[8:11], v[140:143], v[198:201], v[8:11]
	s_setprio 1
	s_barrier
; #define PG8_STAGE(bufoff, gbase, voff) do { _Pragma("unroll") for (int _i = 0; _i < 2; ++_i) \
;         __builtin_amdgcn_global_load_lds((const unsigned*)((const char*)(gbase) + (voff)[_i]), (LAS unsigned*)(lds + (bufoff) + ldsw + _i * 8192), 16, 0, 0); } while (0)
; #define PG8_LDA(dst, b, h) do { _Pragma("unroll") for (int m = 0; m < 4; ++m) _Pragma("unroll") for (int k = 0; k < 2; ++k) dst[m][k] = *(const LAS bf16x8*)(lds + PG8_SA(b, h) + aoff + m * 2048 + k * 1024); } while (0)
; #define PG8_LDB(dst, b, h) do { _Pragma("unroll") for (int n = 0; n < 2; ++n) _Pragma("unroll") for (int k = 0; k < 2; ++k) dst[n][k] = *(const LAS bf16x8*)(lds + PG8_SB(b, h) + boff + n * 2048 + k * 1024); } while (0)
; #define PG8_MMA(ai, bj, At, Bt) do { __builtin_amdgcn_s_setprio(1); _Pragma("unroll") for (int m = 0; m < 4; ++m) _Pragma("unroll") for (int n = 0; n < 2; ++n) _Pragma("unroll") for (int k = 0; k < 2; ++k) \
;         acc[ai][bj][m][n] = __builtin_amdgcn_mfma_f32_16x16x32_bf16(Bt[n][k], At[m][k], acc[ai][bj][m][n], 0, 0, 0); __builtin_amdgcn_s_setprio(0); } while (0)
; #define PG8_WAIT_V(n) asm volatile("s_waitcnt vmcnt(" #n ")" ::: "memory")
; #define PG8_WAIT_L(n) asm volatile("s_waitcnt lgkmcnt(" #n ")" ::: "memory")
; #define PG8_BAR __builtin_amdgcn_s_barrier()
; #define PG8_SCHED __builtin_amdgcn_sched_barrier(0)
; template <class Epi>
; __device__ __forceinline__ void gemm_phase(LAS unsigned char* lds, const Gemm g, const StaticOrder& S, const Epi& E) {
;     ...
;             PG8_STAGE(PG8_SB(0, 1), b2 + hstepB, voffB);
;             PG8_WAIT_V(6); PG8_BAR; PG8_MMA(1, 1, At, B1); PG8_BAR;
;             PG8_LDB(B0, 1, 0); PG8_SCHED; PG8_LDA(At, 1, 0); PG8_STAGE(PG8_SA(0, 1), a2 + hstepA, voffA);
;             PG8_WAIT_L(8); PG8_BAR; PG8_WAIT_L(0); PG8_MMA(0, 0, At, B0); PG8_BAR; PG8_SCHED;
;             PG8_LDB(B1, 1, 1); PG8_STAGE(PG8_SB(1, 0), b3, voffB);
;             PG8_BAR; PG8_WAIT_L(0); PG8_MMA(0, 1, At, B1); PG8_BAR;
;             PG8_LDA(At, 1, 1); PG8_STAGE(PG8_SA(1, 0), a3, voffA);
	s_add_u32 s48, s22, 0x40000
	s_addc_u32 s49, s23, 0
	s_add_i32 s47, s41, s29
	v_lshl_add_u64 v[128:129], s[48:49], 0, v[156:157]
	s_mov_b32 m0, s47
	s_nop 0
	global_load_lds_dwordx4 v[128:129], off
	v_lshl_add_u64 v[128:129], s[48:49], 0, v[160:161]
	s_add_i32 m0, s47, 0x2000
	s_nop 0
	global_load_lds_dwordx4 v[128:129], off
	s_waitcnt vmcnt(6)
	s_barrier
	s_setprio 2
	v_mfma_f32_16x16x32_bf16 v[52:55], v[202:205], v[144:147], 0
	v_mfma_f32_16x16x32_bf16 v[48:51], v[210:213], v[144:147], 0
	v_mfma_f32_16x16x32_bf16 v[36:39], v[202:205], v[170:173], 0
	v_mfma_f32_16x16x32_bf16 v[32:35], v[210:213], v[170:173], 0
	v_mfma_f32_16x16x32_bf16 v[20:23], v[202:205], v[178:181], 0
	v_mfma_f32_16x16x32_bf16 v[16:19], v[210:213], v[178:181], 0
	v_mfma_f32_16x16x32_bf16 v[4:7], v[202:205], v[194:197], 0
	v_mfma_f32_16x16x32_bf16 v[0:3], v[210:213], v[194:197], 0
	v_mfma_f32_16x16x32_bf16 v[52:55], v[206:209], v[148:151], v[52:55]
	v_mfma_f32_16x16x32_bf16 v[48:51], v[214:217], v[148:151], v[48:51]
	v_mfma_f32_16x16x32_bf16 v[36:39], v[206:209], v[174:177], v[36:39]
	v_mfma_f32_16x16x32_bf16 v[32:35], v[214:217], v[174:177], v[32:35]
	v_mfma_f32_16x16x32_bf16 v[20:23], v[206:209], v[182:185], v[20:23]
	v_mfma_f32_16x16x32_bf16 v[16:19], v[214:217], v[182:185], v[16:19]
	v_mfma_f32_16x16x32_bf16 v[4:7], v[206:209], v[198:201], v[4:7]
	v_mfma_f32_16x16x32_bf16 v[0:3], v[214:217], v[198:201], v[0:3]
	s_setprio 1
	s_add_i32 s47, 0, 0x18000
	v_add_u32_e32 v140, s47, v188
	s_barrier
	ds_read_b128 v[128:131], v140
	ds_read_b128 v[132:135], v140 offset:1024
	ds_read_b128 v[136:139], v140 offset:2048
	ds_read_b128 v[140:143], v140 offset:3072
	s_add_u32 s24, s24, 0x140000
	s_addc_u32 s25, s25, 0
	s_mov_b32 m0, s31
	v_lshl_add_u64 v[202:203], s[24:25], 0, v[154:155]
	ds_read_b128 v[144:147], v191 offset:32768
	ds_read_b128 v[148:151], v191 offset:33792
	ds_read_b128 v[170:173], v191 offset:34816
	ds_read_b128 v[174:177], v191 offset:35840
	ds_read_b128 v[178:181], v191 offset:36864
	ds_read_b128 v[182:185], v191 offset:37888
	ds_read_b128 v[194:197], v191 offset:38912
	ds_read_b128 v[198:201], v191 offset:39936
	global_load_lds_dwordx4 v[202:203], off
	v_lshl_add_u64 v[202:203], s[24:25], 0, v[158:159]
	s_mov_b32 m0, s34
	s_nop 0
	global_load_lds_dwordx4 v[202:203], off
	s_waitcnt lgkmcnt(8)
	s_barrier
	s_waitcnt lgkmcnt(0)
	s_setprio 2
	s_waitcnt lgkmcnt(0)
	v_mfma_f32_16x16x32_bf16 v[124:127], v[128:131], v[144:147], v[124:127]
	v_mfma_f32_16x16x32_bf16 v[120:123], v[136:139], v[144:147], v[120:123]
	v_mfma_f32_16x16x32_bf16 v[108:111], v[128:131], v[170:173], v[108:111]
	v_mfma_f32_16x16x32_bf16 v[104:107], v[136:139], v[170:173], v[104:107]
	v_mfma_f32_16x16x32_bf16 v[92:95], v[128:131], v[178:181], v[92:95]
	v_mfma_f32_16x16x32_bf16 v[88:91], v[136:139], v[178:181], v[88:91]
	v_mfma_f32_16x16x32_bf16 v[76:79], v[128:131], v[194:197], v[76:79]
	v_mfma_f32_16x16x32_bf16 v[72:75], v[136:139], v[194:197], v[72:75]
	v_mfma_f32_16x16x32_bf16 v[124:127], v[132:135], v[148:151], v[124:127]
	v_mfma_f32_16x16x32_bf16 v[120:123], v[140:143], v[148:151], v[120:123]
	v_mfma_f32_16x16x32_bf16 v[108:111], v[132:135], v[174:177], v[108:111]
	v_mfma_f32_16x16x32_bf16 v[104:107], v[140:143], v[174:177], v[104:107]
	v_mfma_f32_16x16x32_bf16 v[92:95], v[132:135], v[182:185], v[92:95]
	v_mfma_f32_16x16x32_bf16 v[88:91], v[140:143], v[182:185], v[88:91]
	v_mfma_f32_16x16x32_bf16 v[76:79], v[132:135], v[198:201], v[76:79]
	v_mfma_f32_16x16x32_bf16 v[72:75], v[140:143], v[198:201], v[72:75]
	s_setprio 1
	s_barrier
	s_add_i32 s24, 0, 0x1c000
	s_add_i32 s25, s47, s29
	v_add_u32_e32 v214, s24, v188
	v_lshl_add_u64 v[186:187], v[186:187], 0, s[14:15]
	s_mov_b32 m0, s25
	ds_read_b128 v[202:205], v214
	ds_read_b128 v[206:209], v214 offset:1024
	ds_read_b128 v[210:213], v214 offset:2048
	ds_read_b128 v[214:217], v214 offset:3072
	global_load_lds_dwordx4 v[186:187], off
	v_lshl_add_u64 v[186:187], v[218:219], 0, s[14:15]
	s_add_i32 m0, s25, 0x2000
	s_nop 0
	global_load_lds_dwordx4 v[186:187], off
	s_barrier
	s_waitcnt lgkmcnt(0)
	s_setprio 2
	s_waitcnt lgkmcnt(0)
	v_mfma_f32_16x16x32_bf16 v[116:119], v[202:205], v[144:147], v[116:119]
	v_mfma_f32_16x16x32_bf16 v[112:115], v[210:213], v[144:147], v[112:115]
	v_mfma_f32_16x16x32_bf16 v[100:103], v[202:205], v[170:173], v[100:103]
	v_mfma_f32_16x16x32_bf16 v[96:99], v[210:213], v[170:173], v[96:99]
	v_mfma_f32_16x16x32_bf16 v[84:87], v[202:205], v[178:181], v[84:87]
	v_mfma_f32_16x16x32_bf16 v[80:83], v[210:213], v[178:181], v[80:83]
	v_mfma_f32_16x16x32_bf16 v[68:71], v[202:205], v[194:197], v[68:71]
	v_mfma_f32_16x16x32_bf16 v[64:67], v[210:213], v[194:197], v[64:67]
	v_mfma_f32_16x16x32_bf16 v[116:119], v[206:209], v[148:151], v[116:119]
	v_mfma_f32_16x16x32_bf16 v[112:115], v[214:217], v[148:151], v[112:115]
	v_mfma_f32_16x16x32_bf16 v[100:103], v[206:209], v[174:177], v[100:103]
	v_mfma_f32_16x16x32_bf16 v[96:99], v[214:217], v[174:177], v[96:99]
	v_mfma_f32_16x16x32_bf16 v[84:87], v[206:209], v[182:185], v[84:87]
	v_mfma_f32_16x16x32_bf16 v[80:83], v[214:217], v[182:185], v[80:83]
	v_mfma_f32_16x16x32_bf16 v[68:71], v[206:209], v[198:201], v[68:71]
	v_mfma_f32_16x16x32_bf16 v[64:67], v[214:217], v[198:201], v[64:67]
	s_setprio 1
	s_mov_b32 m0, s36
	v_lshl_add_u64 v[186:187], v[220:221], 0, s[14:15]
	s_barrier
	ds_read_b128 v[144:147], v191 offset:49152
	ds_read_b128 v[148:151], v191 offset:50176
	ds_read_b128 v[170:173], v191 offset:51200
	ds_read_b128 v[174:177], v191 offset:52224
	ds_read_b128 v[178:181], v191 offset:53248
	ds_read_b128 v[182:185], v191 offset:54272
	ds_read_b128 v[194:197], v191 offset:55296
	ds_read_b128 v[198:201], v191 offset:56320
	global_load_lds_dwordx4 v[186:187], off
	v_lshl_add_u64 v[186:187], v[222:223], 0, s[14:15]
	s_mov_b32 m0, s37
	s_nop 0
	global_load_lds_dwordx4 v[186:187], off
	s_barrier
; #define PG8_STAGE(bufoff, gbase, voff) do { _Pragma("unroll") for (int _i = 0; _i < 2; ++_i) \
;         __builtin_amdgcn_global_load_lds((const unsigned*)((const char*)(gbase) + (voff)[_i]), (LAS unsigned*)(lds + (bufoff) + ldsw + _i * 8192), 16, 0, 0); } while (0)
; #define PG8_LDA(dst, b, h) do { _Pragma("unroll") for (int m = 0; m < 4; ++m) _Pragma("unroll") for (int k = 0; k < 2; ++k) dst[m][k] = *(const LAS bf16x8*)(lds + PG8_SA(b, h) + aoff + m * 2048 + k * 1024); } while (0)
; #define PG8_LDB(dst, b, h) do { _Pragma("unroll") for (int n = 0; n < 2; ++n) _Pragma("unroll") for (int k = 0; k < 2; ++k) dst[n][k] = *(const LAS bf16x8*)(lds + PG8_SB(b, h) + boff + n * 2048 + k * 1024); } while (0)
; #define PG8_MMA(ai, bj, At, Bt) do { __builtin_amdgcn_s_setprio(1); _Pragma("unroll") for (int m = 0; m < 4; ++m) _Pragma("unroll") for (int n = 0; n < 2; ++n) _Pragma("unroll") for (int k = 0; k < 2; ++k) \
;         acc[ai][bj][m][n] = __builtin_amdgcn_mfma_f32_16x16x32_bf16(Bt[n][k], At[m][k], acc[ai][bj][m][n], 0, 0, 0); __builtin_amdgcn_s_setprio(0); } while (0)
; #define PG8_WAIT_V(n) asm volatile("s_waitcnt vmcnt(" #n ")" ::: "memory")
; #define PG8_WAIT_L(n) asm volatile("s_waitcnt lgkmcnt(" #n ")" ::: "memory")
; #define PG8_BAR __builtin_amdgcn_s_barrier()
; #define PG8_SCHED __builtin_amdgcn_sched_barrier(0)
; template <class Epi>
; __device__ __forceinline__ void gemm_phase(LAS unsigned char* lds, const Gemm g, const StaticOrder& S, const Epi& E) {
;     ...
;             PG8_LDB(B0, 0, 0); PG8_SCHED; PG8_LDA(At, 0, 0); PG8_STAGE(PG8_SA(1, 1), a1 + hstepA, voffA);
;             PG8_WAIT_L(8); PG8_BAR; PG8_WAIT_L(0); PG8_MMA(0, 0, At, B0); PG8_BAR; PG8_SCHED;
;             PG8_LDB(B1, 0, 1); PG8_STAGE(PG8_SB(0, 0), b2, voffB);
;             PG8_BAR; PG8_WAIT_L(0); PG8_MMA(0, 1, At, B1); PG8_BAR;
;     ...
;             PG8_BAR; PG8_WAIT_L(0); PG8_MMA(1, 0, At, B0); PG8_BAR; PG8_SCHED;
;             PG8_STAGE(PG8_SB(1, 1), b3 + hstepB, voffB);
;             PG8_WAIT_V(6); PG8_BAR; PG8_MMA(1, 1, At, B1); PG8_BAR;
	s_waitcnt lgkmcnt(0)
	s_setprio 2
	s_waitcnt lgkmcnt(0)
	v_mfma_f32_16x16x32_bf16 v[60:63], v[128:131], v[144:147], v[60:63]
	v_mfma_f32_16x16x32_bf16 v[56:59], v[136:139], v[144:147], v[56:59]
	v_mfma_f32_16x16x32_bf16 v[44:47], v[128:131], v[170:173], v[44:47]
	v_mfma_f32_16x16x32_bf16 v[40:43], v[136:139], v[170:173], v[40:43]
	v_mfma_f32_16x16x32_bf16 v[28:31], v[128:131], v[178:181], v[28:31]
	v_mfma_f32_16x16x32_bf16 v[24:27], v[136:139], v[178:181], v[24:27]
	v_mfma_f32_16x16x32_bf16 v[12:15], v[128:131], v[194:197], v[12:15]
	v_mfma_f32_16x16x32_bf16 v[8:11], v[136:139], v[194:197], v[8:11]
	v_mfma_f32_16x16x32_bf16 v[60:63], v[132:135], v[148:151], v[60:63]
	v_mfma_f32_16x16x32_bf16 v[56:59], v[140:143], v[148:151], v[56:59]
	v_mfma_f32_16x16x32_bf16 v[44:47], v[132:135], v[174:177], v[44:47]
	v_mfma_f32_16x16x32_bf16 v[40:43], v[140:143], v[174:177], v[40:43]
	v_mfma_f32_16x16x32_bf16 v[28:31], v[132:135], v[182:185], v[28:31]
	v_mfma_f32_16x16x32_bf16 v[24:27], v[140:143], v[182:185], v[24:27]
	v_mfma_f32_16x16x32_bf16 v[12:15], v[132:135], v[198:201], v[12:15]
	v_mfma_f32_16x16x32_bf16 v[8:11], v[140:143], v[198:201], v[8:11]
	s_setprio 1
	s_barrier
	s_add_u32 s22, s22, 0x40080
	s_addc_u32 s23, s23, 0
	s_add_i32 s24, s24, s29
	v_lshl_add_u64 v[128:129], s[22:23], 0, v[156:157]
	s_mov_b32 m0, s24
	s_nop 0
	global_load_lds_dwordx4 v[128:129], off
	v_lshl_add_u64 v[128:129], s[22:23], 0, v[160:161]
	s_add_i32 m0, s24, 0x2000
	s_nop 0
	global_load_lds_dwordx4 v[128:129], off
	s_waitcnt vmcnt(6)
	s_barrier
	s_setprio 2
	v_mfma_f32_16x16x32_bf16 v[52:55], v[202:205], v[144:147], v[52:55]
	v_mfma_f32_16x16x32_bf16 v[48:51], v[210:213], v[144:147], v[48:51]
	v_mfma_f32_16x16x32_bf16 v[36:39], v[202:205], v[170:173], v[36:39]
	v_mfma_f32_16x16x32_bf16 v[32:35], v[210:213], v[170:173], v[32:35]
	v_mfma_f32_16x16x32_bf16 v[20:23], v[202:205], v[178:181], v[20:23]
	v_mfma_f32_16x16x32_bf16 v[16:19], v[210:213], v[178:181], v[16:19]
	v_mfma_f32_16x16x32_bf16 v[4:7], v[202:205], v[194:197], v[4:7]
	v_mfma_f32_16x16x32_bf16 v[0:3], v[210:213], v[194:197], v[0:3]
	v_mfma_f32_16x16x32_bf16 v[52:55], v[206:209], v[148:151], v[52:55]
	v_mfma_f32_16x16x32_bf16 v[48:51], v[214:217], v[148:151], v[48:51]
	v_mfma_f32_16x16x32_bf16 v[36:39], v[206:209], v[174:177], v[36:39]
	v_mfma_f32_16x16x32_bf16 v[32:35], v[214:217], v[174:177], v[32:35]
	v_mfma_f32_16x16x32_bf16 v[20:23], v[206:209], v[182:185], v[20:23]
	v_mfma_f32_16x16x32_bf16 v[16:19], v[214:217], v[182:185], v[16:19]
	v_mfma_f32_16x16x32_bf16 v[4:7], v[206:209], v[198:201], v[4:7]
	v_mfma_f32_16x16x32_bf16 v[0:3], v[214:217], v[198:201], v[0:3]
	s_setprio 1
	s_add_i32 s46, s46, 2
	s_add_u32 s4, s4, 0x100
	s_addc_u32 s5, s5, 0
	s_add_u32 s44, s44, 0x100
	s_addc_u32 s45, s45, 0
	s_cmp_gt_u32 s46, 13
	s_barrier
.Lkp5_1118:
	ds_read_b128 v[128:131], v190
	ds_read_b128 v[132:135], v190 offset:1024
	ds_read_b128 v[136:139], v190 offset:2048
	ds_read_b128 v[140:143], v190 offset:3072
	s_add_u32 s22, s4, 0xffec0080
	s_addc_u32 s23, s5, -1
	s_cmp_eq_u32 s46, 12
	s_cselect_b32 s25, s19, s23
	s_cselect_b32 s24, s18, s22
	s_cselect_b32 s23, s17, s45
	s_cselect_b32 s22, s43, s44
	v_lshl_add_u64 v[186:187], s[4:5], 0, v[162:163]
	s_add_i32 m0, s9, 0xc000
	ds_read_b128 v[144:147], v191
	ds_read_b128 v[148:151], v191 offset:1024
	ds_read_b128 v[170:173], v191 offset:2048
	ds_read_b128 v[174:177], v191 offset:3072
	ds_read_b128 v[178:181], v191 offset:4096
	ds_read_b128 v[182:185], v191 offset:5120
	ds_read_b128 v[194:197], v191 offset:6144
	ds_read_b128 v[198:201], v191 offset:7168
	global_load_lds_dwordx4 v[186:187], off
	v_lshl_add_u64 v[186:187], s[4:5], 0, v[164:165]
	s_add_i32 m0, s9, 0xe000
	s_nop 0
	global_load_lds_dwordx4 v[186:187], off
	s_waitcnt lgkmcnt(8)
	s_barrier
	s_waitcnt lgkmcnt(0)
	s_setprio 2
	s_waitcnt lgkmcnt(0)
	v_mfma_f32_16x16x32_bf16 v[124:127], v[128:131], v[144:147], v[124:127]
	v_mfma_f32_16x16x32_bf16 v[120:123], v[136:139], v[144:147], v[120:123]
	v_mfma_f32_16x16x32_bf16 v[108:111], v[128:131], v[170:173], v[108:111]
	v_mfma_f32_16x16x32_bf16 v[104:107], v[136:139], v[170:173], v[104:107]
	v_mfma_f32_16x16x32_bf16 v[92:95], v[128:131], v[178:181], v[92:95]
	v_mfma_f32_16x16x32_bf16 v[88:91], v[136:139], v[178:181], v[88:91]
	v_mfma_f32_16x16x32_bf16 v[76:79], v[128:131], v[194:197], v[76:79]
	v_mfma_f32_16x16x32_bf16 v[72:75], v[136:139], v[194:197], v[72:75]
	v_mfma_f32_16x16x32_bf16 v[124:127], v[132:135], v[148:151], v[124:127]
	v_mfma_f32_16x16x32_bf16 v[120:123], v[140:143], v[148:151], v[120:123]
	v_mfma_f32_16x16x32_bf16 v[108:111], v[132:135], v[174:177], v[108:111]
	v_mfma_f32_16x16x32_bf16 v[104:107], v[140:143], v[174:177], v[104:107]
	v_mfma_f32_16x16x32_bf16 v[92:95], v[132:135], v[182:185], v[92:95]
	v_mfma_f32_16x16x32_bf16 v[88:91], v[140:143], v[182:185], v[88:91]
	v_mfma_f32_16x16x32_bf16 v[76:79], v[132:135], v[198:201], v[76:79]
	v_mfma_f32_16x16x32_bf16 v[72:75], v[140:143], v[198:201], v[72:75]
	s_setprio 1
	s_barrier
	s_add_i32 s47, s40, s29
	v_lshl_add_u64 v[186:187], s[22:23], 0, v[156:157]
	s_mov_b32 m0, s47
	ds_read_b128 v[202:205], v192
	ds_read_b128 v[206:209], v192 offset:1024
	ds_read_b128 v[210:213], v192 offset:2048
	ds_read_b128 v[214:217], v192 offset:3072
	global_load_lds_dwordx4 v[186:187], off
	v_lshl_add_u64 v[218:219], s[22:23], 0, v[160:161]
	s_add_i32 m0, s47, 0x2000
	s_nop 0
	global_load_lds_dwordx4 v[218:219], off
	s_barrier
; #define PG8_STAGE(bufoff, gbase, voff) do { _Pragma("unroll") for (int _i = 0; _i < 2; ++_i) \
;         __builtin_amdgcn_global_load_lds((const unsigned*)((const char*)(gbase) + (voff)[_i]), (LAS unsigned*)(lds + (bufoff) + ldsw + _i * 8192), 16, 0, 0); } while (0)
; #define PG8_LDA(dst, b, h) do { _Pragma("unroll") for (int m = 0; m < 4; ++m) _Pragma("unroll") for (int k = 0; k < 2; ++k) dst[m][k] = *(const LAS bf16x8*)(lds + PG8_SA(b, h) + aoff + m * 2048 + k * 1024); } while (0)
; #define PG8_LDB(dst, b, h) do { _Pragma("unroll") for (int n = 0; n < 2; ++n) _Pragma("unroll") for (int k = 0; k < 2; ++k) dst[n][k] = *(const LAS bf16x8*)(lds + PG8_SB(b, h) + boff + n * 2048 + k * 1024); } while (0)
; #define PG8_MMA(ai, bj, At, Bt) do { __builtin_amdgcn_s_setprio(1); _Pragma("unroll") for (int m = 0; m < 4; ++m) _Pragma("unroll") for (int n = 0; n < 2; ++n) _Pragma("unroll") for (int k = 0; k < 2; ++k) \
;         acc[ai][bj][m][n] = __builtin_amdgcn_mfma_f32_16x16x32_bf16(Bt[n][k], At[m][k], acc[ai][bj][m][n], 0, 0, 0); __builtin_amdgcn_s_setprio(0); } while (0)
; #define PG8_WAIT_V(n) asm volatile("s_waitcnt vmcnt(" #n ")" ::: "memory")
; #define PG8_WAIT_L(n) asm volatile("s_waitcnt lgkmcnt(" #n ")" ::: "memory")
; #define PG8_BAR __builtin_amdgcn_s_barrier()
; #define PG8_SCHED __builtin_amdgcn_sched_barrier(0)
; template <class Epi>
; __device__ __forceinline__ void gemm_phase(LAS unsigned char* lds, const Gemm g, const StaticOrder& S, const Epi& E) {
;     ...
;             PG8_BAR; PG8_WAIT_L(0); PG8_MMA(0, 1, At, B1); PG8_BAR;
;             PG8_LDA(At, 0, 1); PG8_STAGE(PG8_SA(0, 0), a2, voffA);
;             PG8_BAR; PG8_WAIT_L(0); PG8_MMA(1, 0, At, B0); PG8_BAR; PG8_SCHED;
;             PG8_STAGE(PG8_SB(0, 1), b2 + hstepB, voffB);
;             PG8_WAIT_V(6); PG8_BAR; PG8_MMA(1, 1, At, B1); PG8_BAR;
;             PG8_LDB(B0, 1, 0); PG8_SCHED; PG8_LDA(At, 1, 0); PG8_STAGE(PG8_SA(0, 1), a2 + hstepA, voffA);
;             PG8_WAIT_L(8); PG8_BAR; PG8_WAIT_L(0); PG8_MMA(0, 0, At, B0); PG8_BAR; PG8_SCHED;
;             PG8_LDB(B1, 1, 1); PG8_STAGE(PG8_SB(1, 0), b3, voffB);
;             PG8_BAR; PG8_WAIT_L(0); PG8_MMA(0, 1, At, B1); PG8_BAR;
;             PG8_LDA(At, 1, 1); PG8_STAGE(PG8_SA(1, 0), a3, voffA);
	s_waitcnt lgkmcnt(0)
	s_setprio 2
	s_waitcnt lgkmcnt(0)
	v_mfma_f32_16x16x32_bf16 v[116:119], v[202:205], v[144:147], v[116:119]
	v_mfma_f32_16x16x32_bf16 v[112:115], v[210:213], v[144:147], v[112:115]
	v_mfma_f32_16x16x32_bf16 v[100:103], v[202:205], v[170:173], v[100:103]
	v_mfma_f32_16x16x32_bf16 v[96:99], v[210:213], v[170:173], v[96:99]
	v_mfma_f32_16x16x32_bf16 v[84:87], v[202:205], v[178:181], v[84:87]
	v_mfma_f32_16x16x32_bf16 v[80:83], v[210:213], v[178:181], v[80:83]
	v_mfma_f32_16x16x32_bf16 v[68:71], v[202:205], v[194:197], v[68:71]
	v_mfma_f32_16x16x32_bf16 v[64:67], v[210:213], v[194:197], v[64:67]
	v_mfma_f32_16x16x32_bf16 v[116:119], v[206:209], v[148:151], v[116:119]
	v_mfma_f32_16x16x32_bf16 v[112:115], v[214:217], v[148:151], v[112:115]
	v_mfma_f32_16x16x32_bf16 v[100:103], v[206:209], v[174:177], v[100:103]
	v_mfma_f32_16x16x32_bf16 v[96:99], v[214:217], v[174:177], v[96:99]
	v_mfma_f32_16x16x32_bf16 v[84:87], v[206:209], v[182:185], v[84:87]
	v_mfma_f32_16x16x32_bf16 v[80:83], v[214:217], v[182:185], v[80:83]
	v_mfma_f32_16x16x32_bf16 v[68:71], v[206:209], v[198:201], v[68:71]
	v_mfma_f32_16x16x32_bf16 v[64:67], v[214:217], v[198:201], v[64:67]
	s_setprio 1
	s_mov_b32 m0, s9
	v_lshl_add_u64 v[220:221], s[24:25], 0, v[154:155]
	s_barrier
	ds_read_b128 v[144:147], v191 offset:16384
	ds_read_b128 v[148:151], v191 offset:17408
	ds_read_b128 v[170:173], v191 offset:18432
	ds_read_b128 v[174:177], v191 offset:19456
	ds_read_b128 v[178:181], v191 offset:20480
	ds_read_b128 v[182:185], v191 offset:21504
	ds_read_b128 v[194:197], v191 offset:22528
	ds_read_b128 v[198:201], v191 offset:23552
	global_load_lds_dwordx4 v[220:221], off
	v_lshl_add_u64 v[222:223], s[24:25], 0, v[158:159]
	s_mov_b32 m0, s30
	s_nop 0
	global_load_lds_dwordx4 v[222:223], off
	s_barrier
	s_waitcnt lgkmcnt(0)
	s_setprio 2
	s_waitcnt lgkmcnt(0)
	v_mfma_f32_16x16x32_bf16 v[60:63], v[128:131], v[144:147], v[60:63]
	v_mfma_f32_16x16x32_bf16 v[56:59], v[136:139], v[144:147], v[56:59]
	v_mfma_f32_16x16x32_bf16 v[44:47], v[128:131], v[170:173], v[44:47]
	v_mfma_f32_16x16x32_bf16 v[40:43], v[136:139], v[170:173], v[40:43]
	v_mfma_f32_16x16x32_bf16 v[28:31], v[128:131], v[178:181], v[28:31]
	v_mfma_f32_16x16x32_bf16 v[24:27], v[136:139], v[178:181], v[24:27]
	v_mfma_f32_16x16x32_bf16 v[12:15], v[128:131], v[194:197], v[12:15]
	v_mfma_f32_16x16x32_bf16 v[8:11], v[136:139], v[194:197], v[8:11]
	v_mfma_f32_16x16x32_bf16 v[60:63], v[132:135], v[148:151], v[60:63]
	v_mfma_f32_16x16x32_bf16 v[56:59], v[140:143], v[148:151], v[56:59]
	v_mfma_f32_16x16x32_bf16 v[44:47], v[132:135], v[174:177], v[44:47]
	v_mfma_f32_16x16x32_bf16 v[40:43], v[140:143], v[174:177], v[40:43]
	v_mfma_f32_16x16x32_bf16 v[28:31], v[132:135], v[182:185], v[28:31]
	v_mfma_f32_16x16x32_bf16 v[24:27], v[140:143], v[182:185], v[24:27]
	v_mfma_f32_16x16x32_bf16 v[12:15], v[132:135], v[198:201], v[12:15]
	v_mfma_f32_16x16x32_bf16 v[8:11], v[140:143], v[198:201], v[8:11]
	s_setprio 1
	s_barrier
	s_add_u32 s48, s22, 0x40000
	s_addc_u32 s49, s23, 0
	s_add_i32 s47, s41, s29
	v_lshl_add_u64 v[128:129], s[48:49], 0, v[156:157]
	s_mov_b32 m0, s47
	s_nop 0
	global_load_lds_dwordx4 v[128:129], off
	v_lshl_add_u64 v[128:129], s[48:49], 0, v[160:161]
	s_add_i32 m0, s47, 0x2000
	s_nop 0
	global_load_lds_dwordx4 v[128:129], off
	s_waitcnt vmcnt(6)
	s_barrier
	s_setprio 2
	v_mfma_f32_16x16x32_bf16 v[52:55], v[202:205], v[144:147], v[52:55]
	v_mfma_f32_16x16x32_bf16 v[48:51], v[210:213], v[144:147], v[48:51]
	v_mfma_f32_16x16x32_bf16 v[36:39], v[202:205], v[170:173], v[36:39]
	v_mfma_f32_16x16x32_bf16 v[32:35], v[210:213], v[170:173], v[32:35]
	v_mfma_f32_16x16x32_bf16 v[20:23], v[202:205], v[178:181], v[20:23]
	v_mfma_f32_16x16x32_bf16 v[16:19], v[210:213], v[178:181], v[16:19]
	v_mfma_f32_16x16x32_bf16 v[4:7], v[202:205], v[194:197], v[4:7]
	v_mfma_f32_16x16x32_bf16 v[0:3], v[210:213], v[194:197], v[0:3]
	v_mfma_f32_16x16x32_bf16 v[52:55], v[206:209], v[148:151], v[52:55]
	v_mfma_f32_16x16x32_bf16 v[48:51], v[214:217], v[148:151], v[48:51]
	v_mfma_f32_16x16x32_bf16 v[36:39], v[206:209], v[174:177], v[36:39]
	v_mfma_f32_16x16x32_bf16 v[32:35], v[214:217], v[174:177], v[32:35]
	v_mfma_f32_16x16x32_bf16 v[20:23], v[206:209], v[182:185], v[20:23]
	v_mfma_f32_16x16x32_bf16 v[16:19], v[214:217], v[182:185], v[16:19]
	v_mfma_f32_16x16x32_bf16 v[4:7], v[206:209], v[198:201], v[4:7]
	v_mfma_f32_16x16x32_bf16 v[0:3], v[214:217], v[198:201], v[0:3]
	s_setprio 1
	s_add_i32 s47, 0, 0x18000
	v_add_u32_e32 v140, s47, v188
	s_barrier
	ds_read_b128 v[128:131], v140
	ds_read_b128 v[132:135], v140 offset:1024
	ds_read_b128 v[136:139], v140 offset:2048
	ds_read_b128 v[140:143], v140 offset:3072
	s_add_u32 s24, s24, 0x140000
	s_addc_u32 s25, s25, 0
	s_mov_b32 m0, s31
	v_lshl_add_u64 v[202:203], s[24:25], 0, v[154:155]
	ds_read_b128 v[144:147], v191 offset:32768
	ds_read_b128 v[148:151], v191 offset:33792
	ds_read_b128 v[170:173], v191 offset:34816
	ds_read_b128 v[174:177], v191 offset:35840
	ds_read_b128 v[178:181], v191 offset:36864
	ds_read_b128 v[182:185], v191 offset:37888
	ds_read_b128 v[194:197], v191 offset:38912
	ds_read_b128 v[198:201], v191 offset:39936
	global_load_lds_dwordx4 v[202:203], off
	v_lshl_add_u64 v[202:203], s[24:25], 0, v[158:159]
	s_mov_b32 m0, s34
	s_nop 0
	global_load_lds_dwordx4 v[202:203], off
	s_waitcnt lgkmcnt(8)
	s_barrier
; #define PG8_STAGE(bufoff, gbase, voff) do { _Pragma("unroll") for (int _i = 0; _i < 2; ++_i) \
;         __builtin_amdgcn_global_load_lds((const unsigned*)((const char*)(gbase) + (voff)[_i]), (LAS unsigned*)(lds + (bufoff) + ldsw + _i * 8192), 16, 0, 0); } while (0)
; #define PG8_LDA(dst, b, h) do { _Pragma("unroll") for (int m = 0; m < 4; ++m) _Pragma("unroll") for (int k = 0; k < 2; ++k) dst[m][k] = *(const LAS bf16x8*)(lds + PG8_SA(b, h) + aoff + m * 2048 + k * 1024); } while (0)
; #define PG8_LDB(dst, b, h) do { _Pragma("unroll") for (int n = 0; n < 2; ++n) _Pragma("unroll") for (int k = 0; k < 2; ++k) dst[n][k] = *(const LAS bf16x8*)(lds + PG8_SB(b, h) + boff + n * 2048 + k * 1024); } while (0)
; #define PG8_MMA(ai, bj, At, Bt) do { __builtin_amdgcn_s_setprio(1); _Pragma("unroll") for (int m = 0; m < 4; ++m) _Pragma("unroll") for (int n = 0; n < 2; ++n) _Pragma("unroll") for (int k = 0; k < 2; ++k) \
;         acc[ai][bj][m][n] = __builtin_amdgcn_mfma_f32_16x16x32_bf16(Bt[n][k], At[m][k], acc[ai][bj][m][n], 0, 0, 0); __builtin_amdgcn_s_setprio(0); } while (0)
; #define PG8_WAIT_V(n) asm volatile("s_waitcnt vmcnt(" #n ")" ::: "memory")
; #define PG8_BAR __builtin_amdgcn_s_barrier()
;     __device__ bool next(int i, Unit& u) const {
;         const long L = (long)i * G + c; if (L >= nwg) return false;
;         int wgid = (int)L; { const int q = nwg / NXCD, r = nwg % NXCD, xcd = wgid % NXCD, off = wgid / NXCD; wgid = (xcd < r ? xcd * (q + 1) : r * (q + 1) + (xcd - r) * q) + off; }
;         const int nig = WGM * nN, gid = wgid / nig, fm = gid * WGM, gsz = (nM - fm) < WGM ? (nM - fm) : WGM;
;         u.pm = fm + ((wgid % nig) % gsz); u.pn = (wgid % nig) / gsz; return true;
; template <class Epi>
; __device__ __forceinline__ void gemm_phase(LAS unsigned char* lds, const Gemm g, const StaticOrder& S, const Epi& E) {
;     ...
;             PG8_WAIT_L(8); PG8_BAR; PG8_WAIT_L(0); PG8_MMA(0, 0, At, B0); PG8_BAR; PG8_SCHED;
;             PG8_LDB(B1, 1, 1); PG8_STAGE(PG8_SB(1, 0), b3, voffB);
;             PG8_BAR; PG8_WAIT_L(0); PG8_MMA(0, 1, At, B1); PG8_BAR;
;             PG8_LDA(At, 1, 1); PG8_STAGE(PG8_SA(1, 0), a3, voffA);
;             PG8_BAR; PG8_WAIT_L(0); PG8_MMA(1, 0, At, B0); PG8_BAR; PG8_SCHED;
;             PG8_STAGE(PG8_SB(1, 1), b3 + hstepB, voffB);
;             PG8_WAIT_V(6); PG8_BAR; PG8_MMA(1, 1, At, B1); PG8_BAR;
;         }
	s_waitcnt lgkmcnt(0)
	s_setprio 2
	s_waitcnt lgkmcnt(0)
	v_mfma_f32_16x16x32_bf16 v[124:127], v[128:131], v[144:147], v[124:127]
	v_mfma_f32_16x16x32_bf16 v[120:123], v[136:139], v[144:147], v[120:123]
	v_mfma_f32_16x16x32_bf16 v[108:111], v[128:131], v[170:173], v[108:111]
	v_mfma_f32_16x16x32_bf16 v[104:107], v[136:139], v[170:173], v[104:107]
	v_mfma_f32_16x16x32_bf16 v[92:95], v[128:131], v[178:181], v[92:95]
	v_mfma_f32_16x16x32_bf16 v[88:91], v[136:139], v[178:181], v[88:91]
	v_mfma_f32_16x16x32_bf16 v[76:79], v[128:131], v[194:197], v[76:79]
	v_mfma_f32_16x16x32_bf16 v[72:75], v[136:139], v[194:197], v[72:75]
	v_mfma_f32_16x16x32_bf16 v[124:127], v[132:135], v[148:151], v[124:127]
	v_mfma_f32_16x16x32_bf16 v[120:123], v[140:143], v[148:151], v[120:123]
	v_mfma_f32_16x16x32_bf16 v[108:111], v[132:135], v[174:177], v[108:111]
	v_mfma_f32_16x16x32_bf16 v[104:107], v[140:143], v[174:177], v[104:107]
	v_mfma_f32_16x16x32_bf16 v[92:95], v[132:135], v[182:185], v[92:95]
	v_mfma_f32_16x16x32_bf16 v[88:91], v[140:143], v[182:185], v[88:91]
	v_mfma_f32_16x16x32_bf16 v[76:79], v[132:135], v[198:201], v[76:79]
	v_mfma_f32_16x16x32_bf16 v[72:75], v[140:143], v[198:201], v[72:75]
	s_setprio 1
	s_barrier
	s_add_i32 s24, 0, 0x1c000
	s_add_i32 s25, s47, s29
	v_add_u32_e32 v214, s24, v188
	v_lshl_add_u64 v[186:187], v[186:187], 0, s[14:15]
	s_mov_b32 m0, s25
	ds_read_b128 v[202:205], v214
	ds_read_b128 v[206:209], v214 offset:1024
	ds_read_b128 v[210:213], v214 offset:2048
	ds_read_b128 v[214:217], v214 offset:3072
	global_load_lds_dwordx4 v[186:187], off
	v_lshl_add_u64 v[186:187], v[218:219], 0, s[14:15]
	s_add_i32 m0, s25, 0x2000
	s_nop 0
	global_load_lds_dwordx4 v[186:187], off
	s_barrier
	s_waitcnt lgkmcnt(0)
	s_setprio 2
	s_waitcnt lgkmcnt(0)
	v_mfma_f32_16x16x32_bf16 v[116:119], v[202:205], v[144:147], v[116:119]
	v_mfma_f32_16x16x32_bf16 v[112:115], v[210:213], v[144:147], v[112:115]
	v_mfma_f32_16x16x32_bf16 v[100:103], v[202:205], v[170:173], v[100:103]
	v_mfma_f32_16x16x32_bf16 v[96:99], v[210:213], v[170:173], v[96:99]
	v_mfma_f32_16x16x32_bf16 v[84:87], v[202:205], v[178:181], v[84:87]
	v_mfma_f32_16x16x32_bf16 v[80:83], v[210:213], v[178:181], v[80:83]
	v_mfma_f32_16x16x32_bf16 v[68:71], v[202:205], v[194:197], v[68:71]
	v_mfma_f32_16x16x32_bf16 v[64:67], v[210:213], v[194:197], v[64:67]
	v_mfma_f32_16x16x32_bf16 v[116:119], v[206:209], v[148:151], v[116:119]
	v_mfma_f32_16x16x32_bf16 v[112:115], v[214:217], v[148:151], v[112:115]
	v_mfma_f32_16x16x32_bf16 v[100:103], v[206:209], v[174:177], v[100:103]
	v_mfma_f32_16x16x32_bf16 v[96:99], v[214:217], v[174:177], v[96:99]
	v_mfma_f32_16x16x32_bf16 v[84:87], v[206:209], v[182:185], v[84:87]
	v_mfma_f32_16x16x32_bf16 v[80:83], v[214:217], v[182:185], v[80:83]
	v_mfma_f32_16x16x32_bf16 v[68:71], v[206:209], v[198:201], v[68:71]
	v_mfma_f32_16x16x32_bf16 v[64:67], v[214:217], v[198:201], v[64:67]
	s_setprio 1
	s_mov_b32 m0, s36
	v_lshl_add_u64 v[186:187], v[220:221], 0, s[14:15]
	s_barrier
	ds_read_b128 v[144:147], v191 offset:49152
	ds_read_b128 v[148:151], v191 offset:50176
	ds_read_b128 v[170:173], v191 offset:51200
	ds_read_b128 v[174:177], v191 offset:52224
	ds_read_b128 v[178:181], v191 offset:53248
	ds_read_b128 v[182:185], v191 offset:54272
	ds_read_b128 v[194:197], v191 offset:55296
	ds_read_b128 v[198:201], v191 offset:56320
	global_load_lds_dwordx4 v[186:187], off
	v_lshl_add_u64 v[186:187], v[222:223], 0, s[14:15]
	s_mov_b32 m0, s37
	s_nop 0
	global_load_lds_dwordx4 v[186:187], off
	s_barrier
	s_waitcnt lgkmcnt(0)
	s_setprio 2
	s_waitcnt lgkmcnt(0)
	v_mfma_f32_16x16x32_bf16 v[60:63], v[128:131], v[144:147], v[60:63]
	v_mfma_f32_16x16x32_bf16 v[56:59], v[136:139], v[144:147], v[56:59]
	v_mfma_f32_16x16x32_bf16 v[44:47], v[128:131], v[170:173], v[44:47]
	v_mfma_f32_16x16x32_bf16 v[40:43], v[136:139], v[170:173], v[40:43]
	v_mfma_f32_16x16x32_bf16 v[28:31], v[128:131], v[178:181], v[28:31]
	v_mfma_f32_16x16x32_bf16 v[24:27], v[136:139], v[178:181], v[24:27]
	v_mfma_f32_16x16x32_bf16 v[12:15], v[128:131], v[194:197], v[12:15]
	v_mfma_f32_16x16x32_bf16 v[8:11], v[136:139], v[194:197], v[8:11]
	v_mfma_f32_16x16x32_bf16 v[60:63], v[132:135], v[148:151], v[60:63]
	v_mfma_f32_16x16x32_bf16 v[56:59], v[140:143], v[148:151], v[56:59]
	v_mfma_f32_16x16x32_bf16 v[44:47], v[132:135], v[174:177], v[44:47]
	v_mfma_f32_16x16x32_bf16 v[40:43], v[140:143], v[174:177], v[40:43]
	v_mfma_f32_16x16x32_bf16 v[28:31], v[132:135], v[182:185], v[28:31]
	v_mfma_f32_16x16x32_bf16 v[24:27], v[140:143], v[182:185], v[24:27]
	v_mfma_f32_16x16x32_bf16 v[12:15], v[132:135], v[198:201], v[12:15]
	v_mfma_f32_16x16x32_bf16 v[8:11], v[140:143], v[198:201], v[8:11]
	s_setprio 1
	s_barrier
	s_add_u32 s22, s22, 0x40080
	s_addc_u32 s23, s23, 0
	s_add_i32 s24, s24, s29
	v_lshl_add_u64 v[128:129], s[22:23], 0, v[156:157]
	s_mov_b32 m0, s24
	s_nop 0
	global_load_lds_dwordx4 v[128:129], off
	v_lshl_add_u64 v[128:129], s[22:23], 0, v[160:161]
	s_add_i32 m0, s24, 0x2000
	s_nop 0
	global_load_lds_dwordx4 v[128:129], off
	s_waitcnt vmcnt(6)
	s_barrier
	s_setprio 2
	v_mfma_f32_16x16x32_bf16 v[52:55], v[202:205], v[144:147], v[52:55]
	v_mfma_f32_16x16x32_bf16 v[48:51], v[210:213], v[144:147], v[48:51]
	v_mfma_f32_16x16x32_bf16 v[36:39], v[202:205], v[170:173], v[36:39]
	v_mfma_f32_16x16x32_bf16 v[32:35], v[210:213], v[170:173], v[32:35]
	v_mfma_f32_16x16x32_bf16 v[20:23], v[202:205], v[178:181], v[20:23]
	v_mfma_f32_16x16x32_bf16 v[16:19], v[210:213], v[178:181], v[16:19]
	v_mfma_f32_16x16x32_bf16 v[4:7], v[202:205], v[194:197], v[4:7]
	v_mfma_f32_16x16x32_bf16 v[0:3], v[210:213], v[194:197], v[0:3]
	v_mfma_f32_16x16x32_bf16 v[52:55], v[206:209], v[148:151], v[52:55]
	v_mfma_f32_16x16x32_bf16 v[48:51], v[214:217], v[148:151], v[48:51]
	v_mfma_f32_16x16x32_bf16 v[36:39], v[206:209], v[174:177], v[36:39]
	v_mfma_f32_16x16x32_bf16 v[32:35], v[214:217], v[174:177], v[32:35]
	v_mfma_f32_16x16x32_bf16 v[20:23], v[206:209], v[182:185], v[20:23]
	v_mfma_f32_16x16x32_bf16 v[16:19], v[214:217], v[182:185], v[16:19]
	v_mfma_f32_16x16x32_bf16 v[4:7], v[206:209], v[198:201], v[4:7]
	v_mfma_f32_16x16x32_bf16 v[0:3], v[214:217], v[198:201], v[0:3]
	s_setprio 1
	s_add_i32 s46, s46, 2
	s_add_u32 s4, s4, 0x100
	s_addc_u32 s5, s5, 0
	s_add_u32 s44, s44, 0x100
	s_addc_u32 s45, s45, 0
	s_cmp_gt_u32 s46, 13
	s_barrier
	s_cbranch_scc0 .Lkp5_1118
	s_branch .Lkp5_epi
.LBB0_1109:
	v_readfirstlane_b32 s98, v152
	s_nop 3
	s_cmp_ge_u32 s98, 0x100
	s_cbranch_scc1 .Lkp5_head
	s_add_i32 s33, s33, 1
	s_mul_i32 s2, s33, s38
	s_mul_hi_u32 s3, s33, s92
	s_add_i32 s3, s3, s2
	s_mul_i32 s2, s33, s92
	s_add_u32 s18, s2, s93
	s_addc_u32 s19, s3, s39
	v_cmp_gt_i64_e64 s[2:3], s[18:19], v[168:169]
	v_cmp_lt_i64_e64 s[4:5], s[18:19], v[166:167]
	s_and_b64 vcc, exec, s[2:3]
	s_cbranch_vccnz .LBB0_1115
	s_ashr_i32 s16, s18, 31
	s_lshr_b32 s16, s16, 29
	s_add_i32 s19, s18, s16
	s_and_b32 s16, s19, -8
	s_sub_i32 s18, s18, s16
	s_cmp_gt_i32 s18, -1
	s_mov_b64 s[16:17], -1
	s_cbranch_scc0 .LBB0_1112
	s_lshl_b32 s20, s18, 7
	s_mov_b64 s[16:17], 0

; __device__ __forceinline__ unsigned pk2(float lo, float hi) { const f32x2 v = (f32x2){lo, hi}; const bf16x2_t b = __builtin_convertvector(v, bf16x2_t); return __builtin_bit_cast(unsigned, b); }
; __device__ __forceinline__ void unpack8(const u32x4 v, float* f) { f[0] = bf_lo(v.x); f[1] = bf_hi(v.x); f[2] = bf_lo(v.y); f[3] = bf_hi(v.y); f[4] = bf_lo(v.z); f[5] = bf_hi(v.z); f[6] = bf_lo(v.w); f[7] = bf_hi(v.w); }
;     __device__ __forceinline__ void operator()(const f32x4 (&acc)[2][2][4][2], const Unit& u, int wr, int wc, int fr, int fq, const float (&)[8]) const {
;         const int row0 = u.pm * BM + wr * 64 + fr, col0 = u.pn * BM + wc * 32 + 8 * fq;
; #pragma unroll
;         for (int ai = 0; ai < 2; ++ai) {
;             u32x4 bv[4][2];
; #pragma unroll
;             for (int m = 0; m < 4; ++m)
; #pragma unroll
;                 for (int bj = 0; bj < 2; ++bj) bv[m][bj] = *(const u32x4*)(xb + (size_t)(row0 + ai * HALF + m * 16) * DM + col0 + bj * HALF);
; #pragma unroll
;             for (int m = 0; m < 4; ++m) { const int row = row0 + ai * HALF + m * 16; const size_t ro = (size_t)row * DM + col0; float s = 0.f;
; #pragma unroll
;                 for (int bj = 0; bj < 2; ++bj) { float b8[8]; unpack8(bv[m][bj], b8);
;                     const f32x4 v0 = (f32x4){b8[0], b8[1], b8[2], b8[3]} + acc[ai][bj][m][0], v1 = (f32x4){b8[4], b8[5], b8[6], b8[7]} + acc[ai][bj][m][1];
;                     s += v0[0] * v0[0] + v0[1] * v0[1] + v0[2] * v0[2] + v0[3] * v0[3] + v1[0] * v1[0] + v1[1] * v1[1] + v1[2] * v1[2] + v1[3] * v1[3];
;                     if (LAST) { *(f32x4*)(out + ro + bj * HALF) = v0; *(f32x4*)(out + ro + bj * HALF + 4) = v1; }
;                     else { u32x4 w; w.x = pk2(v0[0], v0[1]); w.y = pk2(v0[2], v0[3]); w.z = pk2(v1[0], v1[1]); w.w = pk2(v1[2], v1[3]); *(u32x4*)(xb + ro + bj * HALF) = w; } }
;                 s += __shfl_xor(s, 16); s += __shfl_xor(s, 32);
;                 if (fq == 0) ss[(size_t)row * 16 + u.pn * 4 + wc] = s; }
.Lkp5_epi:
	s_setprio 0
	v_lshl_or_b32 v170, s8, 8, v189
	v_lshl_add_u32 v172, s10, 8, v153
	v_ashrrev_i32_e32 v171, 31, v170
	v_lshlrev_b64 v[204:205], 1, v[170:171]
	v_ashrrev_i32_e32 v173, 31, v172
	v_lshl_add_u64 v[174:175], s[76:77], 0, v[204:205]
	v_lshlrev_b64 v[206:207], 11, v[172:173]
	v_lshl_add_u64 v[128:129], v[174:175], 0, v[206:207]
	global_load_dwordx4 v[196:199], v[128:129], off
	global_load_dwordx4 v[200:203], v[128:129], off offset:256
	v_or_b32_e32 v184, 16, v172
	v_or_b32_e32 v180, 32, v172
	v_or_b32_e32 v176, 48, v172
	v_ashrrev_i32_e32 v185, 31, v184
	v_ashrrev_i32_e32 v181, 31, v180
	v_ashrrev_i32_e32 v177, 31, v176
	v_lshlrev_b64 v[186:187], 11, v[184:185]
	v_lshlrev_b64 v[182:183], 11, v[180:181]
	v_lshlrev_b64 v[178:179], 11, v[176:177]
	v_lshl_add_u64 v[128:129], v[174:175], 0, v[186:187]
	v_lshl_add_u64 v[130:131], v[174:175], 0, v[182:183]
	v_lshl_add_u64 v[194:195], v[174:175], 0, v[178:179]
	global_load_dwordx4 v[148:151], v[128:129], off
	global_load_dwordx4 v[144:147], v[128:129], off offset:256
	global_load_dwordx4 v[140:143], v[130:131], off
	global_load_dwordx4 v[136:139], v[130:131], off offset:256
	global_load_dwordx4 v[132:135], v[194:195], off
	s_nop 0
	global_load_dwordx4 v[128:131], v[194:195], off offset:256
	v_add_u32_e32 v226, 0x80, v172
	v_ashrrev_i32_e32 v227, 31, v226
	v_lshlrev_b64 v[226:227], 11, v[226:227]
	v_lshl_add_u64 v[226:227], v[174:175], 0, v[226:227]
	global_load_dwordx4 v[216:219], v[226:227], off
	global_load_dwordx4 v[220:223], v[226:227], off offset:256
	v_add_u32_e32 v226, 0x90, v172
	v_ashrrev_i32_e32 v227, 31, v226
	v_lshlrev_b64 v[226:227], 11, v[226:227]
	v_lshl_add_u64 v[226:227], v[174:175], 0, v[226:227]
	global_load_dwordx4 v[228:231], v[226:227], off
	global_load_dwordx4 v[232:235], v[226:227], off offset:256
	v_add_u32_e32 v226, 0xa0, v172
	v_ashrrev_i32_e32 v227, 31, v226
	v_lshlrev_b64 v[226:227], 11, v[226:227]
	v_lshl_add_u64 v[226:227], v[174:175], 0, v[226:227]
	global_load_dwordx4 v[236:239], v[226:227], off
	global_load_dwordx4 v[240:243], v[226:227], off offset:256
	v_add_u32_e32 v226, 0xb0, v172
	v_ashrrev_i32_e32 v227, 31, v226
	v_lshlrev_b64 v[226:227], 11, v[226:227]
	v_lshl_add_u64 v[226:227], v[174:175], 0, v[226:227]
	global_load_dwordx4 v[244:247], v[226:227], off
	global_load_dwordx4 v[252:255], v[226:227], off offset:256
	v_and_b32_e32 v195, 64, v193
	v_xor_b32_e32 v194, 16, v193
	v_add_u32_e32 v195, 64, v195
	v_xor_b32_e32 v208, 32, v193
	v_cmp_lt_i32_e32 vcc, v194, v195
	s_waitcnt vmcnt(15)
	v_and_b32_e32 v209, 0xffff0000, v196
	v_cndmask_b32_e32 v194, v193, v194, vcc
	v_cmp_lt_i32_e32 vcc, v208, v195
	v_lshlrev_b32_e32 v195, 2, v194
	s_waitcnt vmcnt(14)
	v_lshlrev_b32_e32 v212, 16, v200
	v_cndmask_b32_e32 v208, v193, v208, vcc
	v_lshlrev_b32_e32 v194, 2, v208
	v_lshlrev_b32_e32 v208, 16, v196
	v_and_b32_e32 v213, 0xffff0000, v200
	v_lshlrev_b32_e32 v210, 16, v198
	v_and_b32_e32 v211, 0xffff0000, v198
	v_lshlrev_b32_e32 v198, 16, v199
	v_and_b32_e32 v199, 0xffff0000, v199
	v_lshlrev_b32_e32 v200, 16, v201
	v_and_b32_e32 v201, 0xffff0000, v201
	v_lshlrev_b32_e32 v214, 16, v202
	v_and_b32_e32 v215, 0xffff0000, v202
	v_pk_add_f32 v[124:125], v[124:125], v[208:209]
	v_pk_add_f32 v[116:117], v[116:117], v[212:213]
	v_lshlrev_b32_e32 v196, 16, v197
	v_and_b32_e32 v197, 0xffff0000, v197
	v_pk_add_f32 v[122:123], v[122:123], v[198:199]
	v_pk_add_f32 v[118:119], v[118:119], v[200:201]
	v_pk_add_f32 v[198:199], v[112:113], v[214:215]
	v_mul_f32_e32 v200, v125, v125
	v_cvt_pk_bf16_f32 v112, v124, v125
	v_mul_f32_e32 v125, v117, v117
	v_pk_add_f32 v[126:127], v[126:127], v[196:197]
	v_fmac_f32_e32 v200, v124, v124
	v_fmac_f32_e32 v125, v116, v116
	v_fmac_f32_e32 v200, v126, v126
	v_fmac_f32_e32 v125, v118, v118
	v_pk_add_f32 v[120:121], v[120:121], v[210:211]
	v_fmac_f32_e32 v200, v127, v127
	v_fmac_f32_e32 v125, v119, v119
	v_lshlrev_b32_e32 v202, 16, v203
	v_and_b32_e32 v203, 0xffff0000, v203
	v_fmac_f32_e32 v200, v120, v120
	v_fmac_f32_e32 v125, v198, v198
	v_pk_add_f32 v[196:197], v[114:115], v[202:203]
	v_fmac_f32_e32 v200, v121, v121
	v_fmac_f32_e32 v125, v199, v199
	v_fmac_f32_e32 v200, v122, v122
	v_fmac_f32_e32 v125, v196, v196
	v_fmac_f32_e32 v200, v123, v123
	v_fmac_f32_e32 v125, v197, v197
	v_cvt_pk_bf16_f32 v115, v122, v123
	v_add_f32_e32 v122, v200, v125
	ds_bpermute_b32 v123, v195, v122
	v_cvt_pk_bf16_f32 v114, v120, v121
	v_lshl_add_u64 v[120:121], s[76:77], 0, v[206:207]
	v_cvt_pk_bf16_f32 v113, v126, v127
	v_lshl_add_u64 v[120:121], v[120:121], 0, v[204:205]
	global_store_dwordx4 v[120:121], v[112:115], off
	s_waitcnt lgkmcnt(0)
	s_nop 0
	v_add_f32_e32 v112, v122, v123
	ds_bpermute_b32 v113, v194, v112
	v_cvt_pk_bf16_f32 v114, v116, v117
	v_cvt_pk_bf16_f32 v115, v118, v119
	v_cvt_pk_bf16_f32 v116, v198, v199
	v_cvt_pk_bf16_f32 v117, v196, v197
	global_store_dwordx4 v[120:121], v[114:117], off offset:256
	s_and_saveexec_b64 s[4:5], s[0:1]
	s_cbranch_execz .LBB0_1121
	s_waitcnt lgkmcnt(0)
	v_add_f32_e32 v114, v112, v113
	s_lshl_b32 s22, s8, 2
	v_lshlrev_b64 v[112:113], 6, v[172:173]
	s_ashr_i32 s23, s22, 31
	v_lshl_add_u64 v[112:113], s[12:13], 0, v[112:113]
	v_lshl_add_u64 v[112:113], s[22:23], 2, v[112:113]
	s_lshl_b32 s10, s35, 2
	v_lshl_add_u64 v[112:113], v[112:113], 0, s[10:11]
	global_store_dword v[112:113], v114, off

; #define PG8_STAGE(bufoff, gbase, voff) do { _Pragma("unroll") for (int _i = 0; _i < 2; ++_i) \
;         __builtin_amdgcn_global_load_lds((const unsigned*)((const char*)(gbase) + (voff)[_i]), (LAS unsigned*)(lds + (bufoff) + ldsw + _i * 8192), 16, 0, 0); } while (0)
; #define PG8_WAIT_V(n) asm volatile("s_waitcnt vmcnt(" #n ")" ::: "memory")
; #define PG8_BAR __builtin_amdgcn_s_barrier()
; template <class Epi>
; __device__ __forceinline__ void gemm_phase(LAS unsigned char* lds, const Gemm g, const StaticOrder& S, const Epi& E) {
;     ...
;     for (int i = 0; i < 2; ++i) { int R, C; stage_rc(tid * 16 + i * 8192, R, C); const int Rb = Epi::PERM ? ((R & ~31) + perm32(R & 31)) : R;
;         voffA[i] = (unsigned)(R * lda + C) * 2u; voffB[i] = (unsigned)(Rb * K + C) * 2u; }
;     const size_t kstep = (size_t)(BK * 2);
;     const size_t hstepA = (size_t)HALF * lda * 2, hstepB = (size_t)HALF * K * 2;
;     const size_t tstepA = 2 * hstepA, tstepB = 2 * hstepB;
;     const unsigned ldsw = (unsigned)wid * 1024u;
;     const int aoff = lds_byte(wr * 64 + fr, fq * 8), boff = lds_byte(wc * 32 + fr, fq * 8);
;     ...
;     const char* cA = (const char*)g.A + (size_t)cur.pm * tstepA; const char* cB = (const char*)g.Bt + (size_t)cur.pn * tstepB;
;     PG8_STAGE(PG8_SB(0, 0), cB, voffB); PG8_STAGE(PG8_SA(0, 0), cA, voffA); PG8_STAGE(PG8_SB(0, 1), cB + hstepB, voffB); PG8_STAGE(PG8_SA(0, 1), cA + hstepA, voffA);
;     if (wr == 1) PG8_BAR;
;     PG8_WAIT_V(4); PG8_BAR;
;     PG8_STAGE(PG8_SB(1, 0), cB + kstep, voffB); PG8_STAGE(PG8_SA(1, 0), cA + kstep, voffA); PG8_STAGE(PG8_SB(1, 1), cB + hstepB + kstep, voffB);
;     PG8_WAIT_V(6); PG8_BAR;
.LBB0_1196:
	s_lshl_b32 s4, s4, 5
	s_and_b32 s8, s4, 0x60
	s_mov_b64 s[4:5], 0x80
	s_add_i32 m0, s19, 0x18000
	v_lshl_add_u64 v[6:7], v[6:7], 0, s[4:5]
	s_lshl_b32 s6, s1, 13
	s_lshl_b32 s12, s8, 7
	s_waitcnt vmcnt(4)
	s_barrier
	global_load_lds_dwordx4 v[6:7], off
	v_lshl_add_u64 v[4:5], v[4:5], 0, s[4:5]
	s_add_i32 m0, s19, 0x1a000
	s_add_i32 s34, s19, 0x8000
	s_add_i32 s35, s19, 0xa000
	global_load_lds_dwordx4 v[4:5], off
	v_lshl_add_u64 v[2:3], v[2:3], 0, s[4:5]
	s_mov_b32 m0, s34
	s_add_u32 s10, s22, 0x40080
	global_load_lds_dwordx4 v[2:3], off
	v_lshl_add_u64 v[0:1], v[0:1], 0, s[4:5]
	s_mov_b32 m0, s35
	s_addc_u32 s11, s23, 0
	global_load_lds_dwordx4 v[0:1], off
	s_add_i32 m0, s19, 0x1c000
	v_lshl_add_u64 v[0:1], s[10:11], 0, v[130:131]
	global_load_lds_dwordx4 v[0:1], off
	v_lshl_add_u64 v[0:1], s[10:11], 0, v[134:135]
	s_add_i32 m0, s19, 0x1e000
	v_bfe_u32 v2, v152, 4, 2
	global_load_lds_dwordx4 v[0:1], off
	v_and_b32_e32 v1, 15, v152
	v_lshlrev_b32_e32 v0, 4, v2
	v_lshlrev_b32_e32 v3, 2, v152
	v_lshl_or_b32 v153, s1, 6, v1
	v_lshl_or_b32 v1, v1, 6, v0
	v_and_b32_e32 v3, 32, v3
	s_sext_i32_i8 s40, s0
	v_bitop3_b32 v4, v1, s6, v3 bitop3:0xde
	v_lshlrev_b32_e32 v1, 6, v152
	s_movk_i32 s0, 0x3c0
	v_and_or_b32 v1, v1, s0, v0
	v_bitop3_b32 v174, s12, v1, v3 bitop3:0xf6
	v_mov_b32_e32 v1, v131
	v_lshl_add_u64 v[0:1], s[74:75], 0, v[0:1]
	s_mov_b64 s[0:1], 0x3cbc4000
	v_lshl_add_u64 v[136:137], v[0:1], 0, s[0:1]
	v_lshlrev_b32_e32 v0, 8, v152
	v_and_b32_e32 v0, 0x38000, v0
	v_lshlrev_b32_e32 v1, 11, v10
	v_or3_b32 v0, v8, v0, v1
	v_add_u32_e32 v138, v0, v9
	v_lshlrev_b32_e32 v0, 4, v11
	v_and_b32_e32 v0, 0x78000, v0
	s_waitcnt vmcnt(6)
	v_or3_b32 v0, v8, v0, v1
	v_add_u32_e32 v140, v0, v9
	s_add_i32 s37, 0, 0x10000
	s_add_i32 s38, 0, 0x14000
	v_mbcnt_lo_u32_b32 v0, -1, 0
	s_ashr_i32 s36, s92, 31
	v_lshl_or_b32 v175, v2, 3, s8
	v_mov_b32_e32 v139, v131
	v_mov_b32_e32 v141, v131
	v_mov_b64_e32 v[142:143], 0x1000
	v_mov_b64_e32 v[144:145], 0xfff
	v_add_u32_e32 v176, s37, v174
	v_add_u32_e32 v177, 0, v4
	v_add_u32_e32 v178, s38, v174
	v_mbcnt_hi_u32_b32 v179, -1, v0
	s_mov_b32 s6, 0x3a800000
	s_mov_b32 s8, 0x358637bd
	s_mov_b32 s39, 0x800000
	s_barrier
	s_branch .LBB0_1197

; #define PG8_STAGE(bufoff, gbase, voff) do { _Pragma("unroll") for (int _i = 0; _i < 2; ++_i) \
;         __builtin_amdgcn_global_load_lds((const unsigned*)((const char*)(gbase) + (voff)[_i]), (LAS unsigned*)(lds + (bufoff) + ldsw + _i * 8192), 16, 0, 0); } while (0)
; #define PG8_LDA(dst, b, h) do { _Pragma("unroll") for (int m = 0; m < 4; ++m) _Pragma("unroll") for (int k = 0; k < 2; ++k) dst[m][k] = *(const LAS bf16x8*)(lds + PG8_SA(b, h) + aoff + m * 2048 + k * 1024); } while (0)
; #define PG8_LDB(dst, b, h) do { _Pragma("unroll") for (int n = 0; n < 2; ++n) _Pragma("unroll") for (int k = 0; k < 2; ++k) dst[n][k] = *(const LAS bf16x8*)(lds + PG8_SB(b, h) + boff + n * 2048 + k * 1024); } while (0)
; #define PG8_MMA(ai, bj, At, Bt) do { __builtin_amdgcn_s_setprio(1); _Pragma("unroll") for (int m = 0; m < 4; ++m) _Pragma("unroll") for (int n = 0; n < 2; ++n) _Pragma("unroll") for (int k = 0; k < 2; ++k) \
;         acc[ai][bj][m][n] = __builtin_amdgcn_mfma_f32_16x16x32_bf16(Bt[n][k], At[m][k], acc[ai][bj][m][n], 0, 0, 0); __builtin_amdgcn_s_setprio(0); } while (0)
; #define PG8_WAIT_L(n) asm volatile("s_waitcnt lgkmcnt(" #n ")" ::: "memory")
; template <class Epi>
; __device__ __forceinline__ void gemm_phase(LAS unsigned char* lds, const Gemm g, const StaticOrder& S, const Epi& E) {
;     ...
;         const char* nA = has_next ? (const char*)g.A + (size_t)nxt.pm * tstepA : cA; const char* nB = has_next ? (const char*)g.Bt + (size_t)nxt.pn * tstepB : cB;
;         for (int t = 0; t < nt; t += 2) {
;             const bool last = (t == nt - 2);
;             const char* a1 = cA + (size_t)(t + 1) * kstep;
;             const char* a2 = last ? nA : cA + (size_t)(t + 2) * kstep; const char* b2 = last ? nB : cB + (size_t)(t + 2) * kstep;
;             const char* a3 = a2 + kstep; const char* b3 = b2 + kstep;
;             if (last) E.pre(cur, wr, fr, epre);
;             PG8_LDB(B0, 0, 0); PG8_SCHED; PG8_LDA(At, 0, 0); PG8_STAGE(PG8_SA(1, 1), a1 + hstepA, voffA);
;             PG8_WAIT_L(8); PG8_BAR; PG8_WAIT_L(0); PG8_MMA(0, 0, At, B0); PG8_BAR; PG8_SCHED;
;             PG8_LDB(B1, 0, 1); PG8_STAGE(PG8_SB(0, 0), b2, voffB);
;             PG8_BAR; PG8_WAIT_L(0); PG8_MMA(0, 1, At, B1); PG8_BAR;
;             PG8_LDA(At, 0, 1); PG8_STAGE(PG8_SA(0, 0), a2, voffA);
;             PG8_BAR; PG8_WAIT_L(0); PG8_MMA(1, 0, At, B0); PG8_BAR; PG8_SCHED;
.Lkp6_1203:
	s_ashr_i32 s13, s12, 31
	v_cmp_lt_i64_e32 vcc, s[14:15], v[142:143]
	s_lshl_b64 s[14:15], s[12:13], 19
	s_add_u32 s14, s76, s14
	s_addc_u32 s15, s77, s15
	s_and_b64 s[16:17], vcc, exec
	s_cselect_b32 s13, s15, s21
	s_cselect_b32 s41, s14, s20
	s_ashr_i32 s11, s10, 31
	s_lshl_b64 s[16:17], s[10:11], 19
	s_add_u32 s16, s26, s16
	s_addc_u32 s17, s27, s17
	s_and_b64 s[24:25], vcc, exec
	s_cselect_b32 s11, s17, s23
	s_cselect_b32 s42, s16, s22
	s_add_u32 s20, s20, 0x40080
	s_addc_u32 s21, s21, 0
	s_add_u32 s43, s22, 0x100
	s_addc_u32 s44, s23, 0
	s_mov_b32 s45, -2
	ds_read_b128 v[146:149], v176
	ds_read_b128 v[154:157], v176 offset:1024
	ds_read_b128 v[158:161], v176 offset:2048
	ds_read_b128 v[162:165], v176 offset:3072
	s_add_u32 s22, s20, 0xfffc0080
	s_addc_u32 s23, s21, -1
	s_cmp_eq_u32 s45, 12
	s_cselect_b32 s25, s13, s23
	s_cselect_b32 s24, s41, s22
	s_cselect_b32 s23, s11, s44
	s_cselect_b32 s22, s42, s43
	v_lshl_add_u64 v[150:151], s[20:21], 0, v[138:139]
	s_add_i32 m0, s19, 0xc000
	ds_read_b128 v[166:169], v177
	ds_read_b128 v[170:173], v177 offset:1024
	ds_read_b128 v[180:183], v177 offset:2048
	ds_read_b128 v[184:187], v177 offset:3072
	ds_read_b128 v[188:191], v177 offset:4096
	ds_read_b128 v[192:195], v177 offset:5120
	ds_read_b128 v[196:199], v177 offset:6144
	ds_read_b128 v[200:203], v177 offset:7168
	global_load_lds_dwordx4 v[150:151], off
	v_lshl_add_u64 v[150:151], s[20:21], 0, v[140:141]
	s_add_i32 m0, s19, 0xe000
	s_nop 0
	global_load_lds_dwordx4 v[150:151], off
	s_waitcnt lgkmcnt(8)
	s_barrier
	s_waitcnt lgkmcnt(0)
	s_setprio 2
	s_waitcnt lgkmcnt(0)
	v_mfma_f32_16x16x32_bf16 v[124:127], v[146:149], v[166:169], 0
	v_mfma_f32_16x16x32_bf16 v[120:123], v[158:161], v[166:169], 0
	v_mfma_f32_16x16x32_bf16 v[108:111], v[146:149], v[180:183], 0
	v_mfma_f32_16x16x32_bf16 v[104:107], v[158:161], v[180:183], 0
	v_mfma_f32_16x16x32_bf16 v[92:95], v[146:149], v[188:191], 0
	v_mfma_f32_16x16x32_bf16 v[88:91], v[158:161], v[188:191], 0
	v_mfma_f32_16x16x32_bf16 v[76:79], v[146:149], v[196:199], 0
	v_mfma_f32_16x16x32_bf16 v[72:75], v[158:161], v[196:199], 0
	v_mfma_f32_16x16x32_bf16 v[124:127], v[154:157], v[170:173], v[124:127]
	v_mfma_f32_16x16x32_bf16 v[120:123], v[162:165], v[170:173], v[120:123]
	v_mfma_f32_16x16x32_bf16 v[108:111], v[154:157], v[184:187], v[108:111]
	v_mfma_f32_16x16x32_bf16 v[104:107], v[162:165], v[184:187], v[104:107]
	v_mfma_f32_16x16x32_bf16 v[92:95], v[154:157], v[192:195], v[92:95]
	v_mfma_f32_16x16x32_bf16 v[88:91], v[162:165], v[192:195], v[88:91]
	v_mfma_f32_16x16x32_bf16 v[76:79], v[154:157], v[200:203], v[76:79]
	v_mfma_f32_16x16x32_bf16 v[72:75], v[162:165], v[200:203], v[72:75]
	s_setprio 1
	s_barrier
	s_add_i32 s46, s37, s28
	v_lshl_add_u64 v[150:151], s[22:23], 0, v[130:131]
	s_mov_b32 m0, s46
	ds_read_b128 v[204:207], v178
	ds_read_b128 v[208:211], v178 offset:1024
	ds_read_b128 v[212:215], v178 offset:2048
	ds_read_b128 v[216:219], v178 offset:3072
	global_load_lds_dwordx4 v[150:151], off
	v_lshl_add_u64 v[220:221], s[22:23], 0, v[134:135]
	s_add_i32 m0, s46, 0x2000
	s_nop 0
	global_load_lds_dwordx4 v[220:221], off
	s_barrier
	s_waitcnt lgkmcnt(0)
	s_setprio 2
	s_waitcnt lgkmcnt(0)
	v_mfma_f32_16x16x32_bf16 v[116:119], v[204:207], v[166:169], 0
	v_mfma_f32_16x16x32_bf16 v[112:115], v[212:215], v[166:169], 0
	v_mfma_f32_16x16x32_bf16 v[100:103], v[204:207], v[180:183], 0
	v_mfma_f32_16x16x32_bf16 v[96:99], v[212:215], v[180:183], 0
	v_mfma_f32_16x16x32_bf16 v[84:87], v[204:207], v[188:191], 0
	v_mfma_f32_16x16x32_bf16 v[80:83], v[212:215], v[188:191], 0
	v_mfma_f32_16x16x32_bf16 v[68:71], v[204:207], v[196:199], 0
	v_mfma_f32_16x16x32_bf16 v[64:67], v[212:215], v[196:199], 0
	v_mfma_f32_16x16x32_bf16 v[116:119], v[208:211], v[170:173], v[116:119]
	v_mfma_f32_16x16x32_bf16 v[112:115], v[216:219], v[170:173], v[112:115]
	v_mfma_f32_16x16x32_bf16 v[100:103], v[208:211], v[184:187], v[100:103]
	v_mfma_f32_16x16x32_bf16 v[96:99], v[216:219], v[184:187], v[96:99]
	v_mfma_f32_16x16x32_bf16 v[84:87], v[208:211], v[192:195], v[84:87]
	v_mfma_f32_16x16x32_bf16 v[80:83], v[216:219], v[192:195], v[80:83]
	v_mfma_f32_16x16x32_bf16 v[68:71], v[208:211], v[200:203], v[68:71]
	v_mfma_f32_16x16x32_bf16 v[64:67], v[216:219], v[200:203], v[64:67]
	s_setprio 1
	s_mov_b32 m0, s19
	v_lshl_add_u64 v[222:223], s[24:25], 0, v[128:129]
	s_barrier
	ds_read_b128 v[166:169], v177 offset:16384
	ds_read_b128 v[170:173], v177 offset:17408
	ds_read_b128 v[180:183], v177 offset:18432
	ds_read_b128 v[184:187], v177 offset:19456
	ds_read_b128 v[188:191], v177 offset:20480
	ds_read_b128 v[192:195], v177 offset:21504
	ds_read_b128 v[196:199], v177 offset:22528
	ds_read_b128 v[200:203], v177 offset:23552
	global_load_lds_dwordx4 v[222:223], off
	v_lshl_add_u64 v[224:225], s[24:25], 0, v[132:133]
	s_mov_b32 m0, s29
	s_nop 0
	global_load_lds_dwordx4 v[224:225], off
	s_barrier
	s_waitcnt lgkmcnt(0)
	s_setprio 2
	s_waitcnt lgkmcnt(0)
	v_mfma_f32_16x16x32_bf16 v[60:63], v[146:149], v[166:169], 0
	v_mfma_f32_16x16x32_bf16 v[56:59], v[158:161], v[166:169], 0
	v_mfma_f32_16x16x32_bf16 v[44:47], v[146:149], v[180:183], 0
	v_mfma_f32_16x16x32_bf16 v[40:43], v[158:161], v[180:183], 0
	v_mfma_f32_16x16x32_bf16 v[28:31], v[146:149], v[188:191], 0
	v_mfma_f32_16x16x32_bf16 v[24:27], v[158:161], v[188:191], 0
	v_mfma_f32_16x16x32_bf16 v[12:15], v[146:149], v[196:199], 0
	v_mfma_f32_16x16x32_bf16 v[8:11], v[158:161], v[196:199], 0
	v_mfma_f32_16x16x32_bf16 v[60:63], v[154:157], v[170:173], v[60:63]
	v_mfma_f32_16x16x32_bf16 v[56:59], v[162:165], v[170:173], v[56:59]
	v_mfma_f32_16x16x32_bf16 v[44:47], v[154:157], v[184:187], v[44:47]
	v_mfma_f32_16x16x32_bf16 v[40:43], v[162:165], v[184:187], v[40:43]
	v_mfma_f32_16x16x32_bf16 v[28:31], v[154:157], v[192:195], v[28:31]
	v_mfma_f32_16x16x32_bf16 v[24:27], v[162:165], v[192:195], v[24:27]
	v_mfma_f32_16x16x32_bf16 v[12:15], v[154:157], v[200:203], v[12:15]
	v_mfma_f32_16x16x32_bf16 v[8:11], v[162:165], v[200:203], v[8:11]
	s_setprio 1
	s_barrier
; #define PG8_STAGE(bufoff, gbase, voff) do { _Pragma("unroll") for (int _i = 0; _i < 2; ++_i) \
;         __builtin_amdgcn_global_load_lds((const unsigned*)((const char*)(gbase) + (voff)[_i]), (LAS unsigned*)(lds + (bufoff) + ldsw + _i * 8192), 16, 0, 0); } while (0)
; #define PG8_LDA(dst, b, h) do { _Pragma("unroll") for (int m = 0; m < 4; ++m) _Pragma("unroll") for (int k = 0; k < 2; ++k) dst[m][k] = *(const LAS bf16x8*)(lds + PG8_SA(b, h) + aoff + m * 2048 + k * 1024); } while (0)
; #define PG8_LDB(dst, b, h) do { _Pragma("unroll") for (int n = 0; n < 2; ++n) _Pragma("unroll") for (int k = 0; k < 2; ++k) dst[n][k] = *(const LAS bf16x8*)(lds + PG8_SB(b, h) + boff + n * 2048 + k * 1024); } while (0)
; #define PG8_MMA(ai, bj, At, Bt) do { __builtin_amdgcn_s_setprio(1); _Pragma("unroll") for (int m = 0; m < 4; ++m) _Pragma("unroll") for (int n = 0; n < 2; ++n) _Pragma("unroll") for (int k = 0; k < 2; ++k) \
;         acc[ai][bj][m][n] = __builtin_amdgcn_mfma_f32_16x16x32_bf16(Bt[n][k], At[m][k], acc[ai][bj][m][n], 0, 0, 0); __builtin_amdgcn_s_setprio(0); } while (0)
; #define PG8_WAIT_V(n) asm volatile("s_waitcnt vmcnt(" #n ")" ::: "memory")
; #define PG8_WAIT_L(n) asm volatile("s_waitcnt lgkmcnt(" #n ")" ::: "memory")
; #define PG8_BAR __builtin_amdgcn_s_barrier()
; #define PG8_SCHED __builtin_amdgcn_sched_barrier(0)
; template <class Epi>
; __device__ __forceinline__ void gemm_phase(LAS unsigned char* lds, const Gemm g, const StaticOrder& S, const Epi& E) {
;     ...
;             PG8_STAGE(PG8_SB(0, 1), b2 + hstepB, voffB);
;             PG8_WAIT_V(6); PG8_BAR; PG8_MMA(1, 1, At, B1); PG8_BAR;
;             PG8_LDB(B0, 1, 0); PG8_SCHED; PG8_LDA(At, 1, 0); PG8_STAGE(PG8_SA(0, 1), a2 + hstepA, voffA);
;             PG8_WAIT_L(8); PG8_BAR; PG8_WAIT_L(0); PG8_MMA(0, 0, At, B0); PG8_BAR; PG8_SCHED;
;             PG8_LDB(B1, 1, 1); PG8_STAGE(PG8_SB(1, 0), b3, voffB);
;             PG8_BAR; PG8_WAIT_L(0); PG8_MMA(0, 1, At, B1); PG8_BAR;
;             PG8_LDA(At, 1, 1); PG8_STAGE(PG8_SA(1, 0), a3, voffA);
	s_add_u32 s46, s22, 0x40000
	s_addc_u32 s47, s23, 0
	s_add_i32 s48, s38, s28
	v_lshl_add_u64 v[146:147], s[46:47], 0, v[130:131]
	s_mov_b32 m0, s48
	s_nop 0
	global_load_lds_dwordx4 v[146:147], off
	v_lshl_add_u64 v[146:147], s[46:47], 0, v[134:135]
	s_add_i32 m0, s48, 0x2000
	s_nop 0
	global_load_lds_dwordx4 v[146:147], off
	s_waitcnt vmcnt(6)
	s_barrier
	s_setprio 2
	v_mfma_f32_16x16x32_bf16 v[52:55], v[204:207], v[166:169], 0
	v_mfma_f32_16x16x32_bf16 v[48:51], v[212:215], v[166:169], 0
	v_mfma_f32_16x16x32_bf16 v[36:39], v[204:207], v[180:183], 0
	v_mfma_f32_16x16x32_bf16 v[32:35], v[212:215], v[180:183], 0
	v_mfma_f32_16x16x32_bf16 v[20:23], v[204:207], v[188:191], 0
	v_mfma_f32_16x16x32_bf16 v[16:19], v[212:215], v[188:191], 0
	v_mfma_f32_16x16x32_bf16 v[4:7], v[204:207], v[196:199], 0
	v_mfma_f32_16x16x32_bf16 v[0:3], v[212:215], v[196:199], 0
	v_mfma_f32_16x16x32_bf16 v[52:55], v[208:211], v[170:173], v[52:55]
	v_mfma_f32_16x16x32_bf16 v[48:51], v[216:219], v[170:173], v[48:51]
	v_mfma_f32_16x16x32_bf16 v[36:39], v[208:211], v[184:187], v[36:39]
	v_mfma_f32_16x16x32_bf16 v[32:35], v[216:219], v[184:187], v[32:35]
	v_mfma_f32_16x16x32_bf16 v[20:23], v[208:211], v[192:195], v[20:23]
	v_mfma_f32_16x16x32_bf16 v[16:19], v[216:219], v[192:195], v[16:19]
	v_mfma_f32_16x16x32_bf16 v[4:7], v[208:211], v[200:203], v[4:7]
	v_mfma_f32_16x16x32_bf16 v[0:3], v[216:219], v[200:203], v[0:3]
	s_setprio 1
	s_add_i32 s46, 0, 0x18000
	v_add_u32_e32 v162, s46, v174
	s_barrier
	ds_read_b128 v[146:149], v162
	ds_read_b128 v[154:157], v162 offset:1024
	ds_read_b128 v[158:161], v162 offset:2048
	ds_read_b128 v[162:165], v162 offset:3072
	s_add_u32 s24, s24, 0x40000
	s_addc_u32 s25, s25, 0
	s_mov_b32 m0, s30
	v_lshl_add_u64 v[204:205], s[24:25], 0, v[128:129]
	ds_read_b128 v[166:169], v177 offset:32768
	ds_read_b128 v[170:173], v177 offset:33792
	ds_read_b128 v[180:183], v177 offset:34816
	ds_read_b128 v[184:187], v177 offset:35840
	ds_read_b128 v[188:191], v177 offset:36864
	ds_read_b128 v[192:195], v177 offset:37888
	ds_read_b128 v[196:199], v177 offset:38912
	ds_read_b128 v[200:203], v177 offset:39936
	global_load_lds_dwordx4 v[204:205], off
	v_lshl_add_u64 v[204:205], s[24:25], 0, v[132:133]
	s_mov_b32 m0, s31
	s_nop 0
	global_load_lds_dwordx4 v[204:205], off
	s_waitcnt lgkmcnt(8)
	s_barrier
	s_waitcnt lgkmcnt(0)
	s_setprio 2
	s_waitcnt lgkmcnt(0)
	v_mfma_f32_16x16x32_bf16 v[124:127], v[146:149], v[166:169], v[124:127]
	v_mfma_f32_16x16x32_bf16 v[120:123], v[158:161], v[166:169], v[120:123]
	v_mfma_f32_16x16x32_bf16 v[108:111], v[146:149], v[180:183], v[108:111]
	v_mfma_f32_16x16x32_bf16 v[104:107], v[158:161], v[180:183], v[104:107]
	v_mfma_f32_16x16x32_bf16 v[92:95], v[146:149], v[188:191], v[92:95]
	v_mfma_f32_16x16x32_bf16 v[88:91], v[158:161], v[188:191], v[88:91]
	v_mfma_f32_16x16x32_bf16 v[76:79], v[146:149], v[196:199], v[76:79]
	v_mfma_f32_16x16x32_bf16 v[72:75], v[158:161], v[196:199], v[72:75]
	v_mfma_f32_16x16x32_bf16 v[124:127], v[154:157], v[170:173], v[124:127]
	v_mfma_f32_16x16x32_bf16 v[120:123], v[162:165], v[170:173], v[120:123]
	v_mfma_f32_16x16x32_bf16 v[108:111], v[154:157], v[184:187], v[108:111]
	v_mfma_f32_16x16x32_bf16 v[104:107], v[162:165], v[184:187], v[104:107]
	v_mfma_f32_16x16x32_bf16 v[92:95], v[154:157], v[192:195], v[92:95]
	v_mfma_f32_16x16x32_bf16 v[88:91], v[162:165], v[192:195], v[88:91]
	v_mfma_f32_16x16x32_bf16 v[76:79], v[154:157], v[200:203], v[76:79]
	v_mfma_f32_16x16x32_bf16 v[72:75], v[162:165], v[200:203], v[72:75]
	s_setprio 1
	s_barrier
	s_add_i32 s24, 0, 0x1c000
	s_add_i32 s25, s46, s28
	v_add_u32_e32 v216, s24, v174
	v_lshl_add_u64 v[150:151], v[150:151], 0, s[4:5]
	s_mov_b32 m0, s25
	ds_read_b128 v[204:207], v216
	ds_read_b128 v[208:211], v216 offset:1024
	ds_read_b128 v[212:215], v216 offset:2048
	ds_read_b128 v[216:219], v216 offset:3072
	global_load_lds_dwordx4 v[150:151], off
	v_lshl_add_u64 v[150:151], v[220:221], 0, s[4:5]
	s_add_i32 m0, s25, 0x2000
	s_nop 0
	global_load_lds_dwordx4 v[150:151], off
	s_barrier
	s_waitcnt lgkmcnt(0)
	s_setprio 2
	s_waitcnt lgkmcnt(0)
	v_mfma_f32_16x16x32_bf16 v[116:119], v[204:207], v[166:169], v[116:119]
	v_mfma_f32_16x16x32_bf16 v[112:115], v[212:215], v[166:169], v[112:115]
	v_mfma_f32_16x16x32_bf16 v[100:103], v[204:207], v[180:183], v[100:103]
	v_mfma_f32_16x16x32_bf16 v[96:99], v[212:215], v[180:183], v[96:99]
	v_mfma_f32_16x16x32_bf16 v[84:87], v[204:207], v[188:191], v[84:87]
	v_mfma_f32_16x16x32_bf16 v[80:83], v[212:215], v[188:191], v[80:83]
	v_mfma_f32_16x16x32_bf16 v[68:71], v[204:207], v[196:199], v[68:71]
	v_mfma_f32_16x16x32_bf16 v[64:67], v[212:215], v[196:199], v[64:67]
	v_mfma_f32_16x16x32_bf16 v[116:119], v[208:211], v[170:173], v[116:119]
	v_mfma_f32_16x16x32_bf16 v[112:115], v[216:219], v[170:173], v[112:115]
	v_mfma_f32_16x16x32_bf16 v[100:103], v[208:211], v[184:187], v[100:103]
	v_mfma_f32_16x16x32_bf16 v[96:99], v[216:219], v[184:187], v[96:99]
	v_mfma_f32_16x16x32_bf16 v[84:87], v[208:211], v[192:195], v[84:87]
	v_mfma_f32_16x16x32_bf16 v[80:83], v[216:219], v[192:195], v[80:83]
	v_mfma_f32_16x16x32_bf16 v[68:71], v[208:211], v[200:203], v[68:71]
	v_mfma_f32_16x16x32_bf16 v[64:67], v[216:219], v[200:203], v[64:67]
	s_setprio 1
	s_mov_b32 m0, s34
	v_lshl_add_u64 v[150:151], v[222:223], 0, s[4:5]
	s_barrier
	ds_read_b128 v[166:169], v177 offset:49152
	ds_read_b128 v[170:173], v177 offset:50176
	ds_read_b128 v[180:183], v177 offset:51200
	ds_read_b128 v[184:187], v177 offset:52224
	ds_read_b128 v[188:191], v177 offset:53248
	ds_read_b128 v[192:195], v177 offset:54272
	ds_read_b128 v[196:199], v177 offset:55296
	ds_read_b128 v[200:203], v177 offset:56320
	global_load_lds_dwordx4 v[150:151], off
	v_lshl_add_u64 v[150:151], v[224:225], 0, s[4:5]
	s_mov_b32 m0, s35
	s_nop 0
	global_load_lds_dwordx4 v[150:151], off
	s_barrier
; #define PG8_STAGE(bufoff, gbase, voff) do { _Pragma("unroll") for (int _i = 0; _i < 2; ++_i) \
;         __builtin_amdgcn_global_load_lds((const unsigned*)((const char*)(gbase) + (voff)[_i]), (LAS unsigned*)(lds + (bufoff) + ldsw + _i * 8192), 16, 0, 0); } while (0)
; #define PG8_LDA(dst, b, h) do { _Pragma("unroll") for (int m = 0; m < 4; ++m) _Pragma("unroll") for (int k = 0; k < 2; ++k) dst[m][k] = *(const LAS bf16x8*)(lds + PG8_SA(b, h) + aoff + m * 2048 + k * 1024); } while (0)
; #define PG8_LDB(dst, b, h) do { _Pragma("unroll") for (int n = 0; n < 2; ++n) _Pragma("unroll") for (int k = 0; k < 2; ++k) dst[n][k] = *(const LAS bf16x8*)(lds + PG8_SB(b, h) + boff + n * 2048 + k * 1024); } while (0)
; #define PG8_MMA(ai, bj, At, Bt) do { __builtin_amdgcn_s_setprio(1); _Pragma("unroll") for (int m = 0; m < 4; ++m) _Pragma("unroll") for (int n = 0; n < 2; ++n) _Pragma("unroll") for (int k = 0; k < 2; ++k) \
;         acc[ai][bj][m][n] = __builtin_amdgcn_mfma_f32_16x16x32_bf16(Bt[n][k], At[m][k], acc[ai][bj][m][n], 0, 0, 0); __builtin_amdgcn_s_setprio(0); } while (0)
; #define PG8_WAIT_V(n) asm volatile("s_waitcnt vmcnt(" #n ")" ::: "memory")
; #define PG8_WAIT_L(n) asm volatile("s_waitcnt lgkmcnt(" #n ")" ::: "memory")
; #define PG8_BAR __builtin_amdgcn_s_barrier()
; #define PG8_SCHED __builtin_amdgcn_sched_barrier(0)
; template <class Epi>
; __device__ __forceinline__ void gemm_phase(LAS unsigned char* lds, const Gemm g, const StaticOrder& S, const Epi& E) {
;     ...
;             PG8_LDB(B0, 0, 0); PG8_SCHED; PG8_LDA(At, 0, 0); PG8_STAGE(PG8_SA(1, 1), a1 + hstepA, voffA);
;             PG8_WAIT_L(8); PG8_BAR; PG8_WAIT_L(0); PG8_MMA(0, 0, At, B0); PG8_BAR; PG8_SCHED;
;             PG8_LDB(B1, 0, 1); PG8_STAGE(PG8_SB(0, 0), b2, voffB);
;     ...
;             PG8_BAR; PG8_WAIT_L(0); PG8_MMA(1, 0, At, B0); PG8_BAR; PG8_SCHED;
;             PG8_STAGE(PG8_SB(1, 1), b3 + hstepB, voffB);
;             PG8_WAIT_V(6); PG8_BAR; PG8_MMA(1, 1, At, B1); PG8_BAR;
	s_waitcnt lgkmcnt(0)
	s_setprio 2
	s_waitcnt lgkmcnt(0)
	v_mfma_f32_16x16x32_bf16 v[60:63], v[146:149], v[166:169], v[60:63]
	v_mfma_f32_16x16x32_bf16 v[56:59], v[158:161], v[166:169], v[56:59]
	v_mfma_f32_16x16x32_bf16 v[44:47], v[146:149], v[180:183], v[44:47]
	v_mfma_f32_16x16x32_bf16 v[40:43], v[158:161], v[180:183], v[40:43]
	v_mfma_f32_16x16x32_bf16 v[28:31], v[146:149], v[188:191], v[28:31]
	v_mfma_f32_16x16x32_bf16 v[24:27], v[158:161], v[188:191], v[24:27]
	v_mfma_f32_16x16x32_bf16 v[12:15], v[146:149], v[196:199], v[12:15]
	v_mfma_f32_16x16x32_bf16 v[8:11], v[158:161], v[196:199], v[8:11]
	v_mfma_f32_16x16x32_bf16 v[60:63], v[154:157], v[170:173], v[60:63]
	v_mfma_f32_16x16x32_bf16 v[56:59], v[162:165], v[170:173], v[56:59]
	v_mfma_f32_16x16x32_bf16 v[44:47], v[154:157], v[184:187], v[44:47]
	v_mfma_f32_16x16x32_bf16 v[40:43], v[162:165], v[184:187], v[40:43]
	v_mfma_f32_16x16x32_bf16 v[28:31], v[154:157], v[192:195], v[28:31]
	v_mfma_f32_16x16x32_bf16 v[24:27], v[162:165], v[192:195], v[24:27]
	v_mfma_f32_16x16x32_bf16 v[12:15], v[154:157], v[200:203], v[12:15]
	v_mfma_f32_16x16x32_bf16 v[8:11], v[162:165], v[200:203], v[8:11]
	s_setprio 1
	s_barrier
	s_add_u32 s22, s22, 0x40080
	s_addc_u32 s23, s23, 0
	s_add_i32 s24, s24, s28
	v_lshl_add_u64 v[146:147], s[22:23], 0, v[130:131]
	s_mov_b32 m0, s24
	s_nop 0
	global_load_lds_dwordx4 v[146:147], off
	v_lshl_add_u64 v[146:147], s[22:23], 0, v[134:135]
	s_add_i32 m0, s24, 0x2000
	s_nop 0
	global_load_lds_dwordx4 v[146:147], off
	s_waitcnt vmcnt(6)
	s_barrier
	s_setprio 2
	v_mfma_f32_16x16x32_bf16 v[52:55], v[204:207], v[166:169], v[52:55]
	v_mfma_f32_16x16x32_bf16 v[48:51], v[212:215], v[166:169], v[48:51]
	v_mfma_f32_16x16x32_bf16 v[36:39], v[204:207], v[180:183], v[36:39]
	v_mfma_f32_16x16x32_bf16 v[32:35], v[212:215], v[180:183], v[32:35]
	v_mfma_f32_16x16x32_bf16 v[20:23], v[204:207], v[188:191], v[20:23]
	v_mfma_f32_16x16x32_bf16 v[16:19], v[212:215], v[188:191], v[16:19]
	v_mfma_f32_16x16x32_bf16 v[4:7], v[204:207], v[196:199], v[4:7]
	v_mfma_f32_16x16x32_bf16 v[0:3], v[212:215], v[196:199], v[0:3]
	v_mfma_f32_16x16x32_bf16 v[52:55], v[208:211], v[170:173], v[52:55]
	v_mfma_f32_16x16x32_bf16 v[48:51], v[216:219], v[170:173], v[48:51]
	v_mfma_f32_16x16x32_bf16 v[36:39], v[208:211], v[184:187], v[36:39]
	v_mfma_f32_16x16x32_bf16 v[32:35], v[216:219], v[184:187], v[32:35]
	v_mfma_f32_16x16x32_bf16 v[20:23], v[208:211], v[192:195], v[20:23]
	v_mfma_f32_16x16x32_bf16 v[16:19], v[216:219], v[192:195], v[16:19]
	v_mfma_f32_16x16x32_bf16 v[4:7], v[208:211], v[200:203], v[4:7]
	v_mfma_f32_16x16x32_bf16 v[0:3], v[216:219], v[200:203], v[0:3]
	s_setprio 1
	s_add_i32 s45, s45, 2
	s_add_u32 s20, s20, 0x100
	s_addc_u32 s21, s21, 0
	s_add_u32 s43, s43, 0x100
	s_addc_u32 s44, s44, 0
	s_cmp_gt_u32 s45, 13
	s_barrier
.Lkp6_1204:
	ds_read_b128 v[146:149], v176
	ds_read_b128 v[154:157], v176 offset:1024
	ds_read_b128 v[158:161], v176 offset:2048
	ds_read_b128 v[162:165], v176 offset:3072
	s_add_u32 s22, s20, 0xfffc0080
	s_addc_u32 s23, s21, -1
	s_cmp_eq_u32 s45, 12
	s_cselect_b32 s25, s13, s23
	s_cselect_b32 s24, s41, s22
	s_cselect_b32 s23, s11, s44
	s_cselect_b32 s22, s42, s43
	v_lshl_add_u64 v[150:151], s[20:21], 0, v[138:139]
	s_add_i32 m0, s19, 0xc000
	ds_read_b128 v[166:169], v177
	ds_read_b128 v[170:173], v177 offset:1024
	ds_read_b128 v[180:183], v177 offset:2048
	ds_read_b128 v[184:187], v177 offset:3072
	ds_read_b128 v[188:191], v177 offset:4096
	ds_read_b128 v[192:195], v177 offset:5120
	ds_read_b128 v[196:199], v177 offset:6144
	ds_read_b128 v[200:203], v177 offset:7168
	global_load_lds_dwordx4 v[150:151], off
	v_lshl_add_u64 v[150:151], s[20:21], 0, v[140:141]
	s_add_i32 m0, s19, 0xe000
	s_nop 0
	global_load_lds_dwordx4 v[150:151], off
	s_waitcnt lgkmcnt(8)
	s_barrier
	s_waitcnt lgkmcnt(0)
	s_setprio 2
	s_waitcnt lgkmcnt(0)
	v_mfma_f32_16x16x32_bf16 v[124:127], v[146:149], v[166:169], v[124:127]
	v_mfma_f32_16x16x32_bf16 v[120:123], v[158:161], v[166:169], v[120:123]
	v_mfma_f32_16x16x32_bf16 v[108:111], v[146:149], v[180:183], v[108:111]
	v_mfma_f32_16x16x32_bf16 v[104:107], v[158:161], v[180:183], v[104:107]
	v_mfma_f32_16x16x32_bf16 v[92:95], v[146:149], v[188:191], v[92:95]
	v_mfma_f32_16x16x32_bf16 v[88:91], v[158:161], v[188:191], v[88:91]
	v_mfma_f32_16x16x32_bf16 v[76:79], v[146:149], v[196:199], v[76:79]
	v_mfma_f32_16x16x32_bf16 v[72:75], v[158:161], v[196:199], v[72:75]
	v_mfma_f32_16x16x32_bf16 v[124:127], v[154:157], v[170:173], v[124:127]
	v_mfma_f32_16x16x32_bf16 v[120:123], v[162:165], v[170:173], v[120:123]
	v_mfma_f32_16x16x32_bf16 v[108:111], v[154:157], v[184:187], v[108:111]
	v_mfma_f32_16x16x32_bf16 v[104:107], v[162:165], v[184:187], v[104:107]
	v_mfma_f32_16x16x32_bf16 v[92:95], v[154:157], v[192:195], v[92:95]
	v_mfma_f32_16x16x32_bf16 v[88:91], v[162:165], v[192:195], v[88:91]
	v_mfma_f32_16x16x32_bf16 v[76:79], v[154:157], v[200:203], v[76:79]
	v_mfma_f32_16x16x32_bf16 v[72:75], v[162:165], v[200:203], v[72:75]
	s_setprio 1
	s_barrier
	s_add_i32 s46, s37, s28
	v_lshl_add_u64 v[150:151], s[22:23], 0, v[130:131]
	s_mov_b32 m0, s46
	ds_read_b128 v[204:207], v178
	ds_read_b128 v[208:211], v178 offset:1024
	ds_read_b128 v[212:215], v178 offset:2048
	ds_read_b128 v[216:219], v178 offset:3072
	global_load_lds_dwordx4 v[150:151], off
	v_lshl_add_u64 v[220:221], s[22:23], 0, v[134:135]
	s_add_i32 m0, s46, 0x2000
	s_nop 0
	global_load_lds_dwordx4 v[220:221], off
	s_barrier
; #define PG8_STAGE(bufoff, gbase, voff) do { _Pragma("unroll") for (int _i = 0; _i < 2; ++_i) \
;         __builtin_amdgcn_global_load_lds((const unsigned*)((const char*)(gbase) + (voff)[_i]), (LAS unsigned*)(lds + (bufoff) + ldsw + _i * 8192), 16, 0, 0); } while (0)
; #define PG8_LDA(dst, b, h) do { _Pragma("unroll") for (int m = 0; m < 4; ++m) _Pragma("unroll") for (int k = 0; k < 2; ++k) dst[m][k] = *(const LAS bf16x8*)(lds + PG8_SA(b, h) + aoff + m * 2048 + k * 1024); } while (0)
; #define PG8_LDB(dst, b, h) do { _Pragma("unroll") for (int n = 0; n < 2; ++n) _Pragma("unroll") for (int k = 0; k < 2; ++k) dst[n][k] = *(const LAS bf16x8*)(lds + PG8_SB(b, h) + boff + n * 2048 + k * 1024); } while (0)
; #define PG8_MMA(ai, bj, At, Bt) do { __builtin_amdgcn_s_setprio(1); _Pragma("unroll") for (int m = 0; m < 4; ++m) _Pragma("unroll") for (int n = 0; n < 2; ++n) _Pragma("unroll") for (int k = 0; k < 2; ++k) \
;         acc[ai][bj][m][n] = __builtin_amdgcn_mfma_f32_16x16x32_bf16(Bt[n][k], At[m][k], acc[ai][bj][m][n], 0, 0, 0); __builtin_amdgcn_s_setprio(0); } while (0)
; #define PG8_WAIT_V(n) asm volatile("s_waitcnt vmcnt(" #n ")" ::: "memory")
; #define PG8_WAIT_L(n) asm volatile("s_waitcnt lgkmcnt(" #n ")" ::: "memory")
; #define PG8_BAR __builtin_amdgcn_s_barrier()
; #define PG8_SCHED __builtin_amdgcn_sched_barrier(0)
; template <class Epi>
; __device__ __forceinline__ void gemm_phase(LAS unsigned char* lds, const Gemm g, const StaticOrder& S, const Epi& E) {
;     ...
;             PG8_BAR; PG8_WAIT_L(0); PG8_MMA(0, 1, At, B1); PG8_BAR;
;             PG8_LDA(At, 0, 1); PG8_STAGE(PG8_SA(0, 0), a2, voffA);
;             PG8_BAR; PG8_WAIT_L(0); PG8_MMA(1, 0, At, B0); PG8_BAR; PG8_SCHED;
;             PG8_STAGE(PG8_SB(0, 1), b2 + hstepB, voffB);
;             PG8_WAIT_V(6); PG8_BAR; PG8_MMA(1, 1, At, B1); PG8_BAR;
;             PG8_LDB(B0, 1, 0); PG8_SCHED; PG8_LDA(At, 1, 0); PG8_STAGE(PG8_SA(0, 1), a2 + hstepA, voffA);
;             PG8_WAIT_L(8); PG8_BAR; PG8_WAIT_L(0); PG8_MMA(0, 0, At, B0); PG8_BAR; PG8_SCHED;
	s_waitcnt lgkmcnt(0)
	s_setprio 2
	s_waitcnt lgkmcnt(0)
	v_mfma_f32_16x16x32_bf16 v[116:119], v[204:207], v[166:169], v[116:119]
	v_mfma_f32_16x16x32_bf16 v[112:115], v[212:215], v[166:169], v[112:115]
	v_mfma_f32_16x16x32_bf16 v[100:103], v[204:207], v[180:183], v[100:103]
	v_mfma_f32_16x16x32_bf16 v[96:99], v[212:215], v[180:183], v[96:99]
	v_mfma_f32_16x16x32_bf16 v[84:87], v[204:207], v[188:191], v[84:87]
	v_mfma_f32_16x16x32_bf16 v[80:83], v[212:215], v[188:191], v[80:83]
	v_mfma_f32_16x16x32_bf16 v[68:71], v[204:207], v[196:199], v[68:71]
	v_mfma_f32_16x16x32_bf16 v[64:67], v[212:215], v[196:199], v[64:67]
	v_mfma_f32_16x16x32_bf16 v[116:119], v[208:211], v[170:173], v[116:119]
	v_mfma_f32_16x16x32_bf16 v[112:115], v[216:219], v[170:173], v[112:115]
	v_mfma_f32_16x16x32_bf16 v[100:103], v[208:211], v[184:187], v[100:103]
	v_mfma_f32_16x16x32_bf16 v[96:99], v[216:219], v[184:187], v[96:99]
	v_mfma_f32_16x16x32_bf16 v[84:87], v[208:211], v[192:195], v[84:87]
	v_mfma_f32_16x16x32_bf16 v[80:83], v[216:219], v[192:195], v[80:83]
	v_mfma_f32_16x16x32_bf16 v[68:71], v[208:211], v[200:203], v[68:71]
	v_mfma_f32_16x16x32_bf16 v[64:67], v[216:219], v[200:203], v[64:67]
	s_setprio 1
	s_mov_b32 m0, s19
	v_lshl_add_u64 v[222:223], s[24:25], 0, v[128:129]
	s_barrier
	ds_read_b128 v[166:169], v177 offset:16384
	ds_read_b128 v[170:173], v177 offset:17408
	ds_read_b128 v[180:183], v177 offset:18432
	ds_read_b128 v[184:187], v177 offset:19456
	ds_read_b128 v[188:191], v177 offset:20480
	ds_read_b128 v[192:195], v177 offset:21504
	ds_read_b128 v[196:199], v177 offset:22528
	ds_read_b128 v[200:203], v177 offset:23552
	global_load_lds_dwordx4 v[222:223], off
	v_lshl_add_u64 v[224:225], s[24:25], 0, v[132:133]
	s_mov_b32 m0, s29
	s_nop 0
	global_load_lds_dwordx4 v[224:225], off
	s_barrier
	s_waitcnt lgkmcnt(0)
	s_setprio 2
	s_waitcnt lgkmcnt(0)
	v_mfma_f32_16x16x32_bf16 v[60:63], v[146:149], v[166:169], v[60:63]
	v_mfma_f32_16x16x32_bf16 v[56:59], v[158:161], v[166:169], v[56:59]
	v_mfma_f32_16x16x32_bf16 v[44:47], v[146:149], v[180:183], v[44:47]
	v_mfma_f32_16x16x32_bf16 v[40:43], v[158:161], v[180:183], v[40:43]
	v_mfma_f32_16x16x32_bf16 v[28:31], v[146:149], v[188:191], v[28:31]
	v_mfma_f32_16x16x32_bf16 v[24:27], v[158:161], v[188:191], v[24:27]
	v_mfma_f32_16x16x32_bf16 v[12:15], v[146:149], v[196:199], v[12:15]
	v_mfma_f32_16x16x32_bf16 v[8:11], v[158:161], v[196:199], v[8:11]
	v_mfma_f32_16x16x32_bf16 v[60:63], v[154:157], v[170:173], v[60:63]
	v_mfma_f32_16x16x32_bf16 v[56:59], v[162:165], v[170:173], v[56:59]
	v_mfma_f32_16x16x32_bf16 v[44:47], v[154:157], v[184:187], v[44:47]
	v_mfma_f32_16x16x32_bf16 v[40:43], v[162:165], v[184:187], v[40:43]
	v_mfma_f32_16x16x32_bf16 v[28:31], v[154:157], v[192:195], v[28:31]
	v_mfma_f32_16x16x32_bf16 v[24:27], v[162:165], v[192:195], v[24:27]
	v_mfma_f32_16x16x32_bf16 v[12:15], v[154:157], v[200:203], v[12:15]
	v_mfma_f32_16x16x32_bf16 v[8:11], v[162:165], v[200:203], v[8:11]
	s_setprio 1
	s_barrier
	s_add_u32 s46, s22, 0x40000
	s_addc_u32 s47, s23, 0
	s_add_i32 s48, s38, s28
	v_lshl_add_u64 v[146:147], s[46:47], 0, v[130:131]
	s_mov_b32 m0, s48
	s_nop 0
	global_load_lds_dwordx4 v[146:147], off
	v_lshl_add_u64 v[146:147], s[46:47], 0, v[134:135]
	s_add_i32 m0, s48, 0x2000
	s_nop 0
	global_load_lds_dwordx4 v[146:147], off
	s_waitcnt vmcnt(6)
	s_barrier
	s_setprio 2
	v_mfma_f32_16x16x32_bf16 v[52:55], v[204:207], v[166:169], v[52:55]
	v_mfma_f32_16x16x32_bf16 v[48:51], v[212:215], v[166:169], v[48:51]
	v_mfma_f32_16x16x32_bf16 v[36:39], v[204:207], v[180:183], v[36:39]
	v_mfma_f32_16x16x32_bf16 v[32:35], v[212:215], v[180:183], v[32:35]
	v_mfma_f32_16x16x32_bf16 v[20:23], v[204:207], v[188:191], v[20:23]
	v_mfma_f32_16x16x32_bf16 v[16:19], v[212:215], v[188:191], v[16:19]
	v_mfma_f32_16x16x32_bf16 v[4:7], v[204:207], v[196:199], v[4:7]
	v_mfma_f32_16x16x32_bf16 v[0:3], v[212:215], v[196:199], v[0:3]
	v_mfma_f32_16x16x32_bf16 v[52:55], v[208:211], v[170:173], v[52:55]
	v_mfma_f32_16x16x32_bf16 v[48:51], v[216:219], v[170:173], v[48:51]
	v_mfma_f32_16x16x32_bf16 v[36:39], v[208:211], v[184:187], v[36:39]
	v_mfma_f32_16x16x32_bf16 v[32:35], v[216:219], v[184:187], v[32:35]
	v_mfma_f32_16x16x32_bf16 v[20:23], v[208:211], v[192:195], v[20:23]
	v_mfma_f32_16x16x32_bf16 v[16:19], v[216:219], v[192:195], v[16:19]
	v_mfma_f32_16x16x32_bf16 v[4:7], v[208:211], v[200:203], v[4:7]
	v_mfma_f32_16x16x32_bf16 v[0:3], v[216:219], v[200:203], v[0:3]
	s_setprio 1
	s_add_i32 s46, 0, 0x18000
	v_add_u32_e32 v162, s46, v174
	s_barrier
	ds_read_b128 v[146:149], v162
	ds_read_b128 v[154:157], v162 offset:1024
	ds_read_b128 v[158:161], v162 offset:2048
	ds_read_b128 v[162:165], v162 offset:3072
	s_add_u32 s24, s24, 0x40000
	s_addc_u32 s25, s25, 0
	s_mov_b32 m0, s30
	v_lshl_add_u64 v[204:205], s[24:25], 0, v[128:129]
	ds_read_b128 v[166:169], v177 offset:32768
	ds_read_b128 v[170:173], v177 offset:33792
	ds_read_b128 v[180:183], v177 offset:34816
	ds_read_b128 v[184:187], v177 offset:35840
	ds_read_b128 v[188:191], v177 offset:36864
	ds_read_b128 v[192:195], v177 offset:37888
	ds_read_b128 v[196:199], v177 offset:38912
	ds_read_b128 v[200:203], v177 offset:39936
	global_load_lds_dwordx4 v[204:205], off
	v_lshl_add_u64 v[204:205], s[24:25], 0, v[132:133]
	s_mov_b32 m0, s31
	s_nop 0
	global_load_lds_dwordx4 v[204:205], off
	s_waitcnt lgkmcnt(8)
	s_barrier
; #define PG8_STAGE(bufoff, gbase, voff) do { _Pragma("unroll") for (int _i = 0; _i < 2; ++_i) \
;         __builtin_amdgcn_global_load_lds((const unsigned*)((const char*)(gbase) + (voff)[_i]), (LAS unsigned*)(lds + (bufoff) + ldsw + _i * 8192), 16, 0, 0); } while (0)
; #define PG8_LDA(dst, b, h) do { _Pragma("unroll") for (int m = 0; m < 4; ++m) _Pragma("unroll") for (int k = 0; k < 2; ++k) dst[m][k] = *(const LAS bf16x8*)(lds + PG8_SA(b, h) + aoff + m * 2048 + k * 1024); } while (0)
; #define PG8_LDB(dst, b, h) do { _Pragma("unroll") for (int n = 0; n < 2; ++n) _Pragma("unroll") for (int k = 0; k < 2; ++k) dst[n][k] = *(const LAS bf16x8*)(lds + PG8_SB(b, h) + boff + n * 2048 + k * 1024); } while (0)
; #define PG8_MMA(ai, bj, At, Bt) do { __builtin_amdgcn_s_setprio(1); _Pragma("unroll") for (int m = 0; m < 4; ++m) _Pragma("unroll") for (int n = 0; n < 2; ++n) _Pragma("unroll") for (int k = 0; k < 2; ++k) \
;         acc[ai][bj][m][n] = __builtin_amdgcn_mfma_f32_16x16x32_bf16(Bt[n][k], At[m][k], acc[ai][bj][m][n], 0, 0, 0); __builtin_amdgcn_s_setprio(0); } while (0)
; #define PG8_WAIT_V(n) asm volatile("s_waitcnt vmcnt(" #n ")" ::: "memory")
; #define PG8_WAIT_L(n) asm volatile("s_waitcnt lgkmcnt(" #n ")" ::: "memory")
; #define PG8_BAR __builtin_amdgcn_s_barrier()
; #define PG8_SCHED __builtin_amdgcn_sched_barrier(0)
; template <class Epi>
; __device__ __forceinline__ void gemm_phase(LAS unsigned char* lds, const Gemm g, const StaticOrder& S, const Epi& E) {
;     ...
;             PG8_WAIT_L(8); PG8_BAR; PG8_WAIT_L(0); PG8_MMA(0, 0, At, B0); PG8_BAR; PG8_SCHED;
;             PG8_LDB(B1, 1, 1); PG8_STAGE(PG8_SB(1, 0), b3, voffB);
;             PG8_BAR; PG8_WAIT_L(0); PG8_MMA(0, 1, At, B1); PG8_BAR;
;             PG8_LDA(At, 1, 1); PG8_STAGE(PG8_SA(1, 0), a3, voffA);
;             PG8_BAR; PG8_WAIT_L(0); PG8_MMA(1, 0, At, B0); PG8_BAR; PG8_SCHED;
;             PG8_STAGE(PG8_SB(1, 1), b3 + hstepB, voffB);
;             PG8_WAIT_V(6); PG8_BAR; PG8_MMA(1, 1, At, B1); PG8_BAR;
	s_waitcnt lgkmcnt(0)
	s_setprio 2
	s_waitcnt lgkmcnt(0)
	v_mfma_f32_16x16x32_bf16 v[124:127], v[146:149], v[166:169], v[124:127]
	v_mfma_f32_16x16x32_bf16 v[120:123], v[158:161], v[166:169], v[120:123]
	v_mfma_f32_16x16x32_bf16 v[108:111], v[146:149], v[180:183], v[108:111]
	v_mfma_f32_16x16x32_bf16 v[104:107], v[158:161], v[180:183], v[104:107]
	v_mfma_f32_16x16x32_bf16 v[92:95], v[146:149], v[188:191], v[92:95]
	v_mfma_f32_16x16x32_bf16 v[88:91], v[158:161], v[188:191], v[88:91]
	v_mfma_f32_16x16x32_bf16 v[76:79], v[146:149], v[196:199], v[76:79]
	v_mfma_f32_16x16x32_bf16 v[72:75], v[158:161], v[196:199], v[72:75]
	v_mfma_f32_16x16x32_bf16 v[124:127], v[154:157], v[170:173], v[124:127]
	v_mfma_f32_16x16x32_bf16 v[120:123], v[162:165], v[170:173], v[120:123]
	v_mfma_f32_16x16x32_bf16 v[108:111], v[154:157], v[184:187], v[108:111]
	v_mfma_f32_16x16x32_bf16 v[104:107], v[162:165], v[184:187], v[104:107]
	v_mfma_f32_16x16x32_bf16 v[92:95], v[154:157], v[192:195], v[92:95]
	v_mfma_f32_16x16x32_bf16 v[88:91], v[162:165], v[192:195], v[88:91]
	v_mfma_f32_16x16x32_bf16 v[76:79], v[154:157], v[200:203], v[76:79]
	v_mfma_f32_16x16x32_bf16 v[72:75], v[162:165], v[200:203], v[72:75]
	s_setprio 1
	s_barrier
	s_add_i32 s24, 0, 0x1c000
	s_add_i32 s25, s46, s28
	v_add_u32_e32 v216, s24, v174
	v_lshl_add_u64 v[150:151], v[150:151], 0, s[4:5]
	s_mov_b32 m0, s25
	ds_read_b128 v[204:207], v216
	ds_read_b128 v[208:211], v216 offset:1024
	ds_read_b128 v[212:215], v216 offset:2048
	ds_read_b128 v[216:219], v216 offset:3072
	global_load_lds_dwordx4 v[150:151], off
	v_lshl_add_u64 v[150:151], v[220:221], 0, s[4:5]
	s_add_i32 m0, s25, 0x2000
	s_nop 0
	global_load_lds_dwordx4 v[150:151], off
	s_barrier
	s_waitcnt lgkmcnt(0)
	s_setprio 2
	s_waitcnt lgkmcnt(0)
	v_mfma_f32_16x16x32_bf16 v[116:119], v[204:207], v[166:169], v[116:119]
	v_mfma_f32_16x16x32_bf16 v[112:115], v[212:215], v[166:169], v[112:115]
	v_mfma_f32_16x16x32_bf16 v[100:103], v[204:207], v[180:183], v[100:103]
	v_mfma_f32_16x16x32_bf16 v[96:99], v[212:215], v[180:183], v[96:99]
	v_mfma_f32_16x16x32_bf16 v[84:87], v[204:207], v[188:191], v[84:87]
	v_mfma_f32_16x16x32_bf16 v[80:83], v[212:215], v[188:191], v[80:83]
	v_mfma_f32_16x16x32_bf16 v[68:71], v[204:207], v[196:199], v[68:71]
	v_mfma_f32_16x16x32_bf16 v[64:67], v[212:215], v[196:199], v[64:67]
	v_mfma_f32_16x16x32_bf16 v[116:119], v[208:211], v[170:173], v[116:119]
	v_mfma_f32_16x16x32_bf16 v[112:115], v[216:219], v[170:173], v[112:115]
	v_mfma_f32_16x16x32_bf16 v[100:103], v[208:211], v[184:187], v[100:103]
	v_mfma_f32_16x16x32_bf16 v[96:99], v[216:219], v[184:187], v[96:99]
	v_mfma_f32_16x16x32_bf16 v[84:87], v[208:211], v[192:195], v[84:87]
	v_mfma_f32_16x16x32_bf16 v[80:83], v[216:219], v[192:195], v[80:83]
	v_mfma_f32_16x16x32_bf16 v[68:71], v[208:211], v[200:203], v[68:71]
	v_mfma_f32_16x16x32_bf16 v[64:67], v[216:219], v[200:203], v[64:67]
	s_setprio 1
	s_mov_b32 m0, s34
	v_lshl_add_u64 v[150:151], v[222:223], 0, s[4:5]
	s_barrier
	ds_read_b128 v[166:169], v177 offset:49152
	ds_read_b128 v[170:173], v177 offset:50176
	ds_read_b128 v[180:183], v177 offset:51200
	ds_read_b128 v[184:187], v177 offset:52224
	ds_read_b128 v[188:191], v177 offset:53248
	ds_read_b128 v[192:195], v177 offset:54272
	ds_read_b128 v[196:199], v177 offset:55296
	ds_read_b128 v[200:203], v177 offset:56320
	global_load_lds_dwordx4 v[150:151], off
	v_lshl_add_u64 v[150:151], v[224:225], 0, s[4:5]
	s_mov_b32 m0, s35
	s_nop 0
	global_load_lds_dwordx4 v[150:151], off
	s_barrier
	s_waitcnt lgkmcnt(0)
	s_setprio 2
	s_waitcnt lgkmcnt(0)
	v_mfma_f32_16x16x32_bf16 v[60:63], v[146:149], v[166:169], v[60:63]
	v_mfma_f32_16x16x32_bf16 v[56:59], v[158:161], v[166:169], v[56:59]
	v_mfma_f32_16x16x32_bf16 v[44:47], v[146:149], v[180:183], v[44:47]
	v_mfma_f32_16x16x32_bf16 v[40:43], v[158:161], v[180:183], v[40:43]
	v_mfma_f32_16x16x32_bf16 v[28:31], v[146:149], v[188:191], v[28:31]
	v_mfma_f32_16x16x32_bf16 v[24:27], v[158:161], v[188:191], v[24:27]
	v_mfma_f32_16x16x32_bf16 v[12:15], v[146:149], v[196:199], v[12:15]
	v_mfma_f32_16x16x32_bf16 v[8:11], v[158:161], v[196:199], v[8:11]
	v_mfma_f32_16x16x32_bf16 v[60:63], v[154:157], v[170:173], v[60:63]
	v_mfma_f32_16x16x32_bf16 v[56:59], v[162:165], v[170:173], v[56:59]
	v_mfma_f32_16x16x32_bf16 v[44:47], v[154:157], v[184:187], v[44:47]
	v_mfma_f32_16x16x32_bf16 v[40:43], v[162:165], v[184:187], v[40:43]
	v_mfma_f32_16x16x32_bf16 v[28:31], v[154:157], v[192:195], v[28:31]
	v_mfma_f32_16x16x32_bf16 v[24:27], v[162:165], v[192:195], v[24:27]
	v_mfma_f32_16x16x32_bf16 v[12:15], v[154:157], v[200:203], v[12:15]
	v_mfma_f32_16x16x32_bf16 v[8:11], v[162:165], v[200:203], v[8:11]
	s_setprio 1
	s_barrier
	s_add_u32 s22, s22, 0x40080
	s_addc_u32 s23, s23, 0
	s_add_i32 s24, s24, s28
	v_lshl_add_u64 v[146:147], s[22:23], 0, v[130:131]
	s_mov_b32 m0, s24
	s_nop 0
	global_load_lds_dwordx4 v[146:147], off
	v_lshl_add_u64 v[146:147], s[22:23], 0, v[134:135]
	s_add_i32 m0, s24, 0x2000
	s_nop 0
	global_load_lds_dwordx4 v[146:147], off
	s_waitcnt vmcnt(6)
	s_barrier
	s_setprio 2
	v_mfma_f32_16x16x32_bf16 v[52:55], v[204:207], v[166:169], v[52:55]
	v_mfma_f32_16x16x32_bf16 v[48:51], v[212:215], v[166:169], v[48:51]
	v_mfma_f32_16x16x32_bf16 v[36:39], v[204:207], v[180:183], v[36:39]
	v_mfma_f32_16x16x32_bf16 v[32:35], v[212:215], v[180:183], v[32:35]
	v_mfma_f32_16x16x32_bf16 v[20:23], v[204:207], v[188:191], v[20:23]
	v_mfma_f32_16x16x32_bf16 v[16:19], v[212:215], v[188:191], v[16:19]
	v_mfma_f32_16x16x32_bf16 v[4:7], v[204:207], v[196:199], v[4:7]
	v_mfma_f32_16x16x32_bf16 v[0:3], v[212:215], v[196:199], v[0:3]
	v_mfma_f32_16x16x32_bf16 v[52:55], v[208:211], v[170:173], v[52:55]
	v_mfma_f32_16x16x32_bf16 v[48:51], v[216:219], v[170:173], v[48:51]
	v_mfma_f32_16x16x32_bf16 v[36:39], v[208:211], v[184:187], v[36:39]
	v_mfma_f32_16x16x32_bf16 v[32:35], v[216:219], v[184:187], v[32:35]
	v_mfma_f32_16x16x32_bf16 v[20:23], v[208:211], v[192:195], v[20:23]
	v_mfma_f32_16x16x32_bf16 v[16:19], v[216:219], v[192:195], v[16:19]
	v_mfma_f32_16x16x32_bf16 v[4:7], v[208:211], v[200:203], v[4:7]
	v_mfma_f32_16x16x32_bf16 v[0:3], v[216:219], v[200:203], v[0:3]
	s_setprio 1
	s_add_i32 s45, s45, 2
	s_add_u32 s20, s20, 0x100
	s_addc_u32 s21, s21, 0
	s_add_u32 s43, s43, 0x100
	s_addc_u32 s44, s44, 0
	s_cmp_gt_u32 s45, 13
	s_barrier
	s_cbranch_scc0 .Lkp6_1204
	s_branch .Lkp6_epi
;     __device__ bool next(int i, Unit& u) const {
;         const long L = (long)i * G + c; if (L >= nwg) return false;
;         int wgid = (int)L; { const int q = nwg / NXCD, r = nwg % NXCD, xcd = wgid % NXCD, off = wgid / NXCD; wgid = (xcd < r ? xcd * (q + 1) : r * (q + 1) + (xcd - r) * q) + off; }
;         const int nig = WGM * nN, gid = wgid / nig, fm = gid * WGM, gsz = (nM - fm) < WGM ? (nM - fm) : WGM;
;         u.pm = fm + ((wgid % nig) % gsz); u.pn = (wgid % nig) / gsz; return true;
; template <class Epi>
; __device__ __forceinline__ void gemm_phase(LAS unsigned char* lds, const Gemm g, const StaticOrder& S, const Epi& E) {
;     ...
;         const bool has_next = S.next(ui + 1, nxt);
;         const char* nA = has_next ? (const char*)g.A + (size_t)nxt.pm * tstepA : cA; const char* nB = has_next ? (const char*)g.Bt + (size_t)nxt.pn * tstepB : cB;
.LBB0_1197:
	v_readfirstlane_b32 s98, v152
	s_nop 3
	s_cmp_ge_u32 s98, 0x100
	s_cbranch_scc1 .Lkp6_head
	s_add_i32 s33, s33, 1
	s_mul_i32 s0, s33, s36
	s_mul_hi_u32 s1, s33, s92
	s_add_i32 s1, s1, s0
	s_mul_i32 s0, s33, s92
	s_add_u32 s14, s0, s93
	s_addc_u32 s15, s1, s9
	v_cmp_gt_i64_e64 s[0:1], s[14:15], v[144:145]
	s_and_b64 vcc, exec, s[0:1]
	s_cbranch_vccnz .LBB0_1203
	s_lshr_b32 s10, s14, 3
	s_mov_b32 s13, 0
	s_sub_u32 s11, s10, 0x80
	s_cmp_ge_u32 s10, 0x80
	s_cselect_b32 s10, s11, s10
	s_addc_u32 s13, s13, 0
	s_sub_u32 s11, s10, 0x80
	s_cmp_ge_u32 s10, 0x80
	s_cselect_b32 s10, s11, s10
	s_addc_u32 s13, s13, 0
	s_sub_u32 s11, s10, 0x80
	s_cmp_ge_u32 s10, 0x80
	s_cselect_b32 s10, s11, s10
	s_addc_u32 s13, s13, 0
	s_and_b32 s12, s14, 7
	s_lshl_b32 s12, s12, 2
	s_add_i32 s12, s12, s13
	s_lshl_b32 s12, s12, 3
	s_and_b32 s13, s10, 7
	s_add_i32 s12, s12, s13
	s_lshr_b32 s10, s10, 3

; __device__ __forceinline__ unsigned pk2(float lo, float hi) { const f32x2 v = (f32x2){lo, hi}; const bf16x2_t b = __builtin_convertvector(v, bf16x2_t); return __builtin_bit_cast(unsigned, b); }
;     __device__ __forceinline__ void operator()(const f32x4 (&acc)[2][2][4][2], const Unit& u, int wr, int wc, int fr, int fq, const float (&)[8]) const {
;         const int row0 = u.pm * BM + wr * 64 + fr;
;         float ep[8];
; #pragma unroll
;         for (int ai = 0; ai < 2; ++ai)
; #pragma unroll
;             for (int m = 0; m < 4; ++m) { const int row = row0 + ai * HALF + m * 16;
;                 if (SLOTS == 1) ep[ai * 4 + m] = ss[row];
;                 else { const f32x4 pq = *(const f32x4*)(ss + (size_t)row * 16 + 4 * fq); ep[ai * 4 + m] = (pq[0] + pq[1]) + (pq[2] + pq[3]); } }
;     ...
;         const int col0 = u.pn * BM + wc * 32 + 8 * fq;
; #pragma unroll
;         for (int ai = 0; ai < 2; ++ai)
; #pragma unroll
;             for (int m = 0; m < 4; ++m) { const int row = row0 + ai * HALF + m * 16; const float rs = rsqrtf(ep[ai * 4 + m] * (1.0f / 1024.0f) + EPS);
;                 u16* rowp = O + (size_t)row * ldc + col0;
; #pragma unroll
;                 for (int bj = 0; bj < 2; ++bj) { f32x4 v0 = acc[ai][bj][m][0] * rs, v1 = acc[ai][bj][m][1] * rs;
;                     if (ACT == 1) {
; #pragma unroll
;                         for (int j = 0; j < 4; ++j) { const float a0 = fmaxf(v0[j], 0.f), a1 = fmaxf(v1[j], 0.f); v0[j] = a0 * a0; v1[j] = a1 * a1; } }
;                     u32x4 w; w.x = pk2(v0[0], v0[1]); w.y = pk2(v0[2], v0[3]); w.z = pk2(v1[0], v1[1]); w.w = pk2(v1[2], v1[3]);
;                     *(u32x4*)(rowp + bj * HALF) = w; } }
.Lkp6_epi:
	s_setprio 0
	s_bfe_u32 vcc_lo, s18, 0x20003
	s_lshl_b32 vcc_lo, vcc_lo, 10
	s_add_i32 vcc_lo, vcc_lo, 0x20010
	v_lshl_add_u32 v236, v153, 2, vcc_lo
	ds_read_b32 v228, v236
	ds_read_b32 v229, v236 offset:64
	ds_read_b32 v230, v236 offset:128
	ds_read_b32 v231, v236 offset:192
	ds_read_b32 v232, v236 offset:512
	ds_read_b32 v233, v236 offset:576
	ds_read_b32 v234, v236 offset:640
	ds_read_b32 v235, v236 offset:704
	s_waitcnt lgkmcnt(0)
	v_lshl_add_u32 v148, s18, 8, v153
	v_ashrrev_i32_e32 v149, 31, v148
	v_or_b32_e32 v172, 16, v148
	v_ashrrev_i32_e32 v173, 31, v172
	v_or_b32_e32 v168, 32, v148
	v_or_b32_e32 v164, 48, v148
	v_ashrrev_i32_e32 v169, 31, v168
	v_ashrrev_i32_e32 v165, 31, v164
	v_add_u32_e32 v162, 0x80, v148
	v_add_u32_e32 v156, 0x90, v148
	v_ashrrev_i32_e32 v163, 31, v162
	v_ashrrev_i32_e32 v157, 31, v156
	v_add_u32_e32 v150, 0xa0, v148
	v_ashrrev_i32_e32 v151, 31, v150
	v_add_u32_e32 v146, 0xb0, v148
	v_ashrrev_i32_e32 v147, 31, v146
	v_lshl_or_b32 v166, s40, 8, v175
	v_ashrrev_i32_e32 v167, 31, v166
	v_lshlrev_b64 v[170:171], 13, v[148:149]
	v_lshlrev_b64 v[148:149], 1, v[166:167]
	v_lshl_add_u64 v[166:167], s[96:97], 0, v[170:171]
	v_lshl_add_u64 v[210:211], v[166:167], 0, v[148:149]
	s_mov_b32 s40, s10
	s_mov_b32 s18, s12
	s_mov_b64 s[22:23], s[16:17]
	s_mov_b64 s[20:21], s[14:15]
	s_waitcnt vmcnt(8)
	s_waitcnt lgkmcnt(0)
	s_waitcnt lgkmcnt(0)
	v_mov_b32_e32 v182, v228
	v_pk_mul_f32 v[120:121], v[120:121], v[182:183] op_sel_hi:[1,0]
	v_pk_mul_f32 v[126:127], v[126:127], v[182:183] op_sel_hi:[1,0]
	v_pk_mul_f32 v[124:125], v[124:125], v[182:183] op_sel_hi:[1,0]
	v_pk_mul_f32 v[122:123], v[122:123], v[182:183] op_sel_hi:[1,0]
	v_max_f32_e32 v120, 0, v120
	v_max_f32_e32 v121, 0, v121
	v_max_f32_e32 v124, 0, v124
	v_max_f32_e32 v125, 0, v125
	v_pk_mul_f32 v[188:189], v[120:121], v[120:121]
	v_max_f32_e32 v120, 0, v126
	v_max_f32_e32 v122, 0, v122
	v_max_f32_e32 v121, 0, v127
	v_max_f32_e32 v123, 0, v123
	v_pk_mul_f32 v[124:125], v[124:125], v[124:125]
	v_pk_mul_f32 v[126:127], v[120:121], v[120:121]
	v_pk_mul_f32 v[192:193], v[122:123], v[122:123]
	v_pk_mul_f32 v[114:115], v[114:115], v[182:183] op_sel_hi:[1,0]
	v_cvt_pk_bf16_f32 v120, v124, v125
	v_cvt_pk_bf16_f32 v121, v126, v127
	v_cvt_pk_bf16_f32 v122, v188, v189
	v_cvt_pk_bf16_f32 v123, v192, v193
	v_pk_mul_f32 v[116:117], v[116:117], v[182:183] op_sel_hi:[1,0]
	v_pk_mul_f32 v[112:113], v[112:113], v[182:183] op_sel_hi:[1,0]
	v_max_f32_e32 v114, 0, v114
	v_max_f32_e32 v115, 0, v115
	global_store_dwordx4 v[210:211], v[120:123], off
	v_pk_mul_f32 v[118:119], v[118:119], v[182:183] op_sel_hi:[1,0]
	v_max_f32_e32 v116, 0, v116
	v_max_f32_e32 v112, 0, v112
	v_max_f32_e32 v117, 0, v117
	v_max_f32_e32 v113, 0, v113
	v_pk_mul_f32 v[122:123], v[114:115], v[114:115]
	v_pk_mul_f32 v[116:117], v[116:117], v[116:117]
	v_pk_mul_f32 v[120:121], v[112:113], v[112:113]
	v_max_f32_e32 v112, 0, v118
	v_max_f32_e32 v113, 0, v119
	v_pk_mul_f32 v[118:119], v[112:113], v[112:113]
	v_cvt_pk_bf16_f32 v112, v116, v117
	v_cvt_pk_bf16_f32 v113, v118, v119
	v_cvt_pk_bf16_f32 v114, v120, v121
	v_cvt_pk_bf16_f32 v115, v122, v123
	global_store_dwordx4 v[210:211], v[112:115], off offset:256
	s_nop 1
	v_mov_b32_e32 v112, v229
	v_pk_mul_f32 v[104:105], v[104:105], v[112:113] op_sel_hi:[1,0]
	v_pk_mul_f32 v[110:111], v[110:111], v[112:113] op_sel_hi:[1,0]
	v_pk_mul_f32 v[108:109], v[108:109], v[112:113] op_sel_hi:[1,0]
	v_pk_mul_f32 v[106:107], v[106:107], v[112:113] op_sel_hi:[1,0]
	v_max_f32_e32 v104, 0, v104
	v_max_f32_e32 v105, 0, v105
	v_lshlrev_b64 v[114:115], 13, v[172:173]
	v_max_f32_e32 v108, 0, v108
	v_max_f32_e32 v109, 0, v109
	v_pk_mul_f32 v[116:117], v[104:105], v[104:105]
	v_max_f32_e32 v104, 0, v110
	v_max_f32_e32 v106, 0, v106
	v_max_f32_e32 v105, 0, v111
	v_max_f32_e32 v107, 0, v107
	v_lshl_add_u64 v[114:115], s[96:97], 0, v[114:115]
	v_pk_mul_f32 v[108:109], v[108:109], v[108:109]
	v_pk_mul_f32 v[110:111], v[104:105], v[104:105]
	v_pk_mul_f32 v[118:119], v[106:107], v[106:107]
	v_pk_mul_f32 v[96:97], v[96:97], v[112:113] op_sel_hi:[1,0]
	v_lshl_add_u64 v[114:115], v[114:115], 0, v[148:149]
	v_cvt_pk_bf16_f32 v104, v108, v109
	v_cvt_pk_bf16_f32 v105, v110, v111
	v_cvt_pk_bf16_f32 v106, v116, v117
	v_cvt_pk_bf16_f32 v107, v118, v119
	v_pk_mul_f32 v[102:103], v[102:103], v[112:113] op_sel_hi:[1,0]
	v_max_f32_e32 v96, 0, v96
	v_max_f32_e32 v97, 0, v97
	global_store_dwordx4 v[114:115], v[104:107], off
	v_pk_mul_f32 v[100:101], v[100:101], v[112:113] op_sel_hi:[1,0]
	v_pk_mul_f32 v[98:99], v[98:99], v[112:113] op_sel_hi:[1,0]
	v_pk_mul_f32 v[104:105], v[96:97], v[96:97]
	v_max_f32_e32 v96, 0, v102
	v_max_f32_e32 v97, 0, v103
	v_max_f32_e32 v100, 0, v100
	v_max_f32_e32 v101, 0, v101
	v_pk_mul_f32 v[100:101], v[100:101], v[100:101]
	v_pk_mul_f32 v[108:109], v[96:97], v[96:97]
	v_cvt_pk_bf16_f32 v96, v100, v101
	s_waitcnt lgkmcnt(0)
	v_max_f32_e32 v98, 0, v98
	v_max_f32_e32 v99, 0, v99
	v_pk_mul_f32 v[110:111], v[98:99], v[98:99]
	v_cvt_pk_bf16_f32 v97, v108, v109
	v_cvt_pk_bf16_f32 v98, v104, v105
	v_cvt_pk_bf16_f32 v99, v110, v111
	global_store_dwordx4 v[114:115], v[96:99], off offset:256
	s_waitcnt lgkmcnt(0)
; __device__ __forceinline__ unsigned pk2(float lo, float hi) { const f32x2 v = (f32x2){lo, hi}; const bf16x2_t b = __builtin_convertvector(v, bf16x2_t); return __builtin_bit_cast(unsigned, b); }
;     __device__ __forceinline__ void operator()(const f32x4 (&acc)[2][2][4][2], const Unit& u, int wr, int wc, int fr, int fq, const float (&)[8]) const {
;     ...
;         for (int ai = 0; ai < 2; ++ai)
; #pragma unroll
;             for (int m = 0; m < 4; ++m) { const int row = row0 + ai * HALF + m * 16; const float rs = rsqrtf(ep[ai * 4 + m] * (1.0f / 1024.0f) + EPS);
;                 u16* rowp = O + (size_t)row * ldc + col0;
; #pragma unroll
;                 for (int bj = 0; bj < 2; ++bj) { f32x4 v0 = acc[ai][bj][m][0] * rs, v1 = acc[ai][bj][m][1] * rs;
;                     if (ACT == 1) {
; #pragma unroll
;                         for (int j = 0; j < 4; ++j) { const float a0 = fmaxf(v0[j], 0.f), a1 = fmaxf(v1[j], 0.f); v0[j] = a0 * a0; v1[j] = a1 * a1; } }
;                     u32x4 w; w.x = pk2(v0[0], v0[1]); w.y = pk2(v0[2], v0[3]); w.z = pk2(v1[0], v1[1]); w.w = pk2(v1[2], v1[3]);
;                     *(u32x4*)(rowp + bj * HALF) = w; } }
	s_nop 0
	s_nop 0
	s_nop 0
	s_nop 1
	v_lshlrev_b64 v[98:99], 13, v[168:169]
	v_lshl_add_u64 v[98:99], s[96:97], 0, v[98:99]
	v_lshl_add_u64 v[98:99], v[98:99], 0, v[148:149]
	v_mov_b32_e32 v100, v230
	v_pk_mul_f32 v[88:89], v[88:89], v[100:101] op_sel_hi:[1,0]
	v_pk_mul_f32 v[94:95], v[94:95], v[100:101] op_sel_hi:[1,0]
	v_pk_mul_f32 v[92:93], v[92:93], v[100:101] op_sel_hi:[1,0]
	v_pk_mul_f32 v[90:91], v[90:91], v[100:101] op_sel_hi:[1,0]
	v_max_f32_e32 v88, 0, v88
	v_max_f32_e32 v89, 0, v89
	v_max_f32_e32 v92, 0, v92
	v_max_f32_e32 v93, 0, v93
	v_pk_mul_f32 v[102:103], v[88:89], v[88:89]
	v_max_f32_e32 v88, 0, v94
	v_max_f32_e32 v90, 0, v90
	v_max_f32_e32 v89, 0, v95
	v_max_f32_e32 v91, 0, v91
	v_pk_mul_f32 v[92:93], v[92:93], v[92:93]
	v_pk_mul_f32 v[94:95], v[88:89], v[88:89]
	v_pk_mul_f32 v[104:105], v[90:91], v[90:91]
	v_pk_mul_f32 v[82:83], v[82:83], v[100:101] op_sel_hi:[1,0]
	v_cvt_pk_bf16_f32 v88, v92, v93
	v_cvt_pk_bf16_f32 v89, v94, v95
	v_cvt_pk_bf16_f32 v90, v102, v103
	v_cvt_pk_bf16_f32 v91, v104, v105
	v_pk_mul_f32 v[84:85], v[84:85], v[100:101] op_sel_hi:[1,0]
	v_pk_mul_f32 v[80:81], v[80:81], v[100:101] op_sel_hi:[1,0]
	v_max_f32_e32 v82, 0, v82
	v_max_f32_e32 v83, 0, v83
	global_store_dwordx4 v[98:99], v[88:91], off
	v_pk_mul_f32 v[86:87], v[86:87], v[100:101] op_sel_hi:[1,0]
	v_max_f32_e32 v84, 0, v84
	v_max_f32_e32 v80, 0, v80
	v_max_f32_e32 v85, 0, v85
	v_max_f32_e32 v81, 0, v81
	v_pk_mul_f32 v[90:91], v[82:83], v[82:83]
	v_pk_mul_f32 v[84:85], v[84:85], v[84:85]
	v_pk_mul_f32 v[88:89], v[80:81], v[80:81]
	v_max_f32_e32 v80, 0, v86
	v_max_f32_e32 v81, 0, v87
	v_pk_mul_f32 v[86:87], v[80:81], v[80:81]
	v_cvt_pk_bf16_f32 v80, v84, v85
	v_cvt_pk_bf16_f32 v81, v86, v87
	v_cvt_pk_bf16_f32 v82, v88, v89
	v_cvt_pk_bf16_f32 v83, v90, v91
	global_store_dwordx4 v[98:99], v[80:83], off offset:256
	s_nop 1
	v_mov_b32_e32 v80, v231
	v_pk_mul_f32 v[72:73], v[72:73], v[80:81] op_sel_hi:[1,0]
	v_pk_mul_f32 v[78:79], v[78:79], v[80:81] op_sel_hi:[1,0]
	v_pk_mul_f32 v[76:77], v[76:77], v[80:81] op_sel_hi:[1,0]
	v_pk_mul_f32 v[74:75], v[74:75], v[80:81] op_sel_hi:[1,0]
	v_max_f32_e32 v72, 0, v72
	v_max_f32_e32 v73, 0, v73
	v_lshlrev_b64 v[82:83], 13, v[164:165]
	v_max_f32_e32 v76, 0, v76
	v_max_f32_e32 v77, 0, v77
	v_pk_mul_f32 v[84:85], v[72:73], v[72:73]
	v_max_f32_e32 v72, 0, v78
	v_max_f32_e32 v74, 0, v74
	v_max_f32_e32 v73, 0, v79
	v_max_f32_e32 v75, 0, v75
	v_lshl_add_u64 v[82:83], s[96:97], 0, v[82:83]
	v_pk_mul_f32 v[76:77], v[76:77], v[76:77]
	v_pk_mul_f32 v[78:79], v[72:73], v[72:73]
	v_pk_mul_f32 v[86:87], v[74:75], v[74:75]
	v_pk_mul_f32 v[64:65], v[64:65], v[80:81] op_sel_hi:[1,0]
	v_lshl_add_u64 v[82:83], v[82:83], 0, v[148:149]
	v_cvt_pk_bf16_f32 v72, v76, v77
	v_cvt_pk_bf16_f32 v73, v78, v79
	v_cvt_pk_bf16_f32 v74, v84, v85
	v_cvt_pk_bf16_f32 v75, v86, v87
	v_pk_mul_f32 v[70:71], v[70:71], v[80:81] op_sel_hi:[1,0]
	v_max_f32_e32 v64, 0, v64
	v_max_f32_e32 v65, 0, v65
	global_store_dwordx4 v[82:83], v[72:75], off
	v_pk_mul_f32 v[68:69], v[68:69], v[80:81] op_sel_hi:[1,0]
	v_pk_mul_f32 v[66:67], v[66:67], v[80:81] op_sel_hi:[1,0]
	v_pk_mul_f32 v[72:73], v[64:65], v[64:65]
	v_max_f32_e32 v64, 0, v70
	v_max_f32_e32 v65, 0, v71
	v_max_f32_e32 v68, 0, v68
	v_max_f32_e32 v69, 0, v69
	v_pk_mul_f32 v[68:69], v[68:69], v[68:69]
	v_pk_mul_f32 v[76:77], v[64:65], v[64:65]
	v_cvt_pk_bf16_f32 v64, v68, v69
	s_waitcnt lgkmcnt(0)
	v_max_f32_e32 v66, 0, v66
	v_max_f32_e32 v67, 0, v67
	v_pk_mul_f32 v[78:79], v[66:67], v[66:67]
	v_cvt_pk_bf16_f32 v65, v76, v77
	v_cvt_pk_bf16_f32 v66, v72, v73
	v_cvt_pk_bf16_f32 v67, v78, v79
	global_store_dwordx4 v[82:83], v[64:67], off offset:256
	s_waitcnt lgkmcnt(0)
	s_nop 0
	s_nop 0
	s_nop 0
	s_nop 1
	v_lshlrev_b64 v[66:67], 13, v[162:163]
	v_lshl_add_u64 v[66:67], s[96:97], 0, v[66:67]
	v_lshl_add_u64 v[66:67], v[66:67], 0, v[148:149]
	v_mov_b32_e32 v68, v232
	v_pk_mul_f32 v[56:57], v[56:57], v[68:69] op_sel_hi:[1,0]
	v_pk_mul_f32 v[62:63], v[62:63], v[68:69] op_sel_hi:[1,0]
	v_pk_mul_f32 v[60:61], v[60:61], v[68:69] op_sel_hi:[1,0]
	v_pk_mul_f32 v[58:59], v[58:59], v[68:69] op_sel_hi:[1,0]
	v_max_f32_e32 v56, 0, v56
	v_max_f32_e32 v57, 0, v57
	v_max_f32_e32 v60, 0, v60
	v_max_f32_e32 v61, 0, v61
	v_pk_mul_f32 v[70:71], v[56:57], v[56:57]
	v_max_f32_e32 v56, 0, v62
	v_max_f32_e32 v58, 0, v58
	v_max_f32_e32 v57, 0, v63
	v_max_f32_e32 v59, 0, v59
	v_pk_mul_f32 v[60:61], v[60:61], v[60:61]
	v_pk_mul_f32 v[62:63], v[56:57], v[56:57]
	v_pk_mul_f32 v[72:73], v[58:59], v[58:59]
	v_pk_mul_f32 v[50:51], v[50:51], v[68:69] op_sel_hi:[1,0]
	v_cvt_pk_bf16_f32 v56, v60, v61
	v_cvt_pk_bf16_f32 v57, v62, v63
	v_cvt_pk_bf16_f32 v58, v70, v71
	v_cvt_pk_bf16_f32 v59, v72, v73
	v_pk_mul_f32 v[52:53], v[52:53], v[68:69] op_sel_hi:[1,0]
	v_pk_mul_f32 v[48:49], v[48:49], v[68:69] op_sel_hi:[1,0]
	v_max_f32_e32 v50, 0, v50
	v_max_f32_e32 v51, 0, v51
	global_store_dwordx4 v[66:67], v[56:59], off
	v_pk_mul_f32 v[54:55], v[54:55], v[68:69] op_sel_hi:[1,0]
	v_max_f32_e32 v52, 0, v52
	v_max_f32_e32 v48, 0, v48
	v_max_f32_e32 v53, 0, v53
	v_max_f32_e32 v49, 0, v49
	v_pk_mul_f32 v[58:59], v[50:51], v[50:51]
	v_pk_mul_f32 v[52:53], v[52:53], v[52:53]
	v_pk_mul_f32 v[56:57], v[48:49], v[48:49]
	v_max_f32_e32 v48, 0, v54
	v_max_f32_e32 v49, 0, v55
	v_pk_mul_f32 v[54:55], v[48:49], v[48:49]
	v_cvt_pk_bf16_f32 v48, v52, v53
	v_cvt_pk_bf16_f32 v49, v54, v55
	v_cvt_pk_bf16_f32 v50, v56, v57
	v_cvt_pk_bf16_f32 v51, v58, v59
	global_store_dwordx4 v[66:67], v[48:51], off offset:256
	s_nop 1
	v_mov_b32_e32 v48, v233
	v_pk_mul_f32 v[40:41], v[40:41], v[48:49] op_sel_hi:[1,0]
	v_pk_mul_f32 v[46:47], v[46:47], v[48:49] op_sel_hi:[1,0]
	v_pk_mul_f32 v[44:45], v[44:45], v[48:49] op_sel_hi:[1,0]
	v_pk_mul_f32 v[42:43], v[42:43], v[48:49] op_sel_hi:[1,0]
	v_max_f32_e32 v40, 0, v40
	v_max_f32_e32 v41, 0, v41
	v_lshlrev_b64 v[50:51], 13, v[156:157]
	v_max_f32_e32 v44, 0, v44
	v_max_f32_e32 v45, 0, v45
	v_pk_mul_f32 v[52:53], v[40:41], v[40:41]
	v_max_f32_e32 v40, 0, v46
	v_max_f32_e32 v42, 0, v42
	v_max_f32_e32 v41, 0, v47
	v_max_f32_e32 v43, 0, v43
	v_lshl_add_u64 v[50:51], s[96:97], 0, v[50:51]
	v_pk_mul_f32 v[44:45], v[44:45], v[44:45]
	v_pk_mul_f32 v[46:47], v[40:41], v[40:41]
	v_pk_mul_f32 v[54:55], v[42:43], v[42:43]
	v_pk_mul_f32 v[32:33], v[32:33], v[48:49] op_sel_hi:[1,0]
	v_lshl_add_u64 v[50:51], v[50:51], 0, v[148:149]
	v_cvt_pk_bf16_f32 v40, v44, v45
	v_cvt_pk_bf16_f32 v41, v46, v47
	v_cvt_pk_bf16_f32 v42, v52, v53
	v_cvt_pk_bf16_f32 v43, v54, v55
	v_pk_mul_f32 v[38:39], v[38:39], v[48:49] op_sel_hi:[1,0]
	v_max_f32_e32 v32, 0, v32
	v_max_f32_e32 v33, 0, v33
	global_store_dwordx4 v[50:51], v[40:43], off
	v_pk_mul_f32 v[36:37], v[36:37], v[48:49] op_sel_hi:[1,0]
	v_pk_mul_f32 v[34:35], v[34:35], v[48:49] op_sel_hi:[1,0]
	v_pk_mul_f32 v[40:41], v[32:33], v[32:33]
	v_max_f32_e32 v32, 0, v38
	v_max_f32_e32 v33, 0, v39
	v_max_f32_e32 v36, 0, v36
	v_max_f32_e32 v37, 0, v37
	v_pk_mul_f32 v[36:37], v[36:37], v[36:37]
	v_pk_mul_f32 v[44:45], v[32:33], v[32:33]
	v_cvt_pk_bf16_f32 v32, v36, v37
	s_waitcnt lgkmcnt(0)
; __device__ __forceinline__ unsigned pk2(float lo, float hi) { const f32x2 v = (f32x2){lo, hi}; const bf16x2_t b = __builtin_convertvector(v, bf16x2_t); return __builtin_bit_cast(unsigned, b); }
; #define PG8_WAIT_V(n) asm volatile("s_waitcnt vmcnt(" #n ")" ::: "memory")
; #define PG8_BAR __builtin_amdgcn_s_barrier()
;     __device__ __forceinline__ void operator()(const f32x4 (&acc)[2][2][4][2], const Unit& u, int wr, int wc, int fr, int fq, const float (&)[8]) const {
;     ...
;         for (int ai = 0; ai < 2; ++ai)
; #pragma unroll
;             for (int m = 0; m < 4; ++m) { const int row = row0 + ai * HALF + m * 16; const float rs = rsqrtf(ep[ai * 4 + m] * (1.0f / 1024.0f) + EPS);
;                 u16* rowp = O + (size_t)row * ldc + col0;
; #pragma unroll
;                 for (int bj = 0; bj < 2; ++bj) { f32x4 v0 = acc[ai][bj][m][0] * rs, v1 = acc[ai][bj][m][1] * rs;
;                     if (ACT == 1) {
; #pragma unroll
;                         for (int j = 0; j < 4; ++j) { const float a0 = fmaxf(v0[j], 0.f), a1 = fmaxf(v1[j], 0.f); v0[j] = a0 * a0; v1[j] = a1 * a1; } }
;                     u32x4 w; w.x = pk2(v0[0], v0[1]); w.y = pk2(v0[2], v0[3]); w.z = pk2(v1[0], v1[1]); w.w = pk2(v1[2], v1[3]);
;                     *(u32x4*)(rowp + bj * HALF) = w; } }
; template <class Epi>
; __device__ __forceinline__ void gemm_phase(LAS unsigned char* lds, const Gemm g, const StaticOrder& S, const Epi& E) {
;     ...
;         E(acc, cur, wr, wc, fr, fq, epre);
;         if (!has_next) break;
; #pragma unroll
;         for (int a = 0; a < 2; ++a)
; #pragma unroll
;             for (int b = 0; b < 2; ++b)
; #pragma unroll
;                 for (int m = 0; m < 4; ++m)
; #pragma unroll
;                     for (int n = 0; n < 2; ++n) acc[a][b][m][n] = (f32x4){0.f, 0.f, 0.f, 0.f};
;         cur = nxt; cA = nA; cB = nB; ++ui;
;     }
;     PG8_WAIT_V(0);
;     if (wr == 0) PG8_BAR;
;     PG8_BAR;
	v_max_f32_e32 v34, 0, v34
	v_max_f32_e32 v35, 0, v35
	v_pk_mul_f32 v[46:47], v[34:35], v[34:35]
	v_cvt_pk_bf16_f32 v33, v44, v45
	v_cvt_pk_bf16_f32 v34, v40, v41
	v_cvt_pk_bf16_f32 v35, v46, v47
	global_store_dwordx4 v[50:51], v[32:35], off offset:256
	s_waitcnt lgkmcnt(0)
	s_nop 0
	s_nop 0
	s_nop 0
	s_nop 1
	v_lshlrev_b64 v[34:35], 13, v[150:151]
	v_lshl_add_u64 v[34:35], s[96:97], 0, v[34:35]
	v_lshl_add_u64 v[34:35], v[34:35], 0, v[148:149]
	v_mov_b32_e32 v36, v234
	v_pk_mul_f32 v[24:25], v[24:25], v[36:37] op_sel_hi:[1,0]
	v_pk_mul_f32 v[30:31], v[30:31], v[36:37] op_sel_hi:[1,0]
	v_pk_mul_f32 v[28:29], v[28:29], v[36:37] op_sel_hi:[1,0]
	v_pk_mul_f32 v[26:27], v[26:27], v[36:37] op_sel_hi:[1,0]
	v_max_f32_e32 v24, 0, v24
	v_max_f32_e32 v25, 0, v25
	v_max_f32_e32 v28, 0, v28
	v_max_f32_e32 v29, 0, v29
	v_pk_mul_f32 v[38:39], v[24:25], v[24:25]
	v_max_f32_e32 v24, 0, v30
	v_max_f32_e32 v26, 0, v26
	v_max_f32_e32 v25, 0, v31
	v_max_f32_e32 v27, 0, v27
	v_pk_mul_f32 v[28:29], v[28:29], v[28:29]
	v_pk_mul_f32 v[30:31], v[24:25], v[24:25]
	v_pk_mul_f32 v[40:41], v[26:27], v[26:27]
	v_pk_mul_f32 v[18:19], v[18:19], v[36:37] op_sel_hi:[1,0]
	v_cvt_pk_bf16_f32 v24, v28, v29
	v_cvt_pk_bf16_f32 v25, v30, v31
	v_cvt_pk_bf16_f32 v26, v38, v39
	v_cvt_pk_bf16_f32 v27, v40, v41
	v_pk_mul_f32 v[20:21], v[20:21], v[36:37] op_sel_hi:[1,0]
	v_pk_mul_f32 v[16:17], v[16:17], v[36:37] op_sel_hi:[1,0]
	v_max_f32_e32 v18, 0, v18
	v_max_f32_e32 v19, 0, v19
	global_store_dwordx4 v[34:35], v[24:27], off
	v_pk_mul_f32 v[22:23], v[22:23], v[36:37] op_sel_hi:[1,0]
	v_max_f32_e32 v20, 0, v20
	v_max_f32_e32 v16, 0, v16
	v_max_f32_e32 v21, 0, v21
	v_max_f32_e32 v17, 0, v17
	v_pk_mul_f32 v[26:27], v[18:19], v[18:19]
	v_pk_mul_f32 v[20:21], v[20:21], v[20:21]
	v_pk_mul_f32 v[24:25], v[16:17], v[16:17]
	v_max_f32_e32 v16, 0, v22
	v_max_f32_e32 v17, 0, v23
	v_pk_mul_f32 v[22:23], v[16:17], v[16:17]
	v_cvt_pk_bf16_f32 v16, v20, v21
	v_cvt_pk_bf16_f32 v17, v22, v23
	v_cvt_pk_bf16_f32 v18, v24, v25
	v_cvt_pk_bf16_f32 v19, v26, v27
	global_store_dwordx4 v[34:35], v[16:19], off offset:256
	s_nop 1
	v_mov_b32_e32 v16, v235
	v_pk_mul_f32 v[8:9], v[8:9], v[16:17] op_sel_hi:[1,0]
	v_pk_mul_f32 v[14:15], v[14:15], v[16:17] op_sel_hi:[1,0]
	v_pk_mul_f32 v[12:13], v[12:13], v[16:17] op_sel_hi:[1,0]
	v_pk_mul_f32 v[10:11], v[10:11], v[16:17] op_sel_hi:[1,0]
	v_max_f32_e32 v8, 0, v8
	v_max_f32_e32 v9, 0, v9
	v_lshlrev_b64 v[18:19], 13, v[146:147]
	v_max_f32_e32 v12, 0, v12
	v_max_f32_e32 v13, 0, v13
	v_pk_mul_f32 v[20:21], v[8:9], v[8:9]
	v_max_f32_e32 v8, 0, v14
	v_max_f32_e32 v10, 0, v10
	v_max_f32_e32 v9, 0, v15
	v_max_f32_e32 v11, 0, v11
	v_lshl_add_u64 v[18:19], s[96:97], 0, v[18:19]
	v_pk_mul_f32 v[12:13], v[12:13], v[12:13]
	v_pk_mul_f32 v[14:15], v[8:9], v[8:9]
	v_pk_mul_f32 v[22:23], v[10:11], v[10:11]
	v_pk_mul_f32 v[0:1], v[0:1], v[16:17] op_sel_hi:[1,0]
	v_lshl_add_u64 v[18:19], v[18:19], 0, v[148:149]
	v_cvt_pk_bf16_f32 v8, v12, v13
	v_cvt_pk_bf16_f32 v9, v14, v15
	v_cvt_pk_bf16_f32 v10, v20, v21
	v_cvt_pk_bf16_f32 v11, v22, v23
	v_pk_mul_f32 v[6:7], v[6:7], v[16:17] op_sel_hi:[1,0]
	v_pk_mul_f32 v[4:5], v[4:5], v[16:17] op_sel_hi:[1,0]
	v_pk_mul_f32 v[2:3], v[2:3], v[16:17] op_sel_hi:[1,0]
	v_max_f32_e32 v0, 0, v0
	v_max_f32_e32 v1, 0, v1
	global_store_dwordx4 v[18:19], v[8:11], off
	v_max_f32_e32 v4, 0, v4
	v_max_f32_e32 v5, 0, v5
	v_pk_mul_f32 v[8:9], v[0:1], v[0:1]
	v_max_f32_e32 v0, 0, v6
	v_max_f32_e32 v2, 0, v2
	v_max_f32_e32 v1, 0, v7
	v_max_f32_e32 v3, 0, v3
	v_pk_mul_f32 v[4:5], v[4:5], v[4:5]
	v_pk_mul_f32 v[6:7], v[0:1], v[0:1]
	v_pk_mul_f32 v[10:11], v[2:3], v[2:3]
	v_cvt_pk_bf16_f32 v0, v4, v5
	v_cvt_pk_bf16_f32 v1, v6, v7
	v_cvt_pk_bf16_f32 v2, v8, v9
	v_cvt_pk_bf16_f32 v3, v10, v11
	s_and_b64 vcc, exec, s[0:1]
	global_store_dwordx4 v[18:19], v[0:3], off offset:256
	s_cbranch_vccz .LBB0_1197
	s_waitcnt vmcnt(0)
	s_cmpk_gt_u32 s7, 0xff
	s_cbranch_scc1 .LBB0_1208
	s_barrier

; #define PG8_STAGE(bufoff, gbase, voff) do { _Pragma("unroll") for (int _i = 0; _i < 2; ++_i) \
;         __builtin_amdgcn_global_load_lds((const unsigned*)((const char*)(gbase) + (voff)[_i]), (LAS unsigned*)(lds + (bufoff) + ldsw + _i * 8192), 16, 0, 0); } while (0)
; #define PG8_LDA(dst, b, h) do { _Pragma("unroll") for (int m = 0; m < 4; ++m) _Pragma("unroll") for (int k = 0; k < 2; ++k) dst[m][k] = *(const LAS bf16x8*)(lds + PG8_SA(b, h) + aoff + m * 2048 + k * 1024); } while (0)
; #define PG8_LDB(dst, b, h) do { _Pragma("unroll") for (int n = 0; n < 2; ++n) _Pragma("unroll") for (int k = 0; k < 2; ++k) dst[n][k] = *(const LAS bf16x8*)(lds + PG8_SB(b, h) + boff + n * 2048 + k * 1024); } while (0)
; #define PG8_MMA(ai, bj, At, Bt) do { __builtin_amdgcn_s_setprio(1); _Pragma("unroll") for (int m = 0; m < 4; ++m) _Pragma("unroll") for (int n = 0; n < 2; ++n) _Pragma("unroll") for (int k = 0; k < 2; ++k) \
;         acc[ai][bj][m][n] = __builtin_amdgcn_mfma_f32_16x16x32_bf16(Bt[n][k], At[m][k], acc[ai][bj][m][n], 0, 0, 0); __builtin_amdgcn_s_setprio(0); } while (0)
; #define PG8_WAIT_L(n) asm volatile("s_waitcnt lgkmcnt(" #n ")" ::: "memory")
; template <class Epi>
; __device__ __forceinline__ void gemm_phase(LAS unsigned char* lds, const Gemm g, const StaticOrder& S, const Epi& E) {
;     ...
;         const char* nA = has_next ? (const char*)g.A + (size_t)nxt.pm * tstepA : cA; const char* nB = has_next ? (const char*)g.Bt + (size_t)nxt.pn * tstepB : cB;
;         for (int t = 0; t < nt; t += 2) {
;             const bool last = (t == nt - 2);
;             const char* a1 = cA + (size_t)(t + 1) * kstep;
;             const char* a2 = last ? nA : cA + (size_t)(t + 2) * kstep; const char* b2 = last ? nB : cB + (size_t)(t + 2) * kstep;
;             const char* a3 = a2 + kstep; const char* b3 = b2 + kstep;
;             if (last) E.pre(cur, wr, fr, epre);
;             PG8_LDB(B0, 0, 0); PG8_SCHED; PG8_LDA(At, 0, 0); PG8_STAGE(PG8_SA(1, 1), a1 + hstepA, voffA);
;             PG8_WAIT_L(8); PG8_BAR; PG8_WAIT_L(0); PG8_MMA(0, 0, At, B0); PG8_BAR; PG8_SCHED;
;             PG8_LDB(B1, 0, 1); PG8_STAGE(PG8_SB(0, 0), b2, voffB);
;             PG8_BAR; PG8_WAIT_L(0); PG8_MMA(0, 1, At, B1); PG8_BAR;
;             PG8_LDA(At, 0, 1); PG8_STAGE(PG8_SA(0, 0), a2, voffA);
;             PG8_BAR; PG8_WAIT_L(0); PG8_MMA(1, 0, At, B0); PG8_BAR; PG8_SCHED;
.Lkp7_1277:
	s_ashr_i32 s17, s16, 31
	v_cmp_lt_i64_e32 vcc, s[18:19], v[166:167]
	s_lshl_b64 s[18:19], s[16:17], 21
	s_add_u32 s18, s96, s18
	s_addc_u32 s19, s97, s19
	s_and_b64 s[20:21], vcc, exec
	s_cselect_b32 s17, s19, s23
	s_cselect_b32 s44, s18, s22
	s_ashr_i32 s15, s14, 31
	s_lshl_b64 s[20:21], s[14:15], 21
	s_add_u32 s20, s29, s20
	s_addc_u32 s21, s30, s21
	s_and_b64 s[26:27], vcc, exec
	s_cselect_b32 s15, s21, s25
	s_cselect_b32 s45, s20, s24
	s_add_u32 s22, s22, 0x100080
	s_addc_u32 s23, s23, 0
	s_add_u32 s46, s24, 0x100
	s_addc_u32 s47, s25, 0
	s_mov_b32 s48, -2
	s_waitcnt lgkmcnt(0)
	ds_read_b128 v[128:131], v190
	ds_read_b128 v[132:135], v190 offset:1024
	ds_read_b128 v[136:139], v190 offset:2048
	ds_read_b128 v[140:143], v190 offset:3072
	s_add_u32 s24, s22, 0xfff00080
	s_addc_u32 s25, s23, -1
	s_cmp_eq_u32 s48, 60
	s_cselect_b32 s27, s17, s25
	s_cselect_b32 s26, s44, s24
	s_cselect_b32 s25, s15, s47
	s_cselect_b32 s24, s45, s46
	v_lshl_add_u64 v[186:187], s[22:23], 0, v[162:163]
	s_add_i32 m0, s7, 0xc000
	ds_read_b128 v[144:147], v191
	ds_read_b128 v[148:151], v191 offset:1024
	ds_read_b128 v[170:173], v191 offset:2048
	ds_read_b128 v[174:177], v191 offset:3072
	ds_read_b128 v[178:181], v191 offset:4096
	ds_read_b128 v[182:185], v191 offset:5120
	ds_read_b128 v[194:197], v191 offset:6144
	ds_read_b128 v[198:201], v191 offset:7168
	global_load_lds_dwordx4 v[186:187], off
	v_lshl_add_u64 v[186:187], s[22:23], 0, v[164:165]
	s_add_i32 m0, s7, 0xe000
	s_nop 0
	global_load_lds_dwordx4 v[186:187], off
	s_waitcnt lgkmcnt(8)
	s_barrier
	s_waitcnt lgkmcnt(0)
	s_setprio 2
	s_waitcnt lgkmcnt(0)
	v_mfma_f32_16x16x32_bf16 v[124:127], v[128:131], v[144:147], 0
	v_mfma_f32_16x16x32_bf16 v[120:123], v[136:139], v[144:147], 0
	v_mfma_f32_16x16x32_bf16 v[108:111], v[128:131], v[170:173], 0
	v_mfma_f32_16x16x32_bf16 v[104:107], v[136:139], v[170:173], 0
	v_mfma_f32_16x16x32_bf16 v[92:95], v[128:131], v[178:181], 0
	v_mfma_f32_16x16x32_bf16 v[88:91], v[136:139], v[178:181], 0
	v_mfma_f32_16x16x32_bf16 v[76:79], v[128:131], v[194:197], 0
	v_mfma_f32_16x16x32_bf16 v[72:75], v[136:139], v[194:197], 0
	v_mfma_f32_16x16x32_bf16 v[124:127], v[132:135], v[148:151], v[124:127]
	v_mfma_f32_16x16x32_bf16 v[120:123], v[140:143], v[148:151], v[120:123]
	v_mfma_f32_16x16x32_bf16 v[108:111], v[132:135], v[174:177], v[108:111]
	v_mfma_f32_16x16x32_bf16 v[104:107], v[140:143], v[174:177], v[104:107]
	v_mfma_f32_16x16x32_bf16 v[92:95], v[132:135], v[182:185], v[92:95]
	v_mfma_f32_16x16x32_bf16 v[88:91], v[140:143], v[182:185], v[88:91]
	v_mfma_f32_16x16x32_bf16 v[76:79], v[132:135], v[198:201], v[76:79]
	v_mfma_f32_16x16x32_bf16 v[72:75], v[140:143], v[198:201], v[72:75]
	s_setprio 1
	s_barrier
	s_add_i32 s49, s42, s31
	v_lshl_add_u64 v[186:187], s[24:25], 0, v[156:157]
	s_mov_b32 m0, s49
	ds_read_b128 v[202:205], v192
	ds_read_b128 v[206:209], v192 offset:1024
	ds_read_b128 v[210:213], v192 offset:2048
	ds_read_b128 v[214:217], v192 offset:3072
	global_load_lds_dwordx4 v[186:187], off
	v_lshl_add_u64 v[218:219], s[24:25], 0, v[160:161]
	s_add_i32 m0, s49, 0x2000
	s_nop 0
	global_load_lds_dwordx4 v[218:219], off
	s_barrier
	s_waitcnt lgkmcnt(0)
	s_setprio 2
	s_waitcnt lgkmcnt(0)
	v_mfma_f32_16x16x32_bf16 v[116:119], v[202:205], v[144:147], 0
	v_mfma_f32_16x16x32_bf16 v[112:115], v[210:213], v[144:147], 0
	v_mfma_f32_16x16x32_bf16 v[100:103], v[202:205], v[170:173], 0
	v_mfma_f32_16x16x32_bf16 v[96:99], v[210:213], v[170:173], 0
	v_mfma_f32_16x16x32_bf16 v[84:87], v[202:205], v[178:181], 0
	v_mfma_f32_16x16x32_bf16 v[80:83], v[210:213], v[178:181], 0
	v_mfma_f32_16x16x32_bf16 v[68:71], v[202:205], v[194:197], 0
	v_mfma_f32_16x16x32_bf16 v[64:67], v[210:213], v[194:197], 0
	v_mfma_f32_16x16x32_bf16 v[116:119], v[206:209], v[148:151], v[116:119]
	v_mfma_f32_16x16x32_bf16 v[112:115], v[214:217], v[148:151], v[112:115]
	v_mfma_f32_16x16x32_bf16 v[100:103], v[206:209], v[174:177], v[100:103]
	v_mfma_f32_16x16x32_bf16 v[96:99], v[214:217], v[174:177], v[96:99]
	v_mfma_f32_16x16x32_bf16 v[84:87], v[206:209], v[182:185], v[84:87]
	v_mfma_f32_16x16x32_bf16 v[80:83], v[214:217], v[182:185], v[80:83]
	v_mfma_f32_16x16x32_bf16 v[68:71], v[206:209], v[198:201], v[68:71]
	v_mfma_f32_16x16x32_bf16 v[64:67], v[214:217], v[198:201], v[64:67]
	s_setprio 1
	s_mov_b32 m0, s7
	v_lshl_add_u64 v[220:221], s[26:27], 0, v[154:155]
	s_barrier
	ds_read_b128 v[144:147], v191 offset:16384
	ds_read_b128 v[148:151], v191 offset:17408
	ds_read_b128 v[170:173], v191 offset:18432
	ds_read_b128 v[174:177], v191 offset:19456
	ds_read_b128 v[178:181], v191 offset:20480
	ds_read_b128 v[182:185], v191 offset:21504
	ds_read_b128 v[194:197], v191 offset:22528
	ds_read_b128 v[198:201], v191 offset:23552
	global_load_lds_dwordx4 v[220:221], off
	v_lshl_add_u64 v[222:223], s[26:27], 0, v[158:159]
	s_mov_b32 m0, s34
	s_nop 0
	global_load_lds_dwordx4 v[222:223], off
	s_barrier
	s_waitcnt lgkmcnt(0)
	s_setprio 2
	s_waitcnt lgkmcnt(0)
	v_mfma_f32_16x16x32_bf16 v[60:63], v[128:131], v[144:147], 0
	v_mfma_f32_16x16x32_bf16 v[56:59], v[136:139], v[144:147], 0
	v_mfma_f32_16x16x32_bf16 v[44:47], v[128:131], v[170:173], 0
	v_mfma_f32_16x16x32_bf16 v[40:43], v[136:139], v[170:173], 0
	v_mfma_f32_16x16x32_bf16 v[28:31], v[128:131], v[178:181], 0
	v_mfma_f32_16x16x32_bf16 v[24:27], v[136:139], v[178:181], 0
	v_mfma_f32_16x16x32_bf16 v[12:15], v[128:131], v[194:197], 0
	v_mfma_f32_16x16x32_bf16 v[8:11], v[136:139], v[194:197], 0
	v_mfma_f32_16x16x32_bf16 v[60:63], v[132:135], v[148:151], v[60:63]
	v_mfma_f32_16x16x32_bf16 v[56:59], v[140:143], v[148:151], v[56:59]
	v_mfma_f32_16x16x32_bf16 v[44:47], v[132:135], v[174:177], v[44:47]
	v_mfma_f32_16x16x32_bf16 v[40:43], v[140:143], v[174:177], v[40:43]
	v_mfma_f32_16x16x32_bf16 v[28:31], v[132:135], v[182:185], v[28:31]
	v_mfma_f32_16x16x32_bf16 v[24:27], v[140:143], v[182:185], v[24:27]
	v_mfma_f32_16x16x32_bf16 v[12:15], v[132:135], v[198:201], v[12:15]
	v_mfma_f32_16x16x32_bf16 v[8:11], v[140:143], v[198:201], v[8:11]
	s_setprio 1
	s_barrier
; #define PG8_STAGE(bufoff, gbase, voff) do { _Pragma("unroll") for (int _i = 0; _i < 2; ++_i) \
;         __builtin_amdgcn_global_load_lds((const unsigned*)((const char*)(gbase) + (voff)[_i]), (LAS unsigned*)(lds + (bufoff) + ldsw + _i * 8192), 16, 0, 0); } while (0)
; #define PG8_LDA(dst, b, h) do { _Pragma("unroll") for (int m = 0; m < 4; ++m) _Pragma("unroll") for (int k = 0; k < 2; ++k) dst[m][k] = *(const LAS bf16x8*)(lds + PG8_SA(b, h) + aoff + m * 2048 + k * 1024); } while (0)
; #define PG8_LDB(dst, b, h) do { _Pragma("unroll") for (int n = 0; n < 2; ++n) _Pragma("unroll") for (int k = 0; k < 2; ++k) dst[n][k] = *(const LAS bf16x8*)(lds + PG8_SB(b, h) + boff + n * 2048 + k * 1024); } while (0)
; #define PG8_MMA(ai, bj, At, Bt) do { __builtin_amdgcn_s_setprio(1); _Pragma("unroll") for (int m = 0; m < 4; ++m) _Pragma("unroll") for (int n = 0; n < 2; ++n) _Pragma("unroll") for (int k = 0; k < 2; ++k) \
;         acc[ai][bj][m][n] = __builtin_amdgcn_mfma_f32_16x16x32_bf16(Bt[n][k], At[m][k], acc[ai][bj][m][n], 0, 0, 0); __builtin_amdgcn_s_setprio(0); } while (0)
; #define PG8_WAIT_V(n) asm volatile("s_waitcnt vmcnt(" #n ")" ::: "memory")
; #define PG8_WAIT_L(n) asm volatile("s_waitcnt lgkmcnt(" #n ")" ::: "memory")
; #define PG8_BAR __builtin_amdgcn_s_barrier()
; #define PG8_SCHED __builtin_amdgcn_sched_barrier(0)
; template <class Epi>
; __device__ __forceinline__ void gemm_phase(LAS unsigned char* lds, const Gemm g, const StaticOrder& S, const Epi& E) {
;     ...
;             PG8_STAGE(PG8_SB(0, 1), b2 + hstepB, voffB);
;             PG8_WAIT_V(6); PG8_BAR; PG8_MMA(1, 1, At, B1); PG8_BAR;
;             PG8_LDB(B0, 1, 0); PG8_SCHED; PG8_LDA(At, 1, 0); PG8_STAGE(PG8_SA(0, 1), a2 + hstepA, voffA);
;             PG8_WAIT_L(8); PG8_BAR; PG8_WAIT_L(0); PG8_MMA(0, 0, At, B0); PG8_BAR; PG8_SCHED;
;             PG8_LDB(B1, 1, 1); PG8_STAGE(PG8_SB(1, 0), b3, voffB);
;             PG8_BAR; PG8_WAIT_L(0); PG8_MMA(0, 1, At, B1); PG8_BAR;
;             PG8_LDA(At, 1, 1); PG8_STAGE(PG8_SA(1, 0), a3, voffA);
	s_add_u32 s50, s24, 0x100000
	s_addc_u32 s51, s25, 0
	s_add_i32 s49, s43, s31
	v_lshl_add_u64 v[128:129], s[50:51], 0, v[156:157]
	s_mov_b32 m0, s49
	s_nop 0
	global_load_lds_dwordx4 v[128:129], off
	v_lshl_add_u64 v[128:129], s[50:51], 0, v[160:161]
	s_add_i32 m0, s49, 0x2000
	s_nop 0
	global_load_lds_dwordx4 v[128:129], off
	s_waitcnt vmcnt(6)
	s_barrier
	s_setprio 2
	v_mfma_f32_16x16x32_bf16 v[52:55], v[202:205], v[144:147], 0
	v_mfma_f32_16x16x32_bf16 v[48:51], v[210:213], v[144:147], 0
	v_mfma_f32_16x16x32_bf16 v[36:39], v[202:205], v[170:173], 0
	v_mfma_f32_16x16x32_bf16 v[32:35], v[210:213], v[170:173], 0
	v_mfma_f32_16x16x32_bf16 v[20:23], v[202:205], v[178:181], 0
	v_mfma_f32_16x16x32_bf16 v[16:19], v[210:213], v[178:181], 0
	v_mfma_f32_16x16x32_bf16 v[4:7], v[202:205], v[194:197], 0
	v_mfma_f32_16x16x32_bf16 v[0:3], v[210:213], v[194:197], 0
	v_mfma_f32_16x16x32_bf16 v[52:55], v[206:209], v[148:151], v[52:55]
	v_mfma_f32_16x16x32_bf16 v[48:51], v[214:217], v[148:151], v[48:51]
	v_mfma_f32_16x16x32_bf16 v[36:39], v[206:209], v[174:177], v[36:39]
	v_mfma_f32_16x16x32_bf16 v[32:35], v[214:217], v[174:177], v[32:35]
	v_mfma_f32_16x16x32_bf16 v[20:23], v[206:209], v[182:185], v[20:23]
	v_mfma_f32_16x16x32_bf16 v[16:19], v[214:217], v[182:185], v[16:19]
	v_mfma_f32_16x16x32_bf16 v[4:7], v[206:209], v[198:201], v[4:7]
	v_mfma_f32_16x16x32_bf16 v[0:3], v[214:217], v[198:201], v[0:3]
	s_setprio 1
	s_add_i32 s49, 0, 0x18000
	v_add_u32_e32 v140, s49, v188
	s_barrier
	ds_read_b128 v[128:131], v140
	ds_read_b128 v[132:135], v140 offset:1024
	ds_read_b128 v[136:139], v140 offset:2048
	ds_read_b128 v[140:143], v140 offset:3072
	s_add_u32 s26, s26, 0x100000
	s_addc_u32 s27, s27, 0
	s_mov_b32 m0, s35
	v_lshl_add_u64 v[202:203], s[26:27], 0, v[154:155]
	ds_read_b128 v[144:147], v191 offset:32768
	ds_read_b128 v[148:151], v191 offset:33792
	ds_read_b128 v[170:173], v191 offset:34816
	ds_read_b128 v[174:177], v191 offset:35840
	ds_read_b128 v[178:181], v191 offset:36864
	ds_read_b128 v[182:185], v191 offset:37888
	ds_read_b128 v[194:197], v191 offset:38912
	ds_read_b128 v[198:201], v191 offset:39936
	global_load_lds_dwordx4 v[202:203], off
	v_lshl_add_u64 v[202:203], s[26:27], 0, v[158:159]
	s_mov_b32 m0, s36
	s_nop 0
	global_load_lds_dwordx4 v[202:203], off
	s_waitcnt lgkmcnt(8)
	s_barrier
	s_waitcnt lgkmcnt(0)
	s_setprio 2
	s_waitcnt lgkmcnt(0)
	v_mfma_f32_16x16x32_bf16 v[124:127], v[128:131], v[144:147], v[124:127]
	v_mfma_f32_16x16x32_bf16 v[120:123], v[136:139], v[144:147], v[120:123]
	v_mfma_f32_16x16x32_bf16 v[108:111], v[128:131], v[170:173], v[108:111]
	v_mfma_f32_16x16x32_bf16 v[104:107], v[136:139], v[170:173], v[104:107]
	v_mfma_f32_16x16x32_bf16 v[92:95], v[128:131], v[178:181], v[92:95]
	v_mfma_f32_16x16x32_bf16 v[88:91], v[136:139], v[178:181], v[88:91]
	v_mfma_f32_16x16x32_bf16 v[76:79], v[128:131], v[194:197], v[76:79]
	v_mfma_f32_16x16x32_bf16 v[72:75], v[136:139], v[194:197], v[72:75]
	v_mfma_f32_16x16x32_bf16 v[124:127], v[132:135], v[148:151], v[124:127]
	v_mfma_f32_16x16x32_bf16 v[120:123], v[140:143], v[148:151], v[120:123]
	v_mfma_f32_16x16x32_bf16 v[108:111], v[132:135], v[174:177], v[108:111]
	v_mfma_f32_16x16x32_bf16 v[104:107], v[140:143], v[174:177], v[104:107]
	v_mfma_f32_16x16x32_bf16 v[92:95], v[132:135], v[182:185], v[92:95]
	v_mfma_f32_16x16x32_bf16 v[88:91], v[140:143], v[182:185], v[88:91]
	v_mfma_f32_16x16x32_bf16 v[76:79], v[132:135], v[198:201], v[76:79]
	v_mfma_f32_16x16x32_bf16 v[72:75], v[140:143], v[198:201], v[72:75]
	s_setprio 1
	s_barrier
	s_add_i32 s26, 0, 0x1c000
	s_add_i32 s27, s49, s31
	v_add_u32_e32 v214, s26, v188
	v_lshl_add_u64 v[186:187], v[186:187], 0, s[12:13]
	s_mov_b32 m0, s27
	ds_read_b128 v[202:205], v214
	ds_read_b128 v[206:209], v214 offset:1024
	ds_read_b128 v[210:213], v214 offset:2048
	ds_read_b128 v[214:217], v214 offset:3072
	global_load_lds_dwordx4 v[186:187], off
	v_lshl_add_u64 v[186:187], v[218:219], 0, s[12:13]
	s_add_i32 m0, s27, 0x2000
	s_nop 0
	global_load_lds_dwordx4 v[186:187], off
	s_barrier
	s_waitcnt lgkmcnt(0)
	s_setprio 2
	s_waitcnt lgkmcnt(0)
	v_mfma_f32_16x16x32_bf16 v[116:119], v[202:205], v[144:147], v[116:119]
	v_mfma_f32_16x16x32_bf16 v[112:115], v[210:213], v[144:147], v[112:115]
	v_mfma_f32_16x16x32_bf16 v[100:103], v[202:205], v[170:173], v[100:103]
	v_mfma_f32_16x16x32_bf16 v[96:99], v[210:213], v[170:173], v[96:99]
	v_mfma_f32_16x16x32_bf16 v[84:87], v[202:205], v[178:181], v[84:87]
	v_mfma_f32_16x16x32_bf16 v[80:83], v[210:213], v[178:181], v[80:83]
	v_mfma_f32_16x16x32_bf16 v[68:71], v[202:205], v[194:197], v[68:71]
	v_mfma_f32_16x16x32_bf16 v[64:67], v[210:213], v[194:197], v[64:67]
	v_mfma_f32_16x16x32_bf16 v[116:119], v[206:209], v[148:151], v[116:119]
	v_mfma_f32_16x16x32_bf16 v[112:115], v[214:217], v[148:151], v[112:115]
	v_mfma_f32_16x16x32_bf16 v[100:103], v[206:209], v[174:177], v[100:103]
	v_mfma_f32_16x16x32_bf16 v[96:99], v[214:217], v[174:177], v[96:99]
	v_mfma_f32_16x16x32_bf16 v[84:87], v[206:209], v[182:185], v[84:87]
	v_mfma_f32_16x16x32_bf16 v[80:83], v[214:217], v[182:185], v[80:83]
	v_mfma_f32_16x16x32_bf16 v[68:71], v[206:209], v[198:201], v[68:71]
	v_mfma_f32_16x16x32_bf16 v[64:67], v[214:217], v[198:201], v[64:67]
	s_setprio 1
	s_mov_b32 m0, s38
	v_lshl_add_u64 v[186:187], v[220:221], 0, s[12:13]
	s_barrier
	ds_read_b128 v[144:147], v191 offset:49152
	ds_read_b128 v[148:151], v191 offset:50176
	ds_read_b128 v[170:173], v191 offset:51200
	ds_read_b128 v[174:177], v191 offset:52224
	ds_read_b128 v[178:181], v191 offset:53248
	ds_read_b128 v[182:185], v191 offset:54272
	ds_read_b128 v[194:197], v191 offset:55296
	ds_read_b128 v[198:201], v191 offset:56320
	global_load_lds_dwordx4 v[186:187], off
	v_lshl_add_u64 v[186:187], v[222:223], 0, s[12:13]
	s_mov_b32 m0, s39
	s_nop 0
	global_load_lds_dwordx4 v[186:187], off
	s_barrier
; #define PG8_STAGE(bufoff, gbase, voff) do { _Pragma("unroll") for (int _i = 0; _i < 2; ++_i) \
;         __builtin_amdgcn_global_load_lds((const unsigned*)((const char*)(gbase) + (voff)[_i]), (LAS unsigned*)(lds + (bufoff) + ldsw + _i * 8192), 16, 0, 0); } while (0)
; #define PG8_LDA(dst, b, h) do { _Pragma("unroll") for (int m = 0; m < 4; ++m) _Pragma("unroll") for (int k = 0; k < 2; ++k) dst[m][k] = *(const LAS bf16x8*)(lds + PG8_SA(b, h) + aoff + m * 2048 + k * 1024); } while (0)
; #define PG8_LDB(dst, b, h) do { _Pragma("unroll") for (int n = 0; n < 2; ++n) _Pragma("unroll") for (int k = 0; k < 2; ++k) dst[n][k] = *(const LAS bf16x8*)(lds + PG8_SB(b, h) + boff + n * 2048 + k * 1024); } while (0)
; #define PG8_MMA(ai, bj, At, Bt) do { __builtin_amdgcn_s_setprio(1); _Pragma("unroll") for (int m = 0; m < 4; ++m) _Pragma("unroll") for (int n = 0; n < 2; ++n) _Pragma("unroll") for (int k = 0; k < 2; ++k) \
;         acc[ai][bj][m][n] = __builtin_amdgcn_mfma_f32_16x16x32_bf16(Bt[n][k], At[m][k], acc[ai][bj][m][n], 0, 0, 0); __builtin_amdgcn_s_setprio(0); } while (0)
; #define PG8_WAIT_V(n) asm volatile("s_waitcnt vmcnt(" #n ")" ::: "memory")
; #define PG8_WAIT_L(n) asm volatile("s_waitcnt lgkmcnt(" #n ")" ::: "memory")
; #define PG8_BAR __builtin_amdgcn_s_barrier()
; #define PG8_SCHED __builtin_amdgcn_sched_barrier(0)
; template <class Epi>
; __device__ __forceinline__ void gemm_phase(LAS unsigned char* lds, const Gemm g, const StaticOrder& S, const Epi& E) {
;     ...
;             PG8_LDB(B0, 0, 0); PG8_SCHED; PG8_LDA(At, 0, 0); PG8_STAGE(PG8_SA(1, 1), a1 + hstepA, voffA);
;             PG8_WAIT_L(8); PG8_BAR; PG8_WAIT_L(0); PG8_MMA(0, 0, At, B0); PG8_BAR; PG8_SCHED;
;             PG8_LDB(B1, 0, 1); PG8_STAGE(PG8_SB(0, 0), b2, voffB);
;     ...
;             PG8_BAR; PG8_WAIT_L(0); PG8_MMA(1, 0, At, B0); PG8_BAR; PG8_SCHED;
;             PG8_STAGE(PG8_SB(1, 1), b3 + hstepB, voffB);
;             PG8_WAIT_V(6); PG8_BAR; PG8_MMA(1, 1, At, B1); PG8_BAR;
	s_waitcnt lgkmcnt(0)
	s_setprio 2
	s_waitcnt lgkmcnt(0)
	v_mfma_f32_16x16x32_bf16 v[60:63], v[128:131], v[144:147], v[60:63]
	v_mfma_f32_16x16x32_bf16 v[56:59], v[136:139], v[144:147], v[56:59]
	v_mfma_f32_16x16x32_bf16 v[44:47], v[128:131], v[170:173], v[44:47]
	v_mfma_f32_16x16x32_bf16 v[40:43], v[136:139], v[170:173], v[40:43]
	v_mfma_f32_16x16x32_bf16 v[28:31], v[128:131], v[178:181], v[28:31]
	v_mfma_f32_16x16x32_bf16 v[24:27], v[136:139], v[178:181], v[24:27]
	v_mfma_f32_16x16x32_bf16 v[12:15], v[128:131], v[194:197], v[12:15]
	v_mfma_f32_16x16x32_bf16 v[8:11], v[136:139], v[194:197], v[8:11]
	v_mfma_f32_16x16x32_bf16 v[60:63], v[132:135], v[148:151], v[60:63]
	v_mfma_f32_16x16x32_bf16 v[56:59], v[140:143], v[148:151], v[56:59]
	v_mfma_f32_16x16x32_bf16 v[44:47], v[132:135], v[174:177], v[44:47]
	v_mfma_f32_16x16x32_bf16 v[40:43], v[140:143], v[174:177], v[40:43]
	v_mfma_f32_16x16x32_bf16 v[28:31], v[132:135], v[182:185], v[28:31]
	v_mfma_f32_16x16x32_bf16 v[24:27], v[140:143], v[182:185], v[24:27]
	v_mfma_f32_16x16x32_bf16 v[12:15], v[132:135], v[198:201], v[12:15]
	v_mfma_f32_16x16x32_bf16 v[8:11], v[140:143], v[198:201], v[8:11]
	s_setprio 1
	s_barrier
	s_add_u32 s24, s24, 0x100080
	s_addc_u32 s25, s25, 0
	s_add_i32 s26, s26, s31
	v_lshl_add_u64 v[128:129], s[24:25], 0, v[156:157]
	s_mov_b32 m0, s26
	s_nop 0
	global_load_lds_dwordx4 v[128:129], off
	v_lshl_add_u64 v[128:129], s[24:25], 0, v[160:161]
	s_add_i32 m0, s26, 0x2000
	s_nop 0
	global_load_lds_dwordx4 v[128:129], off
	s_waitcnt vmcnt(6)
	s_barrier
	s_setprio 2
	v_mfma_f32_16x16x32_bf16 v[52:55], v[202:205], v[144:147], v[52:55]
	v_mfma_f32_16x16x32_bf16 v[48:51], v[210:213], v[144:147], v[48:51]
	v_mfma_f32_16x16x32_bf16 v[36:39], v[202:205], v[170:173], v[36:39]
	v_mfma_f32_16x16x32_bf16 v[32:35], v[210:213], v[170:173], v[32:35]
	v_mfma_f32_16x16x32_bf16 v[20:23], v[202:205], v[178:181], v[20:23]
	v_mfma_f32_16x16x32_bf16 v[16:19], v[210:213], v[178:181], v[16:19]
	v_mfma_f32_16x16x32_bf16 v[4:7], v[202:205], v[194:197], v[4:7]
	v_mfma_f32_16x16x32_bf16 v[0:3], v[210:213], v[194:197], v[0:3]
	v_mfma_f32_16x16x32_bf16 v[52:55], v[206:209], v[148:151], v[52:55]
	v_mfma_f32_16x16x32_bf16 v[48:51], v[214:217], v[148:151], v[48:51]
	v_mfma_f32_16x16x32_bf16 v[36:39], v[206:209], v[174:177], v[36:39]
	v_mfma_f32_16x16x32_bf16 v[32:35], v[214:217], v[174:177], v[32:35]
	v_mfma_f32_16x16x32_bf16 v[20:23], v[206:209], v[182:185], v[20:23]
	v_mfma_f32_16x16x32_bf16 v[16:19], v[214:217], v[182:185], v[16:19]
	v_mfma_f32_16x16x32_bf16 v[4:7], v[206:209], v[198:201], v[4:7]
	v_mfma_f32_16x16x32_bf16 v[0:3], v[214:217], v[198:201], v[0:3]
	s_setprio 1
	s_add_i32 s48, s48, 2
	s_add_u32 s22, s22, 0x100
	s_addc_u32 s23, s23, 0
	s_add_u32 s46, s46, 0x100
	s_addc_u32 s47, s47, 0
	s_cmp_gt_u32 s48, 61
	s_barrier
.Lkp7_1278:
	ds_read_b128 v[128:131], v190
	ds_read_b128 v[132:135], v190 offset:1024
	ds_read_b128 v[136:139], v190 offset:2048
	ds_read_b128 v[140:143], v190 offset:3072
	s_add_u32 s24, s22, 0xfff00080
	s_addc_u32 s25, s23, -1
	s_cmp_eq_u32 s48, 60
	s_cselect_b32 s27, s17, s25
	s_cselect_b32 s26, s44, s24
	s_cselect_b32 s25, s15, s47
	s_cselect_b32 s24, s45, s46
	v_lshl_add_u64 v[186:187], s[22:23], 0, v[162:163]
	s_add_i32 m0, s7, 0xc000
	ds_read_b128 v[144:147], v191
	ds_read_b128 v[148:151], v191 offset:1024
	ds_read_b128 v[170:173], v191 offset:2048
	ds_read_b128 v[174:177], v191 offset:3072
	ds_read_b128 v[178:181], v191 offset:4096
	ds_read_b128 v[182:185], v191 offset:5120
	ds_read_b128 v[194:197], v191 offset:6144
	ds_read_b128 v[198:201], v191 offset:7168
	global_load_lds_dwordx4 v[186:187], off
	v_lshl_add_u64 v[186:187], s[22:23], 0, v[164:165]
	s_add_i32 m0, s7, 0xe000
	s_nop 0
	global_load_lds_dwordx4 v[186:187], off
	s_waitcnt lgkmcnt(8)
	s_barrier
	s_waitcnt lgkmcnt(0)
	s_setprio 2
	s_waitcnt lgkmcnt(0)
	v_mfma_f32_16x16x32_bf16 v[124:127], v[128:131], v[144:147], v[124:127]
	v_mfma_f32_16x16x32_bf16 v[120:123], v[136:139], v[144:147], v[120:123]
	v_mfma_f32_16x16x32_bf16 v[108:111], v[128:131], v[170:173], v[108:111]
	v_mfma_f32_16x16x32_bf16 v[104:107], v[136:139], v[170:173], v[104:107]
	v_mfma_f32_16x16x32_bf16 v[92:95], v[128:131], v[178:181], v[92:95]
	v_mfma_f32_16x16x32_bf16 v[88:91], v[136:139], v[178:181], v[88:91]
	v_mfma_f32_16x16x32_bf16 v[76:79], v[128:131], v[194:197], v[76:79]
	v_mfma_f32_16x16x32_bf16 v[72:75], v[136:139], v[194:197], v[72:75]
	v_mfma_f32_16x16x32_bf16 v[124:127], v[132:135], v[148:151], v[124:127]
	v_mfma_f32_16x16x32_bf16 v[120:123], v[140:143], v[148:151], v[120:123]
	v_mfma_f32_16x16x32_bf16 v[108:111], v[132:135], v[174:177], v[108:111]
	v_mfma_f32_16x16x32_bf16 v[104:107], v[140:143], v[174:177], v[104:107]
	v_mfma_f32_16x16x32_bf16 v[92:95], v[132:135], v[182:185], v[92:95]
	v_mfma_f32_16x16x32_bf16 v[88:91], v[140:143], v[182:185], v[88:91]
	v_mfma_f32_16x16x32_bf16 v[76:79], v[132:135], v[198:201], v[76:79]
	v_mfma_f32_16x16x32_bf16 v[72:75], v[140:143], v[198:201], v[72:75]
	s_setprio 1
	s_barrier
	s_add_i32 s49, s42, s31
	v_lshl_add_u64 v[186:187], s[24:25], 0, v[156:157]
	s_mov_b32 m0, s49
	ds_read_b128 v[202:205], v192
	ds_read_b128 v[206:209], v192 offset:1024
	ds_read_b128 v[210:213], v192 offset:2048
	ds_read_b128 v[214:217], v192 offset:3072
	global_load_lds_dwordx4 v[186:187], off
	v_lshl_add_u64 v[218:219], s[24:25], 0, v[160:161]
	s_add_i32 m0, s49, 0x2000
	s_nop 0
	global_load_lds_dwordx4 v[218:219], off
	s_barrier
; #define PG8_STAGE(bufoff, gbase, voff) do { _Pragma("unroll") for (int _i = 0; _i < 2; ++_i) \
;         __builtin_amdgcn_global_load_lds((const unsigned*)((const char*)(gbase) + (voff)[_i]), (LAS unsigned*)(lds + (bufoff) + ldsw + _i * 8192), 16, 0, 0); } while (0)
; #define PG8_LDA(dst, b, h) do { _Pragma("unroll") for (int m = 0; m < 4; ++m) _Pragma("unroll") for (int k = 0; k < 2; ++k) dst[m][k] = *(const LAS bf16x8*)(lds + PG8_SA(b, h) + aoff + m * 2048 + k * 1024); } while (0)
; #define PG8_LDB(dst, b, h) do { _Pragma("unroll") for (int n = 0; n < 2; ++n) _Pragma("unroll") for (int k = 0; k < 2; ++k) dst[n][k] = *(const LAS bf16x8*)(lds + PG8_SB(b, h) + boff + n * 2048 + k * 1024); } while (0)
; #define PG8_MMA(ai, bj, At, Bt) do { __builtin_amdgcn_s_setprio(1); _Pragma("unroll") for (int m = 0; m < 4; ++m) _Pragma("unroll") for (int n = 0; n < 2; ++n) _Pragma("unroll") for (int k = 0; k < 2; ++k) \
;         acc[ai][bj][m][n] = __builtin_amdgcn_mfma_f32_16x16x32_bf16(Bt[n][k], At[m][k], acc[ai][bj][m][n], 0, 0, 0); __builtin_amdgcn_s_setprio(0); } while (0)
; #define PG8_WAIT_V(n) asm volatile("s_waitcnt vmcnt(" #n ")" ::: "memory")
; #define PG8_WAIT_L(n) asm volatile("s_waitcnt lgkmcnt(" #n ")" ::: "memory")
; #define PG8_BAR __builtin_amdgcn_s_barrier()
; #define PG8_SCHED __builtin_amdgcn_sched_barrier(0)
; template <class Epi>
; __device__ __forceinline__ void gemm_phase(LAS unsigned char* lds, const Gemm g, const StaticOrder& S, const Epi& E) {
;     ...
;             PG8_BAR; PG8_WAIT_L(0); PG8_MMA(0, 1, At, B1); PG8_BAR;
;             PG8_LDA(At, 0, 1); PG8_STAGE(PG8_SA(0, 0), a2, voffA);
;             PG8_BAR; PG8_WAIT_L(0); PG8_MMA(1, 0, At, B0); PG8_BAR; PG8_SCHED;
;             PG8_STAGE(PG8_SB(0, 1), b2 + hstepB, voffB);
;             PG8_WAIT_V(6); PG8_BAR; PG8_MMA(1, 1, At, B1); PG8_BAR;
;             PG8_LDB(B0, 1, 0); PG8_SCHED; PG8_LDA(At, 1, 0); PG8_STAGE(PG8_SA(0, 1), a2 + hstepA, voffA);
;             PG8_WAIT_L(8); PG8_BAR; PG8_WAIT_L(0); PG8_MMA(0, 0, At, B0); PG8_BAR; PG8_SCHED;
	s_waitcnt lgkmcnt(0)
	s_setprio 2
	s_waitcnt lgkmcnt(0)
	v_mfma_f32_16x16x32_bf16 v[116:119], v[202:205], v[144:147], v[116:119]
	v_mfma_f32_16x16x32_bf16 v[112:115], v[210:213], v[144:147], v[112:115]
	v_mfma_f32_16x16x32_bf16 v[100:103], v[202:205], v[170:173], v[100:103]
	v_mfma_f32_16x16x32_bf16 v[96:99], v[210:213], v[170:173], v[96:99]
	v_mfma_f32_16x16x32_bf16 v[84:87], v[202:205], v[178:181], v[84:87]
	v_mfma_f32_16x16x32_bf16 v[80:83], v[210:213], v[178:181], v[80:83]
	v_mfma_f32_16x16x32_bf16 v[68:71], v[202:205], v[194:197], v[68:71]
	v_mfma_f32_16x16x32_bf16 v[64:67], v[210:213], v[194:197], v[64:67]
	v_mfma_f32_16x16x32_bf16 v[116:119], v[206:209], v[148:151], v[116:119]
	v_mfma_f32_16x16x32_bf16 v[112:115], v[214:217], v[148:151], v[112:115]
	v_mfma_f32_16x16x32_bf16 v[100:103], v[206:209], v[174:177], v[100:103]
	v_mfma_f32_16x16x32_bf16 v[96:99], v[214:217], v[174:177], v[96:99]
	v_mfma_f32_16x16x32_bf16 v[84:87], v[206:209], v[182:185], v[84:87]
	v_mfma_f32_16x16x32_bf16 v[80:83], v[214:217], v[182:185], v[80:83]
	v_mfma_f32_16x16x32_bf16 v[68:71], v[206:209], v[198:201], v[68:71]
	v_mfma_f32_16x16x32_bf16 v[64:67], v[214:217], v[198:201], v[64:67]
	s_setprio 1
	s_mov_b32 m0, s7
	v_lshl_add_u64 v[220:221], s[26:27], 0, v[154:155]
	s_barrier
	ds_read_b128 v[144:147], v191 offset:16384
	ds_read_b128 v[148:151], v191 offset:17408
	ds_read_b128 v[170:173], v191 offset:18432
	ds_read_b128 v[174:177], v191 offset:19456
	ds_read_b128 v[178:181], v191 offset:20480
	ds_read_b128 v[182:185], v191 offset:21504
	ds_read_b128 v[194:197], v191 offset:22528
	ds_read_b128 v[198:201], v191 offset:23552
	global_load_lds_dwordx4 v[220:221], off
	v_lshl_add_u64 v[222:223], s[26:27], 0, v[158:159]
	s_mov_b32 m0, s34
	s_nop 0
	global_load_lds_dwordx4 v[222:223], off
	s_barrier
	s_waitcnt lgkmcnt(0)
	s_setprio 2
	s_waitcnt lgkmcnt(0)
	v_mfma_f32_16x16x32_bf16 v[60:63], v[128:131], v[144:147], v[60:63]
	v_mfma_f32_16x16x32_bf16 v[56:59], v[136:139], v[144:147], v[56:59]
	v_mfma_f32_16x16x32_bf16 v[44:47], v[128:131], v[170:173], v[44:47]
	v_mfma_f32_16x16x32_bf16 v[40:43], v[136:139], v[170:173], v[40:43]
	v_mfma_f32_16x16x32_bf16 v[28:31], v[128:131], v[178:181], v[28:31]
	v_mfma_f32_16x16x32_bf16 v[24:27], v[136:139], v[178:181], v[24:27]
	v_mfma_f32_16x16x32_bf16 v[12:15], v[128:131], v[194:197], v[12:15]
	v_mfma_f32_16x16x32_bf16 v[8:11], v[136:139], v[194:197], v[8:11]
	v_mfma_f32_16x16x32_bf16 v[60:63], v[132:135], v[148:151], v[60:63]
	v_mfma_f32_16x16x32_bf16 v[56:59], v[140:143], v[148:151], v[56:59]
	v_mfma_f32_16x16x32_bf16 v[44:47], v[132:135], v[174:177], v[44:47]
	v_mfma_f32_16x16x32_bf16 v[40:43], v[140:143], v[174:177], v[40:43]
	v_mfma_f32_16x16x32_bf16 v[28:31], v[132:135], v[182:185], v[28:31]
	v_mfma_f32_16x16x32_bf16 v[24:27], v[140:143], v[182:185], v[24:27]
	v_mfma_f32_16x16x32_bf16 v[12:15], v[132:135], v[198:201], v[12:15]
	v_mfma_f32_16x16x32_bf16 v[8:11], v[140:143], v[198:201], v[8:11]
	s_setprio 1
	s_barrier
	s_add_u32 s50, s24, 0x100000
	s_addc_u32 s51, s25, 0
	s_add_i32 s49, s43, s31
	v_lshl_add_u64 v[128:129], s[50:51], 0, v[156:157]
	s_mov_b32 m0, s49
	s_nop 0
	global_load_lds_dwordx4 v[128:129], off
	v_lshl_add_u64 v[128:129], s[50:51], 0, v[160:161]
	s_add_i32 m0, s49, 0x2000
	s_nop 0
	global_load_lds_dwordx4 v[128:129], off
	s_waitcnt vmcnt(6)
	s_barrier
	s_setprio 2
	v_mfma_f32_16x16x32_bf16 v[52:55], v[202:205], v[144:147], v[52:55]
	v_mfma_f32_16x16x32_bf16 v[48:51], v[210:213], v[144:147], v[48:51]
	v_mfma_f32_16x16x32_bf16 v[36:39], v[202:205], v[170:173], v[36:39]
	v_mfma_f32_16x16x32_bf16 v[32:35], v[210:213], v[170:173], v[32:35]
	v_mfma_f32_16x16x32_bf16 v[20:23], v[202:205], v[178:181], v[20:23]
	v_mfma_f32_16x16x32_bf16 v[16:19], v[210:213], v[178:181], v[16:19]
	v_mfma_f32_16x16x32_bf16 v[4:7], v[202:205], v[194:197], v[4:7]
	v_mfma_f32_16x16x32_bf16 v[0:3], v[210:213], v[194:197], v[0:3]
	v_mfma_f32_16x16x32_bf16 v[52:55], v[206:209], v[148:151], v[52:55]
	v_mfma_f32_16x16x32_bf16 v[48:51], v[214:217], v[148:151], v[48:51]
	v_mfma_f32_16x16x32_bf16 v[36:39], v[206:209], v[174:177], v[36:39]
	v_mfma_f32_16x16x32_bf16 v[32:35], v[214:217], v[174:177], v[32:35]
	v_mfma_f32_16x16x32_bf16 v[20:23], v[206:209], v[182:185], v[20:23]
	v_mfma_f32_16x16x32_bf16 v[16:19], v[214:217], v[182:185], v[16:19]
	v_mfma_f32_16x16x32_bf16 v[4:7], v[206:209], v[198:201], v[4:7]
	v_mfma_f32_16x16x32_bf16 v[0:3], v[214:217], v[198:201], v[0:3]
	s_setprio 1
	s_add_i32 s49, 0, 0x18000
	v_add_u32_e32 v140, s49, v188
	s_barrier
	ds_read_b128 v[128:131], v140
	ds_read_b128 v[132:135], v140 offset:1024
	ds_read_b128 v[136:139], v140 offset:2048
	ds_read_b128 v[140:143], v140 offset:3072
	s_add_u32 s26, s26, 0x100000
	s_addc_u32 s27, s27, 0
	s_mov_b32 m0, s35
	v_lshl_add_u64 v[202:203], s[26:27], 0, v[154:155]
	ds_read_b128 v[144:147], v191 offset:32768
	ds_read_b128 v[148:151], v191 offset:33792
	ds_read_b128 v[170:173], v191 offset:34816
	ds_read_b128 v[174:177], v191 offset:35840
	ds_read_b128 v[178:181], v191 offset:36864
	ds_read_b128 v[182:185], v191 offset:37888
	ds_read_b128 v[194:197], v191 offset:38912
	ds_read_b128 v[198:201], v191 offset:39936
	global_load_lds_dwordx4 v[202:203], off
	v_lshl_add_u64 v[202:203], s[26:27], 0, v[158:159]
	s_mov_b32 m0, s36
	s_nop 0
	global_load_lds_dwordx4 v[202:203], off
	s_waitcnt lgkmcnt(8)
	s_barrier
; #define PG8_STAGE(bufoff, gbase, voff) do { _Pragma("unroll") for (int _i = 0; _i < 2; ++_i) \
;         __builtin_amdgcn_global_load_lds((const unsigned*)((const char*)(gbase) + (voff)[_i]), (LAS unsigned*)(lds + (bufoff) + ldsw + _i * 8192), 16, 0, 0); } while (0)
; #define PG8_LDA(dst, b, h) do { _Pragma("unroll") for (int m = 0; m < 4; ++m) _Pragma("unroll") for (int k = 0; k < 2; ++k) dst[m][k] = *(const LAS bf16x8*)(lds + PG8_SA(b, h) + aoff + m * 2048 + k * 1024); } while (0)
; #define PG8_LDB(dst, b, h) do { _Pragma("unroll") for (int n = 0; n < 2; ++n) _Pragma("unroll") for (int k = 0; k < 2; ++k) dst[n][k] = *(const LAS bf16x8*)(lds + PG8_SB(b, h) + boff + n * 2048 + k * 1024); } while (0)
; #define PG8_MMA(ai, bj, At, Bt) do { __builtin_amdgcn_s_setprio(1); _Pragma("unroll") for (int m = 0; m < 4; ++m) _Pragma("unroll") for (int n = 0; n < 2; ++n) _Pragma("unroll") for (int k = 0; k < 2; ++k) \
;         acc[ai][bj][m][n] = __builtin_amdgcn_mfma_f32_16x16x32_bf16(Bt[n][k], At[m][k], acc[ai][bj][m][n], 0, 0, 0); __builtin_amdgcn_s_setprio(0); } while (0)
; #define PG8_WAIT_V(n) asm volatile("s_waitcnt vmcnt(" #n ")" ::: "memory")
; #define PG8_WAIT_L(n) asm volatile("s_waitcnt lgkmcnt(" #n ")" ::: "memory")
; #define PG8_BAR __builtin_amdgcn_s_barrier()
; #define PG8_SCHED __builtin_amdgcn_sched_barrier(0)
; template <class Epi>
; __device__ __forceinline__ void gemm_phase(LAS unsigned char* lds, const Gemm g, const StaticOrder& S, const Epi& E) {
;     ...
;             PG8_WAIT_L(8); PG8_BAR; PG8_WAIT_L(0); PG8_MMA(0, 0, At, B0); PG8_BAR; PG8_SCHED;
;             PG8_LDB(B1, 1, 1); PG8_STAGE(PG8_SB(1, 0), b3, voffB);
;             PG8_BAR; PG8_WAIT_L(0); PG8_MMA(0, 1, At, B1); PG8_BAR;
;             PG8_LDA(At, 1, 1); PG8_STAGE(PG8_SA(1, 0), a3, voffA);
;             PG8_BAR; PG8_WAIT_L(0); PG8_MMA(1, 0, At, B0); PG8_BAR; PG8_SCHED;
;             PG8_STAGE(PG8_SB(1, 1), b3 + hstepB, voffB);
;             PG8_WAIT_V(6); PG8_BAR; PG8_MMA(1, 1, At, B1); PG8_BAR;
	s_waitcnt lgkmcnt(0)
	s_setprio 2
	s_waitcnt lgkmcnt(0)
	v_mfma_f32_16x16x32_bf16 v[124:127], v[128:131], v[144:147], v[124:127]
	v_mfma_f32_16x16x32_bf16 v[120:123], v[136:139], v[144:147], v[120:123]
	v_mfma_f32_16x16x32_bf16 v[108:111], v[128:131], v[170:173], v[108:111]
	v_mfma_f32_16x16x32_bf16 v[104:107], v[136:139], v[170:173], v[104:107]
	v_mfma_f32_16x16x32_bf16 v[92:95], v[128:131], v[178:181], v[92:95]
	v_mfma_f32_16x16x32_bf16 v[88:91], v[136:139], v[178:181], v[88:91]
	v_mfma_f32_16x16x32_bf16 v[76:79], v[128:131], v[194:197], v[76:79]
	v_mfma_f32_16x16x32_bf16 v[72:75], v[136:139], v[194:197], v[72:75]
	v_mfma_f32_16x16x32_bf16 v[124:127], v[132:135], v[148:151], v[124:127]
	v_mfma_f32_16x16x32_bf16 v[120:123], v[140:143], v[148:151], v[120:123]
	v_mfma_f32_16x16x32_bf16 v[108:111], v[132:135], v[174:177], v[108:111]
	v_mfma_f32_16x16x32_bf16 v[104:107], v[140:143], v[174:177], v[104:107]
	v_mfma_f32_16x16x32_bf16 v[92:95], v[132:135], v[182:185], v[92:95]
	v_mfma_f32_16x16x32_bf16 v[88:91], v[140:143], v[182:185], v[88:91]
	v_mfma_f32_16x16x32_bf16 v[76:79], v[132:135], v[198:201], v[76:79]
	v_mfma_f32_16x16x32_bf16 v[72:75], v[140:143], v[198:201], v[72:75]
	s_setprio 1
	s_barrier
	s_add_i32 s26, 0, 0x1c000
	s_add_i32 s27, s49, s31
	v_add_u32_e32 v214, s26, v188
	v_lshl_add_u64 v[186:187], v[186:187], 0, s[12:13]
	s_mov_b32 m0, s27
	ds_read_b128 v[202:205], v214
	ds_read_b128 v[206:209], v214 offset:1024
	ds_read_b128 v[210:213], v214 offset:2048
	ds_read_b128 v[214:217], v214 offset:3072
	global_load_lds_dwordx4 v[186:187], off
	v_lshl_add_u64 v[186:187], v[218:219], 0, s[12:13]
	s_add_i32 m0, s27, 0x2000
	s_nop 0
	global_load_lds_dwordx4 v[186:187], off
	s_barrier
	s_waitcnt lgkmcnt(0)
	s_setprio 2
	s_waitcnt lgkmcnt(0)
	v_mfma_f32_16x16x32_bf16 v[116:119], v[202:205], v[144:147], v[116:119]
	v_mfma_f32_16x16x32_bf16 v[112:115], v[210:213], v[144:147], v[112:115]
	v_mfma_f32_16x16x32_bf16 v[100:103], v[202:205], v[170:173], v[100:103]
	v_mfma_f32_16x16x32_bf16 v[96:99], v[210:213], v[170:173], v[96:99]
	v_mfma_f32_16x16x32_bf16 v[84:87], v[202:205], v[178:181], v[84:87]
	v_mfma_f32_16x16x32_bf16 v[80:83], v[210:213], v[178:181], v[80:83]
	v_mfma_f32_16x16x32_bf16 v[68:71], v[202:205], v[194:197], v[68:71]
	v_mfma_f32_16x16x32_bf16 v[64:67], v[210:213], v[194:197], v[64:67]
	v_mfma_f32_16x16x32_bf16 v[116:119], v[206:209], v[148:151], v[116:119]
	v_mfma_f32_16x16x32_bf16 v[112:115], v[214:217], v[148:151], v[112:115]
	v_mfma_f32_16x16x32_bf16 v[100:103], v[206:209], v[174:177], v[100:103]
	v_mfma_f32_16x16x32_bf16 v[96:99], v[214:217], v[174:177], v[96:99]
	v_mfma_f32_16x16x32_bf16 v[84:87], v[206:209], v[182:185], v[84:87]
	v_mfma_f32_16x16x32_bf16 v[80:83], v[214:217], v[182:185], v[80:83]
	v_mfma_f32_16x16x32_bf16 v[68:71], v[206:209], v[198:201], v[68:71]
	v_mfma_f32_16x16x32_bf16 v[64:67], v[214:217], v[198:201], v[64:67]
	s_setprio 1
	s_mov_b32 m0, s38
	v_lshl_add_u64 v[186:187], v[220:221], 0, s[12:13]
	s_barrier
	ds_read_b128 v[144:147], v191 offset:49152
	ds_read_b128 v[148:151], v191 offset:50176
	ds_read_b128 v[170:173], v191 offset:51200
	ds_read_b128 v[174:177], v191 offset:52224
	ds_read_b128 v[178:181], v191 offset:53248
	ds_read_b128 v[182:185], v191 offset:54272
	ds_read_b128 v[194:197], v191 offset:55296
	ds_read_b128 v[198:201], v191 offset:56320
	global_load_lds_dwordx4 v[186:187], off
	v_lshl_add_u64 v[186:187], v[222:223], 0, s[12:13]
	s_mov_b32 m0, s39
	s_nop 0
	global_load_lds_dwordx4 v[186:187], off
	s_barrier
	s_waitcnt lgkmcnt(0)
	s_setprio 2
	s_waitcnt lgkmcnt(0)
	v_mfma_f32_16x16x32_bf16 v[60:63], v[128:131], v[144:147], v[60:63]
	v_mfma_f32_16x16x32_bf16 v[56:59], v[136:139], v[144:147], v[56:59]
	v_mfma_f32_16x16x32_bf16 v[44:47], v[128:131], v[170:173], v[44:47]
	v_mfma_f32_16x16x32_bf16 v[40:43], v[136:139], v[170:173], v[40:43]
	v_mfma_f32_16x16x32_bf16 v[28:31], v[128:131], v[178:181], v[28:31]
	v_mfma_f32_16x16x32_bf16 v[24:27], v[136:139], v[178:181], v[24:27]
	v_mfma_f32_16x16x32_bf16 v[12:15], v[128:131], v[194:197], v[12:15]
	v_mfma_f32_16x16x32_bf16 v[8:11], v[136:139], v[194:197], v[8:11]
	v_mfma_f32_16x16x32_bf16 v[60:63], v[132:135], v[148:151], v[60:63]
	v_mfma_f32_16x16x32_bf16 v[56:59], v[140:143], v[148:151], v[56:59]
	v_mfma_f32_16x16x32_bf16 v[44:47], v[132:135], v[174:177], v[44:47]
	v_mfma_f32_16x16x32_bf16 v[40:43], v[140:143], v[174:177], v[40:43]
	v_mfma_f32_16x16x32_bf16 v[28:31], v[132:135], v[182:185], v[28:31]
	v_mfma_f32_16x16x32_bf16 v[24:27], v[140:143], v[182:185], v[24:27]
	v_mfma_f32_16x16x32_bf16 v[12:15], v[132:135], v[198:201], v[12:15]
	v_mfma_f32_16x16x32_bf16 v[8:11], v[140:143], v[198:201], v[8:11]
	s_setprio 1
	s_barrier
	s_add_u32 s24, s24, 0x100080
	s_addc_u32 s25, s25, 0
	s_add_i32 s26, s26, s31
	v_lshl_add_u64 v[128:129], s[24:25], 0, v[156:157]
	s_mov_b32 m0, s26
	s_nop 0
	global_load_lds_dwordx4 v[128:129], off
	v_lshl_add_u64 v[128:129], s[24:25], 0, v[160:161]
	s_add_i32 m0, s26, 0x2000
	s_nop 0
	global_load_lds_dwordx4 v[128:129], off
	s_waitcnt vmcnt(6)
	s_barrier
	s_setprio 2
	v_mfma_f32_16x16x32_bf16 v[52:55], v[202:205], v[144:147], v[52:55]
	v_mfma_f32_16x16x32_bf16 v[48:51], v[210:213], v[144:147], v[48:51]
	v_mfma_f32_16x16x32_bf16 v[36:39], v[202:205], v[170:173], v[36:39]
	v_mfma_f32_16x16x32_bf16 v[32:35], v[210:213], v[170:173], v[32:35]
	v_mfma_f32_16x16x32_bf16 v[20:23], v[202:205], v[178:181], v[20:23]
	v_mfma_f32_16x16x32_bf16 v[16:19], v[210:213], v[178:181], v[16:19]
	v_mfma_f32_16x16x32_bf16 v[4:7], v[202:205], v[194:197], v[4:7]
	v_mfma_f32_16x16x32_bf16 v[0:3], v[210:213], v[194:197], v[0:3]
	v_mfma_f32_16x16x32_bf16 v[52:55], v[206:209], v[148:151], v[52:55]
	v_mfma_f32_16x16x32_bf16 v[48:51], v[214:217], v[148:151], v[48:51]
	v_mfma_f32_16x16x32_bf16 v[36:39], v[206:209], v[174:177], v[36:39]
	v_mfma_f32_16x16x32_bf16 v[32:35], v[214:217], v[174:177], v[32:35]
	v_mfma_f32_16x16x32_bf16 v[20:23], v[206:209], v[182:185], v[20:23]
	v_mfma_f32_16x16x32_bf16 v[16:19], v[214:217], v[182:185], v[16:19]
	v_mfma_f32_16x16x32_bf16 v[4:7], v[206:209], v[198:201], v[4:7]
	v_mfma_f32_16x16x32_bf16 v[0:3], v[214:217], v[198:201], v[0:3]
	s_setprio 1
	s_add_i32 s48, s48, 2
	s_add_u32 s22, s22, 0x100
	s_addc_u32 s23, s23, 0
	s_add_u32 s46, s46, 0x100
	s_addc_u32 s47, s47, 0
	s_cmp_gt_u32 s48, 61
	s_barrier
	s_cbranch_scc0 .Lkp7_1278
	s_branch .Lkp7_epi

; __device__ __forceinline__ unsigned pk2(float lo, float hi) { const f32x2 v = (f32x2){lo, hi}; const bf16x2_t b = __builtin_convertvector(v, bf16x2_t); return __builtin_bit_cast(unsigned, b); }
; __device__ __forceinline__ void unpack8(const u32x4 v, float* f) { f[0] = bf_lo(v.x); f[1] = bf_hi(v.x); f[2] = bf_lo(v.y); f[3] = bf_hi(v.y); f[4] = bf_lo(v.z); f[5] = bf_hi(v.z); f[6] = bf_lo(v.w); f[7] = bf_hi(v.w); }
;     __device__ __forceinline__ void operator()(const f32x4 (&acc)[2][2][4][2], const Unit& u, int wr, int wc, int fr, int fq, const float (&)[8]) const {
;         const int row0 = u.pm * BM + wr * 64 + fr, col0 = u.pn * BM + wc * 32 + 8 * fq;
; #pragma unroll
;         for (int ai = 0; ai < 2; ++ai) {
;             u32x4 bv[4][2];
; #pragma unroll
;             for (int m = 0; m < 4; ++m)
; #pragma unroll
;                 for (int bj = 0; bj < 2; ++bj) bv[m][bj] = *(const u32x4*)(xb + (size_t)(row0 + ai * HALF + m * 16) * DM + col0 + bj * HALF);
; #pragma unroll
;             for (int m = 0; m < 4; ++m) { const int row = row0 + ai * HALF + m * 16; const size_t ro = (size_t)row * DM + col0; float s = 0.f;
; #pragma unroll
;                 for (int bj = 0; bj < 2; ++bj) { float b8[8]; unpack8(bv[m][bj], b8);
;                     const f32x4 v0 = (f32x4){b8[0], b8[1], b8[2], b8[3]} + acc[ai][bj][m][0], v1 = (f32x4){b8[4], b8[5], b8[6], b8[7]} + acc[ai][bj][m][1];
;                     s += v0[0] * v0[0] + v0[1] * v0[1] + v0[2] * v0[2] + v0[3] * v0[3] + v1[0] * v1[0] + v1[1] * v1[1] + v1[2] * v1[2] + v1[3] * v1[3];
;                     if (LAST) { *(f32x4*)(out + ro + bj * HALF) = v0; *(f32x4*)(out + ro + bj * HALF + 4) = v1; }
;                     else { u32x4 w; w.x = pk2(v0[0], v0[1]); w.y = pk2(v0[2], v0[3]); w.z = pk2(v1[0], v1[1]); w.w = pk2(v1[2], v1[3]); *(u32x4*)(xb + ro + bj * HALF) = w; } }
;                 s += __shfl_xor(s, 16); s += __shfl_xor(s, 32);
;                 if (fq == 0) ss[(size_t)row * 16 + u.pn * 4 + wc] = s; }
.Lkp7_epi:
	s_setprio 0
	v_lshl_or_b32 v170, s6, 8, v189
	v_lshl_add_u32 v172, s8, 8, v153
	v_ashrrev_i32_e32 v171, 31, v170
	v_lshlrev_b64 v[204:205], 1, v[170:171]
	v_ashrrev_i32_e32 v173, 31, v172
	v_lshl_add_u64 v[174:175], s[76:77], 0, v[204:205]
	v_lshlrev_b64 v[206:207], 11, v[172:173]
	v_lshl_add_u64 v[128:129], v[174:175], 0, v[206:207]
	global_load_dwordx4 v[196:199], v[128:129], off
	global_load_dwordx4 v[200:203], v[128:129], off offset:256
	v_or_b32_e32 v184, 16, v172
	v_or_b32_e32 v180, 32, v172
	v_or_b32_e32 v176, 48, v172
	v_ashrrev_i32_e32 v185, 31, v184
	v_ashrrev_i32_e32 v181, 31, v180
	v_ashrrev_i32_e32 v177, 31, v176
	v_lshlrev_b64 v[186:187], 11, v[184:185]
	v_lshlrev_b64 v[182:183], 11, v[180:181]
	v_lshlrev_b64 v[178:179], 11, v[176:177]
	v_lshl_add_u64 v[128:129], v[174:175], 0, v[186:187]
	v_lshl_add_u64 v[130:131], v[174:175], 0, v[182:183]
	v_lshl_add_u64 v[194:195], v[174:175], 0, v[178:179]
	global_load_dwordx4 v[148:151], v[128:129], off
	global_load_dwordx4 v[144:147], v[128:129], off offset:256
	global_load_dwordx4 v[140:143], v[130:131], off
	global_load_dwordx4 v[136:139], v[130:131], off offset:256
	global_load_dwordx4 v[132:135], v[194:195], off
	s_nop 0
	global_load_dwordx4 v[128:131], v[194:195], off offset:256
	v_add_u32_e32 v226, 0x80, v172
	v_ashrrev_i32_e32 v227, 31, v226
	v_lshlrev_b64 v[226:227], 11, v[226:227]
	v_lshl_add_u64 v[226:227], v[174:175], 0, v[226:227]
	global_load_dwordx4 v[216:219], v[226:227], off
	global_load_dwordx4 v[220:223], v[226:227], off offset:256
	v_add_u32_e32 v226, 0x90, v172
	v_ashrrev_i32_e32 v227, 31, v226
	v_lshlrev_b64 v[226:227], 11, v[226:227]
	v_lshl_add_u64 v[226:227], v[174:175], 0, v[226:227]
	global_load_dwordx4 v[228:231], v[226:227], off
	global_load_dwordx4 v[232:235], v[226:227], off offset:256
	v_add_u32_e32 v226, 0xa0, v172
	v_ashrrev_i32_e32 v227, 31, v226
	v_lshlrev_b64 v[226:227], 11, v[226:227]
	v_lshl_add_u64 v[226:227], v[174:175], 0, v[226:227]
	global_load_dwordx4 v[236:239], v[226:227], off
	global_load_dwordx4 v[240:243], v[226:227], off offset:256
	v_add_u32_e32 v226, 0xb0, v172
	v_ashrrev_i32_e32 v227, 31, v226
	v_lshlrev_b64 v[226:227], 11, v[226:227]
	v_lshl_add_u64 v[226:227], v[174:175], 0, v[226:227]
	global_load_dwordx4 v[244:247], v[226:227], off
	global_load_dwordx4 v[252:255], v[226:227], off offset:256
	v_and_b32_e32 v195, 64, v193
	v_xor_b32_e32 v194, 16, v193
	v_add_u32_e32 v195, 64, v195
	v_xor_b32_e32 v208, 32, v193
	v_cmp_lt_i32_e32 vcc, v194, v195
	s_waitcnt vmcnt(15)
	v_and_b32_e32 v209, 0xffff0000, v196
	v_cndmask_b32_e32 v194, v193, v194, vcc
	v_cmp_lt_i32_e32 vcc, v208, v195
	v_lshlrev_b32_e32 v195, 2, v194
	s_waitcnt vmcnt(14)
	v_lshlrev_b32_e32 v212, 16, v200
	v_cndmask_b32_e32 v208, v193, v208, vcc
	v_lshlrev_b32_e32 v194, 2, v208
	v_lshlrev_b32_e32 v208, 16, v196
	v_and_b32_e32 v213, 0xffff0000, v200
	v_lshlrev_b32_e32 v210, 16, v198
	v_and_b32_e32 v211, 0xffff0000, v198
	v_lshlrev_b32_e32 v198, 16, v199
	v_and_b32_e32 v199, 0xffff0000, v199
	v_lshlrev_b32_e32 v200, 16, v201
	v_and_b32_e32 v201, 0xffff0000, v201
	v_lshlrev_b32_e32 v214, 16, v202
	v_and_b32_e32 v215, 0xffff0000, v202
	v_pk_add_f32 v[124:125], v[124:125], v[208:209]
	v_pk_add_f32 v[116:117], v[116:117], v[212:213]
	v_lshlrev_b32_e32 v196, 16, v197
	v_and_b32_e32 v197, 0xffff0000, v197
	v_pk_add_f32 v[122:123], v[122:123], v[198:199]
	v_pk_add_f32 v[118:119], v[118:119], v[200:201]
	v_pk_add_f32 v[198:199], v[112:113], v[214:215]
	v_mul_f32_e32 v200, v125, v125
	v_cvt_pk_bf16_f32 v112, v124, v125
	v_mul_f32_e32 v125, v117, v117
	v_pk_add_f32 v[126:127], v[126:127], v[196:197]
	v_fmac_f32_e32 v200, v124, v124
	v_fmac_f32_e32 v125, v116, v116
	v_fmac_f32_e32 v200, v126, v126
	v_fmac_f32_e32 v125, v118, v118
	v_pk_add_f32 v[120:121], v[120:121], v[210:211]
	v_fmac_f32_e32 v200, v127, v127
	v_fmac_f32_e32 v125, v119, v119
	v_lshlrev_b32_e32 v202, 16, v203
	v_and_b32_e32 v203, 0xffff0000, v203
	v_fmac_f32_e32 v200, v120, v120
	v_fmac_f32_e32 v125, v198, v198
	v_pk_add_f32 v[196:197], v[114:115], v[202:203]
	v_fmac_f32_e32 v200, v121, v121
	v_fmac_f32_e32 v125, v199, v199
	v_fmac_f32_e32 v200, v122, v122
	v_fmac_f32_e32 v125, v196, v196
	v_fmac_f32_e32 v200, v123, v123
	v_fmac_f32_e32 v125, v197, v197
	v_cvt_pk_bf16_f32 v115, v122, v123
	v_add_f32_e32 v122, v200, v125
	ds_bpermute_b32 v123, v195, v122
	v_cvt_pk_bf16_f32 v114, v120, v121
	v_lshl_add_u64 v[120:121], s[76:77], 0, v[206:207]
	v_cvt_pk_bf16_f32 v113, v126, v127
	v_lshl_add_u64 v[120:121], v[120:121], 0, v[204:205]
	global_store_dwordx4 v[120:121], v[112:115], off
	s_waitcnt lgkmcnt(0)
	s_nop 0
	v_add_f32_e32 v112, v122, v123
	ds_bpermute_b32 v113, v194, v112
	v_cvt_pk_bf16_f32 v114, v116, v117
	v_cvt_pk_bf16_f32 v115, v118, v119
	v_cvt_pk_bf16_f32 v116, v198, v199
	v_cvt_pk_bf16_f32 v117, v196, v197
	global_store_dwordx4 v[120:121], v[114:117], off offset:256
	s_and_saveexec_b64 s[22:23], s[0:1]
	s_cbranch_execz .LBB0_1281
	s_waitcnt lgkmcnt(0)
	v_add_f32_e32 v114, v112, v113
	s_lshl_b32 s24, s6, 2
	v_lshlrev_b64 v[112:113], 6, v[172:173]
	s_ashr_i32 s25, s24, 31
	v_lshl_add_u64 v[112:113], s[10:11], 0, v[112:113]
	v_lshl_add_u64 v[112:113], s[24:25], 2, v[112:113]
	s_lshl_b32 s8, s37, 2
	v_lshl_add_u64 v[112:113], v[112:113], 0, s[8:9]
	global_store_dword v[112:113], v114, off
